# GEMM K-loops: setprio flips removed + duplicate lgkmcnt(0) after barrier removed
# speedup vs baseline: 1.0381x; 1.0116x over previous
; #define PG8_STAGE(bufoff, gbase, voff) do { _Pragma("unroll") for (int _i = 0; _i < 2; ++_i) \
;         __builtin_amdgcn_global_load_lds((const unsigned*)((const char*)(gbase) + (voff)[_i]), (PG8_LAS unsigned*)(lds + (bufoff) + ldsw + _i * 8192), 16, 0, 0); } while (0)
; #define PG8_LDA(dst, b, h) do { _Pragma("unroll") for (int m = 0; m < 4; ++m) _Pragma("unroll") for (int k = 0; k < 2; ++k) dst[m][k] = *(const PG8_LAS bf16x8*)(lds + PG8_SA(b, h) + aoff + m * 2048 + k * 1024); } while (0)
; #define PG8_LDB(dst, b, h) do { _Pragma("unroll") for (int n = 0; n < 2; ++n) _Pragma("unroll") for (int k = 0; k < 2; ++k) dst[n][k] = *(const PG8_LAS bf16x8*)(lds + PG8_SB(b, h) + boff + n * 2048 + k * 1024); } while (0)
; #define PG8_MMA(ai, bj, At, Bt) do { __builtin_amdgcn_s_setprio(1); _Pragma("unroll") for (int m = 0; m < 4; ++m) _Pragma("unroll") for (int n = 0; n < 2; ++n) _Pragma("unroll") for (int k = 0; k < 2; ++k) \
;         acc[ai][bj][m][n] = __builtin_amdgcn_mfma_f32_16x16x32_bf16(Bt[n][k], At[m][k], acc[ai][bj][m][n], 0, 0, 0); __builtin_amdgcn_s_setprio(0); } while (0)
; #define PG8_WAIT_V(n) asm volatile("s_waitcnt vmcnt(" #n ")" ::: "memory")
; #define PG8_WAIT_L(n) asm volatile("s_waitcnt lgkmcnt(" #n ")" ::: "memory")
; #define PG8_BAR __builtin_amdgcn_s_barrier()
; #define PG8_SCHED __builtin_amdgcn_sched_barrier(0)
; template <class Epi, class Sched>
; __device__ __forceinline__ void gemm_phase(PG8_LAS unsigned char* lds, const Gemm g, const Sched& S, const Epi& E) {
;     ...
;             PG8_LDB(B0, 0, 0); PG8_SCHED; PG8_LDA(At, 0, 0); PG8_STAGE(PG8_SA(1, 1), a1 + hstep, voffA);
;             PG8_WAIT_L(8); PG8_BAR; PG8_WAIT_L(0); PG8_MMA(0, 0, At, B0); PG8_BAR; PG8_SCHED;
;             PG8_LDB(B1, 0, 1); PG8_STAGE(PG8_SB(0, 0), b2, voffB);
;             PG8_BAR; PG8_WAIT_L(0); PG8_MMA(0, 1, At, B1); PG8_BAR;
;             PG8_LDA(At, 0, 1); PG8_STAGE(PG8_SA(0, 0), a2, voffA);
;             PG8_BAR; PG8_WAIT_L(0); PG8_MMA(1, 0, At, B0); PG8_BAR; PG8_SCHED;
;             PG8_STAGE(PG8_SB(0, 1), b2 + hstep, voffB);
;             PG8_WAIT_V(6); PG8_BAR; PG8_MMA(1, 1, At, B1); PG8_BAR;
.LBB0_195:
	ds_read_b128 v[144:147], v151
	ds_read_b128 v[156:159], v151 offset:1024
	ds_read_b128 v[160:163], v151 offset:2048
	ds_read_b128 v[166:169], v151 offset:3072
	s_add_u32 s30, s28, 0xfffc0080
	s_addc_u32 s31, s29, -1
	s_cmp_eq_u32 s58, 12
	s_cselect_b32 s35, s17, s31
	s_cselect_b32 s34, s54, s30
	s_cselect_b32 s31, s15, s57
	s_cselect_b32 s30, s55, s56
	v_lshl_add_u64 v[174:175], s[28:29], 0, v[136:137]
	s_add_i32 m0, s27, 0xc000
	ds_read_b128 v[170:173], v153
	ds_read_b128 v[182:185], v153 offset:1024
	ds_read_b128 v[190:193], v153 offset:2048
	ds_read_b128 v[194:197], v153 offset:3072
	ds_read_b128 v[198:201], v153 offset:4096
	ds_read_b128 v[202:205], v153 offset:5120
	ds_read_b128 v[206:209], v153 offset:6144
	ds_read_b128 v[210:213], v153 offset:7168
	global_load_lds_dwordx4 v[174:175], off
	v_lshl_add_u64 v[174:175], s[28:29], 0, v[138:139]
	s_add_i32 m0, s27, 0xe000
	s_nop 0
	global_load_lds_dwordx4 v[174:175], off
	s_waitcnt lgkmcnt(8)
	s_barrier
	s_waitcnt lgkmcnt(0)
	v_mfma_f32_16x16x32_bf16 v[124:127], v[144:147], v[170:173], v[124:127]
	v_mfma_f32_16x16x32_bf16 v[120:123], v[160:163], v[170:173], v[120:123]
	v_mfma_f32_16x16x32_bf16 v[108:111], v[144:147], v[190:193], v[108:111]
	v_mfma_f32_16x16x32_bf16 v[104:107], v[160:163], v[190:193], v[104:107]
	v_mfma_f32_16x16x32_bf16 v[92:95], v[144:147], v[198:201], v[92:95]
	v_mfma_f32_16x16x32_bf16 v[88:91], v[160:163], v[198:201], v[88:91]
	v_mfma_f32_16x16x32_bf16 v[76:79], v[144:147], v[206:209], v[76:79]
	v_mfma_f32_16x16x32_bf16 v[72:75], v[160:163], v[206:209], v[72:75]
	v_mfma_f32_16x16x32_bf16 v[124:127], v[156:159], v[182:185], v[124:127]
	v_mfma_f32_16x16x32_bf16 v[120:123], v[166:169], v[182:185], v[120:123]
	v_mfma_f32_16x16x32_bf16 v[108:111], v[156:159], v[194:197], v[108:111]
	v_mfma_f32_16x16x32_bf16 v[104:107], v[166:169], v[194:197], v[104:107]
	v_mfma_f32_16x16x32_bf16 v[92:95], v[156:159], v[202:205], v[92:95]
	v_mfma_f32_16x16x32_bf16 v[88:91], v[166:169], v[202:205], v[88:91]
	v_mfma_f32_16x16x32_bf16 v[76:79], v[156:159], v[210:213], v[76:79]
	v_mfma_f32_16x16x32_bf16 v[72:75], v[166:169], v[210:213], v[72:75]
	s_barrier
	s_add_i32 s59, s50, s40
	v_lshl_add_u64 v[174:175], s[30:31], 0, v[132:133]
	s_mov_b32 m0, s59
	ds_read_b128 v[214:217], v154
	ds_read_b128 v[218:221], v154 offset:1024
	ds_read_b128 v[222:225], v154 offset:2048
	ds_read_b128 v[226:229], v154 offset:3072
	global_load_lds_dwordx4 v[174:175], off
	v_lshl_add_u64 v[178:179], s[30:31], 0, v[128:129]
	s_add_i32 m0, s59, 0x2000
	s_nop 0
	global_load_lds_dwordx4 v[178:179], off
	s_barrier
	s_waitcnt lgkmcnt(0)
	v_mfma_f32_16x16x32_bf16 v[116:119], v[214:217], v[170:173], v[116:119]
	v_mfma_f32_16x16x32_bf16 v[112:115], v[222:225], v[170:173], v[112:115]
	v_mfma_f32_16x16x32_bf16 v[100:103], v[214:217], v[190:193], v[100:103]
	v_mfma_f32_16x16x32_bf16 v[96:99], v[222:225], v[190:193], v[96:99]
	v_mfma_f32_16x16x32_bf16 v[84:87], v[214:217], v[198:201], v[84:87]
	v_mfma_f32_16x16x32_bf16 v[80:83], v[222:225], v[198:201], v[80:83]
	v_mfma_f32_16x16x32_bf16 v[68:71], v[214:217], v[206:209], v[68:71]
	v_mfma_f32_16x16x32_bf16 v[64:67], v[222:225], v[206:209], v[64:67]
	v_mfma_f32_16x16x32_bf16 v[116:119], v[218:221], v[182:185], v[116:119]
	v_mfma_f32_16x16x32_bf16 v[112:115], v[226:229], v[182:185], v[112:115]
	v_mfma_f32_16x16x32_bf16 v[100:103], v[218:221], v[194:197], v[100:103]
	v_mfma_f32_16x16x32_bf16 v[96:99], v[226:229], v[194:197], v[96:99]
	v_mfma_f32_16x16x32_bf16 v[84:87], v[218:221], v[202:205], v[84:87]
	v_mfma_f32_16x16x32_bf16 v[80:83], v[226:229], v[202:205], v[80:83]
	v_mfma_f32_16x16x32_bf16 v[68:71], v[218:221], v[210:213], v[68:71]
	v_mfma_f32_16x16x32_bf16 v[64:67], v[226:229], v[210:213], v[64:67]
	s_mov_b32 m0, s27
	v_lshl_add_u64 v[186:187], s[34:35], 0, v[134:135]
	s_barrier
	ds_read_b128 v[170:173], v153 offset:16384
	ds_read_b128 v[182:185], v153 offset:17408
	ds_read_b128 v[190:193], v153 offset:18432
	ds_read_b128 v[194:197], v153 offset:19456
	ds_read_b128 v[198:201], v153 offset:20480
	ds_read_b128 v[202:205], v153 offset:21504
	ds_read_b128 v[206:209], v153 offset:22528
	ds_read_b128 v[210:213], v153 offset:23552
	global_load_lds_dwordx4 v[186:187], off
	v_lshl_add_u64 v[230:231], s[34:35], 0, v[130:131]
	s_mov_b32 m0, s43
	s_nop 0
	global_load_lds_dwordx4 v[230:231], off
	s_barrier
	s_waitcnt lgkmcnt(0)
	v_mfma_f32_16x16x32_bf16 v[60:63], v[144:147], v[170:173], v[60:63]
	v_mfma_f32_16x16x32_bf16 v[56:59], v[160:163], v[170:173], v[56:59]
	v_mfma_f32_16x16x32_bf16 v[44:47], v[144:147], v[190:193], v[44:47]
	v_mfma_f32_16x16x32_bf16 v[40:43], v[160:163], v[190:193], v[40:43]
	v_mfma_f32_16x16x32_bf16 v[28:31], v[144:147], v[198:201], v[28:31]
	v_mfma_f32_16x16x32_bf16 v[24:27], v[160:163], v[198:201], v[24:27]
	v_mfma_f32_16x16x32_bf16 v[12:15], v[144:147], v[206:209], v[12:15]
	v_mfma_f32_16x16x32_bf16 v[8:11], v[160:163], v[206:209], v[8:11]
	v_mfma_f32_16x16x32_bf16 v[60:63], v[156:159], v[182:185], v[60:63]
	v_mfma_f32_16x16x32_bf16 v[56:59], v[166:169], v[182:185], v[56:59]
	v_mfma_f32_16x16x32_bf16 v[44:47], v[156:159], v[194:197], v[44:47]
	v_mfma_f32_16x16x32_bf16 v[40:43], v[166:169], v[194:197], v[40:43]
	v_mfma_f32_16x16x32_bf16 v[28:31], v[156:159], v[202:205], v[28:31]
	v_mfma_f32_16x16x32_bf16 v[24:27], v[166:169], v[202:205], v[24:27]
	v_mfma_f32_16x16x32_bf16 v[12:15], v[156:159], v[210:213], v[12:15]
	v_mfma_f32_16x16x32_bf16 v[8:11], v[166:169], v[210:213], v[8:11]
	s_barrier
; #define PG8_STAGE(bufoff, gbase, voff) do { _Pragma("unroll") for (int _i = 0; _i < 2; ++_i) \
;         __builtin_amdgcn_global_load_lds((const unsigned*)((const char*)(gbase) + (voff)[_i]), (PG8_LAS unsigned*)(lds + (bufoff) + ldsw + _i * 8192), 16, 0, 0); } while (0)
; #define PG8_LDA(dst, b, h) do { _Pragma("unroll") for (int m = 0; m < 4; ++m) _Pragma("unroll") for (int k = 0; k < 2; ++k) dst[m][k] = *(const PG8_LAS bf16x8*)(lds + PG8_SA(b, h) + aoff + m * 2048 + k * 1024); } while (0)
; #define PG8_LDB(dst, b, h) do { _Pragma("unroll") for (int n = 0; n < 2; ++n) _Pragma("unroll") for (int k = 0; k < 2; ++k) dst[n][k] = *(const PG8_LAS bf16x8*)(lds + PG8_SB(b, h) + boff + n * 2048 + k * 1024); } while (0)
; #define PG8_MMA(ai, bj, At, Bt) do { __builtin_amdgcn_s_setprio(1); _Pragma("unroll") for (int m = 0; m < 4; ++m) _Pragma("unroll") for (int n = 0; n < 2; ++n) _Pragma("unroll") for (int k = 0; k < 2; ++k) \
;         acc[ai][bj][m][n] = __builtin_amdgcn_mfma_f32_16x16x32_bf16(Bt[n][k], At[m][k], acc[ai][bj][m][n], 0, 0, 0); __builtin_amdgcn_s_setprio(0); } while (0)
; #define PG8_WAIT_V(n) asm volatile("s_waitcnt vmcnt(" #n ")" ::: "memory")
; #define PG8_WAIT_L(n) asm volatile("s_waitcnt lgkmcnt(" #n ")" ::: "memory")
; #define PG8_BAR __builtin_amdgcn_s_barrier()
; #define PG8_SCHED __builtin_amdgcn_sched_barrier(0)
; template <class Epi, class Sched>
; __device__ __forceinline__ void gemm_phase(PG8_LAS unsigned char* lds, const Gemm g, const Sched& S, const Epi& E) {
;     ...
;             PG8_WAIT_V(6); PG8_BAR; PG8_MMA(1, 1, At, B1); PG8_BAR;
;             PG8_LDB(B0, 1, 0); PG8_SCHED; PG8_LDA(At, 1, 0); PG8_STAGE(PG8_SA(0, 1), a2 + hstep, voffA);
;             PG8_WAIT_L(8); PG8_BAR; PG8_WAIT_L(0); PG8_MMA(0, 0, At, B0); PG8_BAR; PG8_SCHED;
;             PG8_LDB(B1, 1, 1); PG8_STAGE(PG8_SB(1, 0), b3, voffB);
;             PG8_BAR; PG8_WAIT_L(0); PG8_MMA(0, 1, At, B1); PG8_BAR;
;             PG8_LDA(At, 1, 1); PG8_STAGE(PG8_SA(1, 0), a3, voffA);
;             PG8_BAR; PG8_WAIT_L(0); PG8_MMA(1, 0, At, B0); PG8_BAR; PG8_SCHED;
	s_add_u32 s60, s30, 0x40000
	s_addc_u32 s61, s31, 0
	s_add_i32 s59, s51, s40
	v_lshl_add_u64 v[144:145], s[60:61], 0, v[132:133]
	s_mov_b32 m0, s59
	s_nop 0
	global_load_lds_dwordx4 v[144:145], off
	v_lshl_add_u64 v[144:145], s[60:61], 0, v[128:129]
	s_add_i32 m0, s59, 0x2000
	s_nop 0
	global_load_lds_dwordx4 v[144:145], off
	s_waitcnt vmcnt(6)
	s_barrier
	v_mfma_f32_16x16x32_bf16 v[52:55], v[214:217], v[170:173], v[52:55]
	v_mfma_f32_16x16x32_bf16 v[48:51], v[222:225], v[170:173], v[48:51]
	v_mfma_f32_16x16x32_bf16 v[36:39], v[214:217], v[190:193], v[36:39]
	v_mfma_f32_16x16x32_bf16 v[32:35], v[222:225], v[190:193], v[32:35]
	v_mfma_f32_16x16x32_bf16 v[20:23], v[214:217], v[198:201], v[20:23]
	v_mfma_f32_16x16x32_bf16 v[16:19], v[222:225], v[198:201], v[16:19]
	v_mfma_f32_16x16x32_bf16 v[4:7], v[214:217], v[206:209], v[4:7]
	v_mfma_f32_16x16x32_bf16 v[0:3], v[222:225], v[206:209], v[0:3]
	v_mfma_f32_16x16x32_bf16 v[52:55], v[218:221], v[182:185], v[52:55]
	v_mfma_f32_16x16x32_bf16 v[48:51], v[226:229], v[182:185], v[48:51]
	v_mfma_f32_16x16x32_bf16 v[36:39], v[218:221], v[194:197], v[36:39]
	v_mfma_f32_16x16x32_bf16 v[32:35], v[226:229], v[194:197], v[32:35]
	v_mfma_f32_16x16x32_bf16 v[20:23], v[218:221], v[202:205], v[20:23]
	v_mfma_f32_16x16x32_bf16 v[16:19], v[226:229], v[202:205], v[16:19]
	v_mfma_f32_16x16x32_bf16 v[4:7], v[218:221], v[210:213], v[4:7]
	v_mfma_f32_16x16x32_bf16 v[0:3], v[226:229], v[210:213], v[0:3]
	s_add_i32 s59, 0, 0x18000
	v_add_u32_e32 v155, s59, v149
	s_barrier
	ds_read_b128 v[144:147], v155
	ds_read_b128 v[156:159], v155 offset:1024
	ds_read_b128 v[160:163], v155 offset:2048
	ds_read_b128 v[166:169], v155 offset:3072
	s_add_u32 s34, s34, 0x40000
	s_addc_u32 s35, s35, 0
	s_mov_b32 m0, s44
	v_lshl_add_u64 v[214:215], s[34:35], 0, v[134:135]
	ds_read_b128 v[170:173], v153 offset:32768
	ds_read_b128 v[182:185], v153 offset:33792
	ds_read_b128 v[190:193], v153 offset:34816
	ds_read_b128 v[194:197], v153 offset:35840
	ds_read_b128 v[198:201], v153 offset:36864
	ds_read_b128 v[202:205], v153 offset:37888
	ds_read_b128 v[206:209], v153 offset:38912
	ds_read_b128 v[210:213], v153 offset:39936
	global_load_lds_dwordx4 v[214:215], off
	v_lshl_add_u64 v[214:215], s[34:35], 0, v[130:131]
	s_mov_b32 m0, s45
	s_nop 0
	global_load_lds_dwordx4 v[214:215], off
	s_waitcnt lgkmcnt(8)
	s_barrier
	s_waitcnt lgkmcnt(0)
	v_mfma_f32_16x16x32_bf16 v[124:127], v[144:147], v[170:173], v[124:127]
	v_mfma_f32_16x16x32_bf16 v[120:123], v[160:163], v[170:173], v[120:123]
	v_mfma_f32_16x16x32_bf16 v[108:111], v[144:147], v[190:193], v[108:111]
	v_mfma_f32_16x16x32_bf16 v[104:107], v[160:163], v[190:193], v[104:107]
	v_mfma_f32_16x16x32_bf16 v[92:95], v[144:147], v[198:201], v[92:95]
	v_mfma_f32_16x16x32_bf16 v[88:91], v[160:163], v[198:201], v[88:91]
	v_mfma_f32_16x16x32_bf16 v[76:79], v[144:147], v[206:209], v[76:79]
	v_mfma_f32_16x16x32_bf16 v[72:75], v[160:163], v[206:209], v[72:75]
	v_mfma_f32_16x16x32_bf16 v[124:127], v[156:159], v[182:185], v[124:127]
	v_mfma_f32_16x16x32_bf16 v[120:123], v[166:169], v[182:185], v[120:123]
	v_mfma_f32_16x16x32_bf16 v[108:111], v[156:159], v[194:197], v[108:111]
	v_mfma_f32_16x16x32_bf16 v[104:107], v[166:169], v[194:197], v[104:107]
	v_mfma_f32_16x16x32_bf16 v[92:95], v[156:159], v[202:205], v[92:95]
	v_mfma_f32_16x16x32_bf16 v[88:91], v[166:169], v[202:205], v[88:91]
	v_mfma_f32_16x16x32_bf16 v[76:79], v[156:159], v[210:213], v[76:79]
	v_mfma_f32_16x16x32_bf16 v[72:75], v[166:169], v[210:213], v[72:75]
	s_barrier
	s_add_i32 s34, 0, 0x1c000
	s_add_i32 s35, s59, s40
	v_add_u32_e32 v155, s34, v149
	v_lshl_add_u64 v[174:175], v[174:175], 0, s[10:11]
	s_mov_b32 m0, s35
	ds_read_b128 v[214:217], v155
	ds_read_b128 v[218:221], v155 offset:1024
	ds_read_b128 v[222:225], v155 offset:2048
	ds_read_b128 v[226:229], v155 offset:3072
	global_load_lds_dwordx4 v[174:175], off
	v_lshl_add_u64 v[174:175], v[178:179], 0, s[10:11]
	s_add_i32 m0, s35, 0x2000
	s_nop 0
	global_load_lds_dwordx4 v[174:175], off
	s_barrier
	s_waitcnt lgkmcnt(0)
	v_mfma_f32_16x16x32_bf16 v[116:119], v[214:217], v[170:173], v[116:119]
	v_mfma_f32_16x16x32_bf16 v[112:115], v[222:225], v[170:173], v[112:115]
	v_mfma_f32_16x16x32_bf16 v[100:103], v[214:217], v[190:193], v[100:103]
	v_mfma_f32_16x16x32_bf16 v[96:99], v[222:225], v[190:193], v[96:99]
	v_mfma_f32_16x16x32_bf16 v[84:87], v[214:217], v[198:201], v[84:87]
	v_mfma_f32_16x16x32_bf16 v[80:83], v[222:225], v[198:201], v[80:83]
	v_mfma_f32_16x16x32_bf16 v[68:71], v[214:217], v[206:209], v[68:71]
	v_mfma_f32_16x16x32_bf16 v[64:67], v[222:225], v[206:209], v[64:67]
	v_mfma_f32_16x16x32_bf16 v[116:119], v[218:221], v[182:185], v[116:119]
	v_mfma_f32_16x16x32_bf16 v[112:115], v[226:229], v[182:185], v[112:115]
	v_mfma_f32_16x16x32_bf16 v[100:103], v[218:221], v[194:197], v[100:103]
	v_mfma_f32_16x16x32_bf16 v[96:99], v[226:229], v[194:197], v[96:99]
	v_mfma_f32_16x16x32_bf16 v[84:87], v[218:221], v[202:205], v[84:87]
	v_mfma_f32_16x16x32_bf16 v[80:83], v[226:229], v[202:205], v[80:83]
	v_mfma_f32_16x16x32_bf16 v[68:71], v[218:221], v[210:213], v[68:71]
	v_mfma_f32_16x16x32_bf16 v[64:67], v[226:229], v[210:213], v[64:67]
	s_mov_b32 m0, s47
	v_lshl_add_u64 v[174:175], v[186:187], 0, s[10:11]
	s_barrier
	ds_read_b128 v[170:173], v153 offset:49152
	ds_read_b128 v[182:185], v153 offset:50176
	ds_read_b128 v[190:193], v153 offset:51200
	ds_read_b128 v[194:197], v153 offset:52224
	ds_read_b128 v[198:201], v153 offset:53248
	ds_read_b128 v[202:205], v153 offset:54272
	ds_read_b128 v[206:209], v153 offset:55296
	ds_read_b128 v[210:213], v153 offset:56320
	global_load_lds_dwordx4 v[174:175], off
	v_lshl_add_u64 v[174:175], v[230:231], 0, s[10:11]
	s_mov_b32 m0, s48
	s_nop 0
	global_load_lds_dwordx4 v[174:175], off
	s_barrier
; __device__ __forceinline__ unsigned cvt_pk_bf16(float lo, float hi) { unsigned r; asm volatile("v_cvt_pk_bf16_f32 %0, %1, %2" : "=v"(r) : "v"(lo), "v"(hi)); return r; }
; #define PG8_STAGE(bufoff, gbase, voff) do { _Pragma("unroll") for (int _i = 0; _i < 2; ++_i) \
;         __builtin_amdgcn_global_load_lds((const unsigned*)((const char*)(gbase) + (voff)[_i]), (PG8_LAS unsigned*)(lds + (bufoff) + ldsw + _i * 8192), 16, 0, 0); } while (0)
; #define PG8_MMA(ai, bj, At, Bt) do { __builtin_amdgcn_s_setprio(1); _Pragma("unroll") for (int m = 0; m < 4; ++m) _Pragma("unroll") for (int n = 0; n < 2; ++n) _Pragma("unroll") for (int k = 0; k < 2; ++k) \
;         acc[ai][bj][m][n] = __builtin_amdgcn_mfma_f32_16x16x32_bf16(Bt[n][k], At[m][k], acc[ai][bj][m][n], 0, 0, 0); __builtin_amdgcn_s_setprio(0); } while (0)
; #define PG8_WAIT_V(n) asm volatile("s_waitcnt vmcnt(" #n ")" ::: "memory")
; #define PG8_WAIT_L(n) asm volatile("s_waitcnt lgkmcnt(" #n ")" ::: "memory")
; #define PG8_BAR __builtin_amdgcn_s_barrier()
; #define PG8_SCHED __builtin_amdgcn_sched_barrier(0)
;     __device__ __forceinline__ void operator()(const f32x4 (&acc)[2][2][4][2], const Unit& u, int wr, int wc, int fr, int fq) const {
;         const int row0 = u.pm * BM + wr * 64 + fr, col0 = u.pn * HALF + wc * 32 + 8 * fq;
; #pragma unroll
;         for (int ai = 0; ai < 2; ++ai)
; #pragma unroll
;             for (int m = 0; m < 4; ++m) { bf16_t* rowp = O + (size_t)(row0 + ai * HALF + m * 16) * ldc + col0;
;                 f32x4 v0, v1;
; #pragma unroll
;                 for (int j = 0; j < 1; ++j) { v0 = acc[ai][0][m][0] * sigmoid4(acc[ai][0][m][0]) * acc[ai][1][m][0]; v1 = acc[ai][0][m][1] * sigmoid4(acc[ai][0][m][1]) * acc[ai][1][m][1]; }
;                 u32x4 w; w.x = cvt_pk_bf16(v0[0], v0[1]); w.y = cvt_pk_bf16(v0[2], v0[3]); w.z = cvt_pk_bf16(v1[0], v1[1]); w.w = cvt_pk_bf16(v1[2], v1[3]);
;                 *(u32x4*)rowp = w; }
; template <class Epi, class Sched>
; __device__ __forceinline__ void gemm_phase(PG8_LAS unsigned char* lds, const Gemm g, const Sched& S, const Epi& E) {
;     ...
;             PG8_BAR; PG8_WAIT_L(0); PG8_MMA(1, 0, At, B0); PG8_BAR; PG8_SCHED;
;             PG8_STAGE(PG8_SB(1, 1), b3 + hstep, voffB);
;             PG8_WAIT_V(6); PG8_BAR; PG8_MMA(1, 1, At, B1); PG8_BAR;
	s_waitcnt lgkmcnt(0)
	v_mfma_f32_16x16x32_bf16 v[60:63], v[144:147], v[170:173], v[60:63]
	v_mfma_f32_16x16x32_bf16 v[56:59], v[160:163], v[170:173], v[56:59]
	v_mfma_f32_16x16x32_bf16 v[44:47], v[144:147], v[190:193], v[44:47]
	v_mfma_f32_16x16x32_bf16 v[40:43], v[160:163], v[190:193], v[40:43]
	v_mfma_f32_16x16x32_bf16 v[28:31], v[144:147], v[198:201], v[28:31]
	v_mfma_f32_16x16x32_bf16 v[24:27], v[160:163], v[198:201], v[24:27]
	v_mfma_f32_16x16x32_bf16 v[12:15], v[144:147], v[206:209], v[12:15]
	v_mfma_f32_16x16x32_bf16 v[8:11], v[160:163], v[206:209], v[8:11]
	v_mfma_f32_16x16x32_bf16 v[60:63], v[156:159], v[182:185], v[60:63]
	v_mfma_f32_16x16x32_bf16 v[56:59], v[166:169], v[182:185], v[56:59]
	v_mfma_f32_16x16x32_bf16 v[44:47], v[156:159], v[194:197], v[44:47]
	v_mfma_f32_16x16x32_bf16 v[40:43], v[166:169], v[194:197], v[40:43]
	v_mfma_f32_16x16x32_bf16 v[28:31], v[156:159], v[202:205], v[28:31]
	v_mfma_f32_16x16x32_bf16 v[24:27], v[166:169], v[202:205], v[24:27]
	v_mfma_f32_16x16x32_bf16 v[12:15], v[156:159], v[210:213], v[12:15]
	v_mfma_f32_16x16x32_bf16 v[8:11], v[166:169], v[210:213], v[8:11]
	s_barrier
	s_add_u32 s30, s30, 0x40080
	s_addc_u32 s31, s31, 0
	s_add_i32 s34, s34, s40
	v_lshl_add_u64 v[144:145], s[30:31], 0, v[132:133]
	s_mov_b32 m0, s34
	s_nop 0
	global_load_lds_dwordx4 v[144:145], off
	v_lshl_add_u64 v[144:145], s[30:31], 0, v[128:129]
	s_add_i32 m0, s34, 0x2000
	s_nop 0
	global_load_lds_dwordx4 v[144:145], off
	s_waitcnt vmcnt(6)
	s_barrier
	v_mfma_f32_16x16x32_bf16 v[52:55], v[214:217], v[170:173], v[52:55]
	v_mfma_f32_16x16x32_bf16 v[48:51], v[222:225], v[170:173], v[48:51]
	v_mfma_f32_16x16x32_bf16 v[36:39], v[214:217], v[190:193], v[36:39]
	v_mfma_f32_16x16x32_bf16 v[32:35], v[222:225], v[190:193], v[32:35]
	v_mfma_f32_16x16x32_bf16 v[20:23], v[214:217], v[198:201], v[20:23]
	v_mfma_f32_16x16x32_bf16 v[16:19], v[222:225], v[198:201], v[16:19]
	v_mfma_f32_16x16x32_bf16 v[4:7], v[214:217], v[206:209], v[4:7]
	v_mfma_f32_16x16x32_bf16 v[0:3], v[222:225], v[206:209], v[0:3]
	v_mfma_f32_16x16x32_bf16 v[52:55], v[218:221], v[182:185], v[52:55]
	v_mfma_f32_16x16x32_bf16 v[48:51], v[226:229], v[182:185], v[48:51]
	v_mfma_f32_16x16x32_bf16 v[36:39], v[218:221], v[194:197], v[36:39]
	v_mfma_f32_16x16x32_bf16 v[32:35], v[226:229], v[194:197], v[32:35]
	v_mfma_f32_16x16x32_bf16 v[20:23], v[218:221], v[202:205], v[20:23]
	v_mfma_f32_16x16x32_bf16 v[16:19], v[226:229], v[202:205], v[16:19]
	v_mfma_f32_16x16x32_bf16 v[4:7], v[218:221], v[210:213], v[4:7]
	v_mfma_f32_16x16x32_bf16 v[0:3], v[226:229], v[210:213], v[0:3]
	s_add_i32 s58, s58, 2
	s_add_u32 s28, s28, 0x100
	s_addc_u32 s29, s29, 0
	s_add_u32 s56, s56, 0x100
	s_addc_u32 s57, s57, 0
	s_cmp_gt_u32 s58, 13
	s_barrier
	s_cbranch_scc0 .LBB0_195
	v_max_f32_e32 v144, v124, v124
	v_max_f32_e32 v144, 0xc1a00000, v144
	v_mul_f32_e32 v144, 0xbfb8aa3b, v144
	v_exp_f32_e32 v157, v144
	v_max_f32_e32 v144, v125, v125
	v_max_f32_e32 v144, 0xc1a00000, v144
	v_mul_f32_e32 v144, 0xbfb8aa3b, v144
	v_exp_f32_e32 v156, v144
	v_max_f32_e32 v144, v126, v126
	v_max_f32_e32 v144, 0xc1a00000, v144
	v_mul_f32_e32 v144, 0xbfb8aa3b, v144
	v_exp_f32_e32 v159, v144
	v_max_f32_e32 v144, v127, v127
	v_max_f32_e32 v144, 0xc1a00000, v144
	v_mul_f32_e32 v144, 0xbfb8aa3b, v144
	v_exp_f32_e32 v158, v144
	v_pk_add_f32 v[156:157], v[156:157], 1.0 op_sel_hi:[1,0]
	v_lshl_or_b32 v146, s53, 7, v150
	v_mov_b32_e32 v160, v157
	v_pk_add_f32 v[158:159], v[158:159], 1.0 op_sel_hi:[1,0]
	v_mov_b32_e32 v162, v156
	v_mov_b32_e32 v161, v159
	v_mov_b32_e32 v163, v158
	v_pk_mul_f32 v[160:161], v[160:161], v[162:163]
	v_lshl_add_u32 v155, s26, 8, v148
	v_mul_f32_e32 v162, v160, v161
	v_rcp_f32_e32 v166, v162
	v_ashrrev_i32_e32 v147, 31, v146
	v_mov_b64_e32 v[144:145], s[4:5]
	v_mad_i64_i32 v[162:163], s[28:29], v155, s52, v[144:145]
	v_mul_f32_e32 v160, v160, v166
	v_mul_f32_e32 v164, v161, v166
	v_pk_mul_f32 v[158:159], v[158:159], v[160:161] op_sel_hi:[1,0]
	v_max_f32_e32 v160, v120, v120
	v_max_f32_e32 v166, v122, v122
	v_max_f32_e32 v160, 0xc1a00000, v160
	v_max_f32_e32 v166, 0xc1a00000, v166
	v_mul_f32_e32 v160, 0xbfb8aa3b, v160
	v_mul_f32_e32 v166, 0xbfb8aa3b, v166
	v_exp_f32_e32 v161, v160
	v_max_f32_e32 v160, v121, v121
	v_exp_f32_e32 v167, v166
	v_max_f32_e32 v166, v123, v123
	v_max_f32_e32 v160, 0xc1a00000, v160
	v_max_f32_e32 v166, 0xc1a00000, v166
	v_mul_f32_e32 v160, 0xbfb8aa3b, v160
	v_mul_f32_e32 v166, 0xbfb8aa3b, v166
	v_exp_f32_e32 v160, v160
	v_exp_f32_e32 v166, v166
	v_pk_mul_f32 v[156:157], v[156:157], v[164:165] op_sel_hi:[1,0]
	v_pk_mul_f32 v[126:127], v[126:127], v[158:159]
	v_pk_mul_f32 v[124:125], v[124:125], v[156:157]
	v_pk_add_f32 v[156:157], v[160:161], 1.0 op_sel_hi:[1,0]
	v_pk_add_f32 v[160:161], v[166:167], 1.0 op_sel_hi:[1,0]
	v_mov_b32_e32 v166, v157
	v_mov_b32_e32 v167, v161
	v_mov_b32_e32 v168, v156
	v_mov_b32_e32 v169, v160
	v_pk_mul_f32 v[166:167], v[166:167], v[168:169]
	v_pk_mul_f32 v[118:119], v[126:127], v[118:119]
	v_mul_f32_e32 v164, v166, v167
	v_rcp_f32_e32 v164, v164
	v_pk_mul_f32 v[116:117], v[124:125], v[116:117]
	v_lshlrev_b64 v[146:147], 1, v[146:147]
	v_lshl_add_u64 v[162:163], v[162:163], 0, v[146:147]
	v_mul_f32_e32 v124, v167, v164
	v_mul_f32_e32 v126, v166, v164
	v_pk_mul_f32 v[126:127], v[160:161], v[126:127] op_sel_hi:[1,0]
	v_pk_mul_f32 v[124:125], v[156:157], v[124:125] op_sel_hi:[1,0]
	v_pk_mul_f32 v[122:123], v[122:123], v[126:127]
	v_pk_mul_f32 v[120:121], v[120:121], v[124:125]
	v_pk_mul_f32 v[122:123], v[122:123], v[114:115]
	v_pk_mul_f32 v[114:115], v[120:121], v[112:113]
	v_cvt_pk_bf16_f32 v112, v116, v117
	v_cvt_pk_bf16_f32 v113, v118, v119
; __device__ __forceinline__ unsigned cvt_pk_bf16(float lo, float hi) { unsigned r; asm volatile("v_cvt_pk_bf16_f32 %0, %1, %2" : "=v"(r) : "v"(lo), "v"(hi)); return r; }
;     __device__ __forceinline__ void operator()(const f32x4 (&acc)[2][2][4][2], const Unit& u, int wr, int wc, int fr, int fq) const {
;     ...
;         for (int ai = 0; ai < 2; ++ai)
; #pragma unroll
;             for (int m = 0; m < 4; ++m) { bf16_t* rowp = O + (size_t)(row0 + ai * HALF + m * 16) * ldc + col0;
;                 f32x4 v0, v1;
; #pragma unroll
;                 for (int j = 0; j < 1; ++j) { v0 = acc[ai][0][m][0] * sigmoid4(acc[ai][0][m][0]) * acc[ai][1][m][0]; v1 = acc[ai][0][m][1] * sigmoid4(acc[ai][0][m][1]) * acc[ai][1][m][1]; }
;                 u32x4 w; w.x = cvt_pk_bf16(v0[0], v0[1]); w.y = cvt_pk_bf16(v0[2], v0[3]); w.z = cvt_pk_bf16(v1[0], v1[1]); w.w = cvt_pk_bf16(v1[2], v1[3]);
;                 *(u32x4*)rowp = w; }
	v_max_f32_e32 v116, v108, v108
	v_max_f32_e32 v118, v110, v110
	v_max_f32_e32 v116, 0xc1a00000, v116
	v_max_f32_e32 v118, 0xc1a00000, v118
	v_mul_f32_e32 v116, 0xbfb8aa3b, v116
	v_mul_f32_e32 v118, 0xbfb8aa3b, v118
	v_exp_f32_e32 v117, v116
	v_max_f32_e32 v116, v109, v109
	v_exp_f32_e32 v119, v118
	v_max_f32_e32 v118, v111, v111
	v_max_f32_e32 v116, 0xc1a00000, v116
	v_max_f32_e32 v118, 0xc1a00000, v118
	v_mul_f32_e32 v116, 0xbfb8aa3b, v116
	v_mul_f32_e32 v118, 0xbfb8aa3b, v118
	v_exp_f32_e32 v116, v116
	v_exp_f32_e32 v118, v118
	v_cvt_pk_bf16_f32 v114, v114, v115
	v_cvt_pk_bf16_f32 v115, v122, v123
	global_store_dwordx4 v[162:163], v[112:115], off
	v_or_b32_e32 v120, 16, v155
	s_and_b64 vcc, exec, s[2:3]
	v_pk_add_f32 v[112:113], v[116:117], 1.0 op_sel_hi:[1,0]
	v_pk_add_f32 v[114:115], v[118:119], 1.0 op_sel_hi:[1,0]
	v_mov_b32_e32 v116, v113
	v_mov_b32_e32 v117, v115
	v_mov_b32_e32 v118, v112
	v_mov_b32_e32 v119, v114
	v_pk_mul_f32 v[116:117], v[116:117], v[118:119]
	s_mov_b32 s53, s14
	v_mul_f32_e32 v118, v116, v117
	v_rcp_f32_e32 v121, v118
	v_mad_i64_i32 v[118:119], s[28:29], v120, s52, v[144:145]
	v_lshl_add_u64 v[118:119], v[118:119], 0, v[146:147]
	v_mul_f32_e32 v116, v116, v121
	v_mul_f32_e32 v120, v117, v121
	v_pk_mul_f32 v[114:115], v[114:115], v[116:117] op_sel_hi:[1,0]
	v_max_f32_e32 v116, v104, v104
	v_max_f32_e32 v121, v106, v106
	v_max_f32_e32 v116, 0xc1a00000, v116
	v_max_f32_e32 v121, 0xc1a00000, v121
	v_mul_f32_e32 v116, 0xbfb8aa3b, v116
	v_mul_f32_e32 v121, 0xbfb8aa3b, v121
	v_exp_f32_e32 v117, v116
	v_max_f32_e32 v116, v105, v105
	v_exp_f32_e32 v123, v121
	v_max_f32_e32 v121, v107, v107
	v_max_f32_e32 v116, 0xc1a00000, v116
	v_max_f32_e32 v121, 0xc1a00000, v121
	v_mul_f32_e32 v116, 0xbfb8aa3b, v116
	v_mul_f32_e32 v121, 0xbfb8aa3b, v121
	v_exp_f32_e32 v116, v116
	v_exp_f32_e32 v122, v121
	v_pk_mul_f32 v[112:113], v[112:113], v[120:121] op_sel_hi:[1,0]
	v_pk_mul_f32 v[110:111], v[110:111], v[114:115]
	v_pk_mul_f32 v[108:109], v[108:109], v[112:113]
	v_pk_add_f32 v[112:113], v[116:117], 1.0 op_sel_hi:[1,0]
	v_pk_add_f32 v[116:117], v[122:123], 1.0 op_sel_hi:[1,0]
	v_mov_b32_e32 v120, v113
	v_mov_b32_e32 v121, v117
	v_mov_b32_e32 v122, v112
	v_mov_b32_e32 v123, v116
	v_pk_mul_f32 v[120:121], v[120:121], v[122:123]
	v_pk_mul_f32 v[102:103], v[110:111], v[102:103]
	v_mul_f32_e32 v122, v120, v121
	v_rcp_f32_e32 v122, v122
	v_pk_mul_f32 v[100:101], v[108:109], v[100:101]
	s_mov_b32 s26, s16
	s_mov_b64 s[30:31], s[24:25]
	v_mul_f32_e32 v108, v121, v122
	v_mul_f32_e32 v110, v120, v122
	v_pk_mul_f32 v[110:111], v[116:117], v[110:111] op_sel_hi:[1,0]
	v_pk_mul_f32 v[108:109], v[112:113], v[108:109] op_sel_hi:[1,0]
	v_pk_mul_f32 v[106:107], v[106:107], v[110:111]
	v_pk_mul_f32 v[104:105], v[104:105], v[108:109]
	v_pk_mul_f32 v[106:107], v[106:107], v[98:99]
	v_pk_mul_f32 v[98:99], v[104:105], v[96:97]
	v_cvt_pk_bf16_f32 v96, v100, v101
	v_cvt_pk_bf16_f32 v97, v102, v103
	v_max_f32_e32 v100, v92, v92
	v_max_f32_e32 v102, v94, v94
	v_max_f32_e32 v100, 0xc1a00000, v100
	v_max_f32_e32 v102, 0xc1a00000, v102
	v_mul_f32_e32 v100, 0xbfb8aa3b, v100
	v_mul_f32_e32 v102, 0xbfb8aa3b, v102
	v_exp_f32_e32 v101, v100
	v_max_f32_e32 v100, v93, v93
	v_exp_f32_e32 v103, v102
	v_max_f32_e32 v102, v95, v95
	v_max_f32_e32 v100, 0xc1a00000, v100
	v_max_f32_e32 v102, 0xc1a00000, v102
	v_mul_f32_e32 v100, 0xbfb8aa3b, v100
	v_mul_f32_e32 v102, 0xbfb8aa3b, v102
	v_exp_f32_e32 v100, v100
	v_exp_f32_e32 v102, v102
	v_cvt_pk_bf16_f32 v98, v98, v99
	v_cvt_pk_bf16_f32 v99, v106, v107
	global_store_dwordx4 v[118:119], v[96:99], off
	v_or_b32_e32 v104, 32, v155
	s_nop 0
	v_pk_add_f32 v[96:97], v[100:101], 1.0 op_sel_hi:[1,0]
	v_pk_add_f32 v[98:99], v[102:103], 1.0 op_sel_hi:[1,0]
	v_mov_b32_e32 v100, v97
	v_mov_b32_e32 v101, v99
	v_mov_b32_e32 v102, v96
	v_mov_b32_e32 v103, v98
	v_pk_mul_f32 v[100:101], v[100:101], v[102:103]
	s_nop 0
	v_mul_f32_e32 v102, v100, v101
	v_rcp_f32_e32 v105, v102
	v_mad_i64_i32 v[102:103], s[28:29], v104, s52, v[144:145]
	v_lshl_add_u64 v[102:103], v[102:103], 0, v[146:147]
	v_mul_f32_e32 v100, v100, v105
	v_mul_f32_e32 v104, v101, v105
	v_pk_mul_f32 v[98:99], v[98:99], v[100:101] op_sel_hi:[1,0]
	v_max_f32_e32 v100, v88, v88
	v_max_f32_e32 v105, v90, v90
	v_max_f32_e32 v100, 0xc1a00000, v100
	v_max_f32_e32 v105, 0xc1a00000, v105
	v_mul_f32_e32 v100, 0xbfb8aa3b, v100
	v_mul_f32_e32 v105, 0xbfb8aa3b, v105
	v_exp_f32_e32 v101, v100
	v_max_f32_e32 v100, v89, v89
	v_exp_f32_e32 v107, v105
	v_max_f32_e32 v105, v91, v91
	v_max_f32_e32 v100, 0xc1a00000, v100
	v_max_f32_e32 v105, 0xc1a00000, v105
	v_mul_f32_e32 v100, 0xbfb8aa3b, v100
	v_mul_f32_e32 v105, 0xbfb8aa3b, v105
	v_exp_f32_e32 v100, v100
	v_exp_f32_e32 v106, v105
	v_pk_mul_f32 v[96:97], v[96:97], v[104:105] op_sel_hi:[1,0]
	v_pk_mul_f32 v[94:95], v[94:95], v[98:99]
	v_pk_mul_f32 v[92:93], v[92:93], v[96:97]
	v_pk_add_f32 v[96:97], v[100:101], 1.0 op_sel_hi:[1,0]
	v_pk_add_f32 v[100:101], v[106:107], 1.0 op_sel_hi:[1,0]
	v_mov_b32_e32 v104, v97
	v_mov_b32_e32 v105, v101
	v_mov_b32_e32 v106, v96
	v_mov_b32_e32 v107, v100
	v_pk_mul_f32 v[104:105], v[104:105], v[106:107]
	v_pk_mul_f32 v[86:87], v[94:95], v[86:87]
	v_mul_f32_e32 v106, v104, v105
	v_rcp_f32_e32 v106, v106
	v_pk_mul_f32 v[84:85], v[92:93], v[84:85]
	v_mul_f32_e32 v92, v105, v106
	v_mul_f32_e32 v94, v104, v106
	v_pk_mul_f32 v[94:95], v[100:101], v[94:95] op_sel_hi:[1,0]
	v_pk_mul_f32 v[92:93], v[96:97], v[92:93] op_sel_hi:[1,0]
	v_pk_mul_f32 v[90:91], v[90:91], v[94:95]
	v_pk_mul_f32 v[88:89], v[88:89], v[92:93]
	v_pk_mul_f32 v[90:91], v[90:91], v[82:83]
	v_pk_mul_f32 v[82:83], v[88:89], v[80:81]
	v_cvt_pk_bf16_f32 v80, v84, v85
; __device__ __forceinline__ unsigned cvt_pk_bf16(float lo, float hi) { unsigned r; asm volatile("v_cvt_pk_bf16_f32 %0, %1, %2" : "=v"(r) : "v"(lo), "v"(hi)); return r; }
;     __device__ __forceinline__ void operator()(const f32x4 (&acc)[2][2][4][2], const Unit& u, int wr, int wc, int fr, int fq) const {
;     ...
;         for (int ai = 0; ai < 2; ++ai)
; #pragma unroll
;             for (int m = 0; m < 4; ++m) { bf16_t* rowp = O + (size_t)(row0 + ai * HALF + m * 16) * ldc + col0;
;                 f32x4 v0, v1;
; #pragma unroll
;                 for (int j = 0; j < 1; ++j) { v0 = acc[ai][0][m][0] * sigmoid4(acc[ai][0][m][0]) * acc[ai][1][m][0]; v1 = acc[ai][0][m][1] * sigmoid4(acc[ai][0][m][1]) * acc[ai][1][m][1]; }
;                 u32x4 w; w.x = cvt_pk_bf16(v0[0], v0[1]); w.y = cvt_pk_bf16(v0[2], v0[3]); w.z = cvt_pk_bf16(v1[0], v1[1]); w.w = cvt_pk_bf16(v1[2], v1[3]);
;                 *(u32x4*)rowp = w; }
	v_cvt_pk_bf16_f32 v81, v86, v87
	v_max_f32_e32 v84, v76, v76
	v_max_f32_e32 v86, v78, v78
	v_max_f32_e32 v84, 0xc1a00000, v84
	v_max_f32_e32 v86, 0xc1a00000, v86
	v_mul_f32_e32 v84, 0xbfb8aa3b, v84
	v_mul_f32_e32 v86, 0xbfb8aa3b, v86
	v_exp_f32_e32 v85, v84
	v_max_f32_e32 v84, v77, v77
	v_exp_f32_e32 v87, v86
	v_max_f32_e32 v86, v79, v79
	v_max_f32_e32 v84, 0xc1a00000, v84
	v_max_f32_e32 v86, 0xc1a00000, v86
	v_mul_f32_e32 v84, 0xbfb8aa3b, v84
	v_mul_f32_e32 v86, 0xbfb8aa3b, v86
	v_exp_f32_e32 v84, v84
	v_exp_f32_e32 v86, v86
	v_cvt_pk_bf16_f32 v82, v82, v83
	v_cvt_pk_bf16_f32 v83, v90, v91
	global_store_dwordx4 v[102:103], v[80:83], off
	v_or_b32_e32 v88, 48, v155
	s_nop 0
	v_pk_add_f32 v[80:81], v[84:85], 1.0 op_sel_hi:[1,0]
	v_pk_add_f32 v[82:83], v[86:87], 1.0 op_sel_hi:[1,0]
	v_mov_b32_e32 v84, v81
	v_mov_b32_e32 v85, v83
	v_mov_b32_e32 v86, v80
	v_mov_b32_e32 v87, v82
	v_pk_mul_f32 v[84:85], v[84:85], v[86:87]
	s_nop 0
	v_mul_f32_e32 v86, v84, v85
	v_rcp_f32_e32 v89, v86
	v_mad_i64_i32 v[86:87], s[28:29], v88, s52, v[144:145]
	v_lshl_add_u64 v[86:87], v[86:87], 0, v[146:147]
	v_mul_f32_e32 v84, v84, v89
	v_mul_f32_e32 v88, v85, v89
	v_pk_mul_f32 v[82:83], v[82:83], v[84:85] op_sel_hi:[1,0]
	v_max_f32_e32 v84, v72, v72
	v_max_f32_e32 v89, v74, v74
	v_max_f32_e32 v84, 0xc1a00000, v84
	v_max_f32_e32 v89, 0xc1a00000, v89
	v_mul_f32_e32 v84, 0xbfb8aa3b, v84
	v_mul_f32_e32 v89, 0xbfb8aa3b, v89
	v_exp_f32_e32 v85, v84
	v_max_f32_e32 v84, v73, v73
	v_exp_f32_e32 v91, v89
	v_max_f32_e32 v89, v75, v75
	v_max_f32_e32 v84, 0xc1a00000, v84
	v_max_f32_e32 v89, 0xc1a00000, v89
	v_mul_f32_e32 v84, 0xbfb8aa3b, v84
	v_mul_f32_e32 v89, 0xbfb8aa3b, v89
	v_exp_f32_e32 v84, v84
	v_exp_f32_e32 v90, v89
	v_pk_mul_f32 v[80:81], v[80:81], v[88:89] op_sel_hi:[1,0]
	v_pk_mul_f32 v[78:79], v[78:79], v[82:83]
	v_pk_mul_f32 v[76:77], v[76:77], v[80:81]
	v_pk_add_f32 v[80:81], v[84:85], 1.0 op_sel_hi:[1,0]
	v_pk_add_f32 v[84:85], v[90:91], 1.0 op_sel_hi:[1,0]
	v_mov_b32_e32 v88, v81
	v_mov_b32_e32 v89, v85
	v_mov_b32_e32 v90, v80
	v_mov_b32_e32 v91, v84
	v_pk_mul_f32 v[88:89], v[88:89], v[90:91]
	v_pk_mul_f32 v[70:71], v[78:79], v[70:71]
	v_mul_f32_e32 v90, v88, v89
	v_rcp_f32_e32 v90, v90
	v_pk_mul_f32 v[68:69], v[76:77], v[68:69]
	v_mul_f32_e32 v76, v89, v90
	v_mul_f32_e32 v78, v88, v90
	v_pk_mul_f32 v[78:79], v[84:85], v[78:79] op_sel_hi:[1,0]
	v_pk_mul_f32 v[76:77], v[80:81], v[76:77] op_sel_hi:[1,0]
	v_pk_mul_f32 v[74:75], v[74:75], v[78:79]
	v_pk_mul_f32 v[72:73], v[72:73], v[76:77]
	v_pk_mul_f32 v[74:75], v[74:75], v[66:67]
	v_pk_mul_f32 v[66:67], v[72:73], v[64:65]
	v_cvt_pk_bf16_f32 v64, v68, v69
	v_cvt_pk_bf16_f32 v65, v70, v71
	v_max_f32_e32 v68, v60, v60
	v_max_f32_e32 v70, v62, v62
	v_max_f32_e32 v68, 0xc1a00000, v68
	v_max_f32_e32 v70, 0xc1a00000, v70
	v_mul_f32_e32 v68, 0xbfb8aa3b, v68
	v_mul_f32_e32 v70, 0xbfb8aa3b, v70
	v_exp_f32_e32 v69, v68
	v_max_f32_e32 v68, v61, v61
	v_exp_f32_e32 v71, v70
	v_max_f32_e32 v70, v63, v63
	v_max_f32_e32 v68, 0xc1a00000, v68
	v_max_f32_e32 v70, 0xc1a00000, v70
	v_mul_f32_e32 v68, 0xbfb8aa3b, v68
	v_mul_f32_e32 v70, 0xbfb8aa3b, v70
	v_exp_f32_e32 v68, v68
	v_exp_f32_e32 v70, v70
	v_cvt_pk_bf16_f32 v66, v66, v67
	v_cvt_pk_bf16_f32 v67, v74, v75
	global_store_dwordx4 v[86:87], v[64:67], off
	v_add_u32_e32 v72, 0x80, v155
	s_nop 0
	v_pk_add_f32 v[64:65], v[68:69], 1.0 op_sel_hi:[1,0]
	v_pk_add_f32 v[66:67], v[70:71], 1.0 op_sel_hi:[1,0]
	v_mov_b32_e32 v68, v65
	v_mov_b32_e32 v69, v67
	v_mov_b32_e32 v70, v64
	v_mov_b32_e32 v71, v66
	v_pk_mul_f32 v[68:69], v[68:69], v[70:71]
	s_nop 0
	v_mul_f32_e32 v70, v68, v69
	v_rcp_f32_e32 v73, v70
	v_mad_i64_i32 v[70:71], s[28:29], v72, s52, v[144:145]
	v_lshl_add_u64 v[70:71], v[70:71], 0, v[146:147]
	v_mul_f32_e32 v68, v68, v73
	v_mul_f32_e32 v72, v69, v73
	v_pk_mul_f32 v[66:67], v[66:67], v[68:69] op_sel_hi:[1,0]
	v_max_f32_e32 v68, v56, v56
	v_max_f32_e32 v73, v58, v58
	v_max_f32_e32 v68, 0xc1a00000, v68
	v_max_f32_e32 v73, 0xc1a00000, v73
	v_mul_f32_e32 v68, 0xbfb8aa3b, v68
	v_mul_f32_e32 v73, 0xbfb8aa3b, v73
	v_exp_f32_e32 v69, v68
	v_max_f32_e32 v68, v57, v57
	v_exp_f32_e32 v75, v73
	v_max_f32_e32 v73, v59, v59
	v_max_f32_e32 v68, 0xc1a00000, v68
	v_max_f32_e32 v73, 0xc1a00000, v73
	v_mul_f32_e32 v68, 0xbfb8aa3b, v68
	v_mul_f32_e32 v73, 0xbfb8aa3b, v73
	v_exp_f32_e32 v68, v68
	v_exp_f32_e32 v74, v73
	v_pk_mul_f32 v[64:65], v[64:65], v[72:73] op_sel_hi:[1,0]
	v_pk_mul_f32 v[62:63], v[62:63], v[66:67]
	v_pk_mul_f32 v[60:61], v[60:61], v[64:65]
	v_pk_add_f32 v[64:65], v[68:69], 1.0 op_sel_hi:[1,0]
	v_pk_add_f32 v[68:69], v[74:75], 1.0 op_sel_hi:[1,0]
	v_mov_b32_e32 v72, v65
	v_mov_b32_e32 v73, v69
	v_mov_b32_e32 v74, v64
	v_mov_b32_e32 v75, v68
	v_pk_mul_f32 v[72:73], v[72:73], v[74:75]
	v_pk_mul_f32 v[54:55], v[62:63], v[54:55]
	v_mul_f32_e32 v74, v72, v73
	v_rcp_f32_e32 v74, v74
	v_pk_mul_f32 v[52:53], v[60:61], v[52:53]
	v_mul_f32_e32 v60, v73, v74
	v_mul_f32_e32 v62, v72, v74
	v_pk_mul_f32 v[62:63], v[68:69], v[62:63] op_sel_hi:[1,0]
	v_pk_mul_f32 v[60:61], v[64:65], v[60:61] op_sel_hi:[1,0]
	v_pk_mul_f32 v[58:59], v[58:59], v[62:63]
	v_pk_mul_f32 v[56:57], v[56:57], v[60:61]
	v_pk_mul_f32 v[58:59], v[58:59], v[50:51]
	v_pk_mul_f32 v[50:51], v[56:57], v[48:49]
	v_cvt_pk_bf16_f32 v48, v52, v53
	v_cvt_pk_bf16_f32 v49, v54, v55
	v_max_f32_e32 v52, v44, v44
	v_max_f32_e32 v54, v46, v46
	v_max_f32_e32 v52, 0xc1a00000, v52
	v_max_f32_e32 v54, 0xc1a00000, v54
	v_mul_f32_e32 v52, 0xbfb8aa3b, v52
	v_mul_f32_e32 v54, 0xbfb8aa3b, v54
	v_exp_f32_e32 v53, v52
	v_max_f32_e32 v52, v45, v45
	v_exp_f32_e32 v55, v54
	v_max_f32_e32 v54, v47, v47
	v_max_f32_e32 v52, 0xc1a00000, v52
; __device__ __forceinline__ unsigned cvt_pk_bf16(float lo, float hi) { unsigned r; asm volatile("v_cvt_pk_bf16_f32 %0, %1, %2" : "=v"(r) : "v"(lo), "v"(hi)); return r; }
;     __device__ __forceinline__ void operator()(const f32x4 (&acc)[2][2][4][2], const Unit& u, int wr, int wc, int fr, int fq) const {
;     ...
;         for (int ai = 0; ai < 2; ++ai)
; #pragma unroll
;             for (int m = 0; m < 4; ++m) { bf16_t* rowp = O + (size_t)(row0 + ai * HALF + m * 16) * ldc + col0;
;                 f32x4 v0, v1;
; #pragma unroll
;                 for (int j = 0; j < 1; ++j) { v0 = acc[ai][0][m][0] * sigmoid4(acc[ai][0][m][0]) * acc[ai][1][m][0]; v1 = acc[ai][0][m][1] * sigmoid4(acc[ai][0][m][1]) * acc[ai][1][m][1]; }
;                 u32x4 w; w.x = cvt_pk_bf16(v0[0], v0[1]); w.y = cvt_pk_bf16(v0[2], v0[3]); w.z = cvt_pk_bf16(v1[0], v1[1]); w.w = cvt_pk_bf16(v1[2], v1[3]);
;                 *(u32x4*)rowp = w; }
	v_max_f32_e32 v54, 0xc1a00000, v54
	v_mul_f32_e32 v52, 0xbfb8aa3b, v52
	v_mul_f32_e32 v54, 0xbfb8aa3b, v54
	v_exp_f32_e32 v52, v52
	v_exp_f32_e32 v54, v54
	v_cvt_pk_bf16_f32 v50, v50, v51
	v_cvt_pk_bf16_f32 v51, v58, v59
	global_store_dwordx4 v[70:71], v[48:51], off
	v_add_u32_e32 v56, 0x90, v155
	s_nop 0
	v_pk_add_f32 v[48:49], v[52:53], 1.0 op_sel_hi:[1,0]
	v_pk_add_f32 v[50:51], v[54:55], 1.0 op_sel_hi:[1,0]
	v_mov_b32_e32 v52, v49
	v_mov_b32_e32 v53, v51
	v_mov_b32_e32 v54, v48
	v_mov_b32_e32 v55, v50
	v_pk_mul_f32 v[52:53], v[52:53], v[54:55]
	s_nop 0
	v_mul_f32_e32 v54, v52, v53
	v_rcp_f32_e32 v57, v54
	v_mad_i64_i32 v[54:55], s[28:29], v56, s52, v[144:145]
	v_lshl_add_u64 v[54:55], v[54:55], 0, v[146:147]
	v_mul_f32_e32 v52, v52, v57
	v_mul_f32_e32 v56, v53, v57
	v_pk_mul_f32 v[50:51], v[50:51], v[52:53] op_sel_hi:[1,0]
	v_max_f32_e32 v52, v40, v40
	v_max_f32_e32 v57, v42, v42
	v_max_f32_e32 v52, 0xc1a00000, v52
	v_max_f32_e32 v57, 0xc1a00000, v57
	v_mul_f32_e32 v52, 0xbfb8aa3b, v52
	v_mul_f32_e32 v57, 0xbfb8aa3b, v57
	v_exp_f32_e32 v53, v52
	v_max_f32_e32 v52, v41, v41
	v_exp_f32_e32 v59, v57
	v_max_f32_e32 v57, v43, v43
	v_max_f32_e32 v52, 0xc1a00000, v52
	v_max_f32_e32 v57, 0xc1a00000, v57
	v_mul_f32_e32 v52, 0xbfb8aa3b, v52
	v_mul_f32_e32 v57, 0xbfb8aa3b, v57
	v_exp_f32_e32 v52, v52
	v_exp_f32_e32 v58, v57
	v_pk_mul_f32 v[48:49], v[48:49], v[56:57] op_sel_hi:[1,0]
	v_pk_mul_f32 v[46:47], v[46:47], v[50:51]
	v_pk_mul_f32 v[44:45], v[44:45], v[48:49]
	v_pk_add_f32 v[48:49], v[52:53], 1.0 op_sel_hi:[1,0]
	v_pk_add_f32 v[52:53], v[58:59], 1.0 op_sel_hi:[1,0]
	v_mov_b32_e32 v56, v49
	v_mov_b32_e32 v57, v53
	v_mov_b32_e32 v58, v48
	v_mov_b32_e32 v59, v52
	v_pk_mul_f32 v[56:57], v[56:57], v[58:59]
	v_pk_mul_f32 v[38:39], v[46:47], v[38:39]
	v_mul_f32_e32 v58, v56, v57
	v_rcp_f32_e32 v58, v58
	v_pk_mul_f32 v[36:37], v[44:45], v[36:37]
	v_mul_f32_e32 v44, v57, v58
	v_mul_f32_e32 v46, v56, v58
	v_pk_mul_f32 v[46:47], v[52:53], v[46:47] op_sel_hi:[1,0]
	v_pk_mul_f32 v[44:45], v[48:49], v[44:45] op_sel_hi:[1,0]
	v_pk_mul_f32 v[42:43], v[42:43], v[46:47]
	v_pk_mul_f32 v[40:41], v[40:41], v[44:45]
	v_pk_mul_f32 v[42:43], v[42:43], v[34:35]
	v_pk_mul_f32 v[34:35], v[40:41], v[32:33]
	v_cvt_pk_bf16_f32 v32, v36, v37
	v_cvt_pk_bf16_f32 v33, v38, v39
	v_max_f32_e32 v36, v28, v28
	v_max_f32_e32 v38, v30, v30
	v_max_f32_e32 v36, 0xc1a00000, v36
	v_max_f32_e32 v38, 0xc1a00000, v38
	v_mul_f32_e32 v36, 0xbfb8aa3b, v36
	v_mul_f32_e32 v38, 0xbfb8aa3b, v38
	v_exp_f32_e32 v37, v36
	v_max_f32_e32 v36, v29, v29
	v_exp_f32_e32 v39, v38
	v_max_f32_e32 v38, v31, v31
	v_max_f32_e32 v36, 0xc1a00000, v36
	v_max_f32_e32 v38, 0xc1a00000, v38
	v_mul_f32_e32 v36, 0xbfb8aa3b, v36
	v_mul_f32_e32 v38, 0xbfb8aa3b, v38
	v_exp_f32_e32 v36, v36
	v_exp_f32_e32 v38, v38
	v_cvt_pk_bf16_f32 v34, v34, v35
	v_cvt_pk_bf16_f32 v35, v42, v43
	global_store_dwordx4 v[54:55], v[32:35], off
	v_add_u32_e32 v40, 0xa0, v155
	s_nop 0
	v_pk_add_f32 v[32:33], v[36:37], 1.0 op_sel_hi:[1,0]
	v_pk_add_f32 v[34:35], v[38:39], 1.0 op_sel_hi:[1,0]
	v_mov_b32_e32 v36, v33
	v_mov_b32_e32 v37, v35
	v_mov_b32_e32 v38, v32
	v_mov_b32_e32 v39, v34
	v_pk_mul_f32 v[36:37], v[36:37], v[38:39]
	s_nop 0
	v_mul_f32_e32 v38, v36, v37
	v_rcp_f32_e32 v41, v38
	v_mad_i64_i32 v[38:39], s[28:29], v40, s52, v[144:145]
	v_lshl_add_u64 v[38:39], v[38:39], 0, v[146:147]
	v_mul_f32_e32 v36, v36, v41
	v_mul_f32_e32 v40, v37, v41
	v_pk_mul_f32 v[34:35], v[34:35], v[36:37] op_sel_hi:[1,0]
	v_max_f32_e32 v36, v24, v24
	v_max_f32_e32 v41, v26, v26
	v_max_f32_e32 v36, 0xc1a00000, v36
	v_max_f32_e32 v41, 0xc1a00000, v41
	v_mul_f32_e32 v36, 0xbfb8aa3b, v36
	v_mul_f32_e32 v41, 0xbfb8aa3b, v41
	v_exp_f32_e32 v37, v36
	v_max_f32_e32 v36, v25, v25
	v_exp_f32_e32 v43, v41
	v_max_f32_e32 v41, v27, v27
	v_max_f32_e32 v36, 0xc1a00000, v36
	v_max_f32_e32 v41, 0xc1a00000, v41
	v_mul_f32_e32 v36, 0xbfb8aa3b, v36
; __device__ __forceinline__ unsigned cvt_pk_bf16(float lo, float hi) { unsigned r; asm volatile("v_cvt_pk_bf16_f32 %0, %1, %2" : "=v"(r) : "v"(lo), "v"(hi)); return r; }
;     __device__ __forceinline__ void operator()(const f32x4 (&acc)[2][2][4][2], const Unit& u, int wr, int wc, int fr, int fq) const {
;     ...
;         for (int ai = 0; ai < 2; ++ai)
; #pragma unroll
;             for (int m = 0; m < 4; ++m) { bf16_t* rowp = O + (size_t)(row0 + ai * HALF + m * 16) * ldc + col0;
;                 f32x4 v0, v1;
; #pragma unroll
;                 for (int j = 0; j < 1; ++j) { v0 = acc[ai][0][m][0] * sigmoid4(acc[ai][0][m][0]) * acc[ai][1][m][0]; v1 = acc[ai][0][m][1] * sigmoid4(acc[ai][0][m][1]) * acc[ai][1][m][1]; }
;                 u32x4 w; w.x = cvt_pk_bf16(v0[0], v0[1]); w.y = cvt_pk_bf16(v0[2], v0[3]); w.z = cvt_pk_bf16(v1[0], v1[1]); w.w = cvt_pk_bf16(v1[2], v1[3]);
;                 *(u32x4*)rowp = w; }
; template <class Epi, class Sched>
; __device__ __forceinline__ void gemm_phase(PG8_LAS unsigned char* lds, const Gemm g, const Sched& S, const Epi& E) {
;     ...
;         if (!has_next) break;
; #pragma unroll
;         for (int a = 0; a < 2; ++a)
; #pragma unroll
;             for (int b = 0; b < 2; ++b)
; #pragma unroll
;                 for (int m = 0; m < 4; ++m)
; #pragma unroll
;                     for (int n = 0; n < 2; ++n) acc[a][b][m][n] = (f32x4){0.f, 0.f, 0.f, 0.f};
;         cur = nxt; cA = nA; cB = nB; ++ui;
;     }
	v_mul_f32_e32 v41, 0xbfb8aa3b, v41
	v_exp_f32_e32 v36, v36
	v_exp_f32_e32 v42, v41
	v_pk_mul_f32 v[32:33], v[32:33], v[40:41] op_sel_hi:[1,0]
	v_pk_mul_f32 v[30:31], v[30:31], v[34:35]
	v_pk_mul_f32 v[28:29], v[28:29], v[32:33]
	v_pk_add_f32 v[32:33], v[36:37], 1.0 op_sel_hi:[1,0]
	v_pk_add_f32 v[36:37], v[42:43], 1.0 op_sel_hi:[1,0]
	v_mov_b32_e32 v40, v33
	v_mov_b32_e32 v41, v37
	v_mov_b32_e32 v42, v32
	v_mov_b32_e32 v43, v36
	v_pk_mul_f32 v[40:41], v[40:41], v[42:43]
	v_pk_mul_f32 v[22:23], v[30:31], v[22:23]
	v_mul_f32_e32 v42, v40, v41
	v_rcp_f32_e32 v42, v42
	v_pk_mul_f32 v[20:21], v[28:29], v[20:21]
	v_mul_f32_e32 v28, v41, v42
	v_mul_f32_e32 v30, v40, v42
	v_pk_mul_f32 v[30:31], v[36:37], v[30:31] op_sel_hi:[1,0]
	v_pk_mul_f32 v[28:29], v[32:33], v[28:29] op_sel_hi:[1,0]
	v_pk_mul_f32 v[26:27], v[26:27], v[30:31]
	v_pk_mul_f32 v[24:25], v[24:25], v[28:29]
	v_pk_mul_f32 v[26:27], v[26:27], v[18:19]
	v_pk_mul_f32 v[18:19], v[24:25], v[16:17]
	v_cvt_pk_bf16_f32 v16, v20, v21
	v_cvt_pk_bf16_f32 v17, v22, v23
	v_max_f32_e32 v20, v12, v12
	v_max_f32_e32 v22, v14, v14
	v_max_f32_e32 v20, 0xc1a00000, v20
	v_max_f32_e32 v22, 0xc1a00000, v22
	v_mul_f32_e32 v20, 0xbfb8aa3b, v20
	v_mul_f32_e32 v22, 0xbfb8aa3b, v22
	v_exp_f32_e32 v21, v20
	v_max_f32_e32 v20, v13, v13
	v_exp_f32_e32 v23, v22
	v_max_f32_e32 v22, v15, v15
	v_max_f32_e32 v20, 0xc1a00000, v20
	v_max_f32_e32 v22, 0xc1a00000, v22
	v_mul_f32_e32 v20, 0xbfb8aa3b, v20
	v_mul_f32_e32 v22, 0xbfb8aa3b, v22
	v_exp_f32_e32 v20, v20
	v_exp_f32_e32 v22, v22
	v_cvt_pk_bf16_f32 v18, v18, v19
	v_cvt_pk_bf16_f32 v19, v26, v27
	global_store_dwordx4 v[38:39], v[16:19], off
	v_add_u32_e32 v24, 0xb0, v155
	s_nop 0
	v_pk_add_f32 v[16:17], v[20:21], 1.0 op_sel_hi:[1,0]
	v_pk_add_f32 v[18:19], v[22:23], 1.0 op_sel_hi:[1,0]
	v_mov_b32_e32 v20, v17
	v_mov_b32_e32 v21, v19
	v_mov_b32_e32 v22, v16
	v_mov_b32_e32 v23, v18
	v_pk_mul_f32 v[20:21], v[20:21], v[22:23]
	s_nop 0
	v_mul_f32_e32 v22, v20, v21
	v_rcp_f32_e32 v25, v22
	v_mad_i64_i32 v[22:23], s[28:29], v24, s52, v[144:145]
	v_lshl_add_u64 v[22:23], v[22:23], 0, v[146:147]
	v_mul_f32_e32 v20, v20, v25
	v_mul_f32_e32 v24, v21, v25
	v_pk_mul_f32 v[18:19], v[18:19], v[20:21] op_sel_hi:[1,0]
	v_max_f32_e32 v20, v8, v8
	v_max_f32_e32 v25, v10, v10
	v_max_f32_e32 v20, 0xc1a00000, v20
	v_max_f32_e32 v25, 0xc1a00000, v25
	v_mul_f32_e32 v20, 0xbfb8aa3b, v20
	v_mul_f32_e32 v25, 0xbfb8aa3b, v25
	v_exp_f32_e32 v21, v20
	v_max_f32_e32 v20, v9, v9
	v_exp_f32_e32 v27, v25
	v_max_f32_e32 v25, v11, v11
	v_max_f32_e32 v20, 0xc1a00000, v20
	v_max_f32_e32 v25, 0xc1a00000, v25
	v_mul_f32_e32 v20, 0xbfb8aa3b, v20
	v_mul_f32_e32 v25, 0xbfb8aa3b, v25
	v_exp_f32_e32 v20, v20
	v_exp_f32_e32 v26, v25
	v_pk_mul_f32 v[16:17], v[16:17], v[24:25] op_sel_hi:[1,0]
	v_pk_mul_f32 v[14:15], v[14:15], v[18:19]
	v_pk_mul_f32 v[12:13], v[12:13], v[16:17]
	v_pk_add_f32 v[16:17], v[20:21], 1.0 op_sel_hi:[1,0]
	v_pk_add_f32 v[20:21], v[26:27], 1.0 op_sel_hi:[1,0]
	v_mov_b32_e32 v24, v17
	v_mov_b32_e32 v25, v21
	v_mov_b32_e32 v26, v16
	v_mov_b32_e32 v27, v20
	v_pk_mul_f32 v[24:25], v[24:25], v[26:27]
	v_pk_mul_f32 v[6:7], v[14:15], v[6:7]
	v_mul_f32_e32 v26, v24, v25
	v_rcp_f32_e32 v26, v26
	v_pk_mul_f32 v[4:5], v[12:13], v[4:5]
	s_mov_b64 s[28:29], s[18:19]
	v_mul_f32_e32 v12, v25, v26
	v_mul_f32_e32 v14, v24, v26
	v_pk_mul_f32 v[14:15], v[20:21], v[14:15] op_sel_hi:[1,0]
	v_pk_mul_f32 v[12:13], v[16:17], v[12:13] op_sel_hi:[1,0]
	v_pk_mul_f32 v[10:11], v[10:11], v[14:15]
	v_pk_mul_f32 v[8:9], v[8:9], v[12:13]
	v_pk_mul_f32 v[10:11], v[10:11], v[2:3]
	v_pk_mul_f32 v[2:3], v[8:9], v[0:1]
	v_cvt_pk_bf16_f32 v0, v4, v5
	v_cvt_pk_bf16_f32 v1, v6, v7
	s_nop 0
	v_cvt_pk_bf16_f32 v2, v2, v3
	v_cvt_pk_bf16_f32 v3, v10, v11
	global_store_dwordx4 v[22:23], v[0:3], off
	s_cbranch_vccz .LBB0_192
	s_waitcnt vmcnt(0)
	s_cmpk_gt_u32 s37, 0xff
	s_cbranch_scc1 .LBB0_199
	s_barrier

; #define PG8_STAGE(bufoff, gbase, voff) do { _Pragma("unroll") for (int _i = 0; _i < 2; ++_i) \
;         __builtin_amdgcn_global_load_lds((const unsigned*)((const char*)(gbase) + (voff)[_i]), (PG8_LAS unsigned*)(lds + (bufoff) + ldsw + _i * 8192), 16, 0, 0); } while (0)
; #define PG8_LDA(dst, b, h) do { _Pragma("unroll") for (int m = 0; m < 4; ++m) _Pragma("unroll") for (int k = 0; k < 2; ++k) dst[m][k] = *(const PG8_LAS bf16x8*)(lds + PG8_SA(b, h) + aoff + m * 2048 + k * 1024); } while (0)
; #define PG8_LDB(dst, b, h) do { _Pragma("unroll") for (int n = 0; n < 2; ++n) _Pragma("unroll") for (int k = 0; k < 2; ++k) dst[n][k] = *(const PG8_LAS bf16x8*)(lds + PG8_SB(b, h) + boff + n * 2048 + k * 1024); } while (0)
; #define PG8_MMA(ai, bj, At, Bt) do { __builtin_amdgcn_s_setprio(1); _Pragma("unroll") for (int m = 0; m < 4; ++m) _Pragma("unroll") for (int n = 0; n < 2; ++n) _Pragma("unroll") for (int k = 0; k < 2; ++k) \
;         acc[ai][bj][m][n] = __builtin_amdgcn_mfma_f32_16x16x32_bf16(Bt[n][k], At[m][k], acc[ai][bj][m][n], 0, 0, 0); __builtin_amdgcn_s_setprio(0); } while (0)
; #define PG8_WAIT_V(n) asm volatile("s_waitcnt vmcnt(" #n ")" ::: "memory")
; #define PG8_WAIT_L(n) asm volatile("s_waitcnt lgkmcnt(" #n ")" ::: "memory")
; #define PG8_BAR __builtin_amdgcn_s_barrier()
; #define PG8_SCHED __builtin_amdgcn_sched_barrier(0)
; template <class Epi, class Sched>
; __device__ __forceinline__ void gemm_phase(PG8_LAS unsigned char* lds, const Gemm g, const Sched& S, const Epi& E) {
;     ...
;             PG8_LDB(B0, 0, 0); PG8_SCHED; PG8_LDA(At, 0, 0); PG8_STAGE(PG8_SA(1, 1), a1 + hstep, voffA);
;             PG8_WAIT_L(8); PG8_BAR; PG8_WAIT_L(0); PG8_MMA(0, 0, At, B0); PG8_BAR; PG8_SCHED;
;             PG8_LDB(B1, 0, 1); PG8_STAGE(PG8_SB(0, 0), b2, voffB);
;             PG8_BAR; PG8_WAIT_L(0); PG8_MMA(0, 1, At, B1); PG8_BAR;
;             PG8_LDA(At, 0, 1); PG8_STAGE(PG8_SA(0, 0), a2, voffA);
;             PG8_BAR; PG8_WAIT_L(0); PG8_MMA(1, 0, At, B0); PG8_BAR; PG8_SCHED;
;             PG8_STAGE(PG8_SB(0, 1), b2 + hstep, voffB);
;             PG8_WAIT_V(6); PG8_BAR; PG8_MMA(1, 1, At, B1); PG8_BAR;
.LBB0_286:
	ds_read_b128 v[154:157], v149
	ds_read_b128 v[158:161], v149 offset:1024
	ds_read_b128 v[166:169], v149 offset:2048
	ds_read_b128 v[170:173], v149 offset:3072
	s_add_u32 s24, s22, 0x100
	s_addc_u32 s25, s23, 0
	s_cmp_eq_u32 s57, 40
	s_cselect_b32 s29, s1, s25
	s_cselect_b32 s28, s0, s24
	s_cselect_b32 s27, s5, s56
	s_cselect_b32 s26, s4, s55
	v_lshl_add_u64 v[144:145], s[22:23], 0, v[136:137]
	s_add_i32 m0, s38, 0xc000
	ds_read_b128 v[182:185], v150
	ds_read_b128 v[190:193], v150 offset:1024
	ds_read_b128 v[194:197], v150 offset:2048
	ds_read_b128 v[198:201], v150 offset:3072
	ds_read_b128 v[202:205], v150 offset:4096
	ds_read_b128 v[206:209], v150 offset:5120
	ds_read_b128 v[210:213], v150 offset:6144
	ds_read_b128 v[214:217], v150 offset:7168
	global_load_lds_dwordx4 v[144:145], off
	v_lshl_add_u64 v[144:145], s[22:23], 0, v[138:139]
	s_add_i32 m0, s38, 0xe000
	s_nop 0
	global_load_lds_dwordx4 v[144:145], off
	s_waitcnt lgkmcnt(8)
	s_barrier
	s_waitcnt lgkmcnt(0)
	v_mfma_f32_16x16x32_bf16 v[124:127], v[154:157], v[182:185], v[124:127]
	v_mfma_f32_16x16x32_bf16 v[120:123], v[166:169], v[182:185], v[120:123]
	v_mfma_f32_16x16x32_bf16 v[108:111], v[154:157], v[194:197], v[108:111]
	v_mfma_f32_16x16x32_bf16 v[104:107], v[166:169], v[194:197], v[104:107]
	v_mfma_f32_16x16x32_bf16 v[92:95], v[154:157], v[202:205], v[92:95]
	v_mfma_f32_16x16x32_bf16 v[88:91], v[166:169], v[202:205], v[88:91]
	v_mfma_f32_16x16x32_bf16 v[76:79], v[154:157], v[210:213], v[76:79]
	v_mfma_f32_16x16x32_bf16 v[72:75], v[166:169], v[210:213], v[72:75]
	v_mfma_f32_16x16x32_bf16 v[124:127], v[158:161], v[190:193], v[124:127]
	v_mfma_f32_16x16x32_bf16 v[120:123], v[170:173], v[190:193], v[120:123]
	v_mfma_f32_16x16x32_bf16 v[108:111], v[158:161], v[198:201], v[108:111]
	v_mfma_f32_16x16x32_bf16 v[104:107], v[170:173], v[198:201], v[104:107]
	v_mfma_f32_16x16x32_bf16 v[92:95], v[158:161], v[206:209], v[92:95]
	v_mfma_f32_16x16x32_bf16 v[88:91], v[170:173], v[206:209], v[88:91]
	v_mfma_f32_16x16x32_bf16 v[76:79], v[158:161], v[214:217], v[76:79]
	v_mfma_f32_16x16x32_bf16 v[72:75], v[170:173], v[214:217], v[72:75]
	s_barrier
	s_add_i32 s22, s46, s37
	v_lshl_add_u64 v[144:145], s[26:27], 0, v[130:131]
	s_mov_b32 m0, s22
	ds_read_b128 v[218:221], v151
	ds_read_b128 v[222:225], v151 offset:1024
	ds_read_b128 v[226:229], v151 offset:2048
	ds_read_b128 v[230:233], v151 offset:3072
	global_load_lds_dwordx4 v[144:145], off
	v_lshl_add_u64 v[162:163], s[26:27], 0, v[134:135]
	s_add_i32 m0, s22, 0x2000
	s_nop 0
	global_load_lds_dwordx4 v[162:163], off
	s_barrier
	s_waitcnt lgkmcnt(0)
	v_mfma_f32_16x16x32_bf16 v[116:119], v[218:221], v[182:185], v[116:119]
	v_mfma_f32_16x16x32_bf16 v[112:115], v[226:229], v[182:185], v[112:115]
	v_mfma_f32_16x16x32_bf16 v[100:103], v[218:221], v[194:197], v[100:103]
	v_mfma_f32_16x16x32_bf16 v[96:99], v[226:229], v[194:197], v[96:99]
	v_mfma_f32_16x16x32_bf16 v[84:87], v[218:221], v[202:205], v[84:87]
	v_mfma_f32_16x16x32_bf16 v[80:83], v[226:229], v[202:205], v[80:83]
	v_mfma_f32_16x16x32_bf16 v[68:71], v[218:221], v[210:213], v[68:71]
	v_mfma_f32_16x16x32_bf16 v[64:67], v[226:229], v[210:213], v[64:67]
	v_mfma_f32_16x16x32_bf16 v[116:119], v[222:225], v[190:193], v[116:119]
	v_mfma_f32_16x16x32_bf16 v[112:115], v[230:233], v[190:193], v[112:115]
	v_mfma_f32_16x16x32_bf16 v[100:103], v[222:225], v[198:201], v[100:103]
	v_mfma_f32_16x16x32_bf16 v[96:99], v[230:233], v[198:201], v[96:99]
	v_mfma_f32_16x16x32_bf16 v[84:87], v[222:225], v[206:209], v[84:87]
	v_mfma_f32_16x16x32_bf16 v[80:83], v[230:233], v[206:209], v[80:83]
	v_mfma_f32_16x16x32_bf16 v[68:71], v[222:225], v[214:217], v[68:71]
	v_mfma_f32_16x16x32_bf16 v[64:67], v[230:233], v[214:217], v[64:67]
	s_mov_b32 m0, s38
	v_lshl_add_u64 v[174:175], s[28:29], 0, v[128:129]
	s_barrier
	ds_read_b128 v[182:185], v150 offset:16384
	ds_read_b128 v[190:193], v150 offset:17408
	ds_read_b128 v[194:197], v150 offset:18432
	ds_read_b128 v[198:201], v150 offset:19456
	ds_read_b128 v[202:205], v150 offset:20480
	ds_read_b128 v[206:209], v150 offset:21504
	ds_read_b128 v[210:213], v150 offset:22528
	ds_read_b128 v[214:217], v150 offset:23552
	global_load_lds_dwordx4 v[174:175], off
	v_lshl_add_u64 v[178:179], s[28:29], 0, v[132:133]
	s_mov_b32 m0, s39
	s_nop 0
	global_load_lds_dwordx4 v[178:179], off
	s_barrier
	s_waitcnt lgkmcnt(0)
	v_mfma_f32_16x16x32_bf16 v[60:63], v[154:157], v[182:185], v[60:63]
	v_mfma_f32_16x16x32_bf16 v[56:59], v[166:169], v[182:185], v[56:59]
	v_mfma_f32_16x16x32_bf16 v[48:51], v[154:157], v[194:197], v[48:51]
	v_mfma_f32_16x16x32_bf16 v[40:43], v[166:169], v[194:197], v[40:43]
	v_mfma_f32_16x16x32_bf16 v[32:35], v[154:157], v[202:205], v[32:35]
	v_mfma_f32_16x16x32_bf16 v[24:27], v[166:169], v[202:205], v[24:27]
	v_mfma_f32_16x16x32_bf16 v[16:19], v[154:157], v[210:213], v[16:19]
	v_mfma_f32_16x16x32_bf16 v[8:11], v[166:169], v[210:213], v[8:11]
	v_mfma_f32_16x16x32_bf16 v[60:63], v[158:161], v[190:193], v[60:63]
	v_mfma_f32_16x16x32_bf16 v[56:59], v[170:173], v[190:193], v[56:59]
	v_mfma_f32_16x16x32_bf16 v[48:51], v[158:161], v[198:201], v[48:51]
	v_mfma_f32_16x16x32_bf16 v[40:43], v[170:173], v[198:201], v[40:43]
	v_mfma_f32_16x16x32_bf16 v[32:35], v[158:161], v[206:209], v[32:35]
	v_mfma_f32_16x16x32_bf16 v[24:27], v[170:173], v[206:209], v[24:27]
	v_mfma_f32_16x16x32_bf16 v[16:19], v[158:161], v[214:217], v[16:19]
	v_mfma_f32_16x16x32_bf16 v[8:11], v[170:173], v[214:217], v[8:11]
	s_barrier
; #define PG8_STAGE(bufoff, gbase, voff) do { _Pragma("unroll") for (int _i = 0; _i < 2; ++_i) \
;         __builtin_amdgcn_global_load_lds((const unsigned*)((const char*)(gbase) + (voff)[_i]), (PG8_LAS unsigned*)(lds + (bufoff) + ldsw + _i * 8192), 16, 0, 0); } while (0)
; #define PG8_LDA(dst, b, h) do { _Pragma("unroll") for (int m = 0; m < 4; ++m) _Pragma("unroll") for (int k = 0; k < 2; ++k) dst[m][k] = *(const PG8_LAS bf16x8*)(lds + PG8_SA(b, h) + aoff + m * 2048 + k * 1024); } while (0)
; #define PG8_LDB(dst, b, h) do { _Pragma("unroll") for (int n = 0; n < 2; ++n) _Pragma("unroll") for (int k = 0; k < 2; ++k) dst[n][k] = *(const PG8_LAS bf16x8*)(lds + PG8_SB(b, h) + boff + n * 2048 + k * 1024); } while (0)
; #define PG8_MMA(ai, bj, At, Bt) do { __builtin_amdgcn_s_setprio(1); _Pragma("unroll") for (int m = 0; m < 4; ++m) _Pragma("unroll") for (int n = 0; n < 2; ++n) _Pragma("unroll") for (int k = 0; k < 2; ++k) \
;         acc[ai][bj][m][n] = __builtin_amdgcn_mfma_f32_16x16x32_bf16(Bt[n][k], At[m][k], acc[ai][bj][m][n], 0, 0, 0); __builtin_amdgcn_s_setprio(0); } while (0)
; #define PG8_WAIT_V(n) asm volatile("s_waitcnt vmcnt(" #n ")" ::: "memory")
; #define PG8_WAIT_L(n) asm volatile("s_waitcnt lgkmcnt(" #n ")" ::: "memory")
; #define PG8_BAR __builtin_amdgcn_s_barrier()
; #define PG8_SCHED __builtin_amdgcn_sched_barrier(0)
; template <class Epi, class Sched>
; __device__ __forceinline__ void gemm_phase(PG8_LAS unsigned char* lds, const Gemm g, const Sched& S, const Epi& E) {
;     ...
;             PG8_WAIT_V(6); PG8_BAR; PG8_MMA(1, 1, At, B1); PG8_BAR;
;             PG8_LDB(B0, 1, 0); PG8_SCHED; PG8_LDA(At, 1, 0); PG8_STAGE(PG8_SA(0, 1), a2 + hstep, voffA);
;             PG8_WAIT_L(8); PG8_BAR; PG8_WAIT_L(0); PG8_MMA(0, 0, At, B0); PG8_BAR; PG8_SCHED;
;             PG8_LDB(B1, 1, 1); PG8_STAGE(PG8_SB(1, 0), b3, voffB);
;             PG8_BAR; PG8_WAIT_L(0); PG8_MMA(0, 1, At, B1); PG8_BAR;
;             PG8_LDA(At, 1, 1); PG8_STAGE(PG8_SA(1, 0), a3, voffA);
;             PG8_BAR; PG8_WAIT_L(0); PG8_MMA(1, 0, At, B0); PG8_BAR; PG8_SCHED;
	s_add_u32 s22, s26, 0xb0000
	s_addc_u32 s23, s27, 0
	s_add_i32 s58, s47, s37
	v_lshl_add_u64 v[154:155], s[22:23], 0, v[130:131]
	s_mov_b32 m0, s58
	s_nop 0
	global_load_lds_dwordx4 v[154:155], off
	v_lshl_add_u64 v[154:155], s[22:23], 0, v[134:135]
	s_add_i32 m0, s58, 0x2000
	s_nop 0
	global_load_lds_dwordx4 v[154:155], off
	s_waitcnt vmcnt(6)
	s_barrier
	v_mfma_f32_16x16x32_bf16 v[52:55], v[218:221], v[182:185], v[52:55]
	v_mfma_f32_16x16x32_bf16 v[44:47], v[226:229], v[182:185], v[44:47]
	v_mfma_f32_16x16x32_bf16 v[36:39], v[218:221], v[194:197], v[36:39]
	v_mfma_f32_16x16x32_bf16 v[28:31], v[226:229], v[194:197], v[28:31]
	v_mfma_f32_16x16x32_bf16 v[20:23], v[218:221], v[202:205], v[20:23]
	v_mfma_f32_16x16x32_bf16 v[12:15], v[226:229], v[202:205], v[12:15]
	v_mfma_f32_16x16x32_bf16 v[4:7], v[218:221], v[210:213], v[4:7]
	v_mfma_f32_16x16x32_bf16 v[0:3], v[226:229], v[210:213], v[0:3]
	v_mfma_f32_16x16x32_bf16 v[52:55], v[222:225], v[190:193], v[52:55]
	v_mfma_f32_16x16x32_bf16 v[44:47], v[230:233], v[190:193], v[44:47]
	v_mfma_f32_16x16x32_bf16 v[36:39], v[222:225], v[198:201], v[36:39]
	v_mfma_f32_16x16x32_bf16 v[28:31], v[230:233], v[198:201], v[28:31]
	v_mfma_f32_16x16x32_bf16 v[20:23], v[222:225], v[206:209], v[20:23]
	v_mfma_f32_16x16x32_bf16 v[12:15], v[230:233], v[206:209], v[12:15]
	v_mfma_f32_16x16x32_bf16 v[4:7], v[222:225], v[214:217], v[4:7]
	v_mfma_f32_16x16x32_bf16 v[0:3], v[230:233], v[214:217], v[0:3]
	s_add_i32 s58, 0, 0x18000
	v_add_u32_e32 v153, s58, v147
	s_barrier
	ds_read_b128 v[154:157], v153
	ds_read_b128 v[158:161], v153 offset:1024
	ds_read_b128 v[166:169], v153 offset:2048
	ds_read_b128 v[170:173], v153 offset:3072
	s_add_u32 s22, s28, 0xb0000
	s_addc_u32 s23, s29, 0
	s_mov_b32 m0, s40
	v_lshl_add_u64 v[186:187], s[22:23], 0, v[128:129]
	ds_read_b128 v[182:185], v150 offset:32768
	ds_read_b128 v[190:193], v150 offset:33792
	ds_read_b128 v[194:197], v150 offset:34816
	ds_read_b128 v[198:201], v150 offset:35840
	ds_read_b128 v[202:205], v150 offset:36864
	ds_read_b128 v[206:209], v150 offset:37888
	ds_read_b128 v[210:213], v150 offset:38912
	ds_read_b128 v[214:217], v150 offset:39936
	global_load_lds_dwordx4 v[186:187], off
	v_lshl_add_u64 v[186:187], s[22:23], 0, v[132:133]
	s_mov_b32 m0, s41
	s_nop 0
	global_load_lds_dwordx4 v[186:187], off
	s_waitcnt lgkmcnt(8)
	s_barrier
	s_waitcnt lgkmcnt(0)
	v_mfma_f32_16x16x32_bf16 v[124:127], v[154:157], v[182:185], v[124:127]
	v_mfma_f32_16x16x32_bf16 v[120:123], v[166:169], v[182:185], v[120:123]
	v_mfma_f32_16x16x32_bf16 v[108:111], v[154:157], v[194:197], v[108:111]
	v_mfma_f32_16x16x32_bf16 v[104:107], v[166:169], v[194:197], v[104:107]
	v_mfma_f32_16x16x32_bf16 v[92:95], v[154:157], v[202:205], v[92:95]
	v_mfma_f32_16x16x32_bf16 v[88:91], v[166:169], v[202:205], v[88:91]
	v_mfma_f32_16x16x32_bf16 v[76:79], v[154:157], v[210:213], v[76:79]
	v_mfma_f32_16x16x32_bf16 v[72:75], v[166:169], v[210:213], v[72:75]
	v_mfma_f32_16x16x32_bf16 v[124:127], v[158:161], v[190:193], v[124:127]
	v_mfma_f32_16x16x32_bf16 v[120:123], v[170:173], v[190:193], v[120:123]
	v_mfma_f32_16x16x32_bf16 v[108:111], v[158:161], v[198:201], v[108:111]
	v_mfma_f32_16x16x32_bf16 v[104:107], v[170:173], v[198:201], v[104:107]
	v_mfma_f32_16x16x32_bf16 v[92:95], v[158:161], v[206:209], v[92:95]
	v_mfma_f32_16x16x32_bf16 v[88:91], v[170:173], v[206:209], v[88:91]
	v_mfma_f32_16x16x32_bf16 v[76:79], v[158:161], v[214:217], v[76:79]
	v_mfma_f32_16x16x32_bf16 v[72:75], v[170:173], v[214:217], v[72:75]
	s_barrier
	s_add_i32 s28, 0, 0x1c000
	s_add_i32 s22, s58, s37
	v_add_u32_e32 v153, s28, v147
	v_lshl_add_u64 v[144:145], v[144:145], 0, s[14:15]
	s_mov_b32 m0, s22
	ds_read_b128 v[218:221], v153
	ds_read_b128 v[222:225], v153 offset:1024
	ds_read_b128 v[226:229], v153 offset:2048
	ds_read_b128 v[230:233], v153 offset:3072
	global_load_lds_dwordx4 v[144:145], off
	v_lshl_add_u64 v[144:145], v[162:163], 0, s[14:15]
	s_add_i32 m0, s22, 0x2000
	s_nop 0
	global_load_lds_dwordx4 v[144:145], off
	s_barrier
	s_waitcnt lgkmcnt(0)
	v_mfma_f32_16x16x32_bf16 v[116:119], v[218:221], v[182:185], v[116:119]
	v_mfma_f32_16x16x32_bf16 v[112:115], v[226:229], v[182:185], v[112:115]
	v_mfma_f32_16x16x32_bf16 v[100:103], v[218:221], v[194:197], v[100:103]
	v_mfma_f32_16x16x32_bf16 v[96:99], v[226:229], v[194:197], v[96:99]
	v_mfma_f32_16x16x32_bf16 v[84:87], v[218:221], v[202:205], v[84:87]
	v_mfma_f32_16x16x32_bf16 v[80:83], v[226:229], v[202:205], v[80:83]
	v_mfma_f32_16x16x32_bf16 v[68:71], v[218:221], v[210:213], v[68:71]
	v_mfma_f32_16x16x32_bf16 v[64:67], v[226:229], v[210:213], v[64:67]
	v_mfma_f32_16x16x32_bf16 v[116:119], v[222:225], v[190:193], v[116:119]
	v_mfma_f32_16x16x32_bf16 v[112:115], v[230:233], v[190:193], v[112:115]
	v_mfma_f32_16x16x32_bf16 v[100:103], v[222:225], v[198:201], v[100:103]
	v_mfma_f32_16x16x32_bf16 v[96:99], v[230:233], v[198:201], v[96:99]
	v_mfma_f32_16x16x32_bf16 v[84:87], v[222:225], v[206:209], v[84:87]
	v_mfma_f32_16x16x32_bf16 v[80:83], v[230:233], v[206:209], v[80:83]
	v_mfma_f32_16x16x32_bf16 v[68:71], v[222:225], v[214:217], v[68:71]
	v_mfma_f32_16x16x32_bf16 v[64:67], v[230:233], v[214:217], v[64:67]
	s_mov_b32 m0, s43
	v_lshl_add_u64 v[144:145], v[174:175], 0, s[14:15]
	s_barrier
	ds_read_b128 v[182:185], v150 offset:49152
	ds_read_b128 v[190:193], v150 offset:50176
	ds_read_b128 v[194:197], v150 offset:51200
	ds_read_b128 v[198:201], v150 offset:52224
	ds_read_b128 v[202:205], v150 offset:53248
	ds_read_b128 v[206:209], v150 offset:54272
	ds_read_b128 v[210:213], v150 offset:55296
	ds_read_b128 v[214:217], v150 offset:56320
	global_load_lds_dwordx4 v[144:145], off
	v_lshl_add_u64 v[144:145], v[178:179], 0, s[14:15]
	s_mov_b32 m0, s44
	s_nop 0
	global_load_lds_dwordx4 v[144:145], off
	s_barrier
; __device__ __forceinline__ unsigned cvt_pk_bf16(float lo, float hi) { unsigned r; asm volatile("v_cvt_pk_bf16_f32 %0, %1, %2" : "=v"(r) : "v"(lo), "v"(hi)); return r; }
; __device__ __forceinline__ float flogsig16(float x) { return (fminf(x, 0.f) - __logf(1.0f + __expf(-fabsf(x)))) * 0.0625f; }
; #define PG8_WAIT_V(n) asm volatile("s_waitcnt vmcnt(" #n ")" ::: "memory")
; #define PG8_WAIT_L(n) asm volatile("s_waitcnt lgkmcnt(" #n ")" ::: "memory")
;     __device__ __forceinline__ void operator()(const f32x4 (&acc)[2][2][4][2], const Unit& u, int wr, int wc, int fr, int fq) const {
;     ...
;         const int row0 = u.pm * BM + wr * 64 + fr, col0 = u.pn * BM + wc * 32 + 8 * fq, bcol0 = wc * 32 + 8 * fq;
;         f32x4 bv[2][2];
; #pragma unroll
;         for (int bj = 0; bj < 2; ++bj)
; #pragma unroll
;             for (int n = 0; n < 2; ++n) bv[bj][n] = bias ? *(const f32x4*)(bias + bcol0 + bj * HALF + 4 * n) : (f32x4){0.f, 0.f, 0.f, 0.f};
; #pragma unroll
;         for (int ai = 0; ai < 2; ++ai)
; #pragma unroll
;             for (int m = 0; m < 4; ++m) { bf16_t* rowp = O + (size_t)(row0 + ai * HALF + m * 16) * ldc + col0;
; #pragma unroll
;                 for (int bj = 0; bj < 2; ++bj) { f32x4 v0 = acc[ai][bj][m][0] + bv[bj][0], v1 = acc[ai][bj][m][1] + bv[bj][1];
;                     if (act == 1) {
; #pragma unroll
;                         for (int j = 0; j < 1; ++j) { v0 = v0 * sigmoid4(v0); v1 = v1 * sigmoid4(v1); } }
;                     else if (act == 2) {
; #pragma unroll
;                         for (int j = 0; j < 1; ++j) { v0 = sigmoid4(v0); v1 = sigmoid4(v1); } }
;                     else if (act == 3) {
; #pragma unroll
;                         for (int j = 0; j < 4; ++j) { v0[j] = flogsig16(v0[j]); v1[j] = flogsig16(v1[j]); } }
;                     u32x4 w; w.x = cvt_pk_bf16(v0[0], v0[1]); w.y = cvt_pk_bf16(v0[2], v0[3]); w.z = cvt_pk_bf16(v1[0], v1[1]); w.w = cvt_pk_bf16(v1[2], v1[3]);
;                     *(u32x4*)(rowp + bj * HALF) = w; } }
; template <class Epi, class Sched>
; __device__ __forceinline__ void gemm_phase(PG8_LAS unsigned char* lds, const Gemm g, const Sched& S, const Epi& E) {
;     ...
;             PG8_BAR; PG8_WAIT_L(0); PG8_MMA(1, 0, At, B0); PG8_BAR; PG8_SCHED;
;             PG8_STAGE(PG8_SB(1, 1), b3 + hstep, voffB);
;             PG8_WAIT_V(6); PG8_BAR; PG8_MMA(1, 1, At, B1); PG8_BAR;
	s_waitcnt lgkmcnt(0)
	v_mfma_f32_16x16x32_bf16 v[60:63], v[154:157], v[182:185], v[60:63]
	v_mfma_f32_16x16x32_bf16 v[56:59], v[166:169], v[182:185], v[56:59]
	v_mfma_f32_16x16x32_bf16 v[48:51], v[154:157], v[194:197], v[48:51]
	v_mfma_f32_16x16x32_bf16 v[40:43], v[166:169], v[194:197], v[40:43]
	v_mfma_f32_16x16x32_bf16 v[32:35], v[154:157], v[202:205], v[32:35]
	v_mfma_f32_16x16x32_bf16 v[24:27], v[166:169], v[202:205], v[24:27]
	v_mfma_f32_16x16x32_bf16 v[16:19], v[154:157], v[210:213], v[16:19]
	v_mfma_f32_16x16x32_bf16 v[8:11], v[166:169], v[210:213], v[8:11]
	v_mfma_f32_16x16x32_bf16 v[60:63], v[158:161], v[190:193], v[60:63]
	v_mfma_f32_16x16x32_bf16 v[56:59], v[170:173], v[190:193], v[56:59]
	v_mfma_f32_16x16x32_bf16 v[48:51], v[158:161], v[198:201], v[48:51]
	v_mfma_f32_16x16x32_bf16 v[40:43], v[170:173], v[198:201], v[40:43]
	v_mfma_f32_16x16x32_bf16 v[32:35], v[158:161], v[206:209], v[32:35]
	v_mfma_f32_16x16x32_bf16 v[24:27], v[170:173], v[206:209], v[24:27]
	v_mfma_f32_16x16x32_bf16 v[16:19], v[158:161], v[214:217], v[16:19]
	v_mfma_f32_16x16x32_bf16 v[8:11], v[170:173], v[214:217], v[8:11]
	s_barrier
	s_add_u32 s22, s26, 0xb0080
	s_addc_u32 s23, s27, 0
	s_add_i32 s26, s28, s37
	v_lshl_add_u64 v[144:145], s[22:23], 0, v[130:131]
	s_mov_b32 m0, s26
	s_nop 0
	global_load_lds_dwordx4 v[144:145], off
	v_lshl_add_u64 v[144:145], s[22:23], 0, v[134:135]
	s_add_i32 m0, s26, 0x2000
	s_nop 0
	global_load_lds_dwordx4 v[144:145], off
	s_waitcnt vmcnt(6)
	s_barrier
	v_mfma_f32_16x16x32_bf16 v[52:55], v[218:221], v[182:185], v[52:55]
	v_mfma_f32_16x16x32_bf16 v[44:47], v[226:229], v[182:185], v[44:47]
	v_mfma_f32_16x16x32_bf16 v[36:39], v[218:221], v[194:197], v[36:39]
	v_mfma_f32_16x16x32_bf16 v[28:31], v[226:229], v[194:197], v[28:31]
	v_mfma_f32_16x16x32_bf16 v[20:23], v[218:221], v[202:205], v[20:23]
	v_mfma_f32_16x16x32_bf16 v[12:15], v[226:229], v[202:205], v[12:15]
	v_mfma_f32_16x16x32_bf16 v[4:7], v[218:221], v[210:213], v[4:7]
	v_mfma_f32_16x16x32_bf16 v[0:3], v[226:229], v[210:213], v[0:3]
	v_mfma_f32_16x16x32_bf16 v[52:55], v[222:225], v[190:193], v[52:55]
	v_mfma_f32_16x16x32_bf16 v[44:47], v[230:233], v[190:193], v[44:47]
	v_mfma_f32_16x16x32_bf16 v[36:39], v[222:225], v[198:201], v[36:39]
	v_mfma_f32_16x16x32_bf16 v[28:31], v[230:233], v[198:201], v[28:31]
	v_mfma_f32_16x16x32_bf16 v[20:23], v[222:225], v[206:209], v[20:23]
	v_mfma_f32_16x16x32_bf16 v[12:15], v[230:233], v[206:209], v[12:15]
	v_mfma_f32_16x16x32_bf16 v[4:7], v[222:225], v[214:217], v[4:7]
	v_mfma_f32_16x16x32_bf16 v[0:3], v[230:233], v[214:217], v[0:3]
	s_add_i32 s57, s57, 2
	s_add_u32 s55, s55, 0x100
	s_addc_u32 s56, s56, 0
	s_cmp_gt_u32 s57, 41
	s_mov_b64 s[22:23], s[24:25]
	s_barrier
	s_cbranch_scc0 .LBB0_286
	v_lshl_add_u32 v154, s53, 8, v146
	v_lshl_or_b32 v144, s54, 8, v148
	v_ashrrev_i32_e32 v155, 31, v154
	v_ashrrev_i32_e32 v145, 31, v144
	v_lshlrev_b64 v[156:157], 11, v[154:155]
	v_lshl_add_u64 v[156:157], s[10:11], 0, v[156:157]
	v_lshlrev_b64 v[158:159], 1, v[144:145]
	v_lshl_add_u64 v[144:145], v[156:157], 0, v[158:159]
	v_pk_add_f32 v[126:127], v[126:127], 0 op_sel_hi:[1,0]
	v_pk_add_f32 v[124:125], v[124:125], 0 op_sel_hi:[1,0]
	v_pk_add_f32 v[156:157], v[122:123], 0 op_sel_hi:[1,0]
	v_pk_add_f32 v[122:123], v[120:121], 0 op_sel_hi:[1,0]
	v_cvt_pk_bf16_f32 v120, v124, v125
	v_cvt_pk_bf16_f32 v121, v126, v127
	v_pk_add_f32 v[116:117], v[116:117], 0 op_sel_hi:[1,0]
	v_cvt_pk_bf16_f32 v122, v122, v123
	v_cvt_pk_bf16_f32 v123, v156, v157
	global_store_dwordx4 v[144:145], v[120:123], off
	v_pk_add_f32 v[118:119], v[118:119], 0 op_sel_hi:[1,0]
	v_pk_add_f32 v[110:111], v[110:111], 0 op_sel_hi:[1,0]
	v_pk_add_f32 v[120:121], v[114:115], 0 op_sel_hi:[1,0]
	v_pk_add_f32 v[114:115], v[112:113], 0 op_sel_hi:[1,0]
	v_cvt_pk_bf16_f32 v112, v116, v117
	v_cvt_pk_bf16_f32 v113, v118, v119
	v_pk_add_f32 v[108:109], v[108:109], 0 op_sel_hi:[1,0]
	v_cvt_pk_bf16_f32 v114, v114, v115
	v_cvt_pk_bf16_f32 v115, v120, v121
	global_store_dwordx4 v[144:145], v[112:115], off offset:256
	v_pk_add_f32 v[100:101], v[100:101], 0 op_sel_hi:[1,0]
	v_pk_add_f32 v[102:103], v[102:103], 0 op_sel_hi:[1,0]
	v_or_b32_e32 v112, 16, v154
	v_ashrrev_i32_e32 v113, 31, v112
	v_lshlrev_b64 v[112:113], 11, v[112:113]
	v_lshl_add_u64 v[112:113], s[10:11], 0, v[112:113]
	v_lshl_add_u64 v[112:113], v[112:113], 0, v[158:159]
	v_pk_add_f32 v[114:115], v[106:107], 0 op_sel_hi:[1,0]
	v_pk_add_f32 v[106:107], v[104:105], 0 op_sel_hi:[1,0]
	v_cvt_pk_bf16_f32 v104, v108, v109
	v_cvt_pk_bf16_f32 v105, v110, v111
	v_pk_add_f32 v[94:95], v[94:95], 0 op_sel_hi:[1,0]
	v_cvt_pk_bf16_f32 v106, v106, v107
	v_cvt_pk_bf16_f32 v107, v114, v115
	global_store_dwordx4 v[112:113], v[104:107], off
	v_pk_add_f32 v[92:93], v[92:93], 0 op_sel_hi:[1,0]
	v_pk_add_f32 v[84:85], v[84:85], 0 op_sel_hi:[1,0]
	v_pk_add_f32 v[104:105], v[98:99], 0 op_sel_hi:[1,0]
	v_pk_add_f32 v[98:99], v[96:97], 0 op_sel_hi:[1,0]
	v_cvt_pk_bf16_f32 v96, v100, v101
	v_cvt_pk_bf16_f32 v97, v102, v103
	v_pk_add_f32 v[86:87], v[86:87], 0 op_sel_hi:[1,0]
	v_cvt_pk_bf16_f32 v98, v98, v99
	v_cvt_pk_bf16_f32 v99, v104, v105
	global_store_dwordx4 v[112:113], v[96:99], off offset:256
	v_pk_add_f32 v[78:79], v[78:79], 0 op_sel_hi:[1,0]
	v_pk_add_f32 v[76:77], v[76:77], 0 op_sel_hi:[1,0]
	v_or_b32_e32 v96, 32, v154
	v_ashrrev_i32_e32 v97, 31, v96
	v_lshlrev_b64 v[96:97], 11, v[96:97]
	v_lshl_add_u64 v[96:97], s[10:11], 0, v[96:97]
	v_lshl_add_u64 v[96:97], v[96:97], 0, v[158:159]
; __device__ __forceinline__ unsigned cvt_pk_bf16(float lo, float hi) { unsigned r; asm volatile("v_cvt_pk_bf16_f32 %0, %1, %2" : "=v"(r) : "v"(lo), "v"(hi)); return r; }
; __device__ __forceinline__ float flogsig16(float x) { return (fminf(x, 0.f) - __logf(1.0f + __expf(-fabsf(x)))) * 0.0625f; }
; #define PG8_WAIT_V(n) asm volatile("s_waitcnt vmcnt(" #n ")" ::: "memory")
; #define PG8_BAR __builtin_amdgcn_s_barrier()
;     __device__ __forceinline__ void operator()(const f32x4 (&acc)[2][2][4][2], const Unit& u, int wr, int wc, int fr, int fq) const {
;     ...
;         for (int ai = 0; ai < 2; ++ai)
; #pragma unroll
;             for (int m = 0; m < 4; ++m) { bf16_t* rowp = O + (size_t)(row0 + ai * HALF + m * 16) * ldc + col0;
; #pragma unroll
;                 for (int bj = 0; bj < 2; ++bj) { f32x4 v0 = acc[ai][bj][m][0] + bv[bj][0], v1 = acc[ai][bj][m][1] + bv[bj][1];
;                     if (act == 1) {
; #pragma unroll
;                         for (int j = 0; j < 1; ++j) { v0 = v0 * sigmoid4(v0); v1 = v1 * sigmoid4(v1); } }
;                     else if (act == 2) {
; #pragma unroll
;                         for (int j = 0; j < 1; ++j) { v0 = sigmoid4(v0); v1 = sigmoid4(v1); } }
;                     else if (act == 3) {
; #pragma unroll
;                         for (int j = 0; j < 4; ++j) { v0[j] = flogsig16(v0[j]); v1[j] = flogsig16(v1[j]); } }
;                     u32x4 w; w.x = cvt_pk_bf16(v0[0], v0[1]); w.y = cvt_pk_bf16(v0[2], v0[3]); w.z = cvt_pk_bf16(v1[0], v1[1]); w.w = cvt_pk_bf16(v1[2], v1[3]);
;                     *(u32x4*)(rowp + bj * HALF) = w; } }
; template <class Epi, class Sched>
; __device__ __forceinline__ void gemm_phase(PG8_LAS unsigned char* lds, const Gemm g, const Sched& S, const Epi& E) {
;     ...
;         if (!has_next) break;
; #pragma unroll
;         for (int a = 0; a < 2; ++a)
; #pragma unroll
;             for (int b = 0; b < 2; ++b)
; #pragma unroll
;                 for (int m = 0; m < 4; ++m)
; #pragma unroll
;                     for (int n = 0; n < 2; ++n) acc[a][b][m][n] = (f32x4){0.f, 0.f, 0.f, 0.f};
;         cur = nxt; cA = nA; cB = nB; ++ui;
;     }
;     PG8_WAIT_V(0);
;     if (wr == 0) PG8_BAR;
	v_pk_add_f32 v[98:99], v[90:91], 0 op_sel_hi:[1,0]
	v_pk_add_f32 v[90:91], v[88:89], 0 op_sel_hi:[1,0]
	v_cvt_pk_bf16_f32 v88, v92, v93
	v_cvt_pk_bf16_f32 v89, v94, v95
	v_pk_add_f32 v[70:71], v[70:71], 0 op_sel_hi:[1,0]
	v_cvt_pk_bf16_f32 v90, v90, v91
	v_cvt_pk_bf16_f32 v91, v98, v99
	global_store_dwordx4 v[96:97], v[88:91], off
	v_pk_add_f32 v[68:69], v[68:69], 0 op_sel_hi:[1,0]
	s_mov_b64 s[22:23], 0x40000
	v_pk_add_f32 v[88:89], v[82:83], 0 op_sel_hi:[1,0]
	v_pk_add_f32 v[82:83], v[80:81], 0 op_sel_hi:[1,0]
	v_cvt_pk_bf16_f32 v80, v84, v85
	v_cvt_pk_bf16_f32 v81, v86, v87
	v_pk_add_f32 v[60:61], v[60:61], 0 op_sel_hi:[1,0]
	v_cvt_pk_bf16_f32 v82, v82, v83
	v_cvt_pk_bf16_f32 v83, v88, v89
	global_store_dwordx4 v[96:97], v[80:83], off offset:256
	v_pk_add_f32 v[62:63], v[62:63], 0 op_sel_hi:[1,0]
	v_pk_add_f32 v[54:55], v[54:55], 0 op_sel_hi:[1,0]
	v_or_b32_e32 v80, 48, v154
	v_ashrrev_i32_e32 v81, 31, v80
	v_lshlrev_b64 v[80:81], 11, v[80:81]
	v_lshl_add_u64 v[80:81], s[10:11], 0, v[80:81]
	v_lshl_add_u64 v[80:81], v[80:81], 0, v[158:159]
	v_pk_add_f32 v[82:83], v[74:75], 0 op_sel_hi:[1,0]
	v_pk_add_f32 v[74:75], v[72:73], 0 op_sel_hi:[1,0]
	v_cvt_pk_bf16_f32 v72, v76, v77
	v_cvt_pk_bf16_f32 v73, v78, v79
	v_pk_add_f32 v[52:53], v[52:53], 0 op_sel_hi:[1,0]
	v_cvt_pk_bf16_f32 v74, v74, v75
	v_cvt_pk_bf16_f32 v75, v82, v83
	global_store_dwordx4 v[80:81], v[72:75], off
	v_pk_add_f32 v[48:49], v[48:49], 0 op_sel_hi:[1,0]
	v_pk_add_f32 v[38:39], v[38:39], 0 op_sel_hi:[1,0]
	v_pk_add_f32 v[72:73], v[66:67], 0 op_sel_hi:[1,0]
	v_pk_add_f32 v[66:67], v[64:65], 0 op_sel_hi:[1,0]
	v_cvt_pk_bf16_f32 v64, v68, v69
	v_cvt_pk_bf16_f32 v65, v70, v71
	v_pk_add_f32 v[36:37], v[36:37], 0 op_sel_hi:[1,0]
	v_cvt_pk_bf16_f32 v66, v66, v67
	v_cvt_pk_bf16_f32 v67, v72, v73
	global_store_dwordx4 v[80:81], v[64:67], off offset:256
	v_pk_add_f32 v[32:33], v[32:33], 0 op_sel_hi:[1,0]
	v_pk_add_f32 v[22:23], v[22:23], 0 op_sel_hi:[1,0]
	v_lshl_add_u64 v[64:65], v[144:145], 0, s[22:23]
	s_mov_b32 s22, 0x40000
	v_pk_add_f32 v[66:67], v[58:59], 0 op_sel_hi:[1,0]
	v_pk_add_f32 v[58:59], v[56:57], 0 op_sel_hi:[1,0]
	v_cvt_pk_bf16_f32 v56, v60, v61
	v_add_co_u32_e32 v60, vcc, s22, v144
	v_cvt_pk_bf16_f32 v57, v62, v63
	v_cvt_pk_bf16_f32 v58, v58, v59
	v_cvt_pk_bf16_f32 v59, v66, v67
	s_mov_b64 s[22:23], 0x48000
	s_nop 0
	v_addc_co_u32_e32 v61, vcc, 0, v145, vcc
	global_store_dwordx4 v[60:61], v[56:59], off
	v_pk_add_f32 v[20:21], v[20:21], 0 op_sel_hi:[1,0]
	v_pk_add_f32 v[16:17], v[16:17], 0 op_sel_hi:[1,0]
	v_pk_add_f32 v[56:57], v[46:47], 0 op_sel_hi:[1,0]
	v_pk_add_f32 v[46:47], v[44:45], 0 op_sel_hi:[1,0]
	v_cvt_pk_bf16_f32 v44, v52, v53
	v_cvt_pk_bf16_f32 v45, v54, v55
	s_mov_b32 s54, s51
	v_cvt_pk_bf16_f32 v46, v46, v47
	v_cvt_pk_bf16_f32 v47, v56, v57
	global_store_dwordx4 v[64:65], v[44:47], off offset:256
	s_mov_b32 s53, s52
	s_mov_b64 s[24:25], s[4:5]
	v_pk_add_f32 v[46:47], v[50:51], 0 op_sel_hi:[1,0]
	v_pk_add_f32 v[50:51], v[42:43], 0 op_sel_hi:[1,0]
	v_pk_add_f32 v[42:43], v[40:41], 0 op_sel_hi:[1,0]
	v_cvt_pk_bf16_f32 v40, v48, v49
	v_cvt_pk_bf16_f32 v41, v46, v47
	v_add_co_u32_e32 v46, vcc, s48, v144
	v_cvt_pk_bf16_f32 v42, v42, v43
	v_cvt_pk_bf16_f32 v43, v50, v51
	v_lshl_add_u64 v[44:45], v[144:145], 0, s[22:23]
	s_nop 0
	v_addc_co_u32_e32 v47, vcc, 0, v145, vcc
	global_store_dwordx4 v[46:47], v[40:43], off
	s_mov_b64 s[22:23], s[0:1]
	v_pk_add_f32 v[6:7], v[6:7], 0 op_sel_hi:[1,0]
	v_pk_add_f32 v[40:41], v[30:31], 0 op_sel_hi:[1,0]
	v_pk_add_f32 v[30:31], v[28:29], 0 op_sel_hi:[1,0]
	v_cvt_pk_bf16_f32 v28, v36, v37
	v_cvt_pk_bf16_f32 v29, v38, v39
	v_pk_add_f32 v[4:5], v[4:5], 0 op_sel_hi:[1,0]
	v_cvt_pk_bf16_f32 v30, v30, v31
	v_cvt_pk_bf16_f32 v31, v40, v41
	global_store_dwordx4 v[44:45], v[28:31], off offset:256
	s_nop 1
	v_pk_add_f32 v[30:31], v[34:35], 0 op_sel_hi:[1,0]
	v_pk_add_f32 v[34:35], v[26:27], 0 op_sel_hi:[1,0]
	v_pk_add_f32 v[26:27], v[24:25], 0 op_sel_hi:[1,0]
	v_cvt_pk_bf16_f32 v24, v32, v33
	v_cvt_pk_bf16_f32 v25, v30, v31
	v_add_co_u32_e32 v30, vcc, s49, v144
	v_cvt_pk_bf16_f32 v26, v26, v27
	v_cvt_pk_bf16_f32 v27, v34, v35
	v_lshl_add_u64 v[28:29], v[144:145], 0, s[16:17]
	s_nop 0
	v_addc_co_u32_e32 v31, vcc, 0, v145, vcc
	global_store_dwordx4 v[30:31], v[24:27], off
	s_nop 1
	v_pk_add_f32 v[24:25], v[14:15], 0 op_sel_hi:[1,0]
	v_pk_add_f32 v[14:15], v[12:13], 0 op_sel_hi:[1,0]
	v_cvt_pk_bf16_f32 v12, v20, v21
	v_cvt_pk_bf16_f32 v13, v22, v23
	s_nop 0
	v_cvt_pk_bf16_f32 v14, v14, v15
	v_cvt_pk_bf16_f32 v15, v24, v25
	global_store_dwordx4 v[28:29], v[12:15], off offset:256
	s_nop 1
	v_pk_add_f32 v[14:15], v[18:19], 0 op_sel_hi:[1,0]
	v_pk_add_f32 v[18:19], v[10:11], 0 op_sel_hi:[1,0]
	v_pk_add_f32 v[10:11], v[8:9], 0 op_sel_hi:[1,0]
	v_cvt_pk_bf16_f32 v8, v16, v17
	v_cvt_pk_bf16_f32 v9, v14, v15
	v_add_co_u32_e32 v14, vcc, s50, v144
	v_lshl_add_u64 v[12:13], v[144:145], 0, s[18:19]
	s_nop 0
	v_addc_co_u32_e32 v15, vcc, 0, v145, vcc
	v_cvt_pk_bf16_f32 v10, v10, v11
	v_cvt_pk_bf16_f32 v11, v18, v19
	global_store_dwordx4 v[14:15], v[8:11], off
	s_and_b64 vcc, exec, s[2:3]
	s_nop 0
	v_pk_add_f32 v[8:9], v[2:3], 0 op_sel_hi:[1,0]
	v_pk_add_f32 v[2:3], v[0:1], 0 op_sel_hi:[1,0]
	v_cvt_pk_bf16_f32 v0, v4, v5
	v_cvt_pk_bf16_f32 v1, v6, v7
	s_nop 0
	v_cvt_pk_bf16_f32 v2, v2, v3
	v_cvt_pk_bf16_f32 v3, v8, v9
	global_store_dwordx4 v[12:13], v[0:3], off offset:256
	s_cbranch_vccz .LBB0_275
	s_waitcnt vmcnt(0)
	s_cmpk_gt_u32 s31, 0xff
	s_cbranch_scc1 .LBB0_290
	s_barrier

; #define PG8_STAGE(bufoff, gbase, voff) do { _Pragma("unroll") for (int _i = 0; _i < 2; ++_i) \
;         __builtin_amdgcn_global_load_lds((const unsigned*)((const char*)(gbase) + (voff)[_i]), (PG8_LAS unsigned*)(lds + (bufoff) + ldsw + _i * 8192), 16, 0, 0); } while (0)
; #define PG8_LDA(dst, b, h) do { _Pragma("unroll") for (int m = 0; m < 4; ++m) _Pragma("unroll") for (int k = 0; k < 2; ++k) dst[m][k] = *(const PG8_LAS bf16x8*)(lds + PG8_SA(b, h) + aoff + m * 2048 + k * 1024); } while (0)
; #define PG8_LDB(dst, b, h) do { _Pragma("unroll") for (int n = 0; n < 2; ++n) _Pragma("unroll") for (int k = 0; k < 2; ++k) dst[n][k] = *(const PG8_LAS bf16x8*)(lds + PG8_SB(b, h) + boff + n * 2048 + k * 1024); } while (0)
; #define PG8_WAIT_V(n) asm volatile("s_waitcnt vmcnt(" #n ")" ::: "memory")
; #define PG8_WAIT_L(n) asm volatile("s_waitcnt lgkmcnt(" #n ")" ::: "memory")
; #define PG8_BAR __builtin_amdgcn_s_barrier()
; #define PG8_SCHED __builtin_amdgcn_sched_barrier(0)
; template <class Epi, class Sched>
; __device__ __forceinline__ void gemm_phase(PG8_LAS unsigned char* lds, const Gemm g, const Sched& S, const Epi& E) {
;     ...
;             PG8_LDB(B0, 0, 0); PG8_SCHED; PG8_LDA(At, 0, 0); PG8_STAGE(PG8_SA(1, 1), a1 + hstep, voffA);
;             PG8_WAIT_L(8); PG8_BAR; PG8_WAIT_L(0); PG8_MMA(0, 0, At, B0); PG8_BAR; PG8_SCHED;
;             PG8_LDB(B1, 0, 1); PG8_STAGE(PG8_SB(0, 0), b2, voffB);
;             PG8_BAR; PG8_WAIT_L(0); PG8_MMA(0, 1, At, B1); PG8_BAR;
;             PG8_LDA(At, 0, 1); PG8_STAGE(PG8_SA(0, 0), a2, voffA);
;             PG8_BAR; PG8_WAIT_L(0); PG8_MMA(1, 0, At, B0); PG8_BAR; PG8_SCHED;
;             PG8_STAGE(PG8_SB(0, 1), b2 + hstep, voffB);
;             PG8_WAIT_V(6); PG8_BAR; PG8_MMA(1, 1, At, B1); PG8_BAR;
;             PG8_LDB(B0, 1, 0); PG8_SCHED; PG8_LDA(At, 1, 0); PG8_STAGE(PG8_SA(0, 1), a2 + hstep, voffA);
;             PG8_WAIT_L(8); PG8_BAR; PG8_WAIT_L(0); PG8_MMA(0, 0, At, B0); PG8_BAR; PG8_SCHED;
;             PG8_LDB(B1, 1, 1); PG8_STAGE(PG8_SB(1, 0), b3, voffB);
;             PG8_BAR; PG8_WAIT_L(0); PG8_MMA(0, 1, At, B1); PG8_BAR;
;             PG8_LDA(At, 1, 1); PG8_STAGE(PG8_SA(1, 0), a3, voffA);
;             PG8_BAR; PG8_WAIT_L(0); PG8_MMA(1, 0, At, B0); PG8_BAR; PG8_SCHED;
;             PG8_STAGE(PG8_SB(1, 1), b3 + hstep, voffB);
;             PG8_WAIT_V(6); PG8_BAR; PG8_MMA(1, 1, At, B1); PG8_BAR;
.LBB0_416:
	ds_read_b128 v[24:27], v186
	ds_read_b128 v[28:31], v186 offset:1024
	ds_read_b128 v[40:43], v186 offset:2048
	ds_read_b128 v[44:47], v186 offset:3072
	s_add_u32 s4, s0, 0xfffc0080
	s_addc_u32 s5, s1, -1
	s_cmp_eq_u32 s53, 12
	s_cselect_b32 s29, s7, s5
	s_cselect_b32 s28, s10, s4
	s_cselect_b32 s5, s19, s52
	s_cselect_b32 s4, s21, s51
	v_lshl_add_u64 v[174:175], s[0:1], 0, v[166:167]
	s_add_i32 m0, s27, 0xc000
	ds_read_b128 v[144:147], v187
	ds_read_b128 v[148:151], v187 offset:1024
	ds_read_b128 v[182:185], v187 offset:2048
	ds_read_b128 v[192:195], v187 offset:3072
	ds_read_b128 v[196:199], v187 offset:4096
	ds_read_b128 v[200:203], v187 offset:5120
	ds_read_b128 v[204:207], v187 offset:6144
	ds_read_b128 v[208:211], v187 offset:7168
	global_load_lds_dwordx4 v[174:175], off
	v_lshl_add_u64 v[174:175], s[0:1], 0, v[168:169]
	s_add_i32 m0, s27, 0xe000
	s_nop 0
	global_load_lds_dwordx4 v[174:175], off
	s_waitcnt lgkmcnt(8)
	s_barrier
	s_waitcnt lgkmcnt(0)
	v_mfma_f32_16x16x32_bf16 v[140:143], v[24:27], v[144:147], v[140:143]
	v_mfma_f32_16x16x32_bf16 v[136:139], v[40:43], v[144:147], v[136:139]
	v_mfma_f32_16x16x32_bf16 v[124:127], v[24:27], v[182:185], v[124:127]
	v_mfma_f32_16x16x32_bf16 v[120:123], v[40:43], v[182:185], v[120:123]
	v_mfma_f32_16x16x32_bf16 v[108:111], v[24:27], v[196:199], v[108:111]
	v_mfma_f32_16x16x32_bf16 v[104:107], v[40:43], v[196:199], v[104:107]
	v_mfma_f32_16x16x32_bf16 v[92:95], v[24:27], v[204:207], v[92:95]
	v_mfma_f32_16x16x32_bf16 v[88:91], v[40:43], v[204:207], v[88:91]
	v_mfma_f32_16x16x32_bf16 v[140:143], v[28:31], v[148:151], v[140:143]
	v_mfma_f32_16x16x32_bf16 v[136:139], v[44:47], v[148:151], v[136:139]
	v_mfma_f32_16x16x32_bf16 v[124:127], v[28:31], v[192:195], v[124:127]
	v_mfma_f32_16x16x32_bf16 v[120:123], v[44:47], v[192:195], v[120:123]
	v_mfma_f32_16x16x32_bf16 v[108:111], v[28:31], v[200:203], v[108:111]
	v_mfma_f32_16x16x32_bf16 v[104:107], v[44:47], v[200:203], v[104:107]
	v_mfma_f32_16x16x32_bf16 v[92:95], v[28:31], v[208:211], v[92:95]
	v_mfma_f32_16x16x32_bf16 v[88:91], v[44:47], v[208:211], v[88:91]
	s_barrier
	s_add_i32 s54, s43, s35
	v_lshl_add_u64 v[174:175], s[4:5], 0, v[156:157]
	s_mov_b32 m0, s54
	ds_read_b128 v[212:215], v189
	ds_read_b128 v[216:219], v189 offset:1024
	ds_read_b128 v[220:223], v189 offset:2048
	ds_read_b128 v[224:227], v189 offset:3072
	global_load_lds_dwordx4 v[174:175], off
	v_lshl_add_u64 v[228:229], s[4:5], 0, v[160:161]
	s_add_i32 m0, s54, 0x2000
	s_nop 0
	global_load_lds_dwordx4 v[228:229], off
	s_barrier
	s_waitcnt lgkmcnt(0)
	v_mfma_f32_16x16x32_bf16 v[132:135], v[212:215], v[144:147], v[132:135]
	v_mfma_f32_16x16x32_bf16 v[128:131], v[220:223], v[144:147], v[128:131]
	v_mfma_f32_16x16x32_bf16 v[116:119], v[212:215], v[182:185], v[116:119]
	v_mfma_f32_16x16x32_bf16 v[112:115], v[220:223], v[182:185], v[112:115]
	v_mfma_f32_16x16x32_bf16 v[100:103], v[212:215], v[196:199], v[100:103]
	v_mfma_f32_16x16x32_bf16 v[96:99], v[220:223], v[196:199], v[96:99]
	v_mfma_f32_16x16x32_bf16 v[84:87], v[212:215], v[204:207], v[84:87]
	v_mfma_f32_16x16x32_bf16 v[80:83], v[220:223], v[204:207], v[80:83]
	v_mfma_f32_16x16x32_bf16 v[132:135], v[216:219], v[148:151], v[132:135]
	v_mfma_f32_16x16x32_bf16 v[128:131], v[224:227], v[148:151], v[128:131]
	v_mfma_f32_16x16x32_bf16 v[116:119], v[216:219], v[192:195], v[116:119]
	v_mfma_f32_16x16x32_bf16 v[112:115], v[224:227], v[192:195], v[112:115]
	v_mfma_f32_16x16x32_bf16 v[100:103], v[216:219], v[200:203], v[100:103]
	v_mfma_f32_16x16x32_bf16 v[96:99], v[224:227], v[200:203], v[96:99]
	v_mfma_f32_16x16x32_bf16 v[84:87], v[216:219], v[208:211], v[84:87]
	v_mfma_f32_16x16x32_bf16 v[80:83], v[224:227], v[208:211], v[80:83]
	s_mov_b32 m0, s27
	v_lshl_add_u64 v[230:231], s[28:29], 0, v[154:155]
	s_barrier
	ds_read_b128 v[144:147], v187 offset:16384
	ds_read_b128 v[148:151], v187 offset:17408
	ds_read_b128 v[182:185], v187 offset:18432
	ds_read_b128 v[192:195], v187 offset:19456
	ds_read_b128 v[196:199], v187 offset:20480
	ds_read_b128 v[200:203], v187 offset:21504
	ds_read_b128 v[204:207], v187 offset:22528
	ds_read_b128 v[208:211], v187 offset:23552
	global_load_lds_dwordx4 v[230:231], off
	v_lshl_add_u64 v[232:233], s[28:29], 0, v[158:159]
	s_mov_b32 m0, s36
	s_nop 0
	global_load_lds_dwordx4 v[232:233], off
	s_barrier
	s_waitcnt lgkmcnt(0)
	v_mfma_f32_16x16x32_bf16 v[76:79], v[24:27], v[144:147], v[76:79]
	v_mfma_f32_16x16x32_bf16 v[72:75], v[40:43], v[144:147], v[72:75]
	v_mfma_f32_16x16x32_bf16 v[60:63], v[24:27], v[182:185], v[60:63]
	v_mfma_f32_16x16x32_bf16 v[56:59], v[40:43], v[182:185], v[56:59]
	v_mfma_f32_16x16x32_bf16 v[36:39], v[24:27], v[196:199], v[36:39]
	v_mfma_f32_16x16x32_bf16 v[32:35], v[40:43], v[196:199], v[32:35]
	v_mfma_f32_16x16x32_bf16 v[12:15], v[24:27], v[204:207], v[12:15]
	v_mfma_f32_16x16x32_bf16 v[8:11], v[40:43], v[204:207], v[8:11]
	v_mfma_f32_16x16x32_bf16 v[76:79], v[28:31], v[148:151], v[76:79]
	v_mfma_f32_16x16x32_bf16 v[72:75], v[44:47], v[148:151], v[72:75]
	v_mfma_f32_16x16x32_bf16 v[60:63], v[28:31], v[192:195], v[60:63]
	v_mfma_f32_16x16x32_bf16 v[56:59], v[44:47], v[192:195], v[56:59]
	v_mfma_f32_16x16x32_bf16 v[36:39], v[28:31], v[200:203], v[36:39]
	v_mfma_f32_16x16x32_bf16 v[32:35], v[44:47], v[200:203], v[32:35]
	v_mfma_f32_16x16x32_bf16 v[12:15], v[28:31], v[208:211], v[12:15]
	v_mfma_f32_16x16x32_bf16 v[8:11], v[44:47], v[208:211], v[8:11]
	s_barrier
	s_add_u32 s54, s4, 0x40000
	s_addc_u32 s55, s5, 0
	s_add_i32 s56, s44, s35
	v_lshl_add_u64 v[24:25], s[54:55], 0, v[156:157]
	s_mov_b32 m0, s56
	s_nop 0
	global_load_lds_dwordx4 v[24:25], off
	v_lshl_add_u64 v[24:25], s[54:55], 0, v[160:161]
	s_add_i32 m0, s56, 0x2000
	s_nop 0
	global_load_lds_dwordx4 v[24:25], off
	s_waitcnt vmcnt(6)
	s_barrier
; #define PG8_STAGE(bufoff, gbase, voff) do { _Pragma("unroll") for (int _i = 0; _i < 2; ++_i) \
;         __builtin_amdgcn_global_load_lds((const unsigned*)((const char*)(gbase) + (voff)[_i]), (PG8_LAS unsigned*)(lds + (bufoff) + ldsw + _i * 8192), 16, 0, 0); } while (0)
; #define PG8_LDA(dst, b, h) do { _Pragma("unroll") for (int m = 0; m < 4; ++m) _Pragma("unroll") for (int k = 0; k < 2; ++k) dst[m][k] = *(const PG8_LAS bf16x8*)(lds + PG8_SA(b, h) + aoff + m * 2048 + k * 1024); } while (0)
; #define PG8_LDB(dst, b, h) do { _Pragma("unroll") for (int n = 0; n < 2; ++n) _Pragma("unroll") for (int k = 0; k < 2; ++k) dst[n][k] = *(const PG8_LAS bf16x8*)(lds + PG8_SB(b, h) + boff + n * 2048 + k * 1024); } while (0)
; #define PG8_MMA(ai, bj, At, Bt) do { __builtin_amdgcn_s_setprio(1); _Pragma("unroll") for (int m = 0; m < 4; ++m) _Pragma("unroll") for (int n = 0; n < 2; ++n) _Pragma("unroll") for (int k = 0; k < 2; ++k) \
;         acc[ai][bj][m][n] = __builtin_amdgcn_mfma_f32_16x16x32_bf16(Bt[n][k], At[m][k], acc[ai][bj][m][n], 0, 0, 0); __builtin_amdgcn_s_setprio(0); } while (0)
; #define PG8_WAIT_V(n) asm volatile("s_waitcnt vmcnt(" #n ")" ::: "memory")
; #define PG8_WAIT_L(n) asm volatile("s_waitcnt lgkmcnt(" #n ")" ::: "memory")
; #define PG8_BAR __builtin_amdgcn_s_barrier()
; #define PG8_SCHED __builtin_amdgcn_sched_barrier(0)
; template <class Epi, class Sched>
; __device__ __forceinline__ void gemm_phase(PG8_LAS unsigned char* lds, const Gemm g, const Sched& S, const Epi& E) {
;     ...
;             PG8_WAIT_V(6); PG8_BAR; PG8_MMA(1, 1, At, B1); PG8_BAR;
;             PG8_LDB(B0, 1, 0); PG8_SCHED; PG8_LDA(At, 1, 0); PG8_STAGE(PG8_SA(0, 1), a2 + hstep, voffA);
;             PG8_WAIT_L(8); PG8_BAR; PG8_WAIT_L(0); PG8_MMA(0, 0, At, B0); PG8_BAR; PG8_SCHED;
;             PG8_LDB(B1, 1, 1); PG8_STAGE(PG8_SB(1, 0), b3, voffB);
;             PG8_BAR; PG8_WAIT_L(0); PG8_MMA(0, 1, At, B1); PG8_BAR;
;             PG8_LDA(At, 1, 1); PG8_STAGE(PG8_SA(1, 0), a3, voffA);
;             PG8_BAR; PG8_WAIT_L(0); PG8_MMA(1, 0, At, B0); PG8_BAR; PG8_SCHED;
	v_mfma_f32_16x16x32_bf16 v[20:23], v[212:215], v[196:199], v[20:23]
	v_mfma_f32_16x16x32_bf16 v[16:19], v[220:223], v[196:199], v[16:19]
	v_mfma_f32_16x16x32_bf16 v[4:7], v[212:215], v[204:207], v[4:7]
	v_mfma_f32_16x16x32_bf16 v[0:3], v[220:223], v[204:207], v[0:3]
	v_mfma_f32_16x16x32_bf16 v[24:27], v[212:215], v[144:147], v[68:71]
	v_mfma_f32_16x16x32_bf16 v[28:31], v[220:223], v[144:147], v[64:67]
	v_mfma_f32_16x16x32_bf16 v[40:43], v[212:215], v[182:185], v[52:55]
	v_mfma_f32_16x16x32_bf16 v[44:47], v[220:223], v[182:185], v[48:51]
	v_mfma_f32_16x16x32_bf16 v[20:23], v[216:219], v[200:203], v[20:23]
	v_mfma_f32_16x16x32_bf16 v[16:19], v[224:227], v[200:203], v[16:19]
	v_mfma_f32_16x16x32_bf16 v[4:7], v[216:219], v[208:211], v[4:7]
	v_mfma_f32_16x16x32_bf16 v[0:3], v[224:227], v[208:211], v[0:3]
	v_mfma_f32_16x16x32_bf16 v[24:27], v[216:219], v[148:151], v[24:27]
	v_mfma_f32_16x16x32_bf16 v[28:31], v[224:227], v[148:151], v[28:31]
	v_mfma_f32_16x16x32_bf16 v[40:43], v[216:219], v[192:195], v[40:43]
	v_mfma_f32_16x16x32_bf16 v[44:47], v[224:227], v[192:195], v[44:47]
	s_add_i32 s54, 0, 0x18000
	v_add_u32_e32 v68, s54, v179
	s_barrier
	ds_read_b128 v[48:51], v68
	ds_read_b128 v[52:55], v68 offset:1024
	ds_read_b128 v[64:67], v68 offset:2048
	ds_read_b128 v[68:71], v68 offset:3072
	s_add_u32 s28, s28, 0x40000
	s_addc_u32 s29, s29, 0
	s_mov_b32 m0, s37
	v_lshl_add_u64 v[212:213], s[28:29], 0, v[154:155]
	ds_read_b128 v[144:147], v187 offset:32768
	ds_read_b128 v[148:151], v187 offset:33792
	ds_read_b128 v[182:185], v187 offset:34816
	ds_read_b128 v[192:195], v187 offset:35840
	ds_read_b128 v[196:199], v187 offset:36864
	ds_read_b128 v[200:203], v187 offset:37888
	ds_read_b128 v[204:207], v187 offset:38912
	ds_read_b128 v[208:211], v187 offset:39936
	global_load_lds_dwordx4 v[212:213], off
	v_lshl_add_u64 v[212:213], s[28:29], 0, v[158:159]
	s_mov_b32 m0, s38
	s_nop 0
	global_load_lds_dwordx4 v[212:213], off
	s_waitcnt lgkmcnt(8)
	s_barrier
	s_waitcnt lgkmcnt(0)
	v_mfma_f32_16x16x32_bf16 v[140:143], v[48:51], v[144:147], v[140:143]
	v_mfma_f32_16x16x32_bf16 v[136:139], v[64:67], v[144:147], v[136:139]
	v_mfma_f32_16x16x32_bf16 v[124:127], v[48:51], v[182:185], v[124:127]
	v_mfma_f32_16x16x32_bf16 v[120:123], v[64:67], v[182:185], v[120:123]
	v_mfma_f32_16x16x32_bf16 v[108:111], v[48:51], v[196:199], v[108:111]
	v_mfma_f32_16x16x32_bf16 v[104:107], v[64:67], v[196:199], v[104:107]
	v_mfma_f32_16x16x32_bf16 v[92:95], v[48:51], v[204:207], v[92:95]
	v_mfma_f32_16x16x32_bf16 v[88:91], v[64:67], v[204:207], v[88:91]
	v_mfma_f32_16x16x32_bf16 v[140:143], v[52:55], v[148:151], v[140:143]
	v_mfma_f32_16x16x32_bf16 v[136:139], v[68:71], v[148:151], v[136:139]
	v_mfma_f32_16x16x32_bf16 v[124:127], v[52:55], v[192:195], v[124:127]
	v_mfma_f32_16x16x32_bf16 v[120:123], v[68:71], v[192:195], v[120:123]
	v_mfma_f32_16x16x32_bf16 v[108:111], v[52:55], v[200:203], v[108:111]
	v_mfma_f32_16x16x32_bf16 v[104:107], v[68:71], v[200:203], v[104:107]
	v_mfma_f32_16x16x32_bf16 v[92:95], v[52:55], v[208:211], v[92:95]
	v_mfma_f32_16x16x32_bf16 v[88:91], v[68:71], v[208:211], v[88:91]
	s_barrier
	s_add_i32 s28, 0, 0x1c000
	s_add_i32 s29, s54, s35
	v_add_u32_e32 v162, s28, v179
	v_lshl_add_u64 v[174:175], v[174:175], 0, s[14:15]
	s_mov_b32 m0, s29
	ds_read_b128 v[212:215], v162
	ds_read_b128 v[216:219], v162 offset:1024
	ds_read_b128 v[220:223], v162 offset:2048
	ds_read_b128 v[224:227], v162 offset:3072
	global_load_lds_dwordx4 v[174:175], off
	v_lshl_add_u64 v[174:175], v[228:229], 0, s[14:15]
	s_add_i32 m0, s29, 0x2000
	s_nop 0
	global_load_lds_dwordx4 v[174:175], off
	s_barrier
	s_waitcnt lgkmcnt(0)
	v_mfma_f32_16x16x32_bf16 v[132:135], v[212:215], v[144:147], v[132:135]
	v_mfma_f32_16x16x32_bf16 v[128:131], v[220:223], v[144:147], v[128:131]
	v_mfma_f32_16x16x32_bf16 v[116:119], v[212:215], v[182:185], v[116:119]
	v_mfma_f32_16x16x32_bf16 v[112:115], v[220:223], v[182:185], v[112:115]
	v_mfma_f32_16x16x32_bf16 v[100:103], v[212:215], v[196:199], v[100:103]
	v_mfma_f32_16x16x32_bf16 v[96:99], v[220:223], v[196:199], v[96:99]
	v_mfma_f32_16x16x32_bf16 v[84:87], v[212:215], v[204:207], v[84:87]
	v_mfma_f32_16x16x32_bf16 v[80:83], v[220:223], v[204:207], v[80:83]
	v_mfma_f32_16x16x32_bf16 v[132:135], v[216:219], v[148:151], v[132:135]
	v_mfma_f32_16x16x32_bf16 v[128:131], v[224:227], v[148:151], v[128:131]
	v_mfma_f32_16x16x32_bf16 v[116:119], v[216:219], v[192:195], v[116:119]
	v_mfma_f32_16x16x32_bf16 v[112:115], v[224:227], v[192:195], v[112:115]
	v_mfma_f32_16x16x32_bf16 v[100:103], v[216:219], v[200:203], v[100:103]
	v_mfma_f32_16x16x32_bf16 v[96:99], v[224:227], v[200:203], v[96:99]
	v_mfma_f32_16x16x32_bf16 v[84:87], v[216:219], v[208:211], v[84:87]
	v_mfma_f32_16x16x32_bf16 v[80:83], v[224:227], v[208:211], v[80:83]
	s_mov_b32 m0, s39
	v_lshl_add_u64 v[174:175], v[230:231], 0, s[14:15]
	s_barrier
; #define PG8_STAGE(bufoff, gbase, voff) do { _Pragma("unroll") for (int _i = 0; _i < 2; ++_i) \
;         __builtin_amdgcn_global_load_lds((const unsigned*)((const char*)(gbase) + (voff)[_i]), (PG8_LAS unsigned*)(lds + (bufoff) + ldsw + _i * 8192), 16, 0, 0); } while (0)
; #define PG8_LDA(dst, b, h) do { _Pragma("unroll") for (int m = 0; m < 4; ++m) _Pragma("unroll") for (int k = 0; k < 2; ++k) dst[m][k] = *(const PG8_LAS bf16x8*)(lds + PG8_SA(b, h) + aoff + m * 2048 + k * 1024); } while (0)
; #define PG8_MMA(ai, bj, At, Bt) do { __builtin_amdgcn_s_setprio(1); _Pragma("unroll") for (int m = 0; m < 4; ++m) _Pragma("unroll") for (int n = 0; n < 2; ++n) _Pragma("unroll") for (int k = 0; k < 2; ++k) \
;         acc[ai][bj][m][n] = __builtin_amdgcn_mfma_f32_16x16x32_bf16(Bt[n][k], At[m][k], acc[ai][bj][m][n], 0, 0, 0); __builtin_amdgcn_s_setprio(0); } while (0)
; #define PG8_WAIT_V(n) asm volatile("s_waitcnt vmcnt(" #n ")" ::: "memory")
; #define PG8_WAIT_L(n) asm volatile("s_waitcnt lgkmcnt(" #n ")" ::: "memory")
; #define PG8_BAR __builtin_amdgcn_s_barrier()
; #define PG8_SCHED __builtin_amdgcn_sched_barrier(0)
;     __device__ __forceinline__ void operator()(const f32x4 (&acc)[2][2][4][2], const Unit& u, int wr, int wc, int fr, int fq) const {
;     ...
;         if (mode == 1) { if (u.pn >= 8 && u.pn < 12) act = 1; else if (u.pn >= 12) { act = 3; bias = (u.pn >= 14) ? bias_b + (u.pn - 14) * 256 : bias_f + (u.pn - 12) * 256; } }
; template <class Epi, class Sched>
; __device__ __forceinline__ void gemm_phase(PG8_LAS unsigned char* lds, const Gemm g, const Sched& S, const Epi& E) {
;     ...
;             PG8_LDA(At, 1, 1); PG8_STAGE(PG8_SA(1, 0), a3, voffA);
;             PG8_BAR; PG8_WAIT_L(0); PG8_MMA(1, 0, At, B0); PG8_BAR; PG8_SCHED;
;             PG8_STAGE(PG8_SB(1, 1), b3 + hstep, voffB);
;             PG8_WAIT_V(6); PG8_BAR; PG8_MMA(1, 1, At, B1); PG8_BAR;
	ds_read_b128 v[144:147], v187 offset:49152
	ds_read_b128 v[148:151], v187 offset:50176
	ds_read_b128 v[182:185], v187 offset:51200
	ds_read_b128 v[192:195], v187 offset:52224
	ds_read_b128 v[196:199], v187 offset:53248
	ds_read_b128 v[200:203], v187 offset:54272
	ds_read_b128 v[204:207], v187 offset:55296
	ds_read_b128 v[208:211], v187 offset:56320
	global_load_lds_dwordx4 v[174:175], off
	v_lshl_add_u64 v[174:175], v[232:233], 0, s[14:15]
	s_mov_b32 m0, s40
	s_nop 0
	global_load_lds_dwordx4 v[174:175], off
	s_barrier
	s_waitcnt lgkmcnt(0)
	v_mfma_f32_16x16x32_bf16 v[76:79], v[48:51], v[144:147], v[76:79]
	v_mfma_f32_16x16x32_bf16 v[72:75], v[64:67], v[144:147], v[72:75]
	v_mfma_f32_16x16x32_bf16 v[60:63], v[48:51], v[182:185], v[60:63]
	v_mfma_f32_16x16x32_bf16 v[56:59], v[64:67], v[182:185], v[56:59]
	v_mfma_f32_16x16x32_bf16 v[36:39], v[48:51], v[196:199], v[36:39]
	v_mfma_f32_16x16x32_bf16 v[32:35], v[64:67], v[196:199], v[32:35]
	v_mfma_f32_16x16x32_bf16 v[12:15], v[48:51], v[204:207], v[12:15]
	v_mfma_f32_16x16x32_bf16 v[8:11], v[64:67], v[204:207], v[8:11]
	v_mfma_f32_16x16x32_bf16 v[76:79], v[52:55], v[148:151], v[76:79]
	v_mfma_f32_16x16x32_bf16 v[72:75], v[68:71], v[148:151], v[72:75]
	v_mfma_f32_16x16x32_bf16 v[60:63], v[52:55], v[192:195], v[60:63]
	v_mfma_f32_16x16x32_bf16 v[56:59], v[68:71], v[192:195], v[56:59]
	v_mfma_f32_16x16x32_bf16 v[36:39], v[52:55], v[200:203], v[36:39]
	v_mfma_f32_16x16x32_bf16 v[32:35], v[68:71], v[200:203], v[32:35]
	v_mfma_f32_16x16x32_bf16 v[12:15], v[52:55], v[208:211], v[12:15]
	v_mfma_f32_16x16x32_bf16 v[8:11], v[68:71], v[208:211], v[8:11]
	s_barrier
	s_add_u32 s4, s4, 0x40080
	s_addc_u32 s5, s5, 0
	s_add_i32 s28, s28, s35
	v_lshl_add_u64 v[48:49], s[4:5], 0, v[156:157]
	s_mov_b32 m0, s28
	s_nop 0
	global_load_lds_dwordx4 v[48:49], off
	v_lshl_add_u64 v[48:49], s[4:5], 0, v[160:161]
	s_add_i32 m0, s28, 0x2000
	s_nop 0
	global_load_lds_dwordx4 v[48:49], off
	s_waitcnt vmcnt(6)
	s_barrier
	v_mfma_f32_16x16x32_bf16 v[24:27], v[212:215], v[144:147], v[24:27]
	v_mfma_f32_16x16x32_bf16 v[68:71], v[216:219], v[148:151], v[24:27]
	v_mfma_f32_16x16x32_bf16 v[24:27], v[220:223], v[144:147], v[28:31]
	v_mfma_f32_16x16x32_bf16 v[64:67], v[224:227], v[148:151], v[24:27]
	v_mfma_f32_16x16x32_bf16 v[24:27], v[212:215], v[182:185], v[40:43]
	v_mfma_f32_16x16x32_bf16 v[52:55], v[216:219], v[192:195], v[24:27]
	v_mfma_f32_16x16x32_bf16 v[24:27], v[220:223], v[182:185], v[44:47]
	v_mfma_f32_16x16x32_bf16 v[20:23], v[212:215], v[196:199], v[20:23]
	v_mfma_f32_16x16x32_bf16 v[16:19], v[220:223], v[196:199], v[16:19]
	v_mfma_f32_16x16x32_bf16 v[4:7], v[212:215], v[204:207], v[4:7]
	v_mfma_f32_16x16x32_bf16 v[0:3], v[220:223], v[204:207], v[0:3]
	v_mfma_f32_16x16x32_bf16 v[48:51], v[224:227], v[192:195], v[24:27]
	v_mfma_f32_16x16x32_bf16 v[20:23], v[216:219], v[200:203], v[20:23]
	v_mfma_f32_16x16x32_bf16 v[16:19], v[224:227], v[200:203], v[16:19]
	v_mfma_f32_16x16x32_bf16 v[4:7], v[216:219], v[208:211], v[4:7]
	v_mfma_f32_16x16x32_bf16 v[0:3], v[224:227], v[208:211], v[0:3]
	s_add_i32 s53, s53, 2
	s_add_u32 s0, s0, 0x100
	s_addc_u32 s1, s1, 0
	s_add_u32 s51, s51, 0x100
	s_addc_u32 s52, s52, 0
	s_cmp_gt_u32 s53, 13
	s_barrier
	s_cbranch_scc0 .LBB0_416
	s_cmp_gt_i32 s26, 11
	s_cselect_b64 s[4:5], -1, 0
	s_cmp_lt_i32 s26, 12
	s_mov_b64 s[0:1], 0
	s_cbranch_scc1 .LBB0_422
	s_lshl_b32 s10, s26, 8
	s_cmp_lt_u32 s26, 14
	s_mov_b64 s[28:29], -1
	s_cbranch_scc0 .LBB0_420
	s_lshl_b64 s[0:1], s[10:11], 2
	v_readlane_b32 s52, v245, 0
	v_readlane_b32 s53, v245, 1
	s_add_u32 s0, s52, s0
	s_addc_u32 s1, s53, s1
	s_add_u32 s0, s0, 0xffffd000
	v_readlane_b32 s54, v245, 2
	v_readlane_b32 s55, v245, 3
	v_readlane_b32 s56, v245, 4
	v_readlane_b32 s57, v245, 5
	v_readlane_b32 s58, v245, 6
	v_readlane_b32 s59, v245, 7
	v_readlane_b32 s60, v245, 8
	v_readlane_b32 s61, v245, 9
	v_readlane_b32 s62, v245, 10
	v_readlane_b32 s63, v245, 11
	v_readlane_b32 s64, v245, 12
	v_readlane_b32 s65, v245, 13
	v_readlane_b32 s66, v245, 14
	v_readlane_b32 s67, v245, 15
	s_addc_u32 s1, s1, -1
	s_mov_b64 s[28:29], 0

; #define PG8_STAGE(bufoff, gbase, voff) do { _Pragma("unroll") for (int _i = 0; _i < 2; ++_i) \
;         __builtin_amdgcn_global_load_lds((const unsigned*)((const char*)(gbase) + (voff)[_i]), (PG8_LAS unsigned*)(lds + (bufoff) + ldsw + _i * 8192), 16, 0, 0); } while (0)
; #define PG8_LDA(dst, b, h) do { _Pragma("unroll") for (int m = 0; m < 4; ++m) _Pragma("unroll") for (int k = 0; k < 2; ++k) dst[m][k] = *(const PG8_LAS bf16x8*)(lds + PG8_SA(b, h) + aoff + m * 2048 + k * 1024); } while (0)
; #define PG8_LDB(dst, b, h) do { _Pragma("unroll") for (int n = 0; n < 2; ++n) _Pragma("unroll") for (int k = 0; k < 2; ++k) dst[n][k] = *(const PG8_LAS bf16x8*)(lds + PG8_SB(b, h) + boff + n * 2048 + k * 1024); } while (0)
; #define PG8_MMA(ai, bj, At, Bt) do { __builtin_amdgcn_s_setprio(1); _Pragma("unroll") for (int m = 0; m < 4; ++m) _Pragma("unroll") for (int n = 0; n < 2; ++n) _Pragma("unroll") for (int k = 0; k < 2; ++k) \
;         acc[ai][bj][m][n] = __builtin_amdgcn_mfma_f32_16x16x32_bf16(Bt[n][k], At[m][k], acc[ai][bj][m][n], 0, 0, 0); __builtin_amdgcn_s_setprio(0); } while (0)
; #define PG8_WAIT_V(n) asm volatile("s_waitcnt vmcnt(" #n ")" ::: "memory")
; #define PG8_WAIT_L(n) asm volatile("s_waitcnt lgkmcnt(" #n ")" ::: "memory")
; #define PG8_BAR __builtin_amdgcn_s_barrier()
; #define PG8_SCHED __builtin_amdgcn_sched_barrier(0)
; template <class Epi, class Sched>
; __device__ __forceinline__ void gemm_phase(PG8_LAS unsigned char* lds, const Gemm g, const Sched& S, const Epi& E) {
;     ...
;             PG8_LDB(B0, 0, 0); PG8_SCHED; PG8_LDA(At, 0, 0); PG8_STAGE(PG8_SA(1, 1), a1 + hstep, voffA);
;             PG8_WAIT_L(8); PG8_BAR; PG8_WAIT_L(0); PG8_MMA(0, 0, At, B0); PG8_BAR; PG8_SCHED;
;             PG8_LDB(B1, 0, 1); PG8_STAGE(PG8_SB(0, 0), b2, voffB);
;             PG8_BAR; PG8_WAIT_L(0); PG8_MMA(0, 1, At, B1); PG8_BAR;
;             PG8_LDA(At, 0, 1); PG8_STAGE(PG8_SA(0, 0), a2, voffA);
;             PG8_BAR; PG8_WAIT_L(0); PG8_MMA(1, 0, At, B0); PG8_BAR; PG8_SCHED;
;             PG8_STAGE(PG8_SB(0, 1), b2 + hstep, voffB);
;             PG8_WAIT_V(6); PG8_BAR; PG8_MMA(1, 1, At, B1); PG8_BAR;
.LBB0_724:
	ds_read_b128 v[144:147], v151
	ds_read_b128 v[156:159], v151 offset:1024
	ds_read_b128 v[160:163], v151 offset:2048
	ds_read_b128 v[166:169], v151 offset:3072
	s_add_u32 s20, s18, 0xfffc0080
	s_addc_u32 s21, s19, -1
	s_cmp_eq_u32 s48, 12
	s_cselect_b32 s23, s5, s21
	s_cselect_b32 s22, s11, s20
	s_cselect_b32 s21, s9, s47
	s_cselect_b32 s20, s45, s46
	v_lshl_add_u64 v[174:175], s[18:19], 0, v[136:137]
	s_add_i32 m0, s17, 0xc000
	ds_read_b128 v[170:173], v153
	ds_read_b128 v[182:185], v153 offset:1024
	ds_read_b128 v[190:193], v153 offset:2048
	ds_read_b128 v[194:197], v153 offset:3072
	ds_read_b128 v[198:201], v153 offset:4096
	ds_read_b128 v[202:205], v153 offset:5120
	ds_read_b128 v[206:209], v153 offset:6144
	ds_read_b128 v[210:213], v153 offset:7168
	global_load_lds_dwordx4 v[174:175], off
	v_lshl_add_u64 v[174:175], s[18:19], 0, v[138:139]
	s_add_i32 m0, s17, 0xe000
	s_nop 0
	global_load_lds_dwordx4 v[174:175], off
	s_waitcnt lgkmcnt(8)
	s_barrier
	s_waitcnt lgkmcnt(0)
	v_mfma_f32_16x16x32_bf16 v[124:127], v[144:147], v[170:173], v[124:127]
	v_mfma_f32_16x16x32_bf16 v[120:123], v[160:163], v[170:173], v[120:123]
	v_mfma_f32_16x16x32_bf16 v[108:111], v[144:147], v[190:193], v[108:111]
	v_mfma_f32_16x16x32_bf16 v[104:107], v[160:163], v[190:193], v[104:107]
	v_mfma_f32_16x16x32_bf16 v[92:95], v[144:147], v[198:201], v[92:95]
	v_mfma_f32_16x16x32_bf16 v[88:91], v[160:163], v[198:201], v[88:91]
	v_mfma_f32_16x16x32_bf16 v[76:79], v[144:147], v[206:209], v[76:79]
	v_mfma_f32_16x16x32_bf16 v[72:75], v[160:163], v[206:209], v[72:75]
	v_mfma_f32_16x16x32_bf16 v[124:127], v[156:159], v[182:185], v[124:127]
	v_mfma_f32_16x16x32_bf16 v[120:123], v[166:169], v[182:185], v[120:123]
	v_mfma_f32_16x16x32_bf16 v[108:111], v[156:159], v[194:197], v[108:111]
	v_mfma_f32_16x16x32_bf16 v[104:107], v[166:169], v[194:197], v[104:107]
	v_mfma_f32_16x16x32_bf16 v[92:95], v[156:159], v[202:205], v[92:95]
	v_mfma_f32_16x16x32_bf16 v[88:91], v[166:169], v[202:205], v[88:91]
	v_mfma_f32_16x16x32_bf16 v[76:79], v[156:159], v[210:213], v[76:79]
	v_mfma_f32_16x16x32_bf16 v[72:75], v[166:169], v[210:213], v[72:75]
	s_barrier
	s_add_i32 s49, s42, s30
	v_lshl_add_u64 v[174:175], s[20:21], 0, v[130:131]
	s_mov_b32 m0, s49
	ds_read_b128 v[214:217], v154
	ds_read_b128 v[218:221], v154 offset:1024
	ds_read_b128 v[222:225], v154 offset:2048
	ds_read_b128 v[226:229], v154 offset:3072
	global_load_lds_dwordx4 v[174:175], off
	v_lshl_add_u64 v[186:187], s[20:21], 0, v[134:135]
	s_add_i32 m0, s49, 0x2000
	s_nop 0
	global_load_lds_dwordx4 v[186:187], off
	s_barrier
	s_waitcnt lgkmcnt(0)
	v_mfma_f32_16x16x32_bf16 v[116:119], v[214:217], v[170:173], v[116:119]
	v_mfma_f32_16x16x32_bf16 v[112:115], v[222:225], v[170:173], v[112:115]
	v_mfma_f32_16x16x32_bf16 v[100:103], v[214:217], v[190:193], v[100:103]
	v_mfma_f32_16x16x32_bf16 v[96:99], v[222:225], v[190:193], v[96:99]
	v_mfma_f32_16x16x32_bf16 v[84:87], v[214:217], v[198:201], v[84:87]
	v_mfma_f32_16x16x32_bf16 v[80:83], v[222:225], v[198:201], v[80:83]
	v_mfma_f32_16x16x32_bf16 v[68:71], v[214:217], v[206:209], v[68:71]
	v_mfma_f32_16x16x32_bf16 v[64:67], v[222:225], v[206:209], v[64:67]
	v_mfma_f32_16x16x32_bf16 v[116:119], v[218:221], v[182:185], v[116:119]
	v_mfma_f32_16x16x32_bf16 v[112:115], v[226:229], v[182:185], v[112:115]
	v_mfma_f32_16x16x32_bf16 v[100:103], v[218:221], v[194:197], v[100:103]
	v_mfma_f32_16x16x32_bf16 v[96:99], v[226:229], v[194:197], v[96:99]
	v_mfma_f32_16x16x32_bf16 v[84:87], v[218:221], v[202:205], v[84:87]
	v_mfma_f32_16x16x32_bf16 v[80:83], v[226:229], v[202:205], v[80:83]
	v_mfma_f32_16x16x32_bf16 v[68:71], v[218:221], v[210:213], v[68:71]
	v_mfma_f32_16x16x32_bf16 v[64:67], v[226:229], v[210:213], v[64:67]
	s_mov_b32 m0, s17
	v_lshl_add_u64 v[230:231], s[22:23], 0, v[128:129]
	s_barrier
	ds_read_b128 v[170:173], v153 offset:16384
	ds_read_b128 v[182:185], v153 offset:17408
	ds_read_b128 v[190:193], v153 offset:18432
	ds_read_b128 v[194:197], v153 offset:19456
	ds_read_b128 v[198:201], v153 offset:20480
	ds_read_b128 v[202:205], v153 offset:21504
	ds_read_b128 v[206:209], v153 offset:22528
	ds_read_b128 v[210:213], v153 offset:23552
	global_load_lds_dwordx4 v[230:231], off
	v_lshl_add_u64 v[232:233], s[22:23], 0, v[132:133]
	s_mov_b32 m0, s31
	s_nop 0
	global_load_lds_dwordx4 v[232:233], off
	s_barrier
	s_waitcnt lgkmcnt(0)
	v_mfma_f32_16x16x32_bf16 v[60:63], v[144:147], v[170:173], v[60:63]
	v_mfma_f32_16x16x32_bf16 v[56:59], v[160:163], v[170:173], v[56:59]
	v_mfma_f32_16x16x32_bf16 v[44:47], v[144:147], v[190:193], v[44:47]
	v_mfma_f32_16x16x32_bf16 v[40:43], v[160:163], v[190:193], v[40:43]
	v_mfma_f32_16x16x32_bf16 v[28:31], v[144:147], v[198:201], v[28:31]
	v_mfma_f32_16x16x32_bf16 v[24:27], v[160:163], v[198:201], v[24:27]
	v_mfma_f32_16x16x32_bf16 v[12:15], v[144:147], v[206:209], v[12:15]
	v_mfma_f32_16x16x32_bf16 v[8:11], v[160:163], v[206:209], v[8:11]
	v_mfma_f32_16x16x32_bf16 v[60:63], v[156:159], v[182:185], v[60:63]
	v_mfma_f32_16x16x32_bf16 v[56:59], v[166:169], v[182:185], v[56:59]
	v_mfma_f32_16x16x32_bf16 v[44:47], v[156:159], v[194:197], v[44:47]
	v_mfma_f32_16x16x32_bf16 v[40:43], v[166:169], v[194:197], v[40:43]
	v_mfma_f32_16x16x32_bf16 v[28:31], v[156:159], v[202:205], v[28:31]
	v_mfma_f32_16x16x32_bf16 v[24:27], v[166:169], v[202:205], v[24:27]
	v_mfma_f32_16x16x32_bf16 v[12:15], v[156:159], v[210:213], v[12:15]
	v_mfma_f32_16x16x32_bf16 v[8:11], v[166:169], v[210:213], v[8:11]
	s_barrier
; #define PG8_STAGE(bufoff, gbase, voff) do { _Pragma("unroll") for (int _i = 0; _i < 2; ++_i) \
;         __builtin_amdgcn_global_load_lds((const unsigned*)((const char*)(gbase) + (voff)[_i]), (PG8_LAS unsigned*)(lds + (bufoff) + ldsw + _i * 8192), 16, 0, 0); } while (0)
; #define PG8_LDA(dst, b, h) do { _Pragma("unroll") for (int m = 0; m < 4; ++m) _Pragma("unroll") for (int k = 0; k < 2; ++k) dst[m][k] = *(const PG8_LAS bf16x8*)(lds + PG8_SA(b, h) + aoff + m * 2048 + k * 1024); } while (0)
; #define PG8_LDB(dst, b, h) do { _Pragma("unroll") for (int n = 0; n < 2; ++n) _Pragma("unroll") for (int k = 0; k < 2; ++k) dst[n][k] = *(const PG8_LAS bf16x8*)(lds + PG8_SB(b, h) + boff + n * 2048 + k * 1024); } while (0)
; #define PG8_MMA(ai, bj, At, Bt) do { __builtin_amdgcn_s_setprio(1); _Pragma("unroll") for (int m = 0; m < 4; ++m) _Pragma("unroll") for (int n = 0; n < 2; ++n) _Pragma("unroll") for (int k = 0; k < 2; ++k) \
;         acc[ai][bj][m][n] = __builtin_amdgcn_mfma_f32_16x16x32_bf16(Bt[n][k], At[m][k], acc[ai][bj][m][n], 0, 0, 0); __builtin_amdgcn_s_setprio(0); } while (0)
; #define PG8_WAIT_V(n) asm volatile("s_waitcnt vmcnt(" #n ")" ::: "memory")
; #define PG8_WAIT_L(n) asm volatile("s_waitcnt lgkmcnt(" #n ")" ::: "memory")
; #define PG8_BAR __builtin_amdgcn_s_barrier()
; #define PG8_SCHED __builtin_amdgcn_sched_barrier(0)
; template <class Epi, class Sched>
; __device__ __forceinline__ void gemm_phase(PG8_LAS unsigned char* lds, const Gemm g, const Sched& S, const Epi& E) {
;     ...
;             PG8_STAGE(PG8_SB(0, 1), b2 + hstep, voffB);
;             PG8_WAIT_V(6); PG8_BAR; PG8_MMA(1, 1, At, B1); PG8_BAR;
;             PG8_LDB(B0, 1, 0); PG8_SCHED; PG8_LDA(At, 1, 0); PG8_STAGE(PG8_SA(0, 1), a2 + hstep, voffA);
;             PG8_WAIT_L(8); PG8_BAR; PG8_WAIT_L(0); PG8_MMA(0, 0, At, B0); PG8_BAR; PG8_SCHED;
;             PG8_LDB(B1, 1, 1); PG8_STAGE(PG8_SB(1, 0), b3, voffB);
;             PG8_BAR; PG8_WAIT_L(0); PG8_MMA(0, 1, At, B1); PG8_BAR;
;             PG8_LDA(At, 1, 1); PG8_STAGE(PG8_SA(1, 0), a3, voffA);
;             PG8_BAR; PG8_WAIT_L(0); PG8_MMA(1, 0, At, B0); PG8_BAR; PG8_SCHED;
	s_add_u32 s50, s20, 0x40000
	s_addc_u32 s51, s21, 0
	s_add_i32 s49, s43, s30
	v_lshl_add_u64 v[144:145], s[50:51], 0, v[130:131]
	s_mov_b32 m0, s49
	s_nop 0
	global_load_lds_dwordx4 v[144:145], off
	v_lshl_add_u64 v[144:145], s[50:51], 0, v[134:135]
	s_add_i32 m0, s49, 0x2000
	s_nop 0
	global_load_lds_dwordx4 v[144:145], off
	s_waitcnt vmcnt(6)
	s_barrier
	v_mfma_f32_16x16x32_bf16 v[52:55], v[214:217], v[170:173], v[52:55]
	v_mfma_f32_16x16x32_bf16 v[48:51], v[222:225], v[170:173], v[48:51]
	v_mfma_f32_16x16x32_bf16 v[36:39], v[214:217], v[190:193], v[36:39]
	v_mfma_f32_16x16x32_bf16 v[32:35], v[222:225], v[190:193], v[32:35]
	v_mfma_f32_16x16x32_bf16 v[20:23], v[214:217], v[198:201], v[20:23]
	v_mfma_f32_16x16x32_bf16 v[16:19], v[222:225], v[198:201], v[16:19]
	v_mfma_f32_16x16x32_bf16 v[4:7], v[214:217], v[206:209], v[4:7]
	v_mfma_f32_16x16x32_bf16 v[0:3], v[222:225], v[206:209], v[0:3]
	v_mfma_f32_16x16x32_bf16 v[52:55], v[218:221], v[182:185], v[52:55]
	v_mfma_f32_16x16x32_bf16 v[48:51], v[226:229], v[182:185], v[48:51]
	v_mfma_f32_16x16x32_bf16 v[36:39], v[218:221], v[194:197], v[36:39]
	v_mfma_f32_16x16x32_bf16 v[32:35], v[226:229], v[194:197], v[32:35]
	v_mfma_f32_16x16x32_bf16 v[20:23], v[218:221], v[202:205], v[20:23]
	v_mfma_f32_16x16x32_bf16 v[16:19], v[226:229], v[202:205], v[16:19]
	v_mfma_f32_16x16x32_bf16 v[4:7], v[218:221], v[210:213], v[4:7]
	v_mfma_f32_16x16x32_bf16 v[0:3], v[226:229], v[210:213], v[0:3]
	s_add_i32 s49, 0, 0x18000
	v_add_u32_e32 v155, s49, v149
	s_barrier
	ds_read_b128 v[144:147], v155
	ds_read_b128 v[156:159], v155 offset:1024
	ds_read_b128 v[160:163], v155 offset:2048
	ds_read_b128 v[166:169], v155 offset:3072
	s_add_u32 s22, s22, 0x40000
	s_addc_u32 s23, s23, 0
	s_mov_b32 m0, s34
	v_lshl_add_u64 v[214:215], s[22:23], 0, v[128:129]
	ds_read_b128 v[170:173], v153 offset:32768
	ds_read_b128 v[182:185], v153 offset:33792
	ds_read_b128 v[190:193], v153 offset:34816
	ds_read_b128 v[194:197], v153 offset:35840
	ds_read_b128 v[198:201], v153 offset:36864
	ds_read_b128 v[202:205], v153 offset:37888
	ds_read_b128 v[206:209], v153 offset:38912
	ds_read_b128 v[210:213], v153 offset:39936
	global_load_lds_dwordx4 v[214:215], off
	v_lshl_add_u64 v[214:215], s[22:23], 0, v[132:133]
	s_mov_b32 m0, s35
	s_nop 0
	global_load_lds_dwordx4 v[214:215], off
	s_waitcnt lgkmcnt(8)
	s_barrier
	s_waitcnt lgkmcnt(0)
	v_mfma_f32_16x16x32_bf16 v[124:127], v[144:147], v[170:173], v[124:127]
	v_mfma_f32_16x16x32_bf16 v[120:123], v[160:163], v[170:173], v[120:123]
	v_mfma_f32_16x16x32_bf16 v[108:111], v[144:147], v[190:193], v[108:111]
	v_mfma_f32_16x16x32_bf16 v[104:107], v[160:163], v[190:193], v[104:107]
	v_mfma_f32_16x16x32_bf16 v[92:95], v[144:147], v[198:201], v[92:95]
	v_mfma_f32_16x16x32_bf16 v[88:91], v[160:163], v[198:201], v[88:91]
	v_mfma_f32_16x16x32_bf16 v[76:79], v[144:147], v[206:209], v[76:79]
	v_mfma_f32_16x16x32_bf16 v[72:75], v[160:163], v[206:209], v[72:75]
	v_mfma_f32_16x16x32_bf16 v[124:127], v[156:159], v[182:185], v[124:127]
	v_mfma_f32_16x16x32_bf16 v[120:123], v[166:169], v[182:185], v[120:123]
	v_mfma_f32_16x16x32_bf16 v[108:111], v[156:159], v[194:197], v[108:111]
	v_mfma_f32_16x16x32_bf16 v[104:107], v[166:169], v[194:197], v[104:107]
	v_mfma_f32_16x16x32_bf16 v[92:95], v[156:159], v[202:205], v[92:95]
	v_mfma_f32_16x16x32_bf16 v[88:91], v[166:169], v[202:205], v[88:91]
	v_mfma_f32_16x16x32_bf16 v[76:79], v[156:159], v[210:213], v[76:79]
	v_mfma_f32_16x16x32_bf16 v[72:75], v[166:169], v[210:213], v[72:75]
	s_barrier
	s_add_i32 s22, 0, 0x1c000
	s_add_i32 s23, s49, s30
	v_add_u32_e32 v155, s22, v149
	v_lshl_add_u64 v[174:175], v[174:175], 0, s[6:7]
	s_mov_b32 m0, s23
	ds_read_b128 v[214:217], v155
	ds_read_b128 v[218:221], v155 offset:1024
	ds_read_b128 v[222:225], v155 offset:2048
	ds_read_b128 v[226:229], v155 offset:3072
	global_load_lds_dwordx4 v[174:175], off
	v_lshl_add_u64 v[174:175], v[186:187], 0, s[6:7]
	s_add_i32 m0, s23, 0x2000
	s_nop 0
	global_load_lds_dwordx4 v[174:175], off
	s_barrier
	s_waitcnt lgkmcnt(0)
	v_mfma_f32_16x16x32_bf16 v[116:119], v[214:217], v[170:173], v[116:119]
	v_mfma_f32_16x16x32_bf16 v[112:115], v[222:225], v[170:173], v[112:115]
	v_mfma_f32_16x16x32_bf16 v[100:103], v[214:217], v[190:193], v[100:103]
	v_mfma_f32_16x16x32_bf16 v[96:99], v[222:225], v[190:193], v[96:99]
	v_mfma_f32_16x16x32_bf16 v[84:87], v[214:217], v[198:201], v[84:87]
	v_mfma_f32_16x16x32_bf16 v[80:83], v[222:225], v[198:201], v[80:83]
	v_mfma_f32_16x16x32_bf16 v[68:71], v[214:217], v[206:209], v[68:71]
	v_mfma_f32_16x16x32_bf16 v[64:67], v[222:225], v[206:209], v[64:67]
	v_mfma_f32_16x16x32_bf16 v[116:119], v[218:221], v[182:185], v[116:119]
	v_mfma_f32_16x16x32_bf16 v[112:115], v[226:229], v[182:185], v[112:115]
	v_mfma_f32_16x16x32_bf16 v[100:103], v[218:221], v[194:197], v[100:103]
	v_mfma_f32_16x16x32_bf16 v[96:99], v[226:229], v[194:197], v[96:99]
	v_mfma_f32_16x16x32_bf16 v[84:87], v[218:221], v[202:205], v[84:87]
	v_mfma_f32_16x16x32_bf16 v[80:83], v[226:229], v[202:205], v[80:83]
	v_mfma_f32_16x16x32_bf16 v[68:71], v[218:221], v[210:213], v[68:71]
	v_mfma_f32_16x16x32_bf16 v[64:67], v[226:229], v[210:213], v[64:67]
	s_mov_b32 m0, s37
	v_lshl_add_u64 v[174:175], v[230:231], 0, s[6:7]
	s_barrier
	ds_read_b128 v[170:173], v153 offset:49152
	ds_read_b128 v[182:185], v153 offset:50176
	ds_read_b128 v[190:193], v153 offset:51200
	ds_read_b128 v[194:197], v153 offset:52224
	ds_read_b128 v[198:201], v153 offset:53248
	ds_read_b128 v[202:205], v153 offset:54272
	ds_read_b128 v[206:209], v153 offset:55296
	ds_read_b128 v[210:213], v153 offset:56320
	global_load_lds_dwordx4 v[174:175], off
	v_lshl_add_u64 v[174:175], v[232:233], 0, s[6:7]
	s_mov_b32 m0, s38
	s_nop 0
	global_load_lds_dwordx4 v[174:175], off
	s_barrier
; #define PG8_STAGE(bufoff, gbase, voff) do { _Pragma("unroll") for (int _i = 0; _i < 2; ++_i) \
;         __builtin_amdgcn_global_load_lds((const unsigned*)((const char*)(gbase) + (voff)[_i]), (PG8_LAS unsigned*)(lds + (bufoff) + ldsw + _i * 8192), 16, 0, 0); } while (0)
; #define PG8_MMA(ai, bj, At, Bt) do { __builtin_amdgcn_s_setprio(1); _Pragma("unroll") for (int m = 0; m < 4; ++m) _Pragma("unroll") for (int n = 0; n < 2; ++n) _Pragma("unroll") for (int k = 0; k < 2; ++k) \
;         acc[ai][bj][m][n] = __builtin_amdgcn_mfma_f32_16x16x32_bf16(Bt[n][k], At[m][k], acc[ai][bj][m][n], 0, 0, 0); __builtin_amdgcn_s_setprio(0); } while (0)
; #define PG8_WAIT_V(n) asm volatile("s_waitcnt vmcnt(" #n ")" ::: "memory")
; #define PG8_WAIT_L(n) asm volatile("s_waitcnt lgkmcnt(" #n ")" ::: "memory")
;     __device__ __forceinline__ void operator()(const f32x4 (&acc)[2][2][4][2], const Unit& u, int wr, int wc, int fr, int fq) const {
;     ...
;         else if (mode == 2) { if (u.pn >= 6) act = 2; }
;         const int row0 = u.pm * BM + wr * 64 + fr, col0 = u.pn * BM + wc * 32 + 8 * fq, bcol0 = wc * 32 + 8 * fq;
;         f32x4 bv[2][2];
; #pragma unroll
;         for (int bj = 0; bj < 2; ++bj)
; #pragma unroll
;             for (int n = 0; n < 2; ++n) bv[bj][n] = bias ? *(const f32x4*)(bias + bcol0 + bj * HALF + 4 * n) : (f32x4){0.f, 0.f, 0.f, 0.f};
; #pragma unroll
;         for (int ai = 0; ai < 2; ++ai)
; #pragma unroll
;             for (int m = 0; m < 4; ++m) { bf16_t* rowp = O + (size_t)(row0 + ai * HALF + m * 16) * ldc + col0;
; #pragma unroll
;                 for (int bj = 0; bj < 2; ++bj) { f32x4 v0 = acc[ai][bj][m][0] + bv[bj][0], v1 = acc[ai][bj][m][1] + bv[bj][1];
;                     if (act == 1) {
; #pragma unroll
;                         for (int j = 0; j < 1; ++j) { v0 = v0 * sigmoid4(v0); v1 = v1 * sigmoid4(v1); } }
;                     else if (act == 2) {
; #pragma unroll
;                         for (int j = 0; j < 1; ++j) { v0 = sigmoid4(v0); v1 = sigmoid4(v1); } }
; template <class Epi, class Sched>
; __device__ __forceinline__ void gemm_phase(PG8_LAS unsigned char* lds, const Gemm g, const Sched& S, const Epi& E) {
;     ...
;             PG8_BAR; PG8_WAIT_L(0); PG8_MMA(1, 0, At, B0); PG8_BAR; PG8_SCHED;
;             PG8_STAGE(PG8_SB(1, 1), b3 + hstep, voffB);
;             PG8_WAIT_V(6); PG8_BAR; PG8_MMA(1, 1, At, B1); PG8_BAR;
	s_waitcnt lgkmcnt(0)
	v_mfma_f32_16x16x32_bf16 v[60:63], v[144:147], v[170:173], v[60:63]
	v_mfma_f32_16x16x32_bf16 v[56:59], v[160:163], v[170:173], v[56:59]
	v_mfma_f32_16x16x32_bf16 v[44:47], v[144:147], v[190:193], v[44:47]
	v_mfma_f32_16x16x32_bf16 v[40:43], v[160:163], v[190:193], v[40:43]
	v_mfma_f32_16x16x32_bf16 v[28:31], v[144:147], v[198:201], v[28:31]
	v_mfma_f32_16x16x32_bf16 v[24:27], v[160:163], v[198:201], v[24:27]
	v_mfma_f32_16x16x32_bf16 v[12:15], v[144:147], v[206:209], v[12:15]
	v_mfma_f32_16x16x32_bf16 v[8:11], v[160:163], v[206:209], v[8:11]
	v_mfma_f32_16x16x32_bf16 v[60:63], v[156:159], v[182:185], v[60:63]
	v_mfma_f32_16x16x32_bf16 v[56:59], v[166:169], v[182:185], v[56:59]
	v_mfma_f32_16x16x32_bf16 v[44:47], v[156:159], v[194:197], v[44:47]
	v_mfma_f32_16x16x32_bf16 v[40:43], v[166:169], v[194:197], v[40:43]
	v_mfma_f32_16x16x32_bf16 v[28:31], v[156:159], v[202:205], v[28:31]
	v_mfma_f32_16x16x32_bf16 v[24:27], v[166:169], v[202:205], v[24:27]
	v_mfma_f32_16x16x32_bf16 v[12:15], v[156:159], v[210:213], v[12:15]
	v_mfma_f32_16x16x32_bf16 v[8:11], v[166:169], v[210:213], v[8:11]
	s_barrier
	s_add_u32 s20, s20, 0x40080
	s_addc_u32 s21, s21, 0
	s_add_i32 s22, s22, s30
	v_lshl_add_u64 v[144:145], s[20:21], 0, v[130:131]
	s_mov_b32 m0, s22
	s_nop 0
	global_load_lds_dwordx4 v[144:145], off
	v_lshl_add_u64 v[144:145], s[20:21], 0, v[134:135]
	s_add_i32 m0, s22, 0x2000
	s_nop 0
	global_load_lds_dwordx4 v[144:145], off
	s_waitcnt vmcnt(6)
	s_barrier
	v_mfma_f32_16x16x32_bf16 v[52:55], v[214:217], v[170:173], v[52:55]
	v_mfma_f32_16x16x32_bf16 v[48:51], v[222:225], v[170:173], v[48:51]
	v_mfma_f32_16x16x32_bf16 v[36:39], v[214:217], v[190:193], v[36:39]
	v_mfma_f32_16x16x32_bf16 v[32:35], v[222:225], v[190:193], v[32:35]
	v_mfma_f32_16x16x32_bf16 v[20:23], v[214:217], v[198:201], v[20:23]
	v_mfma_f32_16x16x32_bf16 v[16:19], v[222:225], v[198:201], v[16:19]
	v_mfma_f32_16x16x32_bf16 v[4:7], v[214:217], v[206:209], v[4:7]
	v_mfma_f32_16x16x32_bf16 v[0:3], v[222:225], v[206:209], v[0:3]
	v_mfma_f32_16x16x32_bf16 v[52:55], v[218:221], v[182:185], v[52:55]
	v_mfma_f32_16x16x32_bf16 v[48:51], v[226:229], v[182:185], v[48:51]
	v_mfma_f32_16x16x32_bf16 v[36:39], v[218:221], v[194:197], v[36:39]
	v_mfma_f32_16x16x32_bf16 v[32:35], v[226:229], v[194:197], v[32:35]
	v_mfma_f32_16x16x32_bf16 v[20:23], v[218:221], v[202:205], v[20:23]
	v_mfma_f32_16x16x32_bf16 v[16:19], v[226:229], v[202:205], v[16:19]
	v_mfma_f32_16x16x32_bf16 v[4:7], v[218:221], v[210:213], v[4:7]
	v_mfma_f32_16x16x32_bf16 v[0:3], v[226:229], v[210:213], v[0:3]
	s_add_i32 s48, s48, 2
	s_add_u32 s18, s18, 0x100
	s_addc_u32 s19, s19, 0
	s_add_u32 s46, s46, 0x100
	s_addc_u32 s47, s47, 0
	s_cmp_gt_u32 s48, 13
	s_barrier
	s_cbranch_scc0 .LBB0_724
	s_cmp_gt_i32 s4, 5
	s_cselect_b64 s[18:19], -1, 0
	s_cmp_lt_i32 s4, 6
	v_pk_add_f32 v[144:145], v[126:127], 0 op_sel_hi:[1,0]
	v_pk_add_f32 v[146:147], v[124:125], 0 op_sel_hi:[1,0]
	v_pk_add_f32 v[124:125], v[122:123], 0 op_sel_hi:[1,0]
	v_pk_add_f32 v[126:127], v[120:121], 0 op_sel_hi:[1,0]
	s_cbranch_scc1 .LBB0_727
	v_max_f32_e32 v122, v144, v144
	v_max_f32_e32 v122, 0xc1a00000, v122
	v_mul_f32_e32 v122, 0xbfb8aa3b, v122
	v_max_f32_e32 v120, v146, v146
	v_max_f32_e32 v121, v147, v147
	v_exp_f32_e32 v123, v122
	v_max_f32_e32 v122, v145, v145
	v_max_f32_e32 v120, 0xc1a00000, v120
	v_max_f32_e32 v121, 0xc1a00000, v121
	v_max_f32_e32 v122, 0xc1a00000, v122
	v_mul_f32_e32 v120, 0xbfb8aa3b, v120
	v_mul_f32_e32 v121, 0xbfb8aa3b, v121
	v_mul_f32_e32 v122, 0xbfb8aa3b, v122
	v_exp_f32_e32 v120, v120
	v_exp_f32_e32 v121, v121
	v_exp_f32_e32 v122, v122
	v_max_f32_e32 v124, v124, v124
	v_max_f32_e32 v124, 0xc1a00000, v124
	v_pk_add_f32 v[120:121], v[120:121], 1.0 op_sel_hi:[1,0]
	v_pk_add_f32 v[122:123], v[122:123], 1.0 op_sel_hi:[1,0]
	v_mov_b32_e32 v144, v120
	v_mov_b32_e32 v145, v123
	v_pk_mov_b32 v[146:147], v[120:121], v[122:123] op_sel:[1,0]
	v_mul_f32_e32 v124, 0xbfb8aa3b, v124
	v_pk_mul_f32 v[144:145], v[144:145], v[146:147]
	v_max_f32_e32 v126, v126, v126
	v_max_f32_e32 v127, v127, v127
	v_exp_f32_e32 v147, v124
	v_max_f32_e32 v124, v125, v125
	v_max_f32_e32 v126, 0xc1a00000, v126
	v_max_f32_e32 v127, 0xc1a00000, v127
	v_max_f32_e32 v124, 0xc1a00000, v124
	v_mul_f32_e32 v146, v144, v145
	v_mul_f32_e32 v126, 0xbfb8aa3b, v126
	v_mul_f32_e32 v127, 0xbfb8aa3b, v127
	v_mul_f32_e32 v124, 0xbfb8aa3b, v124
	v_rcp_f32_e32 v155, v146
	v_exp_f32_e32 v126, v126
	v_exp_f32_e32 v127, v127
	v_exp_f32_e32 v146, v124
	v_mul_f32_e32 v124, v145, v155
	v_mul_f32_e32 v144, v144, v155
	v_pk_add_f32 v[126:127], v[126:127], 1.0 op_sel_hi:[1,0]
	v_pk_add_f32 v[156:157], v[146:147], 1.0 op_sel_hi:[1,0]
	v_mov_b32_e32 v146, v126
	v_mov_b32_e32 v147, v157
	v_pk_mov_b32 v[158:159], v[126:127], v[156:157] op_sel:[1,0]
	v_pk_mul_f32 v[144:145], v[122:123], v[144:145] op_sel_hi:[1,0]
	v_pk_mul_f32 v[158:159], v[146:147], v[158:159]
	s_nop 0
	v_mul_f32_e32 v125, v158, v159
	v_rcp_f32_e32 v125, v125
	s_nop 0
	v_pk_mul_f32 v[146:147], v[120:121], v[124:125] op_sel:[1,0] op_sel_hi:[0,0]
	v_mul_f32_e32 v120, v159, v125
	v_mul_f32_e32 v122, v158, v125
	v_pk_mul_f32 v[124:125], v[156:157], v[122:123] op_sel_hi:[1,0]
	v_pk_mul_f32 v[126:127], v[126:127], v[120:121] op_sel:[1,0] op_sel_hi:[0,0]

; #define PG8_STAGE(bufoff, gbase, voff) do { _Pragma("unroll") for (int _i = 0; _i < 2; ++_i) \
;         __builtin_amdgcn_global_load_lds((const unsigned*)((const char*)(gbase) + (voff)[_i]), (PG8_LAS unsigned*)(lds + (bufoff) + ldsw + _i * 8192), 16, 0, 0); } while (0)
; #define PG8_LDA(dst, b, h) do { _Pragma("unroll") for (int m = 0; m < 4; ++m) _Pragma("unroll") for (int k = 0; k < 2; ++k) dst[m][k] = *(const PG8_LAS bf16x8*)(lds + PG8_SA(b, h) + aoff + m * 2048 + k * 1024); } while (0)
; #define PG8_LDB(dst, b, h) do { _Pragma("unroll") for (int n = 0; n < 2; ++n) _Pragma("unroll") for (int k = 0; k < 2; ++k) dst[n][k] = *(const PG8_LAS bf16x8*)(lds + PG8_SB(b, h) + boff + n * 2048 + k * 1024); } while (0)
; #define PG8_MMA(ai, bj, At, Bt) do { __builtin_amdgcn_s_setprio(1); _Pragma("unroll") for (int m = 0; m < 4; ++m) _Pragma("unroll") for (int n = 0; n < 2; ++n) _Pragma("unroll") for (int k = 0; k < 2; ++k) \
;         acc[ai][bj][m][n] = __builtin_amdgcn_mfma_f32_16x16x32_bf16(Bt[n][k], At[m][k], acc[ai][bj][m][n], 0, 0, 0); __builtin_amdgcn_s_setprio(0); } while (0)
; #define PG8_WAIT_V(n) asm volatile("s_waitcnt vmcnt(" #n ")" ::: "memory")
; #define PG8_WAIT_L(n) asm volatile("s_waitcnt lgkmcnt(" #n ")" ::: "memory")
; #define PG8_BAR __builtin_amdgcn_s_barrier()
; #define PG8_SCHED __builtin_amdgcn_sched_barrier(0)
; template <class Epi, class Sched>
; __device__ __forceinline__ void gemm_phase(PG8_LAS unsigned char* lds, const Gemm g, const Sched& S, const Epi& E) {
;     ...
;             PG8_LDB(B0, 0, 0); PG8_SCHED; PG8_LDA(At, 0, 0); PG8_STAGE(PG8_SA(1, 1), a1 + hstep, voffA);
;             PG8_WAIT_L(8); PG8_BAR; PG8_WAIT_L(0); PG8_MMA(0, 0, At, B0); PG8_BAR; PG8_SCHED;
;             PG8_LDB(B1, 0, 1); PG8_STAGE(PG8_SB(0, 0), b2, voffB);
;             PG8_BAR; PG8_WAIT_L(0); PG8_MMA(0, 1, At, B1); PG8_BAR;
;             PG8_LDA(At, 0, 1); PG8_STAGE(PG8_SA(0, 0), a2, voffA);
;             PG8_BAR; PG8_WAIT_L(0); PG8_MMA(1, 0, At, B0); PG8_BAR; PG8_SCHED;
;             PG8_STAGE(PG8_SB(0, 1), b2 + hstep, voffB);
;             PG8_WAIT_V(6); PG8_BAR; PG8_MMA(1, 1, At, B1); PG8_BAR;
.LBB0_991:
	ds_read_b128 v[144:147], v153
	ds_read_b128 v[156:159], v153 offset:1024
	ds_read_b128 v[160:163], v153 offset:2048
	ds_read_b128 v[164:167], v153 offset:3072
	s_add_u32 s20, s18, 0xfffc0080
	s_addc_u32 s21, s19, -1
	s_cmp_eq_u32 s47, 12
	s_cselect_b32 s23, s11, s21
	s_cselect_b32 s22, s43, s20
	s_cselect_b32 s21, s9, s46
	s_cselect_b32 s20, s44, s45
	v_lshl_add_u64 v[148:149], s[18:19], 0, v[136:137]
	s_add_i32 m0, s17, 0xc000
	ds_read_b128 v[168:171], v154
	ds_read_b128 v[172:175], v154 offset:1024
	ds_read_b128 v[182:185], v154 offset:2048
	ds_read_b128 v[190:193], v154 offset:3072
	ds_read_b128 v[194:197], v154 offset:4096
	ds_read_b128 v[198:201], v154 offset:5120
	ds_read_b128 v[202:205], v154 offset:6144
	ds_read_b128 v[206:209], v154 offset:7168
	global_load_lds_dwordx4 v[148:149], off
	v_lshl_add_u64 v[148:149], s[18:19], 0, v[138:139]
	s_add_i32 m0, s17, 0xe000
	s_nop 0
	global_load_lds_dwordx4 v[148:149], off
	s_waitcnt lgkmcnt(8)
	s_barrier
	s_waitcnt lgkmcnt(0)
	v_mfma_f32_16x16x32_bf16 v[124:127], v[144:147], v[168:171], v[124:127]
	v_mfma_f32_16x16x32_bf16 v[120:123], v[160:163], v[168:171], v[120:123]
	v_mfma_f32_16x16x32_bf16 v[112:115], v[144:147], v[182:185], v[112:115]
	v_mfma_f32_16x16x32_bf16 v[104:107], v[160:163], v[182:185], v[104:107]
	v_mfma_f32_16x16x32_bf16 v[96:99], v[144:147], v[194:197], v[96:99]
	v_mfma_f32_16x16x32_bf16 v[88:91], v[160:163], v[194:197], v[88:91]
	v_mfma_f32_16x16x32_bf16 v[80:83], v[144:147], v[202:205], v[80:83]
	v_mfma_f32_16x16x32_bf16 v[72:75], v[160:163], v[202:205], v[72:75]
	v_mfma_f32_16x16x32_bf16 v[124:127], v[156:159], v[172:175], v[124:127]
	v_mfma_f32_16x16x32_bf16 v[120:123], v[164:167], v[172:175], v[120:123]
	v_mfma_f32_16x16x32_bf16 v[112:115], v[156:159], v[190:193], v[112:115]
	v_mfma_f32_16x16x32_bf16 v[104:107], v[164:167], v[190:193], v[104:107]
	v_mfma_f32_16x16x32_bf16 v[96:99], v[156:159], v[198:201], v[96:99]
	v_mfma_f32_16x16x32_bf16 v[88:91], v[164:167], v[198:201], v[88:91]
	v_mfma_f32_16x16x32_bf16 v[80:83], v[156:159], v[206:209], v[80:83]
	v_mfma_f32_16x16x32_bf16 v[72:75], v[164:167], v[206:209], v[72:75]
	s_barrier
	s_add_i32 s48, s39, s29
	v_lshl_add_u64 v[148:149], s[20:21], 0, v[130:131]
	s_mov_b32 m0, s48
	ds_read_b128 v[210:213], v155
	ds_read_b128 v[214:217], v155 offset:1024
	ds_read_b128 v[218:221], v155 offset:2048
	ds_read_b128 v[222:225], v155 offset:3072
	global_load_lds_dwordx4 v[148:149], off
	v_lshl_add_u64 v[186:187], s[20:21], 0, v[134:135]
	s_add_i32 m0, s48, 0x2000
	s_nop 0
	global_load_lds_dwordx4 v[186:187], off
	s_barrier
	s_waitcnt lgkmcnt(0)
	v_mfma_f32_16x16x32_bf16 v[116:119], v[210:213], v[168:171], v[116:119]
	v_mfma_f32_16x16x32_bf16 v[108:111], v[218:221], v[168:171], v[108:111]
	v_mfma_f32_16x16x32_bf16 v[100:103], v[210:213], v[182:185], v[100:103]
	v_mfma_f32_16x16x32_bf16 v[92:95], v[218:221], v[182:185], v[92:95]
	v_mfma_f32_16x16x32_bf16 v[84:87], v[210:213], v[194:197], v[84:87]
	v_mfma_f32_16x16x32_bf16 v[76:79], v[218:221], v[194:197], v[76:79]
	v_mfma_f32_16x16x32_bf16 v[68:71], v[210:213], v[202:205], v[68:71]
	v_mfma_f32_16x16x32_bf16 v[64:67], v[218:221], v[202:205], v[64:67]
	v_mfma_f32_16x16x32_bf16 v[116:119], v[214:217], v[172:175], v[116:119]
	v_mfma_f32_16x16x32_bf16 v[108:111], v[222:225], v[172:175], v[108:111]
	v_mfma_f32_16x16x32_bf16 v[100:103], v[214:217], v[190:193], v[100:103]
	v_mfma_f32_16x16x32_bf16 v[92:95], v[222:225], v[190:193], v[92:95]
	v_mfma_f32_16x16x32_bf16 v[84:87], v[214:217], v[198:201], v[84:87]
	v_mfma_f32_16x16x32_bf16 v[76:79], v[222:225], v[198:201], v[76:79]
	v_mfma_f32_16x16x32_bf16 v[68:71], v[214:217], v[206:209], v[68:71]
	v_mfma_f32_16x16x32_bf16 v[64:67], v[222:225], v[206:209], v[64:67]
	s_mov_b32 m0, s17
	v_lshl_add_u64 v[226:227], s[22:23], 0, v[128:129]
	s_barrier
	ds_read_b128 v[168:171], v154 offset:16384
	ds_read_b128 v[172:175], v154 offset:17408
	ds_read_b128 v[182:185], v154 offset:18432
	ds_read_b128 v[190:193], v154 offset:19456
	ds_read_b128 v[194:197], v154 offset:20480
	ds_read_b128 v[198:201], v154 offset:21504
	ds_read_b128 v[202:205], v154 offset:22528
	ds_read_b128 v[206:209], v154 offset:23552
	global_load_lds_dwordx4 v[226:227], off
	v_lshl_add_u64 v[228:229], s[22:23], 0, v[132:133]
	s_mov_b32 m0, s30
	s_nop 0
	global_load_lds_dwordx4 v[228:229], off
	s_barrier
	s_waitcnt lgkmcnt(0)
	v_mfma_f32_16x16x32_bf16 v[60:63], v[144:147], v[168:171], v[60:63]
	v_mfma_f32_16x16x32_bf16 v[56:59], v[160:163], v[168:171], v[56:59]
	v_mfma_f32_16x16x32_bf16 v[48:51], v[144:147], v[182:185], v[48:51]
	v_mfma_f32_16x16x32_bf16 v[40:43], v[160:163], v[182:185], v[40:43]
	v_mfma_f32_16x16x32_bf16 v[32:35], v[144:147], v[194:197], v[32:35]
	v_mfma_f32_16x16x32_bf16 v[24:27], v[160:163], v[194:197], v[24:27]
	v_mfma_f32_16x16x32_bf16 v[16:19], v[144:147], v[202:205], v[16:19]
	v_mfma_f32_16x16x32_bf16 v[8:11], v[160:163], v[202:205], v[8:11]
	v_mfma_f32_16x16x32_bf16 v[60:63], v[156:159], v[172:175], v[60:63]
	v_mfma_f32_16x16x32_bf16 v[56:59], v[164:167], v[172:175], v[56:59]
	v_mfma_f32_16x16x32_bf16 v[48:51], v[156:159], v[190:193], v[48:51]
	v_mfma_f32_16x16x32_bf16 v[40:43], v[164:167], v[190:193], v[40:43]
	v_mfma_f32_16x16x32_bf16 v[32:35], v[156:159], v[198:201], v[32:35]
	v_mfma_f32_16x16x32_bf16 v[24:27], v[164:167], v[198:201], v[24:27]
	v_mfma_f32_16x16x32_bf16 v[16:19], v[156:159], v[206:209], v[16:19]
	v_mfma_f32_16x16x32_bf16 v[8:11], v[164:167], v[206:209], v[8:11]
	s_barrier
; #define PG8_STAGE(bufoff, gbase, voff) do { _Pragma("unroll") for (int _i = 0; _i < 2; ++_i) \
;         __builtin_amdgcn_global_load_lds((const unsigned*)((const char*)(gbase) + (voff)[_i]), (PG8_LAS unsigned*)(lds + (bufoff) + ldsw + _i * 8192), 16, 0, 0); } while (0)
; #define PG8_LDA(dst, b, h) do { _Pragma("unroll") for (int m = 0; m < 4; ++m) _Pragma("unroll") for (int k = 0; k < 2; ++k) dst[m][k] = *(const PG8_LAS bf16x8*)(lds + PG8_SA(b, h) + aoff + m * 2048 + k * 1024); } while (0)
; #define PG8_LDB(dst, b, h) do { _Pragma("unroll") for (int n = 0; n < 2; ++n) _Pragma("unroll") for (int k = 0; k < 2; ++k) dst[n][k] = *(const PG8_LAS bf16x8*)(lds + PG8_SB(b, h) + boff + n * 2048 + k * 1024); } while (0)
; #define PG8_MMA(ai, bj, At, Bt) do { __builtin_amdgcn_s_setprio(1); _Pragma("unroll") for (int m = 0; m < 4; ++m) _Pragma("unroll") for (int n = 0; n < 2; ++n) _Pragma("unroll") for (int k = 0; k < 2; ++k) \
;         acc[ai][bj][m][n] = __builtin_amdgcn_mfma_f32_16x16x32_bf16(Bt[n][k], At[m][k], acc[ai][bj][m][n], 0, 0, 0); __builtin_amdgcn_s_setprio(0); } while (0)
; #define PG8_WAIT_V(n) asm volatile("s_waitcnt vmcnt(" #n ")" ::: "memory")
; #define PG8_WAIT_L(n) asm volatile("s_waitcnt lgkmcnt(" #n ")" ::: "memory")
; #define PG8_BAR __builtin_amdgcn_s_barrier()
; #define PG8_SCHED __builtin_amdgcn_sched_barrier(0)
; template <class Epi, class Sched>
; __device__ __forceinline__ void gemm_phase(PG8_LAS unsigned char* lds, const Gemm g, const Sched& S, const Epi& E) {
;     ...
;             PG8_STAGE(PG8_SB(0, 1), b2 + hstep, voffB);
;             PG8_WAIT_V(6); PG8_BAR; PG8_MMA(1, 1, At, B1); PG8_BAR;
;             PG8_LDB(B0, 1, 0); PG8_SCHED; PG8_LDA(At, 1, 0); PG8_STAGE(PG8_SA(0, 1), a2 + hstep, voffA);
;             PG8_WAIT_L(8); PG8_BAR; PG8_WAIT_L(0); PG8_MMA(0, 0, At, B0); PG8_BAR; PG8_SCHED;
;             PG8_LDB(B1, 1, 1); PG8_STAGE(PG8_SB(1, 0), b3, voffB);
;             PG8_BAR; PG8_WAIT_L(0); PG8_MMA(0, 1, At, B1); PG8_BAR;
;             PG8_LDA(At, 1, 1); PG8_STAGE(PG8_SA(1, 0), a3, voffA);
;             PG8_BAR; PG8_WAIT_L(0); PG8_MMA(1, 0, At, B0); PG8_BAR; PG8_SCHED;
	s_add_u32 s48, s20, 0x40000
	s_addc_u32 s49, s21, 0
	s_add_i32 s50, s40, s29
	v_lshl_add_u64 v[144:145], s[48:49], 0, v[130:131]
	s_mov_b32 m0, s50
	s_nop 0
	global_load_lds_dwordx4 v[144:145], off
	v_lshl_add_u64 v[144:145], s[48:49], 0, v[134:135]
	s_add_i32 m0, s50, 0x2000
	s_nop 0
	global_load_lds_dwordx4 v[144:145], off
	s_waitcnt vmcnt(6)
	s_barrier
	v_mfma_f32_16x16x32_bf16 v[52:55], v[210:213], v[168:171], v[52:55]
	v_mfma_f32_16x16x32_bf16 v[44:47], v[218:221], v[168:171], v[44:47]
	v_mfma_f32_16x16x32_bf16 v[36:39], v[210:213], v[182:185], v[36:39]
	v_mfma_f32_16x16x32_bf16 v[28:31], v[218:221], v[182:185], v[28:31]
	v_mfma_f32_16x16x32_bf16 v[20:23], v[210:213], v[194:197], v[20:23]
	v_mfma_f32_16x16x32_bf16 v[12:15], v[218:221], v[194:197], v[12:15]
	v_mfma_f32_16x16x32_bf16 v[4:7], v[210:213], v[202:205], v[4:7]
	v_mfma_f32_16x16x32_bf16 v[0:3], v[218:221], v[202:205], v[0:3]
	v_mfma_f32_16x16x32_bf16 v[52:55], v[214:217], v[172:175], v[52:55]
	v_mfma_f32_16x16x32_bf16 v[44:47], v[222:225], v[172:175], v[44:47]
	v_mfma_f32_16x16x32_bf16 v[36:39], v[214:217], v[190:193], v[36:39]
	v_mfma_f32_16x16x32_bf16 v[28:31], v[222:225], v[190:193], v[28:31]
	v_mfma_f32_16x16x32_bf16 v[20:23], v[214:217], v[198:201], v[20:23]
	v_mfma_f32_16x16x32_bf16 v[12:15], v[222:225], v[198:201], v[12:15]
	v_mfma_f32_16x16x32_bf16 v[4:7], v[214:217], v[206:209], v[4:7]
	v_mfma_f32_16x16x32_bf16 v[0:3], v[222:225], v[206:209], v[0:3]
	s_add_i32 s48, 0, 0x18000
	v_add_u32_e32 v164, s48, v151
	s_barrier
	ds_read_b128 v[144:147], v164
	ds_read_b128 v[156:159], v164 offset:1024
	ds_read_b128 v[160:163], v164 offset:2048
	ds_read_b128 v[164:167], v164 offset:3072
	s_add_u32 s22, s22, 0x40000
	s_addc_u32 s23, s23, 0
	s_mov_b32 m0, s31
	v_lshl_add_u64 v[210:211], s[22:23], 0, v[128:129]
	ds_read_b128 v[168:171], v154 offset:32768
	ds_read_b128 v[172:175], v154 offset:33792
	ds_read_b128 v[182:185], v154 offset:34816
	ds_read_b128 v[190:193], v154 offset:35840
	ds_read_b128 v[194:197], v154 offset:36864
	ds_read_b128 v[198:201], v154 offset:37888
	ds_read_b128 v[202:205], v154 offset:38912
	ds_read_b128 v[206:209], v154 offset:39936
	global_load_lds_dwordx4 v[210:211], off
	v_lshl_add_u64 v[210:211], s[22:23], 0, v[132:133]
	s_mov_b32 m0, s34
	s_nop 0
	global_load_lds_dwordx4 v[210:211], off
	s_waitcnt lgkmcnt(8)
	s_barrier
	s_waitcnt lgkmcnt(0)
	v_mfma_f32_16x16x32_bf16 v[124:127], v[144:147], v[168:171], v[124:127]
	v_mfma_f32_16x16x32_bf16 v[120:123], v[160:163], v[168:171], v[120:123]
	v_mfma_f32_16x16x32_bf16 v[112:115], v[144:147], v[182:185], v[112:115]
	v_mfma_f32_16x16x32_bf16 v[104:107], v[160:163], v[182:185], v[104:107]
	v_mfma_f32_16x16x32_bf16 v[96:99], v[144:147], v[194:197], v[96:99]
	v_mfma_f32_16x16x32_bf16 v[88:91], v[160:163], v[194:197], v[88:91]
	v_mfma_f32_16x16x32_bf16 v[80:83], v[144:147], v[202:205], v[80:83]
	v_mfma_f32_16x16x32_bf16 v[72:75], v[160:163], v[202:205], v[72:75]
	v_mfma_f32_16x16x32_bf16 v[124:127], v[156:159], v[172:175], v[124:127]
	v_mfma_f32_16x16x32_bf16 v[120:123], v[164:167], v[172:175], v[120:123]
	v_mfma_f32_16x16x32_bf16 v[112:115], v[156:159], v[190:193], v[112:115]
	v_mfma_f32_16x16x32_bf16 v[104:107], v[164:167], v[190:193], v[104:107]
	v_mfma_f32_16x16x32_bf16 v[96:99], v[156:159], v[198:201], v[96:99]
	v_mfma_f32_16x16x32_bf16 v[88:91], v[164:167], v[198:201], v[88:91]
	v_mfma_f32_16x16x32_bf16 v[80:83], v[156:159], v[206:209], v[80:83]
	v_mfma_f32_16x16x32_bf16 v[72:75], v[164:167], v[206:209], v[72:75]
	s_barrier
	s_add_i32 s22, 0, 0x1c000
	s_add_i32 s23, s48, s29
	v_add_u32_e32 v179, s22, v151
	v_lshl_add_u64 v[148:149], v[148:149], 0, s[6:7]
	s_mov_b32 m0, s23
	ds_read_b128 v[210:213], v179
	ds_read_b128 v[214:217], v179 offset:1024
	ds_read_b128 v[218:221], v179 offset:2048
	ds_read_b128 v[222:225], v179 offset:3072
	global_load_lds_dwordx4 v[148:149], off
	v_lshl_add_u64 v[148:149], v[186:187], 0, s[6:7]
	s_add_i32 m0, s23, 0x2000
	s_nop 0
	global_load_lds_dwordx4 v[148:149], off
	s_barrier
	s_waitcnt lgkmcnt(0)
	v_mfma_f32_16x16x32_bf16 v[116:119], v[210:213], v[168:171], v[116:119]
	v_mfma_f32_16x16x32_bf16 v[108:111], v[218:221], v[168:171], v[108:111]
	v_mfma_f32_16x16x32_bf16 v[100:103], v[210:213], v[182:185], v[100:103]
	v_mfma_f32_16x16x32_bf16 v[92:95], v[218:221], v[182:185], v[92:95]
	v_mfma_f32_16x16x32_bf16 v[84:87], v[210:213], v[194:197], v[84:87]
	v_mfma_f32_16x16x32_bf16 v[76:79], v[218:221], v[194:197], v[76:79]
	v_mfma_f32_16x16x32_bf16 v[68:71], v[210:213], v[202:205], v[68:71]
	v_mfma_f32_16x16x32_bf16 v[64:67], v[218:221], v[202:205], v[64:67]
	v_mfma_f32_16x16x32_bf16 v[116:119], v[214:217], v[172:175], v[116:119]
	v_mfma_f32_16x16x32_bf16 v[108:111], v[222:225], v[172:175], v[108:111]
	v_mfma_f32_16x16x32_bf16 v[100:103], v[214:217], v[190:193], v[100:103]
	v_mfma_f32_16x16x32_bf16 v[92:95], v[222:225], v[190:193], v[92:95]
	v_mfma_f32_16x16x32_bf16 v[84:87], v[214:217], v[198:201], v[84:87]
	v_mfma_f32_16x16x32_bf16 v[76:79], v[222:225], v[198:201], v[76:79]
	v_mfma_f32_16x16x32_bf16 v[68:71], v[214:217], v[206:209], v[68:71]
	v_mfma_f32_16x16x32_bf16 v[64:67], v[222:225], v[206:209], v[64:67]
	s_mov_b32 m0, s36
	v_lshl_add_u64 v[148:149], v[226:227], 0, s[6:7]
	s_barrier
	ds_read_b128 v[168:171], v154 offset:49152
	ds_read_b128 v[172:175], v154 offset:50176
	ds_read_b128 v[182:185], v154 offset:51200
	ds_read_b128 v[190:193], v154 offset:52224
	ds_read_b128 v[194:197], v154 offset:53248
	ds_read_b128 v[198:201], v154 offset:54272
	ds_read_b128 v[202:205], v154 offset:55296
	ds_read_b128 v[206:209], v154 offset:56320
	global_load_lds_dwordx4 v[148:149], off
	v_lshl_add_u64 v[148:149], v[228:229], 0, s[6:7]
	s_mov_b32 m0, s37
	s_nop 0
	global_load_lds_dwordx4 v[148:149], off
	s_barrier
; __device__ __forceinline__ unsigned cvt_pk_bf16(float lo, float hi) { unsigned r; asm volatile("v_cvt_pk_bf16_f32 %0, %1, %2" : "=v"(r) : "v"(lo), "v"(hi)); return r; }
; __device__ __forceinline__ float bf_lo(unsigned u) { return __uint_as_float(u << 16); }
; __device__ __forceinline__ float bf_hi(unsigned u) { return __uint_as_float(u & 0xffff0000u); }
; #define PG8_WAIT_V(n) asm volatile("s_waitcnt vmcnt(" #n ")" ::: "memory")
; #define PG8_WAIT_L(n) asm volatile("s_waitcnt lgkmcnt(" #n ")" ::: "memory")
; #define PG8_BAR __builtin_amdgcn_s_barrier()
;     __device__ __forceinline__ void operator()(const f32x4 (&acc)[2][2][4][2], const Unit& u, int wr, int wc, int fr, int fq) const {
;         const int row0 = u.pm * BM + wr * 64 + fr, col0 = u.pn * BM + wc * 32 + 8 * fq;
; #pragma unroll
;         for (int ai = 0; ai < 2; ++ai)
; #pragma unroll
;             for (int m = 0; m < 4; ++m) { const size_t r = (size_t)(row0 + ai * HALF + m * 16); bf16_t* rowp = O + r * ldc + col0; const bf16_t* gp = G + r * ldg + col0;
; #pragma unroll
;                 for (int bj = 0; bj < 2; ++bj) { const u32x4 gw = *(const u32x4*)(gp + bj * HALF);
;                     f32x4 v0 = acc[ai][bj][m][0], v1 = acc[ai][bj][m][1];
;                     v0[0] *= bf_lo(gw.x); v0[1] *= bf_hi(gw.x); v0[2] *= bf_lo(gw.y); v0[3] *= bf_hi(gw.y);
;                     v1[0] *= bf_lo(gw.z); v1[1] *= bf_hi(gw.z); v1[2] *= bf_lo(gw.w); v1[3] *= bf_hi(gw.w);
;                     if (ACCUM) { const u32x4 pw = *(const u32x4*)(rowp + bj * HALF);
;                         v0[0] += bf_lo(pw.x); v0[1] += bf_hi(pw.x); v0[2] += bf_lo(pw.y); v0[3] += bf_hi(pw.y);
;                         v1[0] += bf_lo(pw.z); v1[1] += bf_hi(pw.z); v1[2] += bf_lo(pw.w); v1[3] += bf_hi(pw.w); }
;                     u32x4 w; w.x = cvt_pk_bf16(v0[0], v0[1]); w.y = cvt_pk_bf16(v0[2], v0[3]); w.z = cvt_pk_bf16(v1[0], v1[1]); w.w = cvt_pk_bf16(v1[2], v1[3]);
;                     *(u32x4*)(rowp + bj * HALF) = w; } }
; template <class Epi, class Sched>
; __device__ __forceinline__ void gemm_phase(PG8_LAS unsigned char* lds, const Gemm g, const Sched& S, const Epi& E) {
;     ...
;             PG8_BAR; PG8_WAIT_L(0); PG8_MMA(1, 0, At, B0); PG8_BAR; PG8_SCHED;
;             PG8_STAGE(PG8_SB(1, 1), b3 + hstep, voffB);
;             PG8_WAIT_V(6); PG8_BAR; PG8_MMA(1, 1, At, B1); PG8_BAR;
	s_waitcnt lgkmcnt(0)
	v_mfma_f32_16x16x32_bf16 v[60:63], v[144:147], v[168:171], v[60:63]
	v_mfma_f32_16x16x32_bf16 v[56:59], v[160:163], v[168:171], v[56:59]
	v_mfma_f32_16x16x32_bf16 v[48:51], v[144:147], v[182:185], v[48:51]
	v_mfma_f32_16x16x32_bf16 v[40:43], v[160:163], v[182:185], v[40:43]
	v_mfma_f32_16x16x32_bf16 v[32:35], v[144:147], v[194:197], v[32:35]
	v_mfma_f32_16x16x32_bf16 v[24:27], v[160:163], v[194:197], v[24:27]
	v_mfma_f32_16x16x32_bf16 v[16:19], v[144:147], v[202:205], v[16:19]
	v_mfma_f32_16x16x32_bf16 v[8:11], v[160:163], v[202:205], v[8:11]
	v_mfma_f32_16x16x32_bf16 v[60:63], v[156:159], v[172:175], v[60:63]
	v_mfma_f32_16x16x32_bf16 v[56:59], v[164:167], v[172:175], v[56:59]
	v_mfma_f32_16x16x32_bf16 v[48:51], v[156:159], v[190:193], v[48:51]
	v_mfma_f32_16x16x32_bf16 v[40:43], v[164:167], v[190:193], v[40:43]
	v_mfma_f32_16x16x32_bf16 v[32:35], v[156:159], v[198:201], v[32:35]
	v_mfma_f32_16x16x32_bf16 v[24:27], v[164:167], v[198:201], v[24:27]
	v_mfma_f32_16x16x32_bf16 v[16:19], v[156:159], v[206:209], v[16:19]
	v_mfma_f32_16x16x32_bf16 v[8:11], v[164:167], v[206:209], v[8:11]
	s_barrier
	s_add_u32 s20, s20, 0x40080
	s_addc_u32 s21, s21, 0
	s_add_i32 s22, s22, s29
	v_lshl_add_u64 v[144:145], s[20:21], 0, v[130:131]
	s_mov_b32 m0, s22
	s_nop 0
	global_load_lds_dwordx4 v[144:145], off
	v_lshl_add_u64 v[144:145], s[20:21], 0, v[134:135]
	s_add_i32 m0, s22, 0x2000
	s_nop 0
	global_load_lds_dwordx4 v[144:145], off
	s_waitcnt vmcnt(6)
	s_barrier
	v_mfma_f32_16x16x32_bf16 v[52:55], v[210:213], v[168:171], v[52:55]
	v_mfma_f32_16x16x32_bf16 v[44:47], v[218:221], v[168:171], v[44:47]
	v_mfma_f32_16x16x32_bf16 v[36:39], v[210:213], v[182:185], v[36:39]
	v_mfma_f32_16x16x32_bf16 v[28:31], v[218:221], v[182:185], v[28:31]
	v_mfma_f32_16x16x32_bf16 v[20:23], v[210:213], v[194:197], v[20:23]
	v_mfma_f32_16x16x32_bf16 v[12:15], v[218:221], v[194:197], v[12:15]
	v_mfma_f32_16x16x32_bf16 v[4:7], v[210:213], v[202:205], v[4:7]
	v_mfma_f32_16x16x32_bf16 v[0:3], v[218:221], v[202:205], v[0:3]
	v_mfma_f32_16x16x32_bf16 v[52:55], v[214:217], v[172:175], v[52:55]
	v_mfma_f32_16x16x32_bf16 v[44:47], v[222:225], v[172:175], v[44:47]
	v_mfma_f32_16x16x32_bf16 v[36:39], v[214:217], v[190:193], v[36:39]
	v_mfma_f32_16x16x32_bf16 v[28:31], v[222:225], v[190:193], v[28:31]
	v_mfma_f32_16x16x32_bf16 v[20:23], v[214:217], v[198:201], v[20:23]
	v_mfma_f32_16x16x32_bf16 v[12:15], v[222:225], v[198:201], v[12:15]
	v_mfma_f32_16x16x32_bf16 v[4:7], v[214:217], v[206:209], v[4:7]
	v_mfma_f32_16x16x32_bf16 v[0:3], v[222:225], v[206:209], v[0:3]
	s_add_i32 s47, s47, 2
	s_add_u32 s18, s18, 0x100
	s_addc_u32 s19, s19, 0
	s_add_u32 s45, s45, 0x100
	s_addc_u32 s46, s46, 0
	s_cmp_gt_u32 s47, 13
	s_barrier
	s_cbranch_scc0 .LBB0_991
	v_lshl_or_b32 v144, s42, 8, v152
	v_lshl_add_u32 v146, s16, 8, v150
	v_ashrrev_i32_e32 v145, 31, v144
	v_mov_b64_e32 v[148:149], s[4:5]
	v_lshlrev_b64 v[144:145], 1, v[144:145]
	v_mad_i64_i32 v[156:157], s[18:19], v146, s41, v[148:149]
	v_lshl_add_u64 v[160:161], v[156:157], 0, v[144:145]
	global_load_dwordx4 v[156:159], v[160:161], off offset:3072
	s_and_b64 vcc, exec, s[2:3]
	s_mov_b32 s42, s8
	s_mov_b32 s16, s10
	s_mov_b64 s[20:21], s[14:15]
	s_waitcnt vmcnt(0)
	v_lshlrev_b32_e32 v147, 16, v156
	v_and_b32_e32 v156, 0xffff0000, v156
	v_lshlrev_b32_e32 v162, 16, v157
	v_and_b32_e32 v157, 0xffff0000, v157
	v_lshlrev_b32_e32 v164, 16, v159
	v_and_b32_e32 v159, 0xffff0000, v159
	v_lshlrev_b32_e32 v163, 16, v158
	v_and_b32_e32 v158, 0xffff0000, v158
	v_mul_f32_e32 v124, v124, v147
	v_mul_f32_e32 v125, v125, v156
	v_mul_f32_e32 v126, v126, v162
	v_mul_f32_e32 v127, v127, v157
	v_mul_f32_e32 v123, v123, v159
	v_mul_f32_e32 v147, v120, v163
	v_mul_f32_e32 v156, v121, v158
	v_mul_f32_e32 v157, v122, v164
	v_cvt_pk_bf16_f32 v120, v124, v125
	v_cvt_pk_bf16_f32 v121, v126, v127
	v_cvt_pk_bf16_f32 v122, v147, v156
	v_cvt_pk_bf16_f32 v123, v157, v123
	global_load_dwordx4 v[124:127], v[160:161], off offset:3328
	v_ashrrev_i32_e32 v147, 31, v146
	v_lshlrev_b64 v[158:159], 11, v[146:147]
	v_lshl_add_u64 v[158:159], s[0:1], 0, v[158:159]
	v_or_b32_e32 v156, 16, v146
	v_lshl_add_u64 v[158:159], v[158:159], 0, v[144:145]
	v_mad_i64_i32 v[160:161], s[18:19], v156, s41, v[148:149]
	global_store_dwordx4 v[158:159], v[120:123], off
	v_lshl_add_u64 v[160:161], v[160:161], 0, v[144:145]
	v_ashrrev_i32_e32 v157, 31, v156
	s_waitcnt vmcnt(0)
	v_lshlrev_b32_e32 v120, 16, v124
	v_and_b32_e32 v121, 0xffff0000, v124
	v_lshlrev_b32_e32 v122, 16, v125
	v_and_b32_e32 v123, 0xffff0000, v125
	v_lshlrev_b32_e32 v124, 16, v126
	v_and_b32_e32 v125, 0xffff0000, v126
	v_lshlrev_b32_e32 v126, 16, v127
	v_and_b32_e32 v127, 0xffff0000, v127
	v_mul_f32_e32 v116, v116, v120
	v_mul_f32_e32 v117, v117, v121
	v_mul_f32_e32 v118, v118, v122
	v_mul_f32_e32 v119, v119, v123
	v_mul_f32_e32 v111, v111, v127
	v_mul_f32_e32 v120, v108, v124
	v_mul_f32_e32 v121, v109, v125
	v_mul_f32_e32 v122, v110, v126
	v_cvt_pk_bf16_f32 v108, v116, v117
	v_cvt_pk_bf16_f32 v109, v118, v119
	v_cvt_pk_bf16_f32 v110, v120, v121
	v_cvt_pk_bf16_f32 v111, v122, v111
	global_load_dwordx4 v[116:119], v[160:161], off offset:3072
	s_nop 0
	global_store_dwordx4 v[158:159], v[108:111], off offset:256
	s_waitcnt vmcnt(0)
; __device__ __forceinline__ unsigned cvt_pk_bf16(float lo, float hi) { unsigned r; asm volatile("v_cvt_pk_bf16_f32 %0, %1, %2" : "=v"(r) : "v"(lo), "v"(hi)); return r; }
; __device__ __forceinline__ float bf_lo(unsigned u) { return __uint_as_float(u << 16); }
; __device__ __forceinline__ float bf_hi(unsigned u) { return __uint_as_float(u & 0xffff0000u); }
;     __device__ __forceinline__ void operator()(const f32x4 (&acc)[2][2][4][2], const Unit& u, int wr, int wc, int fr, int fq) const {
;     ...
;             for (int m = 0; m < 4; ++m) { const size_t r = (size_t)(row0 + ai * HALF + m * 16); bf16_t* rowp = O + r * ldc + col0; const bf16_t* gp = G + r * ldg + col0;
; #pragma unroll
;                 for (int bj = 0; bj < 2; ++bj) { const u32x4 gw = *(const u32x4*)(gp + bj * HALF);
;                     f32x4 v0 = acc[ai][bj][m][0], v1 = acc[ai][bj][m][1];
;                     v0[0] *= bf_lo(gw.x); v0[1] *= bf_hi(gw.x); v0[2] *= bf_lo(gw.y); v0[3] *= bf_hi(gw.y);
;                     v1[0] *= bf_lo(gw.z); v1[1] *= bf_hi(gw.z); v1[2] *= bf_lo(gw.w); v1[3] *= bf_hi(gw.w);
;                     if (ACCUM) { const u32x4 pw = *(const u32x4*)(rowp + bj * HALF);
;                         v0[0] += bf_lo(pw.x); v0[1] += bf_hi(pw.x); v0[2] += bf_lo(pw.y); v0[3] += bf_hi(pw.y);
;                         v1[0] += bf_lo(pw.z); v1[1] += bf_hi(pw.z); v1[2] += bf_lo(pw.w); v1[3] += bf_hi(pw.w); }
;                     u32x4 w; w.x = cvt_pk_bf16(v0[0], v0[1]); w.y = cvt_pk_bf16(v0[2], v0[3]); w.z = cvt_pk_bf16(v1[0], v1[1]); w.w = cvt_pk_bf16(v1[2], v1[3]);
;                     *(u32x4*)(rowp + bj * HALF) = w; } }
	s_nop 0
	v_lshlrev_b32_e32 v108, 16, v116
	v_and_b32_e32 v109, 0xffff0000, v116
	v_lshlrev_b32_e32 v110, 16, v117
	v_and_b32_e32 v111, 0xffff0000, v117
	v_lshlrev_b32_e32 v116, 16, v118
	v_and_b32_e32 v117, 0xffff0000, v118
	v_lshlrev_b32_e32 v118, 16, v119
	v_and_b32_e32 v119, 0xffff0000, v119
	v_mul_f32_e32 v108, v112, v108
	v_mul_f32_e32 v109, v113, v109
	v_mul_f32_e32 v110, v114, v110
	v_mul_f32_e32 v111, v115, v111
	v_mul_f32_e32 v107, v107, v119
	v_mul_f32_e32 v112, v104, v116
	v_mul_f32_e32 v113, v105, v117
	v_mul_f32_e32 v114, v106, v118
	v_cvt_pk_bf16_f32 v104, v108, v109
	v_cvt_pk_bf16_f32 v105, v110, v111
	v_cvt_pk_bf16_f32 v106, v112, v113
	v_cvt_pk_bf16_f32 v107, v114, v107
	global_load_dwordx4 v[108:111], v[160:161], off offset:3328
	v_lshlrev_b64 v[116:117], 11, v[156:157]
	v_lshl_add_u64 v[116:117], s[0:1], 0, v[116:117]
	v_or_b32_e32 v112, 32, v146
	v_lshl_add_u64 v[116:117], v[116:117], 0, v[144:145]
	v_mad_i64_i32 v[114:115], s[18:19], v112, s41, v[148:149]
	global_store_dwordx4 v[116:117], v[104:107], off
	v_lshl_add_u64 v[114:115], v[114:115], 0, v[144:145]
	v_ashrrev_i32_e32 v113, 31, v112
	s_waitcnt vmcnt(0)
	v_lshlrev_b32_e32 v104, 16, v108
	v_and_b32_e32 v105, 0xffff0000, v108
	v_lshlrev_b32_e32 v106, 16, v109
	v_and_b32_e32 v107, 0xffff0000, v109
	v_lshlrev_b32_e32 v108, 16, v110
	v_and_b32_e32 v109, 0xffff0000, v110
	v_lshlrev_b32_e32 v110, 16, v111
	v_and_b32_e32 v111, 0xffff0000, v111
	v_mul_f32_e32 v100, v100, v104
	v_mul_f32_e32 v101, v101, v105
	v_mul_f32_e32 v102, v102, v106
	v_mul_f32_e32 v103, v103, v107
	v_mul_f32_e32 v95, v95, v111
	v_mul_f32_e32 v104, v92, v108
	v_mul_f32_e32 v105, v93, v109
	v_mul_f32_e32 v106, v94, v110
	v_cvt_pk_bf16_f32 v92, v100, v101
	v_cvt_pk_bf16_f32 v93, v102, v103
	v_cvt_pk_bf16_f32 v94, v104, v105
	v_cvt_pk_bf16_f32 v95, v106, v95
	global_load_dwordx4 v[100:103], v[114:115], off offset:3072
	s_nop 0
	global_store_dwordx4 v[116:117], v[92:95], off offset:256
	s_waitcnt vmcnt(0)
	s_nop 0
	v_lshlrev_b32_e32 v92, 16, v100
	v_and_b32_e32 v93, 0xffff0000, v100
	v_lshlrev_b32_e32 v94, 16, v101
	v_and_b32_e32 v95, 0xffff0000, v101
	v_lshlrev_b32_e32 v100, 16, v102
	v_and_b32_e32 v101, 0xffff0000, v102
	v_lshlrev_b32_e32 v102, 16, v103
	v_and_b32_e32 v103, 0xffff0000, v103
	v_mul_f32_e32 v92, v96, v92
	v_mul_f32_e32 v93, v97, v93
	v_mul_f32_e32 v94, v98, v94
	v_mul_f32_e32 v95, v99, v95
	v_mul_f32_e32 v91, v91, v103
	v_mul_f32_e32 v96, v88, v100
	v_mul_f32_e32 v97, v89, v101
	v_mul_f32_e32 v98, v90, v102
	v_cvt_pk_bf16_f32 v88, v92, v93
	v_cvt_pk_bf16_f32 v89, v94, v95
	v_cvt_pk_bf16_f32 v90, v96, v97
	v_cvt_pk_bf16_f32 v91, v98, v91
	global_load_dwordx4 v[92:95], v[114:115], off offset:3328
	v_lshlrev_b64 v[100:101], 11, v[112:113]
	v_lshl_add_u64 v[100:101], s[0:1], 0, v[100:101]
	v_or_b32_e32 v96, 48, v146
	v_lshl_add_u64 v[100:101], v[100:101], 0, v[144:145]
	v_mad_i64_i32 v[98:99], s[18:19], v96, s41, v[148:149]
	global_store_dwordx4 v[100:101], v[88:91], off
	v_lshl_add_u64 v[98:99], v[98:99], 0, v[144:145]
	v_ashrrev_i32_e32 v97, 31, v96
	s_waitcnt vmcnt(0)
	v_lshlrev_b32_e32 v88, 16, v92
	v_and_b32_e32 v89, 0xffff0000, v92
	v_lshlrev_b32_e32 v90, 16, v93
	v_and_b32_e32 v91, 0xffff0000, v93
	v_lshlrev_b32_e32 v92, 16, v94
	v_and_b32_e32 v93, 0xffff0000, v94
	v_lshlrev_b32_e32 v94, 16, v95
	v_and_b32_e32 v95, 0xffff0000, v95
	v_mul_f32_e32 v84, v84, v88
	v_mul_f32_e32 v85, v85, v89
	v_mul_f32_e32 v86, v86, v90
	v_mul_f32_e32 v87, v87, v91
	v_mul_f32_e32 v79, v79, v95
	v_mul_f32_e32 v88, v76, v92
	v_mul_f32_e32 v89, v77, v93
	v_mul_f32_e32 v90, v78, v94
	v_cvt_pk_bf16_f32 v76, v84, v85
	v_cvt_pk_bf16_f32 v77, v86, v87
	v_cvt_pk_bf16_f32 v78, v88, v89
	v_cvt_pk_bf16_f32 v79, v90, v79
	global_load_dwordx4 v[84:87], v[98:99], off offset:3072
	s_nop 0
	global_store_dwordx4 v[100:101], v[76:79], off offset:256
	s_waitcnt vmcnt(0)
	s_nop 0
	v_lshlrev_b32_e32 v76, 16, v84
	v_and_b32_e32 v77, 0xffff0000, v84
	v_lshlrev_b32_e32 v78, 16, v85
	v_and_b32_e32 v79, 0xffff0000, v85
	v_lshlrev_b32_e32 v84, 16, v86
	v_and_b32_e32 v85, 0xffff0000, v86
	v_lshlrev_b32_e32 v86, 16, v87
	v_and_b32_e32 v87, 0xffff0000, v87
	v_mul_f32_e32 v76, v80, v76
	v_mul_f32_e32 v77, v81, v77
	v_mul_f32_e32 v78, v82, v78
	v_mul_f32_e32 v79, v83, v79
	v_mul_f32_e32 v75, v75, v87
	v_mul_f32_e32 v80, v72, v84
	v_mul_f32_e32 v81, v73, v85
	v_mul_f32_e32 v82, v74, v86
	v_cvt_pk_bf16_f32 v72, v76, v77
	v_cvt_pk_bf16_f32 v73, v78, v79
	v_cvt_pk_bf16_f32 v74, v80, v81
	v_cvt_pk_bf16_f32 v75, v82, v75
	global_load_dwordx4 v[76:79], v[98:99], off offset:3328
	v_lshlrev_b64 v[84:85], 11, v[96:97]
	v_lshl_add_u64 v[84:85], s[0:1], 0, v[84:85]
	v_add_u32_e32 v80, 0x80, v146
	v_lshl_add_u64 v[84:85], v[84:85], 0, v[144:145]
	v_mad_i64_i32 v[82:83], s[18:19], v80, s41, v[148:149]
	global_store_dwordx4 v[84:85], v[72:75], off
	v_lshl_add_u64 v[82:83], v[82:83], 0, v[144:145]
	v_ashrrev_i32_e32 v81, 31, v80
	s_waitcnt vmcnt(0)
	v_lshlrev_b32_e32 v72, 16, v76
	v_and_b32_e32 v73, 0xffff0000, v76
	v_lshlrev_b32_e32 v74, 16, v77
	v_and_b32_e32 v75, 0xffff0000, v77
	v_lshlrev_b32_e32 v76, 16, v78
	v_and_b32_e32 v77, 0xffff0000, v78
	v_lshlrev_b32_e32 v78, 16, v79
	v_and_b32_e32 v79, 0xffff0000, v79
	v_mul_f32_e32 v68, v68, v72
	v_mul_f32_e32 v69, v69, v73
	v_mul_f32_e32 v70, v70, v74
	v_mul_f32_e32 v71, v71, v75
	v_mul_f32_e32 v67, v67, v79
	v_mul_f32_e32 v72, v64, v76
	v_mul_f32_e32 v73, v65, v77
	v_mul_f32_e32 v74, v66, v78
	v_cvt_pk_bf16_f32 v64, v68, v69
	v_cvt_pk_bf16_f32 v65, v70, v71
	v_cvt_pk_bf16_f32 v66, v72, v73
	v_cvt_pk_bf16_f32 v67, v74, v67
	global_load_dwordx4 v[68:71], v[82:83], off offset:3072
	s_nop 0
	global_store_dwordx4 v[84:85], v[64:67], off offset:256
	s_waitcnt vmcnt(0)
; __device__ __forceinline__ unsigned cvt_pk_bf16(float lo, float hi) { unsigned r; asm volatile("v_cvt_pk_bf16_f32 %0, %1, %2" : "=v"(r) : "v"(lo), "v"(hi)); return r; }
; __device__ __forceinline__ float bf_lo(unsigned u) { return __uint_as_float(u << 16); }
; __device__ __forceinline__ float bf_hi(unsigned u) { return __uint_as_float(u & 0xffff0000u); }
;     __device__ __forceinline__ void operator()(const f32x4 (&acc)[2][2][4][2], const Unit& u, int wr, int wc, int fr, int fq) const {
;     ...
;             for (int m = 0; m < 4; ++m) { const size_t r = (size_t)(row0 + ai * HALF + m * 16); bf16_t* rowp = O + r * ldc + col0; const bf16_t* gp = G + r * ldg + col0;
; #pragma unroll
;                 for (int bj = 0; bj < 2; ++bj) { const u32x4 gw = *(const u32x4*)(gp + bj * HALF);
;                     f32x4 v0 = acc[ai][bj][m][0], v1 = acc[ai][bj][m][1];
;                     v0[0] *= bf_lo(gw.x); v0[1] *= bf_hi(gw.x); v0[2] *= bf_lo(gw.y); v0[3] *= bf_hi(gw.y);
;                     v1[0] *= bf_lo(gw.z); v1[1] *= bf_hi(gw.z); v1[2] *= bf_lo(gw.w); v1[3] *= bf_hi(gw.w);
;                     if (ACCUM) { const u32x4 pw = *(const u32x4*)(rowp + bj * HALF);
;                         v0[0] += bf_lo(pw.x); v0[1] += bf_hi(pw.x); v0[2] += bf_lo(pw.y); v0[3] += bf_hi(pw.y);
;                         v1[0] += bf_lo(pw.z); v1[1] += bf_hi(pw.z); v1[2] += bf_lo(pw.w); v1[3] += bf_hi(pw.w); }
;                     u32x4 w; w.x = cvt_pk_bf16(v0[0], v0[1]); w.y = cvt_pk_bf16(v0[2], v0[3]); w.z = cvt_pk_bf16(v1[0], v1[1]); w.w = cvt_pk_bf16(v1[2], v1[3]);
;                     *(u32x4*)(rowp + bj * HALF) = w; } }
	s_nop 0
	v_lshlrev_b32_e32 v64, 16, v68
	v_and_b32_e32 v65, 0xffff0000, v68
	v_lshlrev_b32_e32 v66, 16, v69
	v_and_b32_e32 v67, 0xffff0000, v69
	v_lshlrev_b32_e32 v68, 16, v70
	v_and_b32_e32 v69, 0xffff0000, v70
	v_lshlrev_b32_e32 v70, 16, v71
	v_and_b32_e32 v71, 0xffff0000, v71
	v_mul_f32_e32 v60, v60, v64
	v_mul_f32_e32 v61, v61, v65
	v_mul_f32_e32 v62, v62, v66
	v_mul_f32_e32 v63, v63, v67
	v_mul_f32_e32 v59, v59, v71
	v_mul_f32_e32 v64, v56, v68
	v_mul_f32_e32 v65, v57, v69
	v_mul_f32_e32 v66, v58, v70
	v_cvt_pk_bf16_f32 v56, v60, v61
	v_cvt_pk_bf16_f32 v57, v62, v63
	v_cvt_pk_bf16_f32 v58, v64, v65
	v_cvt_pk_bf16_f32 v59, v66, v59
	global_load_dwordx4 v[60:63], v[82:83], off offset:3328
	v_lshlrev_b64 v[68:69], 11, v[80:81]
	v_lshl_add_u64 v[68:69], s[0:1], 0, v[68:69]
	v_add_u32_e32 v64, 0x90, v146
	v_lshl_add_u64 v[68:69], v[68:69], 0, v[144:145]
	v_mad_i64_i32 v[66:67], s[18:19], v64, s41, v[148:149]
	global_store_dwordx4 v[68:69], v[56:59], off
	v_lshl_add_u64 v[66:67], v[66:67], 0, v[144:145]
	v_ashrrev_i32_e32 v65, 31, v64
	s_waitcnt vmcnt(0)
	v_lshlrev_b32_e32 v56, 16, v60
	v_and_b32_e32 v57, 0xffff0000, v60
	v_lshlrev_b32_e32 v58, 16, v61
	v_and_b32_e32 v59, 0xffff0000, v61
	v_lshlrev_b32_e32 v60, 16, v62
	v_and_b32_e32 v61, 0xffff0000, v62
	v_lshlrev_b32_e32 v62, 16, v63
	v_and_b32_e32 v63, 0xffff0000, v63
	v_mul_f32_e32 v52, v52, v56
	v_mul_f32_e32 v53, v53, v57
	v_mul_f32_e32 v54, v54, v58
	v_mul_f32_e32 v55, v55, v59
	v_mul_f32_e32 v47, v47, v63
	v_mul_f32_e32 v56, v44, v60
	v_mul_f32_e32 v57, v45, v61
	v_mul_f32_e32 v58, v46, v62
	v_cvt_pk_bf16_f32 v44, v52, v53
	v_cvt_pk_bf16_f32 v45, v54, v55
	v_cvt_pk_bf16_f32 v46, v56, v57
	v_cvt_pk_bf16_f32 v47, v58, v47
	global_load_dwordx4 v[52:55], v[66:67], off offset:3072
	s_nop 0
	global_store_dwordx4 v[68:69], v[44:47], off offset:256
	s_waitcnt vmcnt(0)
	s_nop 0
	v_lshlrev_b32_e32 v44, 16, v52
	v_and_b32_e32 v45, 0xffff0000, v52
	v_lshlrev_b32_e32 v46, 16, v53
	v_and_b32_e32 v47, 0xffff0000, v53
	v_lshlrev_b32_e32 v52, 16, v54
	v_and_b32_e32 v53, 0xffff0000, v54
	v_lshlrev_b32_e32 v54, 16, v55
	v_and_b32_e32 v55, 0xffff0000, v55
	v_mul_f32_e32 v44, v48, v44
	v_mul_f32_e32 v45, v49, v45
	v_mul_f32_e32 v46, v50, v46
	v_mul_f32_e32 v47, v51, v47
	v_mul_f32_e32 v43, v43, v55
	v_mul_f32_e32 v48, v40, v52
	v_mul_f32_e32 v49, v41, v53
	v_mul_f32_e32 v50, v42, v54
	v_cvt_pk_bf16_f32 v40, v44, v45
	v_cvt_pk_bf16_f32 v41, v46, v47
	v_cvt_pk_bf16_f32 v42, v48, v49
	v_cvt_pk_bf16_f32 v43, v50, v43
	global_load_dwordx4 v[44:47], v[66:67], off offset:3328
	v_lshlrev_b64 v[52:53], 11, v[64:65]
	v_lshl_add_u64 v[52:53], s[0:1], 0, v[52:53]
	v_add_u32_e32 v48, 0xa0, v146
	v_lshl_add_u64 v[52:53], v[52:53], 0, v[144:145]
	v_mad_i64_i32 v[50:51], s[18:19], v48, s41, v[148:149]
	global_store_dwordx4 v[52:53], v[40:43], off
	v_lshl_add_u64 v[50:51], v[50:51], 0, v[144:145]
	v_ashrrev_i32_e32 v49, 31, v48
	s_waitcnt vmcnt(0)
	v_lshlrev_b32_e32 v40, 16, v44
	v_and_b32_e32 v41, 0xffff0000, v44
	v_lshlrev_b32_e32 v42, 16, v45
	v_and_b32_e32 v43, 0xffff0000, v45
	v_lshlrev_b32_e32 v44, 16, v46
	v_and_b32_e32 v45, 0xffff0000, v46
	v_lshlrev_b32_e32 v46, 16, v47
	v_and_b32_e32 v47, 0xffff0000, v47
	v_mul_f32_e32 v36, v36, v40
	v_mul_f32_e32 v37, v37, v41
	v_mul_f32_e32 v38, v38, v42
	v_mul_f32_e32 v39, v39, v43
	v_mul_f32_e32 v31, v31, v47
	v_mul_f32_e32 v40, v28, v44
	v_mul_f32_e32 v41, v29, v45
	v_mul_f32_e32 v42, v30, v46
	v_cvt_pk_bf16_f32 v28, v36, v37
	v_cvt_pk_bf16_f32 v29, v38, v39
	v_cvt_pk_bf16_f32 v30, v40, v41
	v_cvt_pk_bf16_f32 v31, v42, v31
	global_load_dwordx4 v[36:39], v[50:51], off offset:3072
	s_nop 0
	global_store_dwordx4 v[52:53], v[28:31], off offset:256
	s_waitcnt vmcnt(0)
; __device__ __forceinline__ unsigned cvt_pk_bf16(float lo, float hi) { unsigned r; asm volatile("v_cvt_pk_bf16_f32 %0, %1, %2" : "=v"(r) : "v"(lo), "v"(hi)); return r; }
; __device__ __forceinline__ float bf_lo(unsigned u) { return __uint_as_float(u << 16); }
; __device__ __forceinline__ float bf_hi(unsigned u) { return __uint_as_float(u & 0xffff0000u); }
; #define PG8_WAIT_V(n) asm volatile("s_waitcnt vmcnt(" #n ")" ::: "memory")
; #define PG8_BAR __builtin_amdgcn_s_barrier()
;     __device__ __forceinline__ void operator()(const f32x4 (&acc)[2][2][4][2], const Unit& u, int wr, int wc, int fr, int fq) const {
;     ...
;             for (int m = 0; m < 4; ++m) { const size_t r = (size_t)(row0 + ai * HALF + m * 16); bf16_t* rowp = O + r * ldc + col0; const bf16_t* gp = G + r * ldg + col0;
; #pragma unroll
;                 for (int bj = 0; bj < 2; ++bj) { const u32x4 gw = *(const u32x4*)(gp + bj * HALF);
;                     f32x4 v0 = acc[ai][bj][m][0], v1 = acc[ai][bj][m][1];
;                     v0[0] *= bf_lo(gw.x); v0[1] *= bf_hi(gw.x); v0[2] *= bf_lo(gw.y); v0[3] *= bf_hi(gw.y);
;                     v1[0] *= bf_lo(gw.z); v1[1] *= bf_hi(gw.z); v1[2] *= bf_lo(gw.w); v1[3] *= bf_hi(gw.w);
;                     if (ACCUM) { const u32x4 pw = *(const u32x4*)(rowp + bj * HALF);
;                         v0[0] += bf_lo(pw.x); v0[1] += bf_hi(pw.x); v0[2] += bf_lo(pw.y); v0[3] += bf_hi(pw.y);
;                         v1[0] += bf_lo(pw.z); v1[1] += bf_hi(pw.z); v1[2] += bf_lo(pw.w); v1[3] += bf_hi(pw.w); }
;                     u32x4 w; w.x = cvt_pk_bf16(v0[0], v0[1]); w.y = cvt_pk_bf16(v0[2], v0[3]); w.z = cvt_pk_bf16(v1[0], v1[1]); w.w = cvt_pk_bf16(v1[2], v1[3]);
;                     *(u32x4*)(rowp + bj * HALF) = w; } }
; template <class Epi, class Sched>
; __device__ __forceinline__ void gemm_phase(PG8_LAS unsigned char* lds, const Gemm g, const Sched& S, const Epi& E) {
;     ...
;         if (!has_next) break;
; #pragma unroll
;         for (int a = 0; a < 2; ++a)
; #pragma unroll
;             for (int b = 0; b < 2; ++b)
; #pragma unroll
;                 for (int m = 0; m < 4; ++m)
; #pragma unroll
;                     for (int n = 0; n < 2; ++n) acc[a][b][m][n] = (f32x4){0.f, 0.f, 0.f, 0.f};
;         cur = nxt; cA = nA; cB = nB; ++ui;
;     }
;     PG8_WAIT_V(0);
;     if (wr == 0) PG8_BAR;
	s_nop 0
	v_lshlrev_b32_e32 v28, 16, v36
	v_and_b32_e32 v29, 0xffff0000, v36
	v_lshlrev_b32_e32 v30, 16, v37
	v_and_b32_e32 v31, 0xffff0000, v37
	v_lshlrev_b32_e32 v36, 16, v38
	v_and_b32_e32 v37, 0xffff0000, v38
	v_lshlrev_b32_e32 v38, 16, v39
	v_and_b32_e32 v39, 0xffff0000, v39
	v_mul_f32_e32 v28, v32, v28
	v_mul_f32_e32 v29, v33, v29
	v_mul_f32_e32 v30, v34, v30
	v_mul_f32_e32 v31, v35, v31
	v_mul_f32_e32 v27, v27, v39
	v_mul_f32_e32 v32, v24, v36
	v_mul_f32_e32 v33, v25, v37
	v_mul_f32_e32 v34, v26, v38
	v_cvt_pk_bf16_f32 v24, v28, v29
	v_cvt_pk_bf16_f32 v25, v30, v31
	v_cvt_pk_bf16_f32 v26, v32, v33
	v_cvt_pk_bf16_f32 v27, v34, v27
	global_load_dwordx4 v[28:31], v[50:51], off offset:3328
	v_lshlrev_b64 v[36:37], 11, v[48:49]
	v_lshl_add_u64 v[36:37], s[0:1], 0, v[36:37]
	v_add_u32_e32 v32, 0xb0, v146
	v_lshl_add_u64 v[36:37], v[36:37], 0, v[144:145]
	v_mad_i64_i32 v[34:35], s[18:19], v32, s41, v[148:149]
	global_store_dwordx4 v[36:37], v[24:27], off
	v_lshl_add_u64 v[34:35], v[34:35], 0, v[144:145]
	v_ashrrev_i32_e32 v33, 31, v32
	s_mov_b64 s[18:19], s[12:13]
	s_waitcnt vmcnt(0)
	v_lshlrev_b32_e32 v24, 16, v28
	v_and_b32_e32 v25, 0xffff0000, v28
	v_lshlrev_b32_e32 v26, 16, v29
	v_and_b32_e32 v27, 0xffff0000, v29
	v_lshlrev_b32_e32 v28, 16, v30
	v_and_b32_e32 v29, 0xffff0000, v30
	v_lshlrev_b32_e32 v30, 16, v31
	v_and_b32_e32 v31, 0xffff0000, v31
	v_mul_f32_e32 v20, v20, v24
	v_mul_f32_e32 v21, v21, v25
	v_mul_f32_e32 v22, v22, v26
	v_mul_f32_e32 v23, v23, v27
	v_mul_f32_e32 v15, v15, v31
	v_mul_f32_e32 v24, v12, v28
	v_mul_f32_e32 v25, v13, v29
	v_mul_f32_e32 v26, v14, v30
	v_cvt_pk_bf16_f32 v12, v20, v21
	v_cvt_pk_bf16_f32 v13, v22, v23
	v_cvt_pk_bf16_f32 v14, v24, v25
	v_cvt_pk_bf16_f32 v15, v26, v15
	global_load_dwordx4 v[20:23], v[34:35], off offset:3072
	s_nop 0
	global_store_dwordx4 v[36:37], v[12:15], off offset:256
	s_waitcnt vmcnt(0)
	s_nop 0
	v_lshlrev_b32_e32 v12, 16, v20
	v_and_b32_e32 v13, 0xffff0000, v20
	v_lshlrev_b32_e32 v14, 16, v21
	v_and_b32_e32 v15, 0xffff0000, v21
	v_lshlrev_b32_e32 v20, 16, v22
	v_and_b32_e32 v21, 0xffff0000, v22
	v_lshlrev_b32_e32 v22, 16, v23
	v_and_b32_e32 v23, 0xffff0000, v23
	v_mul_f32_e32 v12, v16, v12
	v_mul_f32_e32 v13, v17, v13
	v_mul_f32_e32 v14, v18, v14
	v_mul_f32_e32 v15, v19, v15
	v_mul_f32_e32 v11, v11, v23
	v_mul_f32_e32 v16, v8, v20
	v_mul_f32_e32 v17, v9, v21
	v_mul_f32_e32 v18, v10, v22
	v_cvt_pk_bf16_f32 v8, v12, v13
	v_cvt_pk_bf16_f32 v9, v14, v15
	v_cvt_pk_bf16_f32 v10, v16, v17
	v_cvt_pk_bf16_f32 v11, v18, v11
	global_load_dwordx4 v[12:15], v[34:35], off offset:3328
	v_lshlrev_b64 v[16:17], 11, v[32:33]
	v_lshl_add_u64 v[16:17], s[0:1], 0, v[16:17]
	v_lshl_add_u64 v[16:17], v[16:17], 0, v[144:145]
	global_store_dwordx4 v[16:17], v[8:11], off
	s_waitcnt vmcnt(0)
	s_nop 0
	v_lshlrev_b32_e32 v8, 16, v12
	v_and_b32_e32 v9, 0xffff0000, v12
	v_lshlrev_b32_e32 v10, 16, v13
	v_and_b32_e32 v11, 0xffff0000, v13
	v_lshlrev_b32_e32 v12, 16, v14
	v_and_b32_e32 v13, 0xffff0000, v14
	v_lshlrev_b32_e32 v14, 16, v15
	v_and_b32_e32 v15, 0xffff0000, v15
	v_mul_f32_e32 v3, v3, v15
	v_mul_f32_e32 v4, v4, v8
	v_mul_f32_e32 v5, v5, v9
	v_mul_f32_e32 v6, v6, v10
	v_mul_f32_e32 v7, v7, v11
	v_mul_f32_e32 v8, v0, v12
	v_mul_f32_e32 v9, v1, v13
	v_mul_f32_e32 v10, v2, v14
	v_cvt_pk_bf16_f32 v0, v4, v5
	v_cvt_pk_bf16_f32 v1, v6, v7
	v_cvt_pk_bf16_f32 v2, v8, v9
	v_cvt_pk_bf16_f32 v3, v10, v3
	global_store_dwordx4 v[16:17], v[0:3], off offset:256
	s_cbranch_vccz .LBB0_984
	s_waitcnt vmcnt(0)
	s_cmpk_gt_u32 s25, 0xff
	s_cbranch_scc1 .LBB0_995
	s_barrier

; #define PG8_STAGE(bufoff, gbase, voff) do { _Pragma("unroll") for (int _i = 0; _i < 2; ++_i) \
;         __builtin_amdgcn_global_load_lds((const unsigned*)((const char*)(gbase) + (voff)[_i]), (PG8_LAS unsigned*)(lds + (bufoff) + ldsw + _i * 8192), 16, 0, 0); } while (0)
; #define PG8_LDA(dst, b, h) do { _Pragma("unroll") for (int m = 0; m < 4; ++m) _Pragma("unroll") for (int k = 0; k < 2; ++k) dst[m][k] = *(const PG8_LAS bf16x8*)(lds + PG8_SA(b, h) + aoff + m * 2048 + k * 1024); } while (0)
; #define PG8_LDB(dst, b, h) do { _Pragma("unroll") for (int n = 0; n < 2; ++n) _Pragma("unroll") for (int k = 0; k < 2; ++k) dst[n][k] = *(const PG8_LAS bf16x8*)(lds + PG8_SB(b, h) + boff + n * 2048 + k * 1024); } while (0)
; #define PG8_MMA(ai, bj, At, Bt) do { __builtin_amdgcn_s_setprio(1); _Pragma("unroll") for (int m = 0; m < 4; ++m) _Pragma("unroll") for (int n = 0; n < 2; ++n) _Pragma("unroll") for (int k = 0; k < 2; ++k) \
;         acc[ai][bj][m][n] = __builtin_amdgcn_mfma_f32_16x16x32_bf16(Bt[n][k], At[m][k], acc[ai][bj][m][n], 0, 0, 0); __builtin_amdgcn_s_setprio(0); } while (0)
; #define PG8_WAIT_V(n) asm volatile("s_waitcnt vmcnt(" #n ")" ::: "memory")
; #define PG8_WAIT_L(n) asm volatile("s_waitcnt lgkmcnt(" #n ")" ::: "memory")
; #define PG8_BAR __builtin_amdgcn_s_barrier()
; #define PG8_SCHED __builtin_amdgcn_sched_barrier(0)
; template <class Epi, class Sched>
; __device__ __forceinline__ void gemm_phase(PG8_LAS unsigned char* lds, const Gemm g, const Sched& S, const Epi& E) {
;     ...
;             PG8_LDB(B0, 0, 0); PG8_SCHED; PG8_LDA(At, 0, 0); PG8_STAGE(PG8_SA(1, 1), a1 + hstep, voffA);
;             PG8_WAIT_L(8); PG8_BAR; PG8_WAIT_L(0); PG8_MMA(0, 0, At, B0); PG8_BAR; PG8_SCHED;
;             PG8_LDB(B1, 0, 1); PG8_STAGE(PG8_SB(0, 0), b2, voffB);
;             PG8_BAR; PG8_WAIT_L(0); PG8_MMA(0, 1, At, B1); PG8_BAR;
;             PG8_LDA(At, 0, 1); PG8_STAGE(PG8_SA(0, 0), a2, voffA);
;             PG8_BAR; PG8_WAIT_L(0); PG8_MMA(1, 0, At, B0); PG8_BAR; PG8_SCHED;
;             PG8_STAGE(PG8_SB(0, 1), b2 + hstep, voffB);
;             PG8_WAIT_V(6); PG8_BAR; PG8_MMA(1, 1, At, B1); PG8_BAR;
.LBB0_1011:
	ds_read_b128 v[144:147], v153
	ds_read_b128 v[156:159], v153 offset:1024
	ds_read_b128 v[160:163], v153 offset:2048
	ds_read_b128 v[164:167], v153 offset:3072
	s_add_u32 s20, s18, 0xfffc0080
	s_addc_u32 s21, s19, -1
	s_cmp_eq_u32 s47, 12
	s_cselect_b32 s23, s11, s21
	s_cselect_b32 s22, s43, s20
	s_cselect_b32 s21, s9, s46
	s_cselect_b32 s20, s44, s45
	v_lshl_add_u64 v[148:149], s[18:19], 0, v[136:137]
	s_add_i32 m0, s17, 0xc000
	ds_read_b128 v[168:171], v154
	ds_read_b128 v[172:175], v154 offset:1024
	ds_read_b128 v[182:185], v154 offset:2048
	ds_read_b128 v[190:193], v154 offset:3072
	ds_read_b128 v[194:197], v154 offset:4096
	ds_read_b128 v[198:201], v154 offset:5120
	ds_read_b128 v[202:205], v154 offset:6144
	ds_read_b128 v[206:209], v154 offset:7168
	global_load_lds_dwordx4 v[148:149], off
	v_lshl_add_u64 v[148:149], s[18:19], 0, v[138:139]
	s_add_i32 m0, s17, 0xe000
	s_nop 0
	global_load_lds_dwordx4 v[148:149], off
	s_waitcnt lgkmcnt(8)
	s_barrier
	s_waitcnt lgkmcnt(0)
	v_mfma_f32_16x16x32_bf16 v[124:127], v[144:147], v[168:171], v[124:127]
	v_mfma_f32_16x16x32_bf16 v[120:123], v[160:163], v[168:171], v[120:123]
	v_mfma_f32_16x16x32_bf16 v[108:111], v[144:147], v[182:185], v[108:111]
	v_mfma_f32_16x16x32_bf16 v[104:107], v[160:163], v[182:185], v[104:107]
	v_mfma_f32_16x16x32_bf16 v[92:95], v[144:147], v[194:197], v[92:95]
	v_mfma_f32_16x16x32_bf16 v[88:91], v[160:163], v[194:197], v[88:91]
	v_mfma_f32_16x16x32_bf16 v[76:79], v[144:147], v[202:205], v[76:79]
	v_mfma_f32_16x16x32_bf16 v[72:75], v[160:163], v[202:205], v[72:75]
	v_mfma_f32_16x16x32_bf16 v[124:127], v[156:159], v[172:175], v[124:127]
	v_mfma_f32_16x16x32_bf16 v[120:123], v[164:167], v[172:175], v[120:123]
	v_mfma_f32_16x16x32_bf16 v[108:111], v[156:159], v[190:193], v[108:111]
	v_mfma_f32_16x16x32_bf16 v[104:107], v[164:167], v[190:193], v[104:107]
	v_mfma_f32_16x16x32_bf16 v[92:95], v[156:159], v[198:201], v[92:95]
	v_mfma_f32_16x16x32_bf16 v[88:91], v[164:167], v[198:201], v[88:91]
	v_mfma_f32_16x16x32_bf16 v[76:79], v[156:159], v[206:209], v[76:79]
	v_mfma_f32_16x16x32_bf16 v[72:75], v[164:167], v[206:209], v[72:75]
	s_barrier
	s_add_i32 s48, s39, s29
	v_lshl_add_u64 v[148:149], s[20:21], 0, v[130:131]
	s_mov_b32 m0, s48
	ds_read_b128 v[210:213], v155
	ds_read_b128 v[214:217], v155 offset:1024
	ds_read_b128 v[218:221], v155 offset:2048
	ds_read_b128 v[222:225], v155 offset:3072
	global_load_lds_dwordx4 v[148:149], off
	v_lshl_add_u64 v[186:187], s[20:21], 0, v[134:135]
	s_add_i32 m0, s48, 0x2000
	s_nop 0
	global_load_lds_dwordx4 v[186:187], off
	s_barrier
	s_waitcnt lgkmcnt(0)
	v_mfma_f32_16x16x32_bf16 v[116:119], v[210:213], v[168:171], v[116:119]
	v_mfma_f32_16x16x32_bf16 v[112:115], v[218:221], v[168:171], v[112:115]
	v_mfma_f32_16x16x32_bf16 v[100:103], v[210:213], v[182:185], v[100:103]
	v_mfma_f32_16x16x32_bf16 v[96:99], v[218:221], v[182:185], v[96:99]
	v_mfma_f32_16x16x32_bf16 v[84:87], v[210:213], v[194:197], v[84:87]
	v_mfma_f32_16x16x32_bf16 v[80:83], v[218:221], v[194:197], v[80:83]
	v_mfma_f32_16x16x32_bf16 v[68:71], v[210:213], v[202:205], v[68:71]
	v_mfma_f32_16x16x32_bf16 v[64:67], v[218:221], v[202:205], v[64:67]
	v_mfma_f32_16x16x32_bf16 v[116:119], v[214:217], v[172:175], v[116:119]
	v_mfma_f32_16x16x32_bf16 v[112:115], v[222:225], v[172:175], v[112:115]
	v_mfma_f32_16x16x32_bf16 v[100:103], v[214:217], v[190:193], v[100:103]
	v_mfma_f32_16x16x32_bf16 v[96:99], v[222:225], v[190:193], v[96:99]
	v_mfma_f32_16x16x32_bf16 v[84:87], v[214:217], v[198:201], v[84:87]
	v_mfma_f32_16x16x32_bf16 v[80:83], v[222:225], v[198:201], v[80:83]
	v_mfma_f32_16x16x32_bf16 v[68:71], v[214:217], v[206:209], v[68:71]
	v_mfma_f32_16x16x32_bf16 v[64:67], v[222:225], v[206:209], v[64:67]
	s_mov_b32 m0, s17
	v_lshl_add_u64 v[226:227], s[22:23], 0, v[128:129]
	s_barrier
	ds_read_b128 v[168:171], v154 offset:16384
	ds_read_b128 v[172:175], v154 offset:17408
	ds_read_b128 v[182:185], v154 offset:18432
	ds_read_b128 v[190:193], v154 offset:19456
	ds_read_b128 v[194:197], v154 offset:20480
	ds_read_b128 v[198:201], v154 offset:21504
	ds_read_b128 v[202:205], v154 offset:22528
	ds_read_b128 v[206:209], v154 offset:23552
	global_load_lds_dwordx4 v[226:227], off
	v_lshl_add_u64 v[228:229], s[22:23], 0, v[132:133]
	s_mov_b32 m0, s30
	s_nop 0
	global_load_lds_dwordx4 v[228:229], off
	s_barrier
	s_waitcnt lgkmcnt(0)
	v_mfma_f32_16x16x32_bf16 v[60:63], v[144:147], v[168:171], v[60:63]
	v_mfma_f32_16x16x32_bf16 v[56:59], v[160:163], v[168:171], v[56:59]
	v_mfma_f32_16x16x32_bf16 v[44:47], v[144:147], v[182:185], v[44:47]
	v_mfma_f32_16x16x32_bf16 v[40:43], v[160:163], v[182:185], v[40:43]
	v_mfma_f32_16x16x32_bf16 v[28:31], v[144:147], v[194:197], v[28:31]
	v_mfma_f32_16x16x32_bf16 v[24:27], v[160:163], v[194:197], v[24:27]
	v_mfma_f32_16x16x32_bf16 v[12:15], v[144:147], v[202:205], v[12:15]
	v_mfma_f32_16x16x32_bf16 v[8:11], v[160:163], v[202:205], v[8:11]
	v_mfma_f32_16x16x32_bf16 v[60:63], v[156:159], v[172:175], v[60:63]
	v_mfma_f32_16x16x32_bf16 v[56:59], v[164:167], v[172:175], v[56:59]
	v_mfma_f32_16x16x32_bf16 v[44:47], v[156:159], v[190:193], v[44:47]
	v_mfma_f32_16x16x32_bf16 v[40:43], v[164:167], v[190:193], v[40:43]
	v_mfma_f32_16x16x32_bf16 v[28:31], v[156:159], v[198:201], v[28:31]
	v_mfma_f32_16x16x32_bf16 v[24:27], v[164:167], v[198:201], v[24:27]
	v_mfma_f32_16x16x32_bf16 v[12:15], v[156:159], v[206:209], v[12:15]
	v_mfma_f32_16x16x32_bf16 v[8:11], v[164:167], v[206:209], v[8:11]
	s_barrier
; #define PG8_STAGE(bufoff, gbase, voff) do { _Pragma("unroll") for (int _i = 0; _i < 2; ++_i) \
;         __builtin_amdgcn_global_load_lds((const unsigned*)((const char*)(gbase) + (voff)[_i]), (PG8_LAS unsigned*)(lds + (bufoff) + ldsw + _i * 8192), 16, 0, 0); } while (0)
; #define PG8_LDA(dst, b, h) do { _Pragma("unroll") for (int m = 0; m < 4; ++m) _Pragma("unroll") for (int k = 0; k < 2; ++k) dst[m][k] = *(const PG8_LAS bf16x8*)(lds + PG8_SA(b, h) + aoff + m * 2048 + k * 1024); } while (0)
; #define PG8_LDB(dst, b, h) do { _Pragma("unroll") for (int n = 0; n < 2; ++n) _Pragma("unroll") for (int k = 0; k < 2; ++k) dst[n][k] = *(const PG8_LAS bf16x8*)(lds + PG8_SB(b, h) + boff + n * 2048 + k * 1024); } while (0)
; #define PG8_MMA(ai, bj, At, Bt) do { __builtin_amdgcn_s_setprio(1); _Pragma("unroll") for (int m = 0; m < 4; ++m) _Pragma("unroll") for (int n = 0; n < 2; ++n) _Pragma("unroll") for (int k = 0; k < 2; ++k) \
;         acc[ai][bj][m][n] = __builtin_amdgcn_mfma_f32_16x16x32_bf16(Bt[n][k], At[m][k], acc[ai][bj][m][n], 0, 0, 0); __builtin_amdgcn_s_setprio(0); } while (0)
; #define PG8_WAIT_V(n) asm volatile("s_waitcnt vmcnt(" #n ")" ::: "memory")
; #define PG8_WAIT_L(n) asm volatile("s_waitcnt lgkmcnt(" #n ")" ::: "memory")
; #define PG8_BAR __builtin_amdgcn_s_barrier()
; #define PG8_SCHED __builtin_amdgcn_sched_barrier(0)
; template <class Epi, class Sched>
; __device__ __forceinline__ void gemm_phase(PG8_LAS unsigned char* lds, const Gemm g, const Sched& S, const Epi& E) {
;     ...
;             PG8_STAGE(PG8_SB(0, 1), b2 + hstep, voffB);
;             PG8_WAIT_V(6); PG8_BAR; PG8_MMA(1, 1, At, B1); PG8_BAR;
;             PG8_LDB(B0, 1, 0); PG8_SCHED; PG8_LDA(At, 1, 0); PG8_STAGE(PG8_SA(0, 1), a2 + hstep, voffA);
;             PG8_WAIT_L(8); PG8_BAR; PG8_WAIT_L(0); PG8_MMA(0, 0, At, B0); PG8_BAR; PG8_SCHED;
;             PG8_LDB(B1, 1, 1); PG8_STAGE(PG8_SB(1, 0), b3, voffB);
;             PG8_BAR; PG8_WAIT_L(0); PG8_MMA(0, 1, At, B1); PG8_BAR;
;             PG8_LDA(At, 1, 1); PG8_STAGE(PG8_SA(1, 0), a3, voffA);
;             PG8_BAR; PG8_WAIT_L(0); PG8_MMA(1, 0, At, B0); PG8_BAR; PG8_SCHED;
	s_add_u32 s48, s20, 0x40000
	s_addc_u32 s49, s21, 0
	s_add_i32 s50, s40, s29
	v_lshl_add_u64 v[144:145], s[48:49], 0, v[130:131]
	s_mov_b32 m0, s50
	s_nop 0
	global_load_lds_dwordx4 v[144:145], off
	v_lshl_add_u64 v[144:145], s[48:49], 0, v[134:135]
	s_add_i32 m0, s50, 0x2000
	s_nop 0
	global_load_lds_dwordx4 v[144:145], off
	s_waitcnt vmcnt(6)
	s_barrier
	v_mfma_f32_16x16x32_bf16 v[52:55], v[210:213], v[168:171], v[52:55]
	v_mfma_f32_16x16x32_bf16 v[48:51], v[218:221], v[168:171], v[48:51]
	v_mfma_f32_16x16x32_bf16 v[36:39], v[210:213], v[182:185], v[36:39]
	v_mfma_f32_16x16x32_bf16 v[32:35], v[218:221], v[182:185], v[32:35]
	v_mfma_f32_16x16x32_bf16 v[20:23], v[210:213], v[194:197], v[20:23]
	v_mfma_f32_16x16x32_bf16 v[16:19], v[218:221], v[194:197], v[16:19]
	v_mfma_f32_16x16x32_bf16 v[4:7], v[210:213], v[202:205], v[4:7]
	v_mfma_f32_16x16x32_bf16 v[0:3], v[218:221], v[202:205], v[0:3]
	v_mfma_f32_16x16x32_bf16 v[52:55], v[214:217], v[172:175], v[52:55]
	v_mfma_f32_16x16x32_bf16 v[48:51], v[222:225], v[172:175], v[48:51]
	v_mfma_f32_16x16x32_bf16 v[36:39], v[214:217], v[190:193], v[36:39]
	v_mfma_f32_16x16x32_bf16 v[32:35], v[222:225], v[190:193], v[32:35]
	v_mfma_f32_16x16x32_bf16 v[20:23], v[214:217], v[198:201], v[20:23]
	v_mfma_f32_16x16x32_bf16 v[16:19], v[222:225], v[198:201], v[16:19]
	v_mfma_f32_16x16x32_bf16 v[4:7], v[214:217], v[206:209], v[4:7]
	v_mfma_f32_16x16x32_bf16 v[0:3], v[222:225], v[206:209], v[0:3]
	s_add_i32 s48, 0, 0x18000
	v_add_u32_e32 v164, s48, v151
	s_barrier
	ds_read_b128 v[144:147], v164
	ds_read_b128 v[156:159], v164 offset:1024
	ds_read_b128 v[160:163], v164 offset:2048
	ds_read_b128 v[164:167], v164 offset:3072
	s_add_u32 s22, s22, 0x40000
	s_addc_u32 s23, s23, 0
	s_mov_b32 m0, s31
	v_lshl_add_u64 v[210:211], s[22:23], 0, v[128:129]
	ds_read_b128 v[168:171], v154 offset:32768
	ds_read_b128 v[172:175], v154 offset:33792
	ds_read_b128 v[182:185], v154 offset:34816
	ds_read_b128 v[190:193], v154 offset:35840
	ds_read_b128 v[194:197], v154 offset:36864
	ds_read_b128 v[198:201], v154 offset:37888
	ds_read_b128 v[202:205], v154 offset:38912
	ds_read_b128 v[206:209], v154 offset:39936
	global_load_lds_dwordx4 v[210:211], off
	v_lshl_add_u64 v[210:211], s[22:23], 0, v[132:133]
	s_mov_b32 m0, s34
	s_nop 0
	global_load_lds_dwordx4 v[210:211], off
	s_waitcnt lgkmcnt(8)
	s_barrier
	s_waitcnt lgkmcnt(0)
	v_mfma_f32_16x16x32_bf16 v[124:127], v[144:147], v[168:171], v[124:127]
	v_mfma_f32_16x16x32_bf16 v[120:123], v[160:163], v[168:171], v[120:123]
	v_mfma_f32_16x16x32_bf16 v[108:111], v[144:147], v[182:185], v[108:111]
	v_mfma_f32_16x16x32_bf16 v[104:107], v[160:163], v[182:185], v[104:107]
	v_mfma_f32_16x16x32_bf16 v[92:95], v[144:147], v[194:197], v[92:95]
	v_mfma_f32_16x16x32_bf16 v[88:91], v[160:163], v[194:197], v[88:91]
	v_mfma_f32_16x16x32_bf16 v[76:79], v[144:147], v[202:205], v[76:79]
	v_mfma_f32_16x16x32_bf16 v[72:75], v[160:163], v[202:205], v[72:75]
	v_mfma_f32_16x16x32_bf16 v[124:127], v[156:159], v[172:175], v[124:127]
	v_mfma_f32_16x16x32_bf16 v[120:123], v[164:167], v[172:175], v[120:123]
	v_mfma_f32_16x16x32_bf16 v[108:111], v[156:159], v[190:193], v[108:111]
	v_mfma_f32_16x16x32_bf16 v[104:107], v[164:167], v[190:193], v[104:107]
	v_mfma_f32_16x16x32_bf16 v[92:95], v[156:159], v[198:201], v[92:95]
	v_mfma_f32_16x16x32_bf16 v[88:91], v[164:167], v[198:201], v[88:91]
	v_mfma_f32_16x16x32_bf16 v[76:79], v[156:159], v[206:209], v[76:79]
	v_mfma_f32_16x16x32_bf16 v[72:75], v[164:167], v[206:209], v[72:75]
	s_barrier
	s_add_i32 s22, 0, 0x1c000
	s_add_i32 s23, s48, s29
	v_add_u32_e32 v179, s22, v151
	v_lshl_add_u64 v[148:149], v[148:149], 0, s[6:7]
	s_mov_b32 m0, s23
	ds_read_b128 v[210:213], v179
	ds_read_b128 v[214:217], v179 offset:1024
	ds_read_b128 v[218:221], v179 offset:2048
	ds_read_b128 v[222:225], v179 offset:3072
	global_load_lds_dwordx4 v[148:149], off
	v_lshl_add_u64 v[148:149], v[186:187], 0, s[6:7]
	s_add_i32 m0, s23, 0x2000
	s_nop 0
	global_load_lds_dwordx4 v[148:149], off
	s_barrier
	s_waitcnt lgkmcnt(0)
	v_mfma_f32_16x16x32_bf16 v[116:119], v[210:213], v[168:171], v[116:119]
	v_mfma_f32_16x16x32_bf16 v[112:115], v[218:221], v[168:171], v[112:115]
	v_mfma_f32_16x16x32_bf16 v[100:103], v[210:213], v[182:185], v[100:103]
	v_mfma_f32_16x16x32_bf16 v[96:99], v[218:221], v[182:185], v[96:99]
	v_mfma_f32_16x16x32_bf16 v[84:87], v[210:213], v[194:197], v[84:87]
	v_mfma_f32_16x16x32_bf16 v[80:83], v[218:221], v[194:197], v[80:83]
	v_mfma_f32_16x16x32_bf16 v[68:71], v[210:213], v[202:205], v[68:71]
	v_mfma_f32_16x16x32_bf16 v[64:67], v[218:221], v[202:205], v[64:67]
	v_mfma_f32_16x16x32_bf16 v[116:119], v[214:217], v[172:175], v[116:119]
	v_mfma_f32_16x16x32_bf16 v[112:115], v[222:225], v[172:175], v[112:115]
	v_mfma_f32_16x16x32_bf16 v[100:103], v[214:217], v[190:193], v[100:103]
	v_mfma_f32_16x16x32_bf16 v[96:99], v[222:225], v[190:193], v[96:99]
	v_mfma_f32_16x16x32_bf16 v[84:87], v[214:217], v[198:201], v[84:87]
	v_mfma_f32_16x16x32_bf16 v[80:83], v[222:225], v[198:201], v[80:83]
	v_mfma_f32_16x16x32_bf16 v[68:71], v[214:217], v[206:209], v[68:71]
	v_mfma_f32_16x16x32_bf16 v[64:67], v[222:225], v[206:209], v[64:67]
	s_mov_b32 m0, s36
	v_lshl_add_u64 v[148:149], v[226:227], 0, s[6:7]
	s_barrier
	ds_read_b128 v[168:171], v154 offset:49152
	ds_read_b128 v[172:175], v154 offset:50176
	ds_read_b128 v[182:185], v154 offset:51200
	ds_read_b128 v[190:193], v154 offset:52224
	ds_read_b128 v[194:197], v154 offset:53248
	ds_read_b128 v[198:201], v154 offset:54272
	ds_read_b128 v[202:205], v154 offset:55296
	ds_read_b128 v[206:209], v154 offset:56320
	global_load_lds_dwordx4 v[148:149], off
	v_lshl_add_u64 v[148:149], v[228:229], 0, s[6:7]
	s_mov_b32 m0, s37
	s_nop 0
	global_load_lds_dwordx4 v[148:149], off
	s_barrier
; __device__ __forceinline__ unsigned cvt_pk_bf16(float lo, float hi) { unsigned r; asm volatile("v_cvt_pk_bf16_f32 %0, %1, %2" : "=v"(r) : "v"(lo), "v"(hi)); return r; }
; __device__ __forceinline__ float bf_lo(unsigned u) { return __uint_as_float(u << 16); }
; __device__ __forceinline__ float bf_hi(unsigned u) { return __uint_as_float(u & 0xffff0000u); }
; #define PG8_WAIT_V(n) asm volatile("s_waitcnt vmcnt(" #n ")" ::: "memory")
; #define PG8_WAIT_L(n) asm volatile("s_waitcnt lgkmcnt(" #n ")" ::: "memory")
; #define PG8_BAR __builtin_amdgcn_s_barrier()
;     __device__ __forceinline__ void operator()(const f32x4 (&acc)[2][2][4][2], const Unit& u, int wr, int wc, int fr, int fq) const {
;         const int row0 = u.pm * BM + wr * 64 + fr, col0 = u.pn * BM + wc * 32 + 8 * fq;
; #pragma unroll
;         for (int ai = 0; ai < 2; ++ai)
; #pragma unroll
;             for (int m = 0; m < 4; ++m) { const size_t r = (size_t)(row0 + ai * HALF + m * 16); bf16_t* rowp = O + r * ldc + col0; const bf16_t* gp = G + r * ldg + col0;
; #pragma unroll
;                 for (int bj = 0; bj < 2; ++bj) { const u32x4 gw = *(const u32x4*)(gp + bj * HALF);
;                     f32x4 v0 = acc[ai][bj][m][0], v1 = acc[ai][bj][m][1];
;                     v0[0] *= bf_lo(gw.x); v0[1] *= bf_hi(gw.x); v0[2] *= bf_lo(gw.y); v0[3] *= bf_hi(gw.y);
;                     v1[0] *= bf_lo(gw.z); v1[1] *= bf_hi(gw.z); v1[2] *= bf_lo(gw.w); v1[3] *= bf_hi(gw.w);
;                     if (ACCUM) { const u32x4 pw = *(const u32x4*)(rowp + bj * HALF);
;                         v0[0] += bf_lo(pw.x); v0[1] += bf_hi(pw.x); v0[2] += bf_lo(pw.y); v0[3] += bf_hi(pw.y);
;                         v1[0] += bf_lo(pw.z); v1[1] += bf_hi(pw.z); v1[2] += bf_lo(pw.w); v1[3] += bf_hi(pw.w); }
;                     u32x4 w; w.x = cvt_pk_bf16(v0[0], v0[1]); w.y = cvt_pk_bf16(v0[2], v0[3]); w.z = cvt_pk_bf16(v1[0], v1[1]); w.w = cvt_pk_bf16(v1[2], v1[3]);
;                     *(u32x4*)(rowp + bj * HALF) = w; } }
; template <class Epi, class Sched>
; __device__ __forceinline__ void gemm_phase(PG8_LAS unsigned char* lds, const Gemm g, const Sched& S, const Epi& E) {
;     ...
;             PG8_BAR; PG8_WAIT_L(0); PG8_MMA(1, 0, At, B0); PG8_BAR; PG8_SCHED;
;             PG8_STAGE(PG8_SB(1, 1), b3 + hstep, voffB);
;             PG8_WAIT_V(6); PG8_BAR; PG8_MMA(1, 1, At, B1); PG8_BAR;
	s_waitcnt lgkmcnt(0)
	v_mfma_f32_16x16x32_bf16 v[60:63], v[144:147], v[168:171], v[60:63]
	v_mfma_f32_16x16x32_bf16 v[56:59], v[160:163], v[168:171], v[56:59]
	v_mfma_f32_16x16x32_bf16 v[44:47], v[144:147], v[182:185], v[44:47]
	v_mfma_f32_16x16x32_bf16 v[40:43], v[160:163], v[182:185], v[40:43]
	v_mfma_f32_16x16x32_bf16 v[28:31], v[144:147], v[194:197], v[28:31]
	v_mfma_f32_16x16x32_bf16 v[24:27], v[160:163], v[194:197], v[24:27]
	v_mfma_f32_16x16x32_bf16 v[12:15], v[144:147], v[202:205], v[12:15]
	v_mfma_f32_16x16x32_bf16 v[8:11], v[160:163], v[202:205], v[8:11]
	v_mfma_f32_16x16x32_bf16 v[60:63], v[156:159], v[172:175], v[60:63]
	v_mfma_f32_16x16x32_bf16 v[56:59], v[164:167], v[172:175], v[56:59]
	v_mfma_f32_16x16x32_bf16 v[44:47], v[156:159], v[190:193], v[44:47]
	v_mfma_f32_16x16x32_bf16 v[40:43], v[164:167], v[190:193], v[40:43]
	v_mfma_f32_16x16x32_bf16 v[28:31], v[156:159], v[198:201], v[28:31]
	v_mfma_f32_16x16x32_bf16 v[24:27], v[164:167], v[198:201], v[24:27]
	v_mfma_f32_16x16x32_bf16 v[12:15], v[156:159], v[206:209], v[12:15]
	v_mfma_f32_16x16x32_bf16 v[8:11], v[164:167], v[206:209], v[8:11]
	s_barrier
	s_add_u32 s20, s20, 0x40080
	s_addc_u32 s21, s21, 0
	s_add_i32 s22, s22, s29
	v_lshl_add_u64 v[144:145], s[20:21], 0, v[130:131]
	s_mov_b32 m0, s22
	s_nop 0
	global_load_lds_dwordx4 v[144:145], off
	v_lshl_add_u64 v[144:145], s[20:21], 0, v[134:135]
	s_add_i32 m0, s22, 0x2000
	s_nop 0
	global_load_lds_dwordx4 v[144:145], off
	s_waitcnt vmcnt(6)
	s_barrier
	v_mfma_f32_16x16x32_bf16 v[52:55], v[210:213], v[168:171], v[52:55]
	v_mfma_f32_16x16x32_bf16 v[48:51], v[218:221], v[168:171], v[48:51]
	v_mfma_f32_16x16x32_bf16 v[36:39], v[210:213], v[182:185], v[36:39]
	v_mfma_f32_16x16x32_bf16 v[32:35], v[218:221], v[182:185], v[32:35]
	v_mfma_f32_16x16x32_bf16 v[20:23], v[210:213], v[194:197], v[20:23]
	v_mfma_f32_16x16x32_bf16 v[16:19], v[218:221], v[194:197], v[16:19]
	v_mfma_f32_16x16x32_bf16 v[4:7], v[210:213], v[202:205], v[4:7]
	v_mfma_f32_16x16x32_bf16 v[0:3], v[218:221], v[202:205], v[0:3]
	v_mfma_f32_16x16x32_bf16 v[52:55], v[214:217], v[172:175], v[52:55]
	v_mfma_f32_16x16x32_bf16 v[48:51], v[222:225], v[172:175], v[48:51]
	v_mfma_f32_16x16x32_bf16 v[36:39], v[214:217], v[190:193], v[36:39]
	v_mfma_f32_16x16x32_bf16 v[32:35], v[222:225], v[190:193], v[32:35]
	v_mfma_f32_16x16x32_bf16 v[20:23], v[214:217], v[198:201], v[20:23]
	v_mfma_f32_16x16x32_bf16 v[16:19], v[222:225], v[198:201], v[16:19]
	v_mfma_f32_16x16x32_bf16 v[4:7], v[214:217], v[206:209], v[4:7]
	v_mfma_f32_16x16x32_bf16 v[0:3], v[222:225], v[206:209], v[0:3]
	s_add_i32 s47, s47, 2
	s_add_u32 s18, s18, 0x100
	s_addc_u32 s19, s19, 0
	s_add_u32 s45, s45, 0x100
	s_addc_u32 s46, s46, 0
	s_cmp_gt_u32 s47, 13
	s_barrier
	s_cbranch_scc0 .LBB0_1011
	v_lshl_add_u32 v146, s16, 8, v150
	v_lshl_or_b32 v144, s42, 8, v152
	v_ashrrev_i32_e32 v147, 31, v146
	v_ashrrev_i32_e32 v145, 31, v144
	v_mov_b64_e32 v[148:149], s[4:5]
	v_lshlrev_b64 v[160:161], 11, v[146:147]
	v_lshlrev_b64 v[144:145], 1, v[144:145]
	v_mad_i64_i32 v[156:157], s[18:19], v146, s41, v[148:149]
	v_lshl_add_u64 v[160:161], s[0:1], 0, v[160:161]
	v_lshl_add_u64 v[164:165], v[156:157], 0, v[144:145]
	v_lshl_add_u64 v[166:167], v[160:161], 0, v[144:145]
	global_load_dwordx4 v[156:159], v[164:165], off
	global_load_dwordx4 v[160:163], v[166:167], off
	s_and_b64 vcc, exec, s[2:3]
	s_mov_b32 s42, s8
	s_mov_b32 s16, s10
	s_mov_b64 s[20:21], s[14:15]
	s_waitcnt vmcnt(0)
	v_lshlrev_b32_e32 v147, 16, v156
	v_and_b32_e32 v156, 0xffff0000, v156
	v_lshlrev_b32_e32 v168, 16, v157
	v_and_b32_e32 v157, 0xffff0000, v157
	v_lshlrev_b32_e32 v169, 16, v158
	v_and_b32_e32 v158, 0xffff0000, v158
	v_lshlrev_b32_e32 v170, 16, v159
	v_and_b32_e32 v159, 0xffff0000, v159
	v_lshlrev_b32_e32 v171, 16, v160
	v_and_b32_e32 v160, 0xffff0000, v160
	v_lshlrev_b32_e32 v172, 16, v161
	v_and_b32_e32 v161, 0xffff0000, v161
	v_lshlrev_b32_e32 v173, 16, v162
	v_and_b32_e32 v162, 0xffff0000, v162
	v_lshlrev_b32_e32 v174, 16, v163
	v_and_b32_e32 v163, 0xffff0000, v163
	v_fmac_f32_e32 v171, v124, v147
	v_fmac_f32_e32 v160, v125, v156
	v_fmac_f32_e32 v172, v126, v168
	v_fmac_f32_e32 v161, v127, v157
	v_fmac_f32_e32 v173, v120, v169
	v_fmac_f32_e32 v162, v121, v158
	v_fmac_f32_e32 v174, v122, v170
	v_fmac_f32_e32 v163, v123, v159
	v_cvt_pk_bf16_f32 v120, v171, v160
	v_cvt_pk_bf16_f32 v121, v172, v161
	v_cvt_pk_bf16_f32 v122, v173, v162
	v_cvt_pk_bf16_f32 v123, v174, v163
	global_load_dwordx4 v[124:127], v[164:165], off offset:256
	global_load_dwordx4 v[156:159], v[166:167], off offset:256
	v_or_b32_e32 v160, 16, v146
	global_store_dwordx4 v[166:167], v[120:123], off
	v_mad_i64_i32 v[162:163], s[18:19], v160, s41, v[148:149]
	v_lshl_add_u64 v[162:163], v[162:163], 0, v[144:145]
	s_waitcnt vmcnt(0)
	v_lshlrev_b32_e32 v122, 16, v125
	v_lshlrev_b32_e32 v161, 16, v157
	v_lshlrev_b32_e32 v120, 16, v124
	v_and_b32_e32 v121, 0xffff0000, v124
	v_and_b32_e32 v123, 0xffff0000, v125
	v_lshlrev_b32_e32 v124, 16, v126
	v_and_b32_e32 v125, 0xffff0000, v126
	v_lshlrev_b32_e32 v147, 16, v156
	v_and_b32_e32 v156, 0xffff0000, v156
	v_and_b32_e32 v157, 0xffff0000, v157
	v_lshlrev_b32_e32 v164, 16, v158
	v_and_b32_e32 v158, 0xffff0000, v158
	v_fmac_f32_e32 v161, v118, v122
	v_fmac_f32_e32 v147, v116, v120
	v_fmac_f32_e32 v156, v117, v121
	v_fmac_f32_e32 v157, v119, v123
	v_fmac_f32_e32 v164, v112, v124
	v_fmac_f32_e32 v158, v113, v125
	v_cvt_pk_bf16_f32 v112, v147, v156
	v_cvt_pk_bf16_f32 v113, v161, v157
	v_ashrrev_i32_e32 v161, 31, v160
	v_lshlrev_b64 v[120:121], 11, v[160:161]
	v_lshl_add_u64 v[120:121], s[0:1], 0, v[120:121]
	v_lshlrev_b32_e32 v126, 16, v127
	v_and_b32_e32 v127, 0xffff0000, v127
	v_lshlrev_b32_e32 v165, 16, v159
	v_and_b32_e32 v159, 0xffff0000, v159
	v_lshl_add_u64 v[124:125], v[120:121], 0, v[144:145]
	v_fmac_f32_e32 v165, v114, v126
	v_fmac_f32_e32 v159, v115, v127
	v_cvt_pk_bf16_f32 v114, v164, v158
	v_cvt_pk_bf16_f32 v115, v165, v159
	global_load_dwordx4 v[116:119], v[162:163], off
	global_load_dwordx4 v[120:123], v[124:125], off
	s_waitcnt vmcnt(0)
; __device__ __forceinline__ unsigned cvt_pk_bf16(float lo, float hi) { unsigned r; asm volatile("v_cvt_pk_bf16_f32 %0, %1, %2" : "=v"(r) : "v"(lo), "v"(hi)); return r; }
; __device__ __forceinline__ float bf_lo(unsigned u) { return __uint_as_float(u << 16); }
; __device__ __forceinline__ float bf_hi(unsigned u) { return __uint_as_float(u & 0xffff0000u); }
;     __device__ __forceinline__ void operator()(const f32x4 (&acc)[2][2][4][2], const Unit& u, int wr, int wc, int fr, int fq) const {
;     ...
;             for (int m = 0; m < 4; ++m) { const size_t r = (size_t)(row0 + ai * HALF + m * 16); bf16_t* rowp = O + r * ldc + col0; const bf16_t* gp = G + r * ldg + col0;
; #pragma unroll
;                 for (int bj = 0; bj < 2; ++bj) { const u32x4 gw = *(const u32x4*)(gp + bj * HALF);
;                     f32x4 v0 = acc[ai][bj][m][0], v1 = acc[ai][bj][m][1];
;                     v0[0] *= bf_lo(gw.x); v0[1] *= bf_hi(gw.x); v0[2] *= bf_lo(gw.y); v0[3] *= bf_hi(gw.y);
;                     v1[0] *= bf_lo(gw.z); v1[1] *= bf_hi(gw.z); v1[2] *= bf_lo(gw.w); v1[3] *= bf_hi(gw.w);
;                     if (ACCUM) { const u32x4 pw = *(const u32x4*)(rowp + bj * HALF);
;                         v0[0] += bf_lo(pw.x); v0[1] += bf_hi(pw.x); v0[2] += bf_lo(pw.y); v0[3] += bf_hi(pw.y);
;                         v1[0] += bf_lo(pw.z); v1[1] += bf_hi(pw.z); v1[2] += bf_lo(pw.w); v1[3] += bf_hi(pw.w); }
;                     u32x4 w; w.x = cvt_pk_bf16(v0[0], v0[1]); w.y = cvt_pk_bf16(v0[2], v0[3]); w.z = cvt_pk_bf16(v1[0], v1[1]); w.w = cvt_pk_bf16(v1[2], v1[3]);
;                     *(u32x4*)(rowp + bj * HALF) = w; } }
	v_lshlrev_b32_e32 v126, 16, v120
	global_store_dwordx4 v[166:167], v[112:115], off offset:256
	v_and_b32_e32 v120, 0xffff0000, v120
	v_lshlrev_b32_e32 v127, 16, v121
	v_lshlrev_b32_e32 v112, 16, v116
	v_and_b32_e32 v113, 0xffff0000, v116
	v_lshlrev_b32_e32 v114, 16, v117
	v_and_b32_e32 v115, 0xffff0000, v117
	v_lshlrev_b32_e32 v116, 16, v118
	v_and_b32_e32 v117, 0xffff0000, v118
	v_lshlrev_b32_e32 v118, 16, v119
	v_and_b32_e32 v119, 0xffff0000, v119
	v_and_b32_e32 v121, 0xffff0000, v121
	v_lshlrev_b32_e32 v147, 16, v122
	v_and_b32_e32 v122, 0xffff0000, v122
	v_lshlrev_b32_e32 v156, 16, v123
	v_and_b32_e32 v123, 0xffff0000, v123
	v_fmac_f32_e32 v126, v108, v112
	v_fmac_f32_e32 v120, v109, v113
	v_fmac_f32_e32 v127, v110, v114
	v_fmac_f32_e32 v121, v111, v115
	v_fmac_f32_e32 v147, v104, v116
	v_fmac_f32_e32 v122, v105, v117
	v_fmac_f32_e32 v156, v106, v118
	v_fmac_f32_e32 v123, v107, v119
	v_cvt_pk_bf16_f32 v104, v126, v120
	v_cvt_pk_bf16_f32 v105, v127, v121
	v_cvt_pk_bf16_f32 v106, v147, v122
	v_cvt_pk_bf16_f32 v107, v156, v123
	global_load_dwordx4 v[108:111], v[162:163], off offset:256
	global_load_dwordx4 v[112:115], v[124:125], off offset:256
	v_or_b32_e32 v116, 32, v146
	global_store_dwordx4 v[124:125], v[104:107], off
	v_mad_i64_i32 v[118:119], s[18:19], v116, s41, v[148:149]
	v_lshl_add_u64 v[118:119], v[118:119], 0, v[144:145]
	s_waitcnt vmcnt(0)
	v_lshlrev_b32_e32 v104, 16, v108
	v_lshlrev_b32_e32 v117, 16, v112
	v_and_b32_e32 v105, 0xffff0000, v108
	v_lshlrev_b32_e32 v108, 16, v110
	v_and_b32_e32 v112, 0xffff0000, v112
	v_lshlrev_b32_e32 v121, 16, v114
	v_fmac_f32_e32 v117, v100, v104
	v_fmac_f32_e32 v112, v101, v105
	v_fmac_f32_e32 v121, v96, v108
	v_cvt_pk_bf16_f32 v96, v117, v112
	v_ashrrev_i32_e32 v117, 31, v116
	v_lshlrev_b64 v[104:105], 11, v[116:117]
	v_lshlrev_b32_e32 v106, 16, v109
	v_and_b32_e32 v107, 0xffff0000, v109
	v_and_b32_e32 v109, 0xffff0000, v110
	v_and_b32_e32 v114, 0xffff0000, v114
	v_lshl_add_u64 v[104:105], s[0:1], 0, v[104:105]
	v_lshlrev_b32_e32 v110, 16, v111
	v_and_b32_e32 v111, 0xffff0000, v111
	v_lshlrev_b32_e32 v120, 16, v113
	v_and_b32_e32 v113, 0xffff0000, v113
	v_lshlrev_b32_e32 v122, 16, v115
	v_and_b32_e32 v115, 0xffff0000, v115
	v_fmac_f32_e32 v114, v97, v109
	v_lshl_add_u64 v[108:109], v[104:105], 0, v[144:145]
	v_fmac_f32_e32 v120, v102, v106
	v_fmac_f32_e32 v113, v103, v107
	v_fmac_f32_e32 v122, v98, v110
	v_fmac_f32_e32 v115, v99, v111
	v_cvt_pk_bf16_f32 v97, v120, v113
	v_cvt_pk_bf16_f32 v98, v121, v114
	v_cvt_pk_bf16_f32 v99, v122, v115
	global_load_dwordx4 v[100:103], v[118:119], off
	global_load_dwordx4 v[104:107], v[108:109], off
	s_waitcnt vmcnt(0)
	v_lshlrev_b32_e32 v110, 16, v104
	global_store_dwordx4 v[124:125], v[96:99], off offset:256
	v_and_b32_e32 v104, 0xffff0000, v104
	v_lshlrev_b32_e32 v111, 16, v105
	v_lshlrev_b32_e32 v96, 16, v100
	v_and_b32_e32 v97, 0xffff0000, v100
	v_lshlrev_b32_e32 v98, 16, v101
	v_and_b32_e32 v99, 0xffff0000, v101
	v_lshlrev_b32_e32 v100, 16, v102
	v_and_b32_e32 v101, 0xffff0000, v102
	v_lshlrev_b32_e32 v102, 16, v103
	v_and_b32_e32 v103, 0xffff0000, v103
	v_and_b32_e32 v105, 0xffff0000, v105
	v_lshlrev_b32_e32 v112, 16, v106
	v_and_b32_e32 v106, 0xffff0000, v106
	v_lshlrev_b32_e32 v113, 16, v107
	v_and_b32_e32 v107, 0xffff0000, v107
	v_fmac_f32_e32 v110, v92, v96
	v_fmac_f32_e32 v104, v93, v97
	v_fmac_f32_e32 v111, v94, v98
	v_fmac_f32_e32 v105, v95, v99
	v_fmac_f32_e32 v112, v88, v100
	v_fmac_f32_e32 v106, v89, v101
	v_fmac_f32_e32 v113, v90, v102
	v_fmac_f32_e32 v107, v91, v103
	v_cvt_pk_bf16_f32 v88, v110, v104
	v_cvt_pk_bf16_f32 v89, v111, v105
	v_cvt_pk_bf16_f32 v90, v112, v106
	v_cvt_pk_bf16_f32 v91, v113, v107
	global_load_dwordx4 v[92:95], v[118:119], off offset:256
	global_load_dwordx4 v[96:99], v[108:109], off offset:256
	v_or_b32_e32 v100, 48, v146
	global_store_dwordx4 v[108:109], v[88:91], off
	v_mad_i64_i32 v[102:103], s[18:19], v100, s41, v[148:149]
	v_lshl_add_u64 v[102:103], v[102:103], 0, v[144:145]
	s_waitcnt vmcnt(0)
	v_lshlrev_b32_e32 v88, 16, v92
	v_lshlrev_b32_e32 v101, 16, v96
	v_and_b32_e32 v89, 0xffff0000, v92
	v_lshlrev_b32_e32 v92, 16, v94
	v_and_b32_e32 v96, 0xffff0000, v96
	v_lshlrev_b32_e32 v105, 16, v98
	v_fmac_f32_e32 v101, v84, v88
	v_fmac_f32_e32 v96, v85, v89
	v_fmac_f32_e32 v105, v80, v92
	v_cvt_pk_bf16_f32 v80, v101, v96
	v_ashrrev_i32_e32 v101, 31, v100
	v_lshlrev_b64 v[88:89], 11, v[100:101]
	v_lshlrev_b32_e32 v90, 16, v93
	v_and_b32_e32 v91, 0xffff0000, v93
	v_and_b32_e32 v93, 0xffff0000, v94
	v_and_b32_e32 v98, 0xffff0000, v98
	v_lshl_add_u64 v[88:89], s[0:1], 0, v[88:89]
	v_lshlrev_b32_e32 v94, 16, v95
	v_and_b32_e32 v95, 0xffff0000, v95
	v_lshlrev_b32_e32 v104, 16, v97
	v_and_b32_e32 v97, 0xffff0000, v97
	v_lshlrev_b32_e32 v106, 16, v99
	v_and_b32_e32 v99, 0xffff0000, v99
	v_fmac_f32_e32 v98, v81, v93
	v_lshl_add_u64 v[92:93], v[88:89], 0, v[144:145]
	v_fmac_f32_e32 v104, v86, v90
	v_fmac_f32_e32 v97, v87, v91
	v_fmac_f32_e32 v106, v82, v94
	v_fmac_f32_e32 v99, v83, v95
	v_cvt_pk_bf16_f32 v81, v104, v97
	v_cvt_pk_bf16_f32 v82, v105, v98
	v_cvt_pk_bf16_f32 v83, v106, v99
	global_load_dwordx4 v[84:87], v[102:103], off
	global_load_dwordx4 v[88:91], v[92:93], off
	s_waitcnt vmcnt(0)
; __device__ __forceinline__ unsigned cvt_pk_bf16(float lo, float hi) { unsigned r; asm volatile("v_cvt_pk_bf16_f32 %0, %1, %2" : "=v"(r) : "v"(lo), "v"(hi)); return r; }
; __device__ __forceinline__ float bf_lo(unsigned u) { return __uint_as_float(u << 16); }
; __device__ __forceinline__ float bf_hi(unsigned u) { return __uint_as_float(u & 0xffff0000u); }
;     __device__ __forceinline__ void operator()(const f32x4 (&acc)[2][2][4][2], const Unit& u, int wr, int wc, int fr, int fq) const {
;     ...
;             for (int m = 0; m < 4; ++m) { const size_t r = (size_t)(row0 + ai * HALF + m * 16); bf16_t* rowp = O + r * ldc + col0; const bf16_t* gp = G + r * ldg + col0;
; #pragma unroll
;                 for (int bj = 0; bj < 2; ++bj) { const u32x4 gw = *(const u32x4*)(gp + bj * HALF);
;                     f32x4 v0 = acc[ai][bj][m][0], v1 = acc[ai][bj][m][1];
;                     v0[0] *= bf_lo(gw.x); v0[1] *= bf_hi(gw.x); v0[2] *= bf_lo(gw.y); v0[3] *= bf_hi(gw.y);
;                     v1[0] *= bf_lo(gw.z); v1[1] *= bf_hi(gw.z); v1[2] *= bf_lo(gw.w); v1[3] *= bf_hi(gw.w);
;                     if (ACCUM) { const u32x4 pw = *(const u32x4*)(rowp + bj * HALF);
;                         v0[0] += bf_lo(pw.x); v0[1] += bf_hi(pw.x); v0[2] += bf_lo(pw.y); v0[3] += bf_hi(pw.y);
;                         v1[0] += bf_lo(pw.z); v1[1] += bf_hi(pw.z); v1[2] += bf_lo(pw.w); v1[3] += bf_hi(pw.w); }
;                     u32x4 w; w.x = cvt_pk_bf16(v0[0], v0[1]); w.y = cvt_pk_bf16(v0[2], v0[3]); w.z = cvt_pk_bf16(v1[0], v1[1]); w.w = cvt_pk_bf16(v1[2], v1[3]);
;                     *(u32x4*)(rowp + bj * HALF) = w; } }
	v_lshlrev_b32_e32 v94, 16, v88
	global_store_dwordx4 v[108:109], v[80:83], off offset:256
	v_and_b32_e32 v88, 0xffff0000, v88
	v_lshlrev_b32_e32 v95, 16, v89
	v_lshlrev_b32_e32 v80, 16, v84
	v_and_b32_e32 v81, 0xffff0000, v84
	v_lshlrev_b32_e32 v82, 16, v85
	v_and_b32_e32 v83, 0xffff0000, v85
	v_lshlrev_b32_e32 v84, 16, v86
	v_and_b32_e32 v85, 0xffff0000, v86
	v_lshlrev_b32_e32 v86, 16, v87
	v_and_b32_e32 v87, 0xffff0000, v87
	v_and_b32_e32 v89, 0xffff0000, v89
	v_lshlrev_b32_e32 v96, 16, v90
	v_and_b32_e32 v90, 0xffff0000, v90
	v_lshlrev_b32_e32 v97, 16, v91
	v_and_b32_e32 v91, 0xffff0000, v91
	v_fmac_f32_e32 v94, v76, v80
	v_fmac_f32_e32 v88, v77, v81
	v_fmac_f32_e32 v95, v78, v82
	v_fmac_f32_e32 v89, v79, v83
	v_fmac_f32_e32 v96, v72, v84
	v_fmac_f32_e32 v90, v73, v85
	v_fmac_f32_e32 v97, v74, v86
	v_fmac_f32_e32 v91, v75, v87
	v_cvt_pk_bf16_f32 v72, v94, v88
	v_cvt_pk_bf16_f32 v73, v95, v89
	v_cvt_pk_bf16_f32 v74, v96, v90
	v_cvt_pk_bf16_f32 v75, v97, v91
	global_load_dwordx4 v[76:79], v[102:103], off offset:256
	global_load_dwordx4 v[80:83], v[92:93], off offset:256
	v_add_u32_e32 v84, 0x80, v146
	global_store_dwordx4 v[92:93], v[72:75], off
	v_mad_i64_i32 v[86:87], s[18:19], v84, s41, v[148:149]
	v_lshl_add_u64 v[86:87], v[86:87], 0, v[144:145]
	s_waitcnt vmcnt(0)
	v_lshlrev_b32_e32 v72, 16, v76
	v_lshlrev_b32_e32 v85, 16, v80
	v_and_b32_e32 v73, 0xffff0000, v76
	v_lshlrev_b32_e32 v76, 16, v78
	v_and_b32_e32 v80, 0xffff0000, v80
	v_lshlrev_b32_e32 v89, 16, v82
	v_fmac_f32_e32 v85, v68, v72
	v_fmac_f32_e32 v80, v69, v73
	v_fmac_f32_e32 v89, v64, v76
	v_cvt_pk_bf16_f32 v64, v85, v80
	v_ashrrev_i32_e32 v85, 31, v84
	v_lshlrev_b64 v[72:73], 11, v[84:85]
	v_lshlrev_b32_e32 v74, 16, v77
	v_and_b32_e32 v75, 0xffff0000, v77
	v_and_b32_e32 v77, 0xffff0000, v78
	v_and_b32_e32 v82, 0xffff0000, v82
	v_lshl_add_u64 v[72:73], s[0:1], 0, v[72:73]
	v_lshlrev_b32_e32 v78, 16, v79
	v_and_b32_e32 v79, 0xffff0000, v79
	v_lshlrev_b32_e32 v88, 16, v81
	v_and_b32_e32 v81, 0xffff0000, v81
	v_lshlrev_b32_e32 v90, 16, v83
	v_and_b32_e32 v83, 0xffff0000, v83
	v_fmac_f32_e32 v82, v65, v77
	v_lshl_add_u64 v[76:77], v[72:73], 0, v[144:145]
	v_fmac_f32_e32 v88, v70, v74
	v_fmac_f32_e32 v81, v71, v75
	v_fmac_f32_e32 v90, v66, v78
	v_fmac_f32_e32 v83, v67, v79
	v_cvt_pk_bf16_f32 v65, v88, v81
	v_cvt_pk_bf16_f32 v66, v89, v82
	v_cvt_pk_bf16_f32 v67, v90, v83
	global_load_dwordx4 v[68:71], v[86:87], off
	global_load_dwordx4 v[72:75], v[76:77], off
	s_waitcnt vmcnt(0)
	v_lshlrev_b32_e32 v78, 16, v72
	global_store_dwordx4 v[92:93], v[64:67], off offset:256
	v_and_b32_e32 v72, 0xffff0000, v72
	v_lshlrev_b32_e32 v79, 16, v73
	v_lshlrev_b32_e32 v64, 16, v68
	v_and_b32_e32 v65, 0xffff0000, v68
	v_lshlrev_b32_e32 v66, 16, v69
	v_and_b32_e32 v67, 0xffff0000, v69
	v_lshlrev_b32_e32 v68, 16, v70
	v_and_b32_e32 v69, 0xffff0000, v70
	v_lshlrev_b32_e32 v70, 16, v71
	v_and_b32_e32 v71, 0xffff0000, v71
	v_and_b32_e32 v73, 0xffff0000, v73
	v_lshlrev_b32_e32 v80, 16, v74
	v_and_b32_e32 v74, 0xffff0000, v74
	v_lshlrev_b32_e32 v81, 16, v75
	v_and_b32_e32 v75, 0xffff0000, v75
	v_fmac_f32_e32 v78, v60, v64
	v_fmac_f32_e32 v72, v61, v65
	v_fmac_f32_e32 v79, v62, v66
	v_fmac_f32_e32 v73, v63, v67
	v_fmac_f32_e32 v80, v56, v68
	v_fmac_f32_e32 v74, v57, v69
	v_fmac_f32_e32 v81, v58, v70
	v_fmac_f32_e32 v75, v59, v71
	v_cvt_pk_bf16_f32 v56, v78, v72
	v_cvt_pk_bf16_f32 v57, v79, v73
	v_cvt_pk_bf16_f32 v58, v80, v74
	v_cvt_pk_bf16_f32 v59, v81, v75
	global_load_dwordx4 v[60:63], v[86:87], off offset:256
	global_load_dwordx4 v[64:67], v[76:77], off offset:256
	v_add_u32_e32 v68, 0x90, v146
	global_store_dwordx4 v[76:77], v[56:59], off
	v_mad_i64_i32 v[70:71], s[18:19], v68, s41, v[148:149]
	v_lshl_add_u64 v[70:71], v[70:71], 0, v[144:145]
	s_waitcnt vmcnt(0)
	v_lshlrev_b32_e32 v56, 16, v60
	v_lshlrev_b32_e32 v69, 16, v64
	v_and_b32_e32 v57, 0xffff0000, v60
	v_lshlrev_b32_e32 v60, 16, v62
	v_and_b32_e32 v64, 0xffff0000, v64
	v_lshlrev_b32_e32 v73, 16, v66
	v_fmac_f32_e32 v69, v52, v56
	v_fmac_f32_e32 v64, v53, v57
	v_fmac_f32_e32 v73, v48, v60
	v_cvt_pk_bf16_f32 v48, v69, v64
	v_ashrrev_i32_e32 v69, 31, v68
	v_lshlrev_b64 v[56:57], 11, v[68:69]
	v_lshlrev_b32_e32 v58, 16, v61
	v_and_b32_e32 v59, 0xffff0000, v61
	v_and_b32_e32 v61, 0xffff0000, v62
	v_and_b32_e32 v66, 0xffff0000, v66
	v_lshl_add_u64 v[56:57], s[0:1], 0, v[56:57]
	v_lshlrev_b32_e32 v62, 16, v63
	v_and_b32_e32 v63, 0xffff0000, v63
	v_lshlrev_b32_e32 v72, 16, v65
	v_and_b32_e32 v65, 0xffff0000, v65
	v_lshlrev_b32_e32 v74, 16, v67
	v_and_b32_e32 v67, 0xffff0000, v67
	v_fmac_f32_e32 v66, v49, v61
	v_lshl_add_u64 v[60:61], v[56:57], 0, v[144:145]
	v_fmac_f32_e32 v72, v54, v58
	v_fmac_f32_e32 v65, v55, v59
	v_fmac_f32_e32 v74, v50, v62
	v_fmac_f32_e32 v67, v51, v63
	v_cvt_pk_bf16_f32 v49, v72, v65
	v_cvt_pk_bf16_f32 v50, v73, v66
	v_cvt_pk_bf16_f32 v51, v74, v67
	global_load_dwordx4 v[52:55], v[70:71], off
	global_load_dwordx4 v[56:59], v[60:61], off
	s_waitcnt vmcnt(0)
	v_lshlrev_b32_e32 v62, 16, v56
	global_store_dwordx4 v[76:77], v[48:51], off offset:256
	v_and_b32_e32 v56, 0xffff0000, v56
	v_lshlrev_b32_e32 v63, 16, v57
	v_lshlrev_b32_e32 v48, 16, v52
	v_and_b32_e32 v49, 0xffff0000, v52
	v_lshlrev_b32_e32 v50, 16, v53
	v_and_b32_e32 v51, 0xffff0000, v53
	v_lshlrev_b32_e32 v52, 16, v54
	v_and_b32_e32 v53, 0xffff0000, v54
	v_lshlrev_b32_e32 v54, 16, v55
	v_and_b32_e32 v55, 0xffff0000, v55
	v_and_b32_e32 v57, 0xffff0000, v57
	v_lshlrev_b32_e32 v64, 16, v58
	v_and_b32_e32 v58, 0xffff0000, v58
	v_lshlrev_b32_e32 v65, 16, v59
	v_and_b32_e32 v59, 0xffff0000, v59
	v_fmac_f32_e32 v62, v44, v48
	v_fmac_f32_e32 v56, v45, v49
	v_fmac_f32_e32 v63, v46, v50
	v_fmac_f32_e32 v57, v47, v51
	v_fmac_f32_e32 v64, v40, v52
	v_fmac_f32_e32 v58, v41, v53
	v_fmac_f32_e32 v65, v42, v54
	v_fmac_f32_e32 v59, v43, v55
	v_cvt_pk_bf16_f32 v40, v62, v56
	v_cvt_pk_bf16_f32 v41, v63, v57
	v_cvt_pk_bf16_f32 v42, v64, v58
	v_cvt_pk_bf16_f32 v43, v65, v59
	global_load_dwordx4 v[44:47], v[70:71], off offset:256
	global_load_dwordx4 v[48:51], v[60:61], off offset:256
	v_add_u32_e32 v52, 0xa0, v146
	global_store_dwordx4 v[60:61], v[40:43], off
	v_mad_i64_i32 v[54:55], s[18:19], v52, s41, v[148:149]
	v_lshl_add_u64 v[54:55], v[54:55], 0, v[144:145]
	s_waitcnt vmcnt(0)
; __device__ __forceinline__ unsigned cvt_pk_bf16(float lo, float hi) { unsigned r; asm volatile("v_cvt_pk_bf16_f32 %0, %1, %2" : "=v"(r) : "v"(lo), "v"(hi)); return r; }
; __device__ __forceinline__ float bf_lo(unsigned u) { return __uint_as_float(u << 16); }
; __device__ __forceinline__ float bf_hi(unsigned u) { return __uint_as_float(u & 0xffff0000u); }
; #define PG8_WAIT_V(n) asm volatile("s_waitcnt vmcnt(" #n ")" ::: "memory")
; #define PG8_BAR __builtin_amdgcn_s_barrier()
;     __device__ __forceinline__ void operator()(const f32x4 (&acc)[2][2][4][2], const Unit& u, int wr, int wc, int fr, int fq) const {
;     ...
;             for (int m = 0; m < 4; ++m) { const size_t r = (size_t)(row0 + ai * HALF + m * 16); bf16_t* rowp = O + r * ldc + col0; const bf16_t* gp = G + r * ldg + col0;
; #pragma unroll
;                 for (int bj = 0; bj < 2; ++bj) { const u32x4 gw = *(const u32x4*)(gp + bj * HALF);
;                     f32x4 v0 = acc[ai][bj][m][0], v1 = acc[ai][bj][m][1];
;                     v0[0] *= bf_lo(gw.x); v0[1] *= bf_hi(gw.x); v0[2] *= bf_lo(gw.y); v0[3] *= bf_hi(gw.y);
;                     v1[0] *= bf_lo(gw.z); v1[1] *= bf_hi(gw.z); v1[2] *= bf_lo(gw.w); v1[3] *= bf_hi(gw.w);
;                     if (ACCUM) { const u32x4 pw = *(const u32x4*)(rowp + bj * HALF);
;                         v0[0] += bf_lo(pw.x); v0[1] += bf_hi(pw.x); v0[2] += bf_lo(pw.y); v0[3] += bf_hi(pw.y);
;                         v1[0] += bf_lo(pw.z); v1[1] += bf_hi(pw.z); v1[2] += bf_lo(pw.w); v1[3] += bf_hi(pw.w); }
;                     u32x4 w; w.x = cvt_pk_bf16(v0[0], v0[1]); w.y = cvt_pk_bf16(v0[2], v0[3]); w.z = cvt_pk_bf16(v1[0], v1[1]); w.w = cvt_pk_bf16(v1[2], v1[3]);
;                     *(u32x4*)(rowp + bj * HALF) = w; } }
; template <class Epi, class Sched>
; __device__ __forceinline__ void gemm_phase(PG8_LAS unsigned char* lds, const Gemm g, const Sched& S, const Epi& E) {
;     ...
;         if (!has_next) break;
; #pragma unroll
;         for (int a = 0; a < 2; ++a)
; #pragma unroll
;             for (int b = 0; b < 2; ++b)
; #pragma unroll
;                 for (int m = 0; m < 4; ++m)
; #pragma unroll
;                     for (int n = 0; n < 2; ++n) acc[a][b][m][n] = (f32x4){0.f, 0.f, 0.f, 0.f};
;         cur = nxt; cA = nA; cB = nB; ++ui;
;     }
;     PG8_WAIT_V(0);
;     if (wr == 0) PG8_BAR;
	v_lshlrev_b32_e32 v40, 16, v44
	v_lshlrev_b32_e32 v53, 16, v48
	v_and_b32_e32 v41, 0xffff0000, v44
	v_lshlrev_b32_e32 v44, 16, v46
	v_and_b32_e32 v48, 0xffff0000, v48
	v_lshlrev_b32_e32 v57, 16, v50
	v_fmac_f32_e32 v53, v36, v40
	v_fmac_f32_e32 v48, v37, v41
	v_fmac_f32_e32 v57, v32, v44
	v_cvt_pk_bf16_f32 v32, v53, v48
	v_ashrrev_i32_e32 v53, 31, v52
	v_lshlrev_b64 v[40:41], 11, v[52:53]
	v_lshlrev_b32_e32 v42, 16, v45
	v_and_b32_e32 v43, 0xffff0000, v45
	v_and_b32_e32 v45, 0xffff0000, v46
	v_and_b32_e32 v50, 0xffff0000, v50
	v_lshl_add_u64 v[40:41], s[0:1], 0, v[40:41]
	v_lshlrev_b32_e32 v46, 16, v47
	v_and_b32_e32 v47, 0xffff0000, v47
	v_lshlrev_b32_e32 v56, 16, v49
	v_and_b32_e32 v49, 0xffff0000, v49
	v_lshlrev_b32_e32 v58, 16, v51
	v_and_b32_e32 v51, 0xffff0000, v51
	v_fmac_f32_e32 v50, v33, v45
	v_lshl_add_u64 v[44:45], v[40:41], 0, v[144:145]
	v_fmac_f32_e32 v56, v38, v42
	v_fmac_f32_e32 v49, v39, v43
	v_fmac_f32_e32 v58, v34, v46
	v_fmac_f32_e32 v51, v35, v47
	v_cvt_pk_bf16_f32 v33, v56, v49
	v_cvt_pk_bf16_f32 v34, v57, v50
	v_cvt_pk_bf16_f32 v35, v58, v51
	global_load_dwordx4 v[36:39], v[54:55], off
	global_load_dwordx4 v[40:43], v[44:45], off
	s_waitcnt vmcnt(0)
	v_lshlrev_b32_e32 v46, 16, v40
	global_store_dwordx4 v[60:61], v[32:35], off offset:256
	v_and_b32_e32 v40, 0xffff0000, v40
	v_lshlrev_b32_e32 v47, 16, v41
	v_lshlrev_b32_e32 v32, 16, v36
	v_and_b32_e32 v33, 0xffff0000, v36
	v_lshlrev_b32_e32 v34, 16, v37
	v_and_b32_e32 v35, 0xffff0000, v37
	v_lshlrev_b32_e32 v36, 16, v38
	v_and_b32_e32 v37, 0xffff0000, v38
	v_lshlrev_b32_e32 v38, 16, v39
	v_and_b32_e32 v39, 0xffff0000, v39
	v_and_b32_e32 v41, 0xffff0000, v41
	v_lshlrev_b32_e32 v48, 16, v42
	v_and_b32_e32 v42, 0xffff0000, v42
	v_lshlrev_b32_e32 v49, 16, v43
	v_and_b32_e32 v43, 0xffff0000, v43
	v_fmac_f32_e32 v46, v28, v32
	v_fmac_f32_e32 v40, v29, v33
	v_fmac_f32_e32 v47, v30, v34
	v_fmac_f32_e32 v41, v31, v35
	v_fmac_f32_e32 v48, v24, v36
	v_fmac_f32_e32 v42, v25, v37
	v_fmac_f32_e32 v49, v26, v38
	v_fmac_f32_e32 v43, v27, v39
	v_cvt_pk_bf16_f32 v24, v46, v40
	v_cvt_pk_bf16_f32 v25, v47, v41
	v_cvt_pk_bf16_f32 v26, v48, v42
	v_cvt_pk_bf16_f32 v27, v49, v43
	global_load_dwordx4 v[28:31], v[54:55], off offset:256
	global_load_dwordx4 v[32:35], v[44:45], off offset:256
	v_add_u32_e32 v36, 0xb0, v146
	global_store_dwordx4 v[44:45], v[24:27], off
	v_mad_i64_i32 v[38:39], s[18:19], v36, s41, v[148:149]
	v_lshl_add_u64 v[38:39], v[38:39], 0, v[144:145]
	s_mov_b64 s[18:19], s[12:13]
	s_waitcnt vmcnt(0)
	v_lshlrev_b32_e32 v24, 16, v28
	v_lshlrev_b32_e32 v37, 16, v32
	v_and_b32_e32 v25, 0xffff0000, v28
	v_lshlrev_b32_e32 v28, 16, v30
	v_and_b32_e32 v32, 0xffff0000, v32
	v_lshlrev_b32_e32 v41, 16, v34
	v_fmac_f32_e32 v37, v20, v24
	v_fmac_f32_e32 v32, v21, v25
	v_fmac_f32_e32 v41, v16, v28
	v_cvt_pk_bf16_f32 v16, v37, v32
	v_ashrrev_i32_e32 v37, 31, v36
	v_lshlrev_b64 v[24:25], 11, v[36:37]
	v_lshlrev_b32_e32 v26, 16, v29
	v_and_b32_e32 v27, 0xffff0000, v29
	v_and_b32_e32 v29, 0xffff0000, v30
	v_and_b32_e32 v34, 0xffff0000, v34
	v_lshl_add_u64 v[24:25], s[0:1], 0, v[24:25]
	v_lshlrev_b32_e32 v30, 16, v31
	v_and_b32_e32 v31, 0xffff0000, v31
	v_lshlrev_b32_e32 v40, 16, v33
	v_and_b32_e32 v33, 0xffff0000, v33
	v_lshlrev_b32_e32 v42, 16, v35
	v_and_b32_e32 v35, 0xffff0000, v35
	v_fmac_f32_e32 v34, v17, v29
	v_lshl_add_u64 v[28:29], v[24:25], 0, v[144:145]
	v_fmac_f32_e32 v40, v22, v26
	v_fmac_f32_e32 v33, v23, v27
	v_fmac_f32_e32 v42, v18, v30
	v_fmac_f32_e32 v35, v19, v31
	v_cvt_pk_bf16_f32 v17, v40, v33
	v_cvt_pk_bf16_f32 v18, v41, v34
	v_cvt_pk_bf16_f32 v19, v42, v35
	global_load_dwordx4 v[20:23], v[38:39], off
	global_load_dwordx4 v[24:27], v[28:29], off
	s_waitcnt vmcnt(0)
	v_lshlrev_b32_e32 v30, 16, v24
	global_store_dwordx4 v[44:45], v[16:19], off offset:256
	v_and_b32_e32 v24, 0xffff0000, v24
	v_lshlrev_b32_e32 v31, 16, v25
	v_lshlrev_b32_e32 v16, 16, v20
	v_and_b32_e32 v17, 0xffff0000, v20
	v_lshlrev_b32_e32 v18, 16, v21
	v_and_b32_e32 v19, 0xffff0000, v21
	v_lshlrev_b32_e32 v20, 16, v22
	v_and_b32_e32 v21, 0xffff0000, v22
	v_lshlrev_b32_e32 v22, 16, v23
	v_and_b32_e32 v23, 0xffff0000, v23
	v_and_b32_e32 v25, 0xffff0000, v25
	v_lshlrev_b32_e32 v32, 16, v26
	v_and_b32_e32 v26, 0xffff0000, v26
	v_lshlrev_b32_e32 v33, 16, v27
	v_and_b32_e32 v27, 0xffff0000, v27
	v_fmac_f32_e32 v30, v12, v16
	v_fmac_f32_e32 v24, v13, v17
	v_fmac_f32_e32 v31, v14, v18
	v_fmac_f32_e32 v25, v15, v19
	v_fmac_f32_e32 v32, v8, v20
	v_fmac_f32_e32 v26, v9, v21
	v_fmac_f32_e32 v33, v10, v22
	v_fmac_f32_e32 v27, v11, v23
	v_cvt_pk_bf16_f32 v8, v30, v24
	v_cvt_pk_bf16_f32 v9, v31, v25
	v_cvt_pk_bf16_f32 v10, v32, v26
	v_cvt_pk_bf16_f32 v11, v33, v27
	global_load_dwordx4 v[12:15], v[38:39], off offset:256
	global_load_dwordx4 v[16:19], v[28:29], off offset:256
	s_waitcnt vmcnt(0)
	v_lshlrev_b32_e32 v20, 16, v16
	global_store_dwordx4 v[28:29], v[8:11], off
	v_and_b32_e32 v16, 0xffff0000, v16
	v_lshlrev_b32_e32 v21, 16, v17
	v_lshlrev_b32_e32 v8, 16, v12
	v_and_b32_e32 v9, 0xffff0000, v12
	v_lshlrev_b32_e32 v10, 16, v13
	v_and_b32_e32 v11, 0xffff0000, v13
	v_lshlrev_b32_e32 v12, 16, v14
	v_and_b32_e32 v13, 0xffff0000, v14
	v_lshlrev_b32_e32 v14, 16, v15
	v_and_b32_e32 v15, 0xffff0000, v15
	v_and_b32_e32 v17, 0xffff0000, v17
	v_lshlrev_b32_e32 v22, 16, v18
	v_and_b32_e32 v18, 0xffff0000, v18
	v_lshlrev_b32_e32 v23, 16, v19
	v_and_b32_e32 v19, 0xffff0000, v19
	v_fmac_f32_e32 v20, v4, v8
	v_fmac_f32_e32 v16, v5, v9
	v_fmac_f32_e32 v21, v6, v10
	v_fmac_f32_e32 v17, v7, v11
	v_fmac_f32_e32 v22, v0, v12
	v_fmac_f32_e32 v18, v1, v13
	v_fmac_f32_e32 v23, v2, v14
	v_fmac_f32_e32 v19, v3, v15
	v_cvt_pk_bf16_f32 v0, v20, v16
	v_cvt_pk_bf16_f32 v1, v21, v17
	v_cvt_pk_bf16_f32 v2, v22, v18
	v_cvt_pk_bf16_f32 v3, v23, v19
	global_store_dwordx4 v[28:29], v[0:3], off offset:256
	s_cbranch_vccz .LBB0_1004
	s_waitcnt vmcnt(0)
	s_cmpk_gt_u32 s25, 0xff
	s_cbranch_scc1 .LBB0_1015
	s_barrier

; #define PG8_STAGE(bufoff, gbase, voff) do { _Pragma("unroll") for (int _i = 0; _i < 2; ++_i) \
;         __builtin_amdgcn_global_load_lds((const unsigned*)((const char*)(gbase) + (voff)[_i]), (PG8_LAS unsigned*)(lds + (bufoff) + ldsw + _i * 8192), 16, 0, 0); } while (0)
; #define PG8_LDA(dst, b, h) do { _Pragma("unroll") for (int m = 0; m < 4; ++m) _Pragma("unroll") for (int k = 0; k < 2; ++k) dst[m][k] = *(const PG8_LAS bf16x8*)(lds + PG8_SA(b, h) + aoff + m * 2048 + k * 1024); } while (0)
; #define PG8_LDB(dst, b, h) do { _Pragma("unroll") for (int n = 0; n < 2; ++n) _Pragma("unroll") for (int k = 0; k < 2; ++k) dst[n][k] = *(const PG8_LAS bf16x8*)(lds + PG8_SB(b, h) + boff + n * 2048 + k * 1024); } while (0)
; #define PG8_MMA(ai, bj, At, Bt) do { __builtin_amdgcn_s_setprio(1); _Pragma("unroll") for (int m = 0; m < 4; ++m) _Pragma("unroll") for (int n = 0; n < 2; ++n) _Pragma("unroll") for (int k = 0; k < 2; ++k) \
;         acc[ai][bj][m][n] = __builtin_amdgcn_mfma_f32_16x16x32_bf16(Bt[n][k], At[m][k], acc[ai][bj][m][n], 0, 0, 0); __builtin_amdgcn_s_setprio(0); } while (0)
; #define PG8_WAIT_V(n) asm volatile("s_waitcnt vmcnt(" #n ")" ::: "memory")
; #define PG8_WAIT_L(n) asm volatile("s_waitcnt lgkmcnt(" #n ")" ::: "memory")
; #define PG8_BAR __builtin_amdgcn_s_barrier()
; #define PG8_SCHED __builtin_amdgcn_sched_barrier(0)
; template <class Epi, class Sched>
; __device__ __forceinline__ void gemm_phase(PG8_LAS unsigned char* lds, const Gemm g, const Sched& S, const Epi& E) {
;     ...
;             PG8_LDB(B0, 0, 0); PG8_SCHED; PG8_LDA(At, 0, 0); PG8_STAGE(PG8_SA(1, 1), a1 + hstep, voffA);
;             PG8_WAIT_L(8); PG8_BAR; PG8_WAIT_L(0); PG8_MMA(0, 0, At, B0); PG8_BAR; PG8_SCHED;
;             PG8_LDB(B1, 0, 1); PG8_STAGE(PG8_SB(0, 0), b2, voffB);
;             PG8_BAR; PG8_WAIT_L(0); PG8_MMA(0, 1, At, B1); PG8_BAR;
;             PG8_LDA(At, 0, 1); PG8_STAGE(PG8_SA(0, 0), a2, voffA);
;             PG8_BAR; PG8_WAIT_L(0); PG8_MMA(1, 0, At, B0); PG8_BAR; PG8_SCHED;
;             PG8_STAGE(PG8_SB(0, 1), b2 + hstep, voffB);
;             PG8_WAIT_V(6); PG8_BAR; PG8_MMA(1, 1, At, B1); PG8_BAR;
.LBB0_1083:
	ds_read_b128 v[152:155], v149
	ds_read_b128 v[156:159], v149 offset:1024
	ds_read_b128 v[160:163], v149 offset:2048
	ds_read_b128 v[164:167], v149 offset:3072
	s_add_u32 s26, s24, 0xfffc0080
	s_addc_u32 s27, s25, -1
	s_cmp_eq_u32 s56, 12
	s_cselect_b32 s29, s17, s27
	s_cselect_b32 s28, s52, s26
	s_cselect_b32 s27, s15, s55
	s_cselect_b32 s26, s53, s54
	v_lshl_add_u64 v[144:145], s[24:25], 0, v[136:137]
	s_add_i32 m0, s23, 0xc000
	ds_read_b128 v[168:171], v150
	ds_read_b128 v[172:175], v150 offset:1024
	ds_read_b128 v[182:185], v150 offset:2048
	ds_read_b128 v[190:193], v150 offset:3072
	ds_read_b128 v[194:197], v150 offset:4096
	ds_read_b128 v[198:201], v150 offset:5120
	ds_read_b128 v[202:205], v150 offset:6144
	ds_read_b128 v[206:209], v150 offset:7168
	global_load_lds_dwordx4 v[144:145], off
	v_lshl_add_u64 v[144:145], s[24:25], 0, v[138:139]
	s_add_i32 m0, s23, 0xe000
	s_nop 0
	global_load_lds_dwordx4 v[144:145], off
	s_waitcnt lgkmcnt(8)
	s_barrier
	s_waitcnt lgkmcnt(0)
	v_mfma_f32_16x16x32_bf16 v[124:127], v[152:155], v[168:171], v[124:127]
	v_mfma_f32_16x16x32_bf16 v[120:123], v[160:163], v[168:171], v[120:123]
	v_mfma_f32_16x16x32_bf16 v[108:111], v[152:155], v[182:185], v[108:111]
	v_mfma_f32_16x16x32_bf16 v[104:107], v[160:163], v[182:185], v[104:107]
	v_mfma_f32_16x16x32_bf16 v[92:95], v[152:155], v[194:197], v[92:95]
	v_mfma_f32_16x16x32_bf16 v[88:91], v[160:163], v[194:197], v[88:91]
	v_mfma_f32_16x16x32_bf16 v[76:79], v[152:155], v[202:205], v[76:79]
	v_mfma_f32_16x16x32_bf16 v[72:75], v[160:163], v[202:205], v[72:75]
	v_mfma_f32_16x16x32_bf16 v[124:127], v[156:159], v[172:175], v[124:127]
	v_mfma_f32_16x16x32_bf16 v[120:123], v[164:167], v[172:175], v[120:123]
	v_mfma_f32_16x16x32_bf16 v[108:111], v[156:159], v[190:193], v[108:111]
	v_mfma_f32_16x16x32_bf16 v[104:107], v[164:167], v[190:193], v[104:107]
	v_mfma_f32_16x16x32_bf16 v[92:95], v[156:159], v[198:201], v[92:95]
	v_mfma_f32_16x16x32_bf16 v[88:91], v[164:167], v[198:201], v[88:91]
	v_mfma_f32_16x16x32_bf16 v[76:79], v[156:159], v[206:209], v[76:79]
	v_mfma_f32_16x16x32_bf16 v[72:75], v[164:167], v[206:209], v[72:75]
	s_barrier
	s_add_i32 s57, s45, s37
	v_lshl_add_u64 v[144:145], s[26:27], 0, v[130:131]
	s_mov_b32 m0, s57
	ds_read_b128 v[210:213], v151
	ds_read_b128 v[214:217], v151 offset:1024
	ds_read_b128 v[218:221], v151 offset:2048
	ds_read_b128 v[222:225], v151 offset:3072
	global_load_lds_dwordx4 v[144:145], off
	v_lshl_add_u64 v[186:187], s[26:27], 0, v[134:135]
	s_add_i32 m0, s57, 0x2000
	s_nop 0
	global_load_lds_dwordx4 v[186:187], off
	s_barrier
	s_waitcnt lgkmcnt(0)
	v_mfma_f32_16x16x32_bf16 v[116:119], v[210:213], v[168:171], v[116:119]
	v_mfma_f32_16x16x32_bf16 v[112:115], v[218:221], v[168:171], v[112:115]
	v_mfma_f32_16x16x32_bf16 v[100:103], v[210:213], v[182:185], v[100:103]
	v_mfma_f32_16x16x32_bf16 v[96:99], v[218:221], v[182:185], v[96:99]
	v_mfma_f32_16x16x32_bf16 v[84:87], v[210:213], v[194:197], v[84:87]
	v_mfma_f32_16x16x32_bf16 v[80:83], v[218:221], v[194:197], v[80:83]
	v_mfma_f32_16x16x32_bf16 v[68:71], v[210:213], v[202:205], v[68:71]
	v_mfma_f32_16x16x32_bf16 v[64:67], v[218:221], v[202:205], v[64:67]
	v_mfma_f32_16x16x32_bf16 v[116:119], v[214:217], v[172:175], v[116:119]
	v_mfma_f32_16x16x32_bf16 v[112:115], v[222:225], v[172:175], v[112:115]
	v_mfma_f32_16x16x32_bf16 v[100:103], v[214:217], v[190:193], v[100:103]
	v_mfma_f32_16x16x32_bf16 v[96:99], v[222:225], v[190:193], v[96:99]
	v_mfma_f32_16x16x32_bf16 v[84:87], v[214:217], v[198:201], v[84:87]
	v_mfma_f32_16x16x32_bf16 v[80:83], v[222:225], v[198:201], v[80:83]
	v_mfma_f32_16x16x32_bf16 v[68:71], v[214:217], v[206:209], v[68:71]
	v_mfma_f32_16x16x32_bf16 v[64:67], v[222:225], v[206:209], v[64:67]
	s_mov_b32 m0, s23
	v_lshl_add_u64 v[226:227], s[28:29], 0, v[128:129]
	s_barrier
	ds_read_b128 v[168:171], v150 offset:16384
	ds_read_b128 v[172:175], v150 offset:17408
	ds_read_b128 v[182:185], v150 offset:18432
	ds_read_b128 v[190:193], v150 offset:19456
	ds_read_b128 v[194:197], v150 offset:20480
	ds_read_b128 v[198:201], v150 offset:21504
	ds_read_b128 v[202:205], v150 offset:22528
	ds_read_b128 v[206:209], v150 offset:23552
	global_load_lds_dwordx4 v[226:227], off
	v_lshl_add_u64 v[228:229], s[28:29], 0, v[132:133]
	s_mov_b32 m0, s38
	s_nop 0
	global_load_lds_dwordx4 v[228:229], off
	s_barrier
	s_waitcnt lgkmcnt(0)
	v_mfma_f32_16x16x32_bf16 v[60:63], v[152:155], v[168:171], v[60:63]
	v_mfma_f32_16x16x32_bf16 v[56:59], v[160:163], v[168:171], v[56:59]
	v_mfma_f32_16x16x32_bf16 v[48:51], v[152:155], v[182:185], v[48:51]
	v_mfma_f32_16x16x32_bf16 v[40:43], v[160:163], v[182:185], v[40:43]
	v_mfma_f32_16x16x32_bf16 v[32:35], v[152:155], v[194:197], v[32:35]
	v_mfma_f32_16x16x32_bf16 v[24:27], v[160:163], v[194:197], v[24:27]
	v_mfma_f32_16x16x32_bf16 v[16:19], v[152:155], v[202:205], v[16:19]
	v_mfma_f32_16x16x32_bf16 v[8:11], v[160:163], v[202:205], v[8:11]
	v_mfma_f32_16x16x32_bf16 v[60:63], v[156:159], v[172:175], v[60:63]
	v_mfma_f32_16x16x32_bf16 v[56:59], v[164:167], v[172:175], v[56:59]
	v_mfma_f32_16x16x32_bf16 v[48:51], v[156:159], v[190:193], v[48:51]
	v_mfma_f32_16x16x32_bf16 v[40:43], v[164:167], v[190:193], v[40:43]
	v_mfma_f32_16x16x32_bf16 v[32:35], v[156:159], v[198:201], v[32:35]
	v_mfma_f32_16x16x32_bf16 v[24:27], v[164:167], v[198:201], v[24:27]
	v_mfma_f32_16x16x32_bf16 v[16:19], v[156:159], v[206:209], v[16:19]
	v_mfma_f32_16x16x32_bf16 v[8:11], v[164:167], v[206:209], v[8:11]
	s_barrier
; #define PG8_STAGE(bufoff, gbase, voff) do { _Pragma("unroll") for (int _i = 0; _i < 2; ++_i) \
;         __builtin_amdgcn_global_load_lds((const unsigned*)((const char*)(gbase) + (voff)[_i]), (PG8_LAS unsigned*)(lds + (bufoff) + ldsw + _i * 8192), 16, 0, 0); } while (0)
; #define PG8_LDA(dst, b, h) do { _Pragma("unroll") for (int m = 0; m < 4; ++m) _Pragma("unroll") for (int k = 0; k < 2; ++k) dst[m][k] = *(const PG8_LAS bf16x8*)(lds + PG8_SA(b, h) + aoff + m * 2048 + k * 1024); } while (0)
; #define PG8_LDB(dst, b, h) do { _Pragma("unroll") for (int n = 0; n < 2; ++n) _Pragma("unroll") for (int k = 0; k < 2; ++k) dst[n][k] = *(const PG8_LAS bf16x8*)(lds + PG8_SB(b, h) + boff + n * 2048 + k * 1024); } while (0)
; #define PG8_MMA(ai, bj, At, Bt) do { __builtin_amdgcn_s_setprio(1); _Pragma("unroll") for (int m = 0; m < 4; ++m) _Pragma("unroll") for (int n = 0; n < 2; ++n) _Pragma("unroll") for (int k = 0; k < 2; ++k) \
;         acc[ai][bj][m][n] = __builtin_amdgcn_mfma_f32_16x16x32_bf16(Bt[n][k], At[m][k], acc[ai][bj][m][n], 0, 0, 0); __builtin_amdgcn_s_setprio(0); } while (0)
; #define PG8_WAIT_V(n) asm volatile("s_waitcnt vmcnt(" #n ")" ::: "memory")
; #define PG8_WAIT_L(n) asm volatile("s_waitcnt lgkmcnt(" #n ")" ::: "memory")
; #define PG8_BAR __builtin_amdgcn_s_barrier()
; #define PG8_SCHED __builtin_amdgcn_sched_barrier(0)
; template <class Epi, class Sched>
; __device__ __forceinline__ void gemm_phase(PG8_LAS unsigned char* lds, const Gemm g, const Sched& S, const Epi& E) {
;     ...
;             PG8_STAGE(PG8_SB(0, 1), b2 + hstep, voffB);
;             PG8_WAIT_V(6); PG8_BAR; PG8_MMA(1, 1, At, B1); PG8_BAR;
;             PG8_LDB(B0, 1, 0); PG8_SCHED; PG8_LDA(At, 1, 0); PG8_STAGE(PG8_SA(0, 1), a2 + hstep, voffA);
;             PG8_WAIT_L(8); PG8_BAR; PG8_WAIT_L(0); PG8_MMA(0, 0, At, B0); PG8_BAR; PG8_SCHED;
;             PG8_LDB(B1, 1, 1); PG8_STAGE(PG8_SB(1, 0), b3, voffB);
;             PG8_BAR; PG8_WAIT_L(0); PG8_MMA(0, 1, At, B1); PG8_BAR;
;             PG8_LDA(At, 1, 1); PG8_STAGE(PG8_SA(1, 0), a3, voffA);
;             PG8_BAR; PG8_WAIT_L(0); PG8_MMA(1, 0, At, B0); PG8_BAR; PG8_SCHED;
	s_add_u32 s58, s26, 0x40000
	s_addc_u32 s59, s27, 0
	s_add_i32 s57, s46, s37
	v_lshl_add_u64 v[152:153], s[58:59], 0, v[130:131]
	s_mov_b32 m0, s57
	s_nop 0
	global_load_lds_dwordx4 v[152:153], off
	v_lshl_add_u64 v[152:153], s[58:59], 0, v[134:135]
	s_add_i32 m0, s57, 0x2000
	s_nop 0
	global_load_lds_dwordx4 v[152:153], off
	s_waitcnt vmcnt(6)
	s_barrier
	v_mfma_f32_16x16x32_bf16 v[52:55], v[210:213], v[168:171], v[52:55]
	v_mfma_f32_16x16x32_bf16 v[44:47], v[218:221], v[168:171], v[44:47]
	v_mfma_f32_16x16x32_bf16 v[36:39], v[210:213], v[182:185], v[36:39]
	v_mfma_f32_16x16x32_bf16 v[28:31], v[218:221], v[182:185], v[28:31]
	v_mfma_f32_16x16x32_bf16 v[20:23], v[210:213], v[194:197], v[20:23]
	v_mfma_f32_16x16x32_bf16 v[12:15], v[218:221], v[194:197], v[12:15]
	v_mfma_f32_16x16x32_bf16 v[4:7], v[210:213], v[202:205], v[4:7]
	v_mfma_f32_16x16x32_bf16 v[0:3], v[218:221], v[202:205], v[0:3]
	v_mfma_f32_16x16x32_bf16 v[52:55], v[214:217], v[172:175], v[52:55]
	v_mfma_f32_16x16x32_bf16 v[44:47], v[222:225], v[172:175], v[44:47]
	v_mfma_f32_16x16x32_bf16 v[36:39], v[214:217], v[190:193], v[36:39]
	v_mfma_f32_16x16x32_bf16 v[28:31], v[222:225], v[190:193], v[28:31]
	v_mfma_f32_16x16x32_bf16 v[20:23], v[214:217], v[198:201], v[20:23]
	v_mfma_f32_16x16x32_bf16 v[12:15], v[222:225], v[198:201], v[12:15]
	v_mfma_f32_16x16x32_bf16 v[4:7], v[214:217], v[206:209], v[4:7]
	v_mfma_f32_16x16x32_bf16 v[0:3], v[222:225], v[206:209], v[0:3]
	s_add_i32 s57, 0, 0x18000
	v_add_u32_e32 v164, s57, v147
	s_barrier
	ds_read_b128 v[152:155], v164
	ds_read_b128 v[156:159], v164 offset:1024
	ds_read_b128 v[160:163], v164 offset:2048
	ds_read_b128 v[164:167], v164 offset:3072
	s_add_u32 s28, s28, 0x40000
	s_addc_u32 s29, s29, 0
	s_mov_b32 m0, s39
	v_lshl_add_u64 v[210:211], s[28:29], 0, v[128:129]
	ds_read_b128 v[168:171], v150 offset:32768
	ds_read_b128 v[172:175], v150 offset:33792
	ds_read_b128 v[182:185], v150 offset:34816
	ds_read_b128 v[190:193], v150 offset:35840
	ds_read_b128 v[194:197], v150 offset:36864
	ds_read_b128 v[198:201], v150 offset:37888
	ds_read_b128 v[202:205], v150 offset:38912
	ds_read_b128 v[206:209], v150 offset:39936
	global_load_lds_dwordx4 v[210:211], off
	v_lshl_add_u64 v[210:211], s[28:29], 0, v[132:133]
	s_mov_b32 m0, s40
	s_nop 0
	global_load_lds_dwordx4 v[210:211], off
	s_waitcnt lgkmcnt(8)
	s_barrier
	s_waitcnt lgkmcnt(0)
	v_mfma_f32_16x16x32_bf16 v[124:127], v[152:155], v[168:171], v[124:127]
	v_mfma_f32_16x16x32_bf16 v[120:123], v[160:163], v[168:171], v[120:123]
	v_mfma_f32_16x16x32_bf16 v[108:111], v[152:155], v[182:185], v[108:111]
	v_mfma_f32_16x16x32_bf16 v[104:107], v[160:163], v[182:185], v[104:107]
	v_mfma_f32_16x16x32_bf16 v[92:95], v[152:155], v[194:197], v[92:95]
	v_mfma_f32_16x16x32_bf16 v[88:91], v[160:163], v[194:197], v[88:91]
	v_mfma_f32_16x16x32_bf16 v[76:79], v[152:155], v[202:205], v[76:79]
	v_mfma_f32_16x16x32_bf16 v[72:75], v[160:163], v[202:205], v[72:75]
	v_mfma_f32_16x16x32_bf16 v[124:127], v[156:159], v[172:175], v[124:127]
	v_mfma_f32_16x16x32_bf16 v[120:123], v[164:167], v[172:175], v[120:123]
	v_mfma_f32_16x16x32_bf16 v[108:111], v[156:159], v[190:193], v[108:111]
	v_mfma_f32_16x16x32_bf16 v[104:107], v[164:167], v[190:193], v[104:107]
	v_mfma_f32_16x16x32_bf16 v[92:95], v[156:159], v[198:201], v[92:95]
	v_mfma_f32_16x16x32_bf16 v[88:91], v[164:167], v[198:201], v[88:91]
	v_mfma_f32_16x16x32_bf16 v[76:79], v[156:159], v[206:209], v[76:79]
	v_mfma_f32_16x16x32_bf16 v[72:75], v[164:167], v[206:209], v[72:75]
	s_barrier
	s_add_i32 s28, 0, 0x1c000
	s_add_i32 s29, s57, s37
	v_add_u32_e32 v179, s28, v147
	v_lshl_add_u64 v[144:145], v[144:145], 0, s[6:7]
	s_mov_b32 m0, s29
	ds_read_b128 v[210:213], v179
	ds_read_b128 v[214:217], v179 offset:1024
	ds_read_b128 v[218:221], v179 offset:2048
	ds_read_b128 v[222:225], v179 offset:3072
	global_load_lds_dwordx4 v[144:145], off
	v_lshl_add_u64 v[144:145], v[186:187], 0, s[6:7]
	s_add_i32 m0, s29, 0x2000
	s_nop 0
	global_load_lds_dwordx4 v[144:145], off
	s_barrier
	s_waitcnt lgkmcnt(0)
	v_mfma_f32_16x16x32_bf16 v[116:119], v[210:213], v[168:171], v[116:119]
	v_mfma_f32_16x16x32_bf16 v[112:115], v[218:221], v[168:171], v[112:115]
	v_mfma_f32_16x16x32_bf16 v[100:103], v[210:213], v[182:185], v[100:103]
	v_mfma_f32_16x16x32_bf16 v[96:99], v[218:221], v[182:185], v[96:99]
	v_mfma_f32_16x16x32_bf16 v[84:87], v[210:213], v[194:197], v[84:87]
	v_mfma_f32_16x16x32_bf16 v[80:83], v[218:221], v[194:197], v[80:83]
	v_mfma_f32_16x16x32_bf16 v[68:71], v[210:213], v[202:205], v[68:71]
	v_mfma_f32_16x16x32_bf16 v[64:67], v[218:221], v[202:205], v[64:67]
	v_mfma_f32_16x16x32_bf16 v[116:119], v[214:217], v[172:175], v[116:119]
	v_mfma_f32_16x16x32_bf16 v[112:115], v[222:225], v[172:175], v[112:115]
	v_mfma_f32_16x16x32_bf16 v[100:103], v[214:217], v[190:193], v[100:103]
	v_mfma_f32_16x16x32_bf16 v[96:99], v[222:225], v[190:193], v[96:99]
	v_mfma_f32_16x16x32_bf16 v[84:87], v[214:217], v[198:201], v[84:87]
	v_mfma_f32_16x16x32_bf16 v[80:83], v[222:225], v[198:201], v[80:83]
	v_mfma_f32_16x16x32_bf16 v[68:71], v[214:217], v[206:209], v[68:71]
	v_mfma_f32_16x16x32_bf16 v[64:67], v[222:225], v[206:209], v[64:67]
	s_mov_b32 m0, s42
	v_lshl_add_u64 v[144:145], v[226:227], 0, s[6:7]
	s_barrier
	ds_read_b128 v[168:171], v150 offset:49152
	ds_read_b128 v[172:175], v150 offset:50176
	ds_read_b128 v[182:185], v150 offset:51200
	ds_read_b128 v[190:193], v150 offset:52224
	ds_read_b128 v[194:197], v150 offset:53248
	ds_read_b128 v[198:201], v150 offset:54272
	ds_read_b128 v[202:205], v150 offset:55296
	ds_read_b128 v[206:209], v150 offset:56320
	global_load_lds_dwordx4 v[144:145], off
	v_lshl_add_u64 v[144:145], v[228:229], 0, s[6:7]
	s_mov_b32 m0, s43
	s_nop 0
	global_load_lds_dwordx4 v[144:145], off
	s_barrier
; __device__ __forceinline__ unsigned cvt_pk_bf16(float lo, float hi) { unsigned r; asm volatile("v_cvt_pk_bf16_f32 %0, %1, %2" : "=v"(r) : "v"(lo), "v"(hi)); return r; }
; __device__ __forceinline__ float flogsig16(float x) { return (fminf(x, 0.f) - __logf(1.0f + __expf(-fabsf(x)))) * 0.0625f; }
; #define PG8_STAGE(bufoff, gbase, voff) do { _Pragma("unroll") for (int _i = 0; _i < 2; ++_i) \
;         __builtin_amdgcn_global_load_lds((const unsigned*)((const char*)(gbase) + (voff)[_i]), (PG8_LAS unsigned*)(lds + (bufoff) + ldsw + _i * 8192), 16, 0, 0); } while (0)
; #define PG8_WAIT_V(n) asm volatile("s_waitcnt vmcnt(" #n ")" ::: "memory")
; #define PG8_WAIT_L(n) asm volatile("s_waitcnt lgkmcnt(" #n ")" ::: "memory")
; #define PG8_BAR __builtin_amdgcn_s_barrier()
; #define PG8_SCHED __builtin_amdgcn_sched_barrier(0)
;     __device__ __forceinline__ void operator()(const f32x4 (&acc)[2][2][4][2], const Unit& u, int wr, int wc, int fr, int fq) const {
;     ...
;         for (int ai = 0; ai < 2; ++ai)
; #pragma unroll
;             for (int m = 0; m < 4; ++m) { bf16_t* rowp = O + (size_t)(row0 + ai * HALF + m * 16) * ldc + col0;
; #pragma unroll
;                 for (int bj = 0; bj < 2; ++bj) { f32x4 v0 = acc[ai][bj][m][0] + bv[bj][0], v1 = acc[ai][bj][m][1] + bv[bj][1];
;                     if (act == 1) {
; #pragma unroll
;                         for (int j = 0; j < 1; ++j) { v0 = v0 * sigmoid4(v0); v1 = v1 * sigmoid4(v1); } }
;                     else if (act == 2) {
; #pragma unroll
;                         for (int j = 0; j < 1; ++j) { v0 = sigmoid4(v0); v1 = sigmoid4(v1); } }
;                     else if (act == 3) {
; #pragma unroll
;                         for (int j = 0; j < 4; ++j) { v0[j] = flogsig16(v0[j]); v1[j] = flogsig16(v1[j]); } }
;                     u32x4 w; w.x = cvt_pk_bf16(v0[0], v0[1]); w.y = cvt_pk_bf16(v0[2], v0[3]); w.z = cvt_pk_bf16(v1[0], v1[1]); w.w = cvt_pk_bf16(v1[2], v1[3]);
;                     *(u32x4*)(rowp + bj * HALF) = w; } }
; template <class Epi, class Sched>
; __device__ __forceinline__ void gemm_phase(PG8_LAS unsigned char* lds, const Gemm g, const Sched& S, const Epi& E) {
;     ...
;             PG8_BAR; PG8_WAIT_L(0); PG8_MMA(1, 0, At, B0); PG8_BAR; PG8_SCHED;
;             PG8_STAGE(PG8_SB(1, 1), b3 + hstep, voffB);
;             PG8_WAIT_V(6); PG8_BAR; PG8_MMA(1, 1, At, B1); PG8_BAR;
	s_waitcnt lgkmcnt(0)
	v_mfma_f32_16x16x32_bf16 v[60:63], v[152:155], v[168:171], v[60:63]
	v_mfma_f32_16x16x32_bf16 v[56:59], v[160:163], v[168:171], v[56:59]
	v_mfma_f32_16x16x32_bf16 v[48:51], v[152:155], v[182:185], v[48:51]
	v_mfma_f32_16x16x32_bf16 v[40:43], v[160:163], v[182:185], v[40:43]
	v_mfma_f32_16x16x32_bf16 v[32:35], v[152:155], v[194:197], v[32:35]
	v_mfma_f32_16x16x32_bf16 v[24:27], v[160:163], v[194:197], v[24:27]
	v_mfma_f32_16x16x32_bf16 v[16:19], v[152:155], v[202:205], v[16:19]
	v_mfma_f32_16x16x32_bf16 v[8:11], v[160:163], v[202:205], v[8:11]
	v_mfma_f32_16x16x32_bf16 v[60:63], v[156:159], v[172:175], v[60:63]
	v_mfma_f32_16x16x32_bf16 v[56:59], v[164:167], v[172:175], v[56:59]
	v_mfma_f32_16x16x32_bf16 v[48:51], v[156:159], v[190:193], v[48:51]
	v_mfma_f32_16x16x32_bf16 v[40:43], v[164:167], v[190:193], v[40:43]
	v_mfma_f32_16x16x32_bf16 v[32:35], v[156:159], v[198:201], v[32:35]
	v_mfma_f32_16x16x32_bf16 v[24:27], v[164:167], v[198:201], v[24:27]
	v_mfma_f32_16x16x32_bf16 v[16:19], v[156:159], v[206:209], v[16:19]
	v_mfma_f32_16x16x32_bf16 v[8:11], v[164:167], v[206:209], v[8:11]
	s_barrier
	s_add_u32 s26, s26, 0x40080
	s_addc_u32 s27, s27, 0
	s_add_i32 s28, s28, s37
	v_lshl_add_u64 v[144:145], s[26:27], 0, v[130:131]
	s_mov_b32 m0, s28
	s_nop 0
	global_load_lds_dwordx4 v[144:145], off
	v_lshl_add_u64 v[144:145], s[26:27], 0, v[134:135]
	s_add_i32 m0, s28, 0x2000
	s_nop 0
	global_load_lds_dwordx4 v[144:145], off
	s_waitcnt vmcnt(6)
	s_barrier
	v_mfma_f32_16x16x32_bf16 v[52:55], v[210:213], v[168:171], v[52:55]
	v_mfma_f32_16x16x32_bf16 v[44:47], v[218:221], v[168:171], v[44:47]
	v_mfma_f32_16x16x32_bf16 v[36:39], v[210:213], v[182:185], v[36:39]
	v_mfma_f32_16x16x32_bf16 v[28:31], v[218:221], v[182:185], v[28:31]
	v_mfma_f32_16x16x32_bf16 v[20:23], v[210:213], v[194:197], v[20:23]
	v_mfma_f32_16x16x32_bf16 v[12:15], v[218:221], v[194:197], v[12:15]
	v_mfma_f32_16x16x32_bf16 v[4:7], v[210:213], v[202:205], v[4:7]
	v_mfma_f32_16x16x32_bf16 v[0:3], v[218:221], v[202:205], v[0:3]
	v_mfma_f32_16x16x32_bf16 v[52:55], v[214:217], v[172:175], v[52:55]
	v_mfma_f32_16x16x32_bf16 v[44:47], v[222:225], v[172:175], v[44:47]
	v_mfma_f32_16x16x32_bf16 v[36:39], v[214:217], v[190:193], v[36:39]
	v_mfma_f32_16x16x32_bf16 v[28:31], v[222:225], v[190:193], v[28:31]
	v_mfma_f32_16x16x32_bf16 v[20:23], v[214:217], v[198:201], v[20:23]
	v_mfma_f32_16x16x32_bf16 v[12:15], v[222:225], v[198:201], v[12:15]
	v_mfma_f32_16x16x32_bf16 v[4:7], v[214:217], v[206:209], v[4:7]
	v_mfma_f32_16x16x32_bf16 v[0:3], v[222:225], v[206:209], v[0:3]
	s_add_i32 s56, s56, 2
	s_add_u32 s24, s24, 0x100
	s_addc_u32 s25, s25, 0
	s_add_u32 s54, s54, 0x100
	s_addc_u32 s55, s55, 0
	s_cmp_gt_u32 s56, 13
	s_barrier
	s_cbranch_scc0 .LBB0_1083
	v_lshl_add_u32 v152, s22, 8, v146
	v_lshl_or_b32 v144, s51, 8, v148
	v_ashrrev_i32_e32 v153, 31, v152
	v_ashrrev_i32_e32 v145, 31, v144
	v_lshlrev_b64 v[154:155], 11, v[152:153]
	v_lshl_add_u64 v[154:155], s[4:5], 0, v[154:155]
	v_lshlrev_b64 v[156:157], 1, v[144:145]
	v_lshl_add_u64 v[144:145], v[154:155], 0, v[156:157]
	v_pk_add_f32 v[126:127], v[126:127], 0 op_sel_hi:[1,0]
	v_pk_add_f32 v[124:125], v[124:125], 0 op_sel_hi:[1,0]
	v_pk_add_f32 v[154:155], v[122:123], 0 op_sel_hi:[1,0]
	v_pk_add_f32 v[122:123], v[120:121], 0 op_sel_hi:[1,0]
	v_cvt_pk_bf16_f32 v120, v124, v125
	v_cvt_pk_bf16_f32 v121, v126, v127
	v_pk_add_f32 v[116:117], v[116:117], 0 op_sel_hi:[1,0]
	v_cvt_pk_bf16_f32 v122, v122, v123
	v_cvt_pk_bf16_f32 v123, v154, v155
	global_store_dwordx4 v[144:145], v[120:123], off
	v_pk_add_f32 v[118:119], v[118:119], 0 op_sel_hi:[1,0]
	v_pk_add_f32 v[110:111], v[110:111], 0 op_sel_hi:[1,0]
	v_pk_add_f32 v[120:121], v[114:115], 0 op_sel_hi:[1,0]
	v_pk_add_f32 v[114:115], v[112:113], 0 op_sel_hi:[1,0]
	v_cvt_pk_bf16_f32 v112, v116, v117
	v_cvt_pk_bf16_f32 v113, v118, v119
	v_pk_add_f32 v[108:109], v[108:109], 0 op_sel_hi:[1,0]
	v_cvt_pk_bf16_f32 v114, v114, v115
	v_cvt_pk_bf16_f32 v115, v120, v121
	global_store_dwordx4 v[144:145], v[112:115], off offset:256
	v_pk_add_f32 v[100:101], v[100:101], 0 op_sel_hi:[1,0]
	v_pk_add_f32 v[102:103], v[102:103], 0 op_sel_hi:[1,0]
	v_or_b32_e32 v112, 16, v152
	v_ashrrev_i32_e32 v113, 31, v112
	v_lshlrev_b64 v[112:113], 11, v[112:113]
	v_lshl_add_u64 v[112:113], s[4:5], 0, v[112:113]
	v_lshl_add_u64 v[112:113], v[112:113], 0, v[156:157]
	v_pk_add_f32 v[114:115], v[106:107], 0 op_sel_hi:[1,0]
	v_pk_add_f32 v[106:107], v[104:105], 0 op_sel_hi:[1,0]
	v_cvt_pk_bf16_f32 v104, v108, v109
	v_cvt_pk_bf16_f32 v105, v110, v111
	v_pk_add_f32 v[94:95], v[94:95], 0 op_sel_hi:[1,0]
	v_cvt_pk_bf16_f32 v106, v106, v107
	v_cvt_pk_bf16_f32 v107, v114, v115
	global_store_dwordx4 v[112:113], v[104:107], off
	v_pk_add_f32 v[92:93], v[92:93], 0 op_sel_hi:[1,0]
	v_pk_add_f32 v[84:85], v[84:85], 0 op_sel_hi:[1,0]
	v_pk_add_f32 v[104:105], v[98:99], 0 op_sel_hi:[1,0]
	v_pk_add_f32 v[98:99], v[96:97], 0 op_sel_hi:[1,0]
	v_cvt_pk_bf16_f32 v96, v100, v101
	v_cvt_pk_bf16_f32 v97, v102, v103
	v_pk_add_f32 v[86:87], v[86:87], 0 op_sel_hi:[1,0]
	v_cvt_pk_bf16_f32 v98, v98, v99
	v_cvt_pk_bf16_f32 v99, v104, v105
	global_store_dwordx4 v[112:113], v[96:99], off offset:256
	v_pk_add_f32 v[78:79], v[78:79], 0 op_sel_hi:[1,0]
	v_pk_add_f32 v[76:77], v[76:77], 0 op_sel_hi:[1,0]
	v_or_b32_e32 v96, 32, v152
	v_ashrrev_i32_e32 v97, 31, v96
	v_lshlrev_b64 v[96:97], 11, v[96:97]
	v_lshl_add_u64 v[96:97], s[4:5], 0, v[96:97]
; __device__ __forceinline__ unsigned cvt_pk_bf16(float lo, float hi) { unsigned r; asm volatile("v_cvt_pk_bf16_f32 %0, %1, %2" : "=v"(r) : "v"(lo), "v"(hi)); return r; }
; __device__ __forceinline__ float flogsig16(float x) { return (fminf(x, 0.f) - __logf(1.0f + __expf(-fabsf(x)))) * 0.0625f; }
; #define PG8_WAIT_V(n) asm volatile("s_waitcnt vmcnt(" #n ")" ::: "memory")
; #define PG8_BAR __builtin_amdgcn_s_barrier()
;     __device__ __forceinline__ void operator()(const f32x4 (&acc)[2][2][4][2], const Unit& u, int wr, int wc, int fr, int fq) const {
;     ...
;         for (int ai = 0; ai < 2; ++ai)
; #pragma unroll
;             for (int m = 0; m < 4; ++m) { bf16_t* rowp = O + (size_t)(row0 + ai * HALF + m * 16) * ldc + col0;
; #pragma unroll
;                 for (int bj = 0; bj < 2; ++bj) { f32x4 v0 = acc[ai][bj][m][0] + bv[bj][0], v1 = acc[ai][bj][m][1] + bv[bj][1];
;                     if (act == 1) {
; #pragma unroll
;                         for (int j = 0; j < 1; ++j) { v0 = v0 * sigmoid4(v0); v1 = v1 * sigmoid4(v1); } }
;                     else if (act == 2) {
; #pragma unroll
;                         for (int j = 0; j < 1; ++j) { v0 = sigmoid4(v0); v1 = sigmoid4(v1); } }
;                     else if (act == 3) {
; #pragma unroll
;                         for (int j = 0; j < 4; ++j) { v0[j] = flogsig16(v0[j]); v1[j] = flogsig16(v1[j]); } }
;                     u32x4 w; w.x = cvt_pk_bf16(v0[0], v0[1]); w.y = cvt_pk_bf16(v0[2], v0[3]); w.z = cvt_pk_bf16(v1[0], v1[1]); w.w = cvt_pk_bf16(v1[2], v1[3]);
;                     *(u32x4*)(rowp + bj * HALF) = w; } }
; template <class Epi, class Sched>
; __device__ __forceinline__ void gemm_phase(PG8_LAS unsigned char* lds, const Gemm g, const Sched& S, const Epi& E) {
;     ...
;         if (!has_next) break;
; #pragma unroll
;         for (int a = 0; a < 2; ++a)
; #pragma unroll
;             for (int b = 0; b < 2; ++b)
; #pragma unroll
;                 for (int m = 0; m < 4; ++m)
; #pragma unroll
;                     for (int n = 0; n < 2; ++n) acc[a][b][m][n] = (f32x4){0.f, 0.f, 0.f, 0.f};
;         cur = nxt; cA = nA; cB = nB; ++ui;
;     }
;     PG8_WAIT_V(0);
;     if (wr == 0) PG8_BAR;
	v_lshl_add_u64 v[96:97], v[96:97], 0, v[156:157]
	v_pk_add_f32 v[98:99], v[90:91], 0 op_sel_hi:[1,0]
	v_pk_add_f32 v[90:91], v[88:89], 0 op_sel_hi:[1,0]
	v_cvt_pk_bf16_f32 v88, v92, v93
	v_cvt_pk_bf16_f32 v89, v94, v95
	v_pk_add_f32 v[70:71], v[70:71], 0 op_sel_hi:[1,0]
	v_cvt_pk_bf16_f32 v90, v90, v91
	v_cvt_pk_bf16_f32 v91, v98, v99
	global_store_dwordx4 v[96:97], v[88:91], off
	v_pk_add_f32 v[68:69], v[68:69], 0 op_sel_hi:[1,0]
	v_pk_add_f32 v[60:61], v[60:61], 0 op_sel_hi:[1,0]
	v_pk_add_f32 v[88:89], v[82:83], 0 op_sel_hi:[1,0]
	v_pk_add_f32 v[82:83], v[80:81], 0 op_sel_hi:[1,0]
	v_cvt_pk_bf16_f32 v80, v84, v85
	v_cvt_pk_bf16_f32 v81, v86, v87
	v_pk_add_f32 v[62:63], v[62:63], 0 op_sel_hi:[1,0]
	v_cvt_pk_bf16_f32 v82, v82, v83
	v_cvt_pk_bf16_f32 v83, v88, v89
	global_store_dwordx4 v[96:97], v[80:83], off offset:256
	v_pk_add_f32 v[54:55], v[54:55], 0 op_sel_hi:[1,0]
	v_pk_add_f32 v[52:53], v[52:53], 0 op_sel_hi:[1,0]
	v_or_b32_e32 v80, 48, v152
	v_ashrrev_i32_e32 v81, 31, v80
	v_lshlrev_b64 v[80:81], 11, v[80:81]
	v_lshl_add_u64 v[80:81], s[4:5], 0, v[80:81]
	v_lshl_add_u64 v[80:81], v[80:81], 0, v[156:157]
	v_pk_add_f32 v[82:83], v[74:75], 0 op_sel_hi:[1,0]
	v_pk_add_f32 v[74:75], v[72:73], 0 op_sel_hi:[1,0]
	v_cvt_pk_bf16_f32 v72, v76, v77
	v_cvt_pk_bf16_f32 v73, v78, v79
	v_pk_add_f32 v[48:49], v[48:49], 0 op_sel_hi:[1,0]
	v_cvt_pk_bf16_f32 v74, v74, v75
	v_cvt_pk_bf16_f32 v75, v82, v83
	global_store_dwordx4 v[80:81], v[72:75], off
	v_pk_add_f32 v[38:39], v[38:39], 0 op_sel_hi:[1,0]
	v_pk_add_f32 v[36:37], v[36:37], 0 op_sel_hi:[1,0]
	v_pk_add_f32 v[72:73], v[66:67], 0 op_sel_hi:[1,0]
	v_pk_add_f32 v[66:67], v[64:65], 0 op_sel_hi:[1,0]
	v_cvt_pk_bf16_f32 v64, v68, v69
	v_cvt_pk_bf16_f32 v65, v70, v71
	v_pk_add_f32 v[32:33], v[32:33], 0 op_sel_hi:[1,0]
	v_cvt_pk_bf16_f32 v66, v66, v67
	v_cvt_pk_bf16_f32 v67, v72, v73
	global_store_dwordx4 v[80:81], v[64:67], off offset:256
	v_pk_add_f32 v[22:23], v[22:23], 0 op_sel_hi:[1,0]
	v_pk_add_f32 v[20:21], v[20:21], 0 op_sel_hi:[1,0]
	v_pk_add_f32 v[66:67], v[58:59], 0 op_sel_hi:[1,0]
	v_pk_add_f32 v[58:59], v[56:57], 0 op_sel_hi:[1,0]
	v_cvt_pk_bf16_f32 v56, v60, v61
	v_add_co_u32_e32 v60, vcc, s47, v144
	v_cvt_pk_bf16_f32 v57, v62, v63
	v_cvt_pk_bf16_f32 v58, v58, v59
	v_cvt_pk_bf16_f32 v59, v66, v67
	v_lshl_add_u64 v[64:65], v[144:145], 0, s[0:1]
	s_nop 0
	v_addc_co_u32_e32 v61, vcc, 0, v145, vcc
	global_store_dwordx4 v[60:61], v[56:59], off
	v_pk_add_f32 v[16:17], v[16:17], 0 op_sel_hi:[1,0]
	s_mov_b32 s51, s14
	v_pk_add_f32 v[56:57], v[46:47], 0 op_sel_hi:[1,0]
	v_pk_add_f32 v[46:47], v[44:45], 0 op_sel_hi:[1,0]
	v_cvt_pk_bf16_f32 v44, v52, v53
	v_cvt_pk_bf16_f32 v45, v54, v55
	s_mov_b32 s22, s16
	v_cvt_pk_bf16_f32 v46, v46, v47
	v_cvt_pk_bf16_f32 v47, v56, v57
	global_store_dwordx4 v[64:65], v[44:47], off offset:256
	s_mov_b64 s[26:27], s[20:21]
	s_mov_b64 s[24:25], s[18:19]
	v_pk_add_f32 v[46:47], v[50:51], 0 op_sel_hi:[1,0]
	v_pk_add_f32 v[50:51], v[42:43], 0 op_sel_hi:[1,0]
	v_pk_add_f32 v[42:43], v[40:41], 0 op_sel_hi:[1,0]
	v_cvt_pk_bf16_f32 v40, v48, v49
	v_cvt_pk_bf16_f32 v41, v46, v47
	v_add_co_u32_e32 v46, vcc, s48, v144
	v_cvt_pk_bf16_f32 v42, v42, v43
	v_cvt_pk_bf16_f32 v43, v50, v51
	v_lshl_add_u64 v[44:45], v[144:145], 0, s[8:9]
	s_nop 0
	v_addc_co_u32_e32 v47, vcc, 0, v145, vcc
	global_store_dwordx4 v[46:47], v[40:43], off
	v_pk_add_f32 v[6:7], v[6:7], 0 op_sel_hi:[1,0]
	v_pk_add_f32 v[4:5], v[4:5], 0 op_sel_hi:[1,0]
	v_pk_add_f32 v[40:41], v[30:31], 0 op_sel_hi:[1,0]
	v_pk_add_f32 v[30:31], v[28:29], 0 op_sel_hi:[1,0]
	v_cvt_pk_bf16_f32 v28, v36, v37
	v_cvt_pk_bf16_f32 v29, v38, v39
	s_nop 0
	v_cvt_pk_bf16_f32 v30, v30, v31
	v_cvt_pk_bf16_f32 v31, v40, v41
	global_store_dwordx4 v[44:45], v[28:31], off offset:256
	s_nop 1
	v_pk_add_f32 v[30:31], v[34:35], 0 op_sel_hi:[1,0]
	v_pk_add_f32 v[34:35], v[26:27], 0 op_sel_hi:[1,0]
	v_pk_add_f32 v[26:27], v[24:25], 0 op_sel_hi:[1,0]
	v_cvt_pk_bf16_f32 v24, v32, v33
	v_cvt_pk_bf16_f32 v25, v30, v31
	v_add_co_u32_e32 v30, vcc, s49, v144
	v_cvt_pk_bf16_f32 v26, v26, v27
	v_cvt_pk_bf16_f32 v27, v34, v35
	v_lshl_add_u64 v[28:29], v[144:145], 0, s[10:11]
	s_nop 0
	v_addc_co_u32_e32 v31, vcc, 0, v145, vcc
	global_store_dwordx4 v[30:31], v[24:27], off
	s_nop 1
	v_pk_add_f32 v[24:25], v[14:15], 0 op_sel_hi:[1,0]
	v_pk_add_f32 v[14:15], v[12:13], 0 op_sel_hi:[1,0]
	v_cvt_pk_bf16_f32 v12, v20, v21
	v_cvt_pk_bf16_f32 v13, v22, v23
	s_nop 0
	v_cvt_pk_bf16_f32 v14, v14, v15
	v_cvt_pk_bf16_f32 v15, v24, v25
	global_store_dwordx4 v[28:29], v[12:15], off offset:256
	s_nop 1
	v_pk_add_f32 v[14:15], v[18:19], 0 op_sel_hi:[1,0]
	v_pk_add_f32 v[18:19], v[10:11], 0 op_sel_hi:[1,0]
	v_pk_add_f32 v[10:11], v[8:9], 0 op_sel_hi:[1,0]
	v_cvt_pk_bf16_f32 v8, v16, v17
	v_cvt_pk_bf16_f32 v9, v14, v15
	v_add_co_u32_e32 v14, vcc, s50, v144
	v_lshl_add_u64 v[12:13], v[144:145], 0, s[12:13]
	s_nop 0
	v_addc_co_u32_e32 v15, vcc, 0, v145, vcc
	v_cvt_pk_bf16_f32 v10, v10, v11
	v_cvt_pk_bf16_f32 v11, v18, v19
	global_store_dwordx4 v[14:15], v[8:11], off
	s_and_b64 vcc, exec, s[2:3]
	s_nop 0
	v_pk_add_f32 v[8:9], v[2:3], 0 op_sel_hi:[1,0]
	v_pk_add_f32 v[2:3], v[0:1], 0 op_sel_hi:[1,0]
	v_cvt_pk_bf16_f32 v0, v4, v5
	v_cvt_pk_bf16_f32 v1, v6, v7
	s_nop 0
	v_cvt_pk_bf16_f32 v2, v2, v3
	v_cvt_pk_bf16_f32 v3, v8, v9
	global_store_dwordx4 v[12:13], v[0:3], off offset:256
	s_cbranch_vccz .LBB0_1076
	s_waitcnt vmcnt(0)
	s_cmpk_gt_u32 s31, 0xff
	s_cbranch_scc1 .LBB0_1087
	s_barrier

; #define PG8_STAGE(bufoff, gbase, voff) do { _Pragma("unroll") for (int _i = 0; _i < 2; ++_i) \
;         __builtin_amdgcn_global_load_lds((const unsigned*)((const char*)(gbase) + (voff)[_i]), (PG8_LAS unsigned*)(lds + (bufoff) + ldsw + _i * 8192), 16, 0, 0); } while (0)
; #define PG8_LDA(dst, b, h) do { _Pragma("unroll") for (int m = 0; m < 4; ++m) _Pragma("unroll") for (int k = 0; k < 2; ++k) dst[m][k] = *(const PG8_LAS bf16x8*)(lds + PG8_SA(b, h) + aoff + m * 2048 + k * 1024); } while (0)
; #define PG8_LDB(dst, b, h) do { _Pragma("unroll") for (int n = 0; n < 2; ++n) _Pragma("unroll") for (int k = 0; k < 2; ++k) dst[n][k] = *(const PG8_LAS bf16x8*)(lds + PG8_SB(b, h) + boff + n * 2048 + k * 1024); } while (0)
; #define PG8_MMA(ai, bj, At, Bt) do { __builtin_amdgcn_s_setprio(1); _Pragma("unroll") for (int m = 0; m < 4; ++m) _Pragma("unroll") for (int n = 0; n < 2; ++n) _Pragma("unroll") for (int k = 0; k < 2; ++k) \
;         acc[ai][bj][m][n] = __builtin_amdgcn_mfma_f32_16x16x32_bf16(Bt[n][k], At[m][k], acc[ai][bj][m][n], 0, 0, 0); __builtin_amdgcn_s_setprio(0); } while (0)
; #define PG8_WAIT_L(n) asm volatile("s_waitcnt lgkmcnt(" #n ")" ::: "memory")
; #define PG8_BAR __builtin_amdgcn_s_barrier()
; #define PG8_SCHED __builtin_amdgcn_sched_barrier(0)
; template <class Epi, class Sched>
; __device__ __forceinline__ void gemm_phase(PG8_LAS unsigned char* lds, const Gemm g, const Sched& S, const Epi& E) {
;     ...
;             PG8_LDB(B0, 0, 0); PG8_SCHED; PG8_LDA(At, 0, 0); PG8_STAGE(PG8_SA(1, 1), a1 + hstep, voffA);
;             PG8_WAIT_L(8); PG8_BAR; PG8_WAIT_L(0); PG8_MMA(0, 0, At, B0); PG8_BAR; PG8_SCHED;
;             PG8_LDB(B1, 0, 1); PG8_STAGE(PG8_SB(0, 0), b2, voffB);
;             PG8_BAR; PG8_WAIT_L(0); PG8_MMA(0, 1, At, B1); PG8_BAR;
;             PG8_LDA(At, 0, 1); PG8_STAGE(PG8_SA(0, 0), a2, voffA);
;             PG8_BAR; PG8_WAIT_L(0); PG8_MMA(1, 0, At, B0); PG8_BAR; PG8_SCHED;
.LBB0_1202:
	ds_read_b128 v[144:147], v151
	ds_read_b128 v[154:157], v151 offset:1024
	ds_read_b128 v[158:161], v151 offset:2048
	ds_read_b128 v[162:165], v151 offset:3072
	s_add_u32 s18, s16, 0xfffc0080
	s_addc_u32 s19, s17, -1
	s_cmp_eq_u32 s46, 12
	s_cselect_b32 s21, s9, s19
	s_cselect_b32 s20, s42, s18
	s_cselect_b32 s19, s7, s45
	s_cselect_b32 s18, s43, s44
	v_lshl_add_u64 v[174:175], s[16:17], 0, v[136:137]
	s_add_i32 m0, s15, 0xc000
	ds_read_b128 v[166:169], v152
	ds_read_b128 v[170:173], v152 offset:1024
	ds_read_b128 v[182:185], v152 offset:2048
	ds_read_b128 v[190:193], v152 offset:3072
	ds_read_b128 v[194:197], v152 offset:4096
	ds_read_b128 v[198:201], v152 offset:5120
	ds_read_b128 v[202:205], v152 offset:6144
	ds_read_b128 v[206:209], v152 offset:7168
	global_load_lds_dwordx4 v[174:175], off
	v_lshl_add_u64 v[174:175], s[16:17], 0, v[138:139]
	s_add_i32 m0, s15, 0xe000
	s_nop 0
	global_load_lds_dwordx4 v[174:175], off
	s_waitcnt lgkmcnt(8)
	s_barrier
	s_waitcnt lgkmcnt(0)
	v_mfma_f32_16x16x32_bf16 v[124:127], v[144:147], v[166:169], v[124:127]
	v_mfma_f32_16x16x32_bf16 v[120:123], v[158:161], v[166:169], v[120:123]
	v_mfma_f32_16x16x32_bf16 v[108:111], v[144:147], v[182:185], v[108:111]
	v_mfma_f32_16x16x32_bf16 v[104:107], v[158:161], v[182:185], v[104:107]
	v_mfma_f32_16x16x32_bf16 v[92:95], v[144:147], v[194:197], v[92:95]
	v_mfma_f32_16x16x32_bf16 v[88:91], v[158:161], v[194:197], v[88:91]
	v_mfma_f32_16x16x32_bf16 v[76:79], v[144:147], v[202:205], v[76:79]
	v_mfma_f32_16x16x32_bf16 v[72:75], v[158:161], v[202:205], v[72:75]
	v_mfma_f32_16x16x32_bf16 v[124:127], v[154:157], v[170:173], v[124:127]
	v_mfma_f32_16x16x32_bf16 v[120:123], v[162:165], v[170:173], v[120:123]
	v_mfma_f32_16x16x32_bf16 v[108:111], v[154:157], v[190:193], v[108:111]
	v_mfma_f32_16x16x32_bf16 v[104:107], v[162:165], v[190:193], v[104:107]
	v_mfma_f32_16x16x32_bf16 v[92:95], v[154:157], v[198:201], v[92:95]
	v_mfma_f32_16x16x32_bf16 v[88:91], v[162:165], v[198:201], v[88:91]
	v_mfma_f32_16x16x32_bf16 v[76:79], v[154:157], v[206:209], v[76:79]
	v_mfma_f32_16x16x32_bf16 v[72:75], v[162:165], v[206:209], v[72:75]
	s_barrier
	s_add_i32 s47, s38, s26
	v_lshl_add_u64 v[174:175], s[18:19], 0, v[132:133]
	s_mov_b32 m0, s47
	ds_read_b128 v[210:213], v153
	ds_read_b128 v[214:217], v153 offset:1024
	ds_read_b128 v[218:221], v153 offset:2048
	ds_read_b128 v[222:225], v153 offset:3072
	global_load_lds_dwordx4 v[174:175], off
	v_lshl_add_u64 v[186:187], s[18:19], 0, v[128:129]
	s_add_i32 m0, s47, 0x2000
	s_nop 0
	global_load_lds_dwordx4 v[186:187], off
	s_barrier
	s_waitcnt lgkmcnt(0)
	v_mfma_f32_16x16x32_bf16 v[116:119], v[210:213], v[166:169], v[116:119]
	v_mfma_f32_16x16x32_bf16 v[112:115], v[218:221], v[166:169], v[112:115]
	v_mfma_f32_16x16x32_bf16 v[100:103], v[210:213], v[182:185], v[100:103]
	v_mfma_f32_16x16x32_bf16 v[96:99], v[218:221], v[182:185], v[96:99]
	v_mfma_f32_16x16x32_bf16 v[84:87], v[210:213], v[194:197], v[84:87]
	v_mfma_f32_16x16x32_bf16 v[80:83], v[218:221], v[194:197], v[80:83]
	v_mfma_f32_16x16x32_bf16 v[68:71], v[210:213], v[202:205], v[68:71]
	v_mfma_f32_16x16x32_bf16 v[64:67], v[218:221], v[202:205], v[64:67]
	v_mfma_f32_16x16x32_bf16 v[116:119], v[214:217], v[170:173], v[116:119]
	v_mfma_f32_16x16x32_bf16 v[112:115], v[222:225], v[170:173], v[112:115]
	v_mfma_f32_16x16x32_bf16 v[100:103], v[214:217], v[190:193], v[100:103]
	v_mfma_f32_16x16x32_bf16 v[96:99], v[222:225], v[190:193], v[96:99]
	v_mfma_f32_16x16x32_bf16 v[84:87], v[214:217], v[198:201], v[84:87]
	v_mfma_f32_16x16x32_bf16 v[80:83], v[222:225], v[198:201], v[80:83]
	v_mfma_f32_16x16x32_bf16 v[68:71], v[214:217], v[206:209], v[68:71]
	v_mfma_f32_16x16x32_bf16 v[64:67], v[222:225], v[206:209], v[64:67]
	s_mov_b32 m0, s15
	v_lshl_add_u64 v[226:227], s[20:21], 0, v[134:135]
	s_barrier
	ds_read_b128 v[166:169], v152 offset:16384
	ds_read_b128 v[170:173], v152 offset:17408
	ds_read_b128 v[182:185], v152 offset:18432
	ds_read_b128 v[190:193], v152 offset:19456
	ds_read_b128 v[194:197], v152 offset:20480
	ds_read_b128 v[198:201], v152 offset:21504
	ds_read_b128 v[202:205], v152 offset:22528
	ds_read_b128 v[206:209], v152 offset:23552
	global_load_lds_dwordx4 v[226:227], off
	v_lshl_add_u64 v[228:229], s[20:21], 0, v[130:131]
	s_mov_b32 m0, s29
	s_nop 0
	global_load_lds_dwordx4 v[228:229], off
	s_barrier
	s_waitcnt lgkmcnt(0)
	v_mfma_f32_16x16x32_bf16 v[60:63], v[144:147], v[166:169], v[60:63]
	v_mfma_f32_16x16x32_bf16 v[56:59], v[158:161], v[166:169], v[56:59]
	v_mfma_f32_16x16x32_bf16 v[44:47], v[144:147], v[182:185], v[44:47]
	v_mfma_f32_16x16x32_bf16 v[40:43], v[158:161], v[182:185], v[40:43]
	v_mfma_f32_16x16x32_bf16 v[28:31], v[144:147], v[194:197], v[28:31]
	v_mfma_f32_16x16x32_bf16 v[24:27], v[158:161], v[194:197], v[24:27]
	v_mfma_f32_16x16x32_bf16 v[12:15], v[144:147], v[202:205], v[12:15]
	v_mfma_f32_16x16x32_bf16 v[8:11], v[158:161], v[202:205], v[8:11]
	v_mfma_f32_16x16x32_bf16 v[60:63], v[154:157], v[170:173], v[60:63]
	v_mfma_f32_16x16x32_bf16 v[56:59], v[162:165], v[170:173], v[56:59]
	v_mfma_f32_16x16x32_bf16 v[44:47], v[154:157], v[190:193], v[44:47]
	v_mfma_f32_16x16x32_bf16 v[40:43], v[162:165], v[190:193], v[40:43]
	v_mfma_f32_16x16x32_bf16 v[28:31], v[154:157], v[198:201], v[28:31]
	v_mfma_f32_16x16x32_bf16 v[24:27], v[162:165], v[198:201], v[24:27]
	v_mfma_f32_16x16x32_bf16 v[12:15], v[154:157], v[206:209], v[12:15]
	v_mfma_f32_16x16x32_bf16 v[8:11], v[162:165], v[206:209], v[8:11]
	s_barrier
; #define PG8_STAGE(bufoff, gbase, voff) do { _Pragma("unroll") for (int _i = 0; _i < 2; ++_i) \
;         __builtin_amdgcn_global_load_lds((const unsigned*)((const char*)(gbase) + (voff)[_i]), (PG8_LAS unsigned*)(lds + (bufoff) + ldsw + _i * 8192), 16, 0, 0); } while (0)
; #define PG8_LDA(dst, b, h) do { _Pragma("unroll") for (int m = 0; m < 4; ++m) _Pragma("unroll") for (int k = 0; k < 2; ++k) dst[m][k] = *(const PG8_LAS bf16x8*)(lds + PG8_SA(b, h) + aoff + m * 2048 + k * 1024); } while (0)
; #define PG8_LDB(dst, b, h) do { _Pragma("unroll") for (int n = 0; n < 2; ++n) _Pragma("unroll") for (int k = 0; k < 2; ++k) dst[n][k] = *(const PG8_LAS bf16x8*)(lds + PG8_SB(b, h) + boff + n * 2048 + k * 1024); } while (0)
; #define PG8_MMA(ai, bj, At, Bt) do { __builtin_amdgcn_s_setprio(1); _Pragma("unroll") for (int m = 0; m < 4; ++m) _Pragma("unroll") for (int n = 0; n < 2; ++n) _Pragma("unroll") for (int k = 0; k < 2; ++k) \
;         acc[ai][bj][m][n] = __builtin_amdgcn_mfma_f32_16x16x32_bf16(Bt[n][k], At[m][k], acc[ai][bj][m][n], 0, 0, 0); __builtin_amdgcn_s_setprio(0); } while (0)
; #define PG8_WAIT_V(n) asm volatile("s_waitcnt vmcnt(" #n ")" ::: "memory")
; #define PG8_WAIT_L(n) asm volatile("s_waitcnt lgkmcnt(" #n ")" ::: "memory")
; #define PG8_BAR __builtin_amdgcn_s_barrier()
; #define PG8_SCHED __builtin_amdgcn_sched_barrier(0)
; template <class Epi, class Sched>
; __device__ __forceinline__ void gemm_phase(PG8_LAS unsigned char* lds, const Gemm g, const Sched& S, const Epi& E) {
;     ...
;             PG8_STAGE(PG8_SB(0, 1), b2 + hstep, voffB);
;             PG8_WAIT_V(6); PG8_BAR; PG8_MMA(1, 1, At, B1); PG8_BAR;
;             PG8_LDB(B0, 1, 0); PG8_SCHED; PG8_LDA(At, 1, 0); PG8_STAGE(PG8_SA(0, 1), a2 + hstep, voffA);
;             PG8_WAIT_L(8); PG8_BAR; PG8_WAIT_L(0); PG8_MMA(0, 0, At, B0); PG8_BAR; PG8_SCHED;
;             PG8_LDB(B1, 1, 1); PG8_STAGE(PG8_SB(1, 0), b3, voffB);
;             PG8_BAR; PG8_WAIT_L(0); PG8_MMA(0, 1, At, B1); PG8_BAR;
;             PG8_LDA(At, 1, 1); PG8_STAGE(PG8_SA(1, 0), a3, voffA);
	s_add_u32 s48, s18, 0x40000
	s_addc_u32 s49, s19, 0
	s_add_i32 s47, s39, s26
	v_lshl_add_u64 v[144:145], s[48:49], 0, v[132:133]
	s_mov_b32 m0, s47
	s_nop 0
	global_load_lds_dwordx4 v[144:145], off
	v_lshl_add_u64 v[144:145], s[48:49], 0, v[128:129]
	s_add_i32 m0, s47, 0x2000
	s_nop 0
	global_load_lds_dwordx4 v[144:145], off
	s_waitcnt vmcnt(6)
	s_barrier
	v_mfma_f32_16x16x32_bf16 v[52:55], v[210:213], v[166:169], v[52:55]
	v_mfma_f32_16x16x32_bf16 v[48:51], v[218:221], v[166:169], v[48:51]
	v_mfma_f32_16x16x32_bf16 v[36:39], v[210:213], v[182:185], v[36:39]
	v_mfma_f32_16x16x32_bf16 v[32:35], v[218:221], v[182:185], v[32:35]
	v_mfma_f32_16x16x32_bf16 v[20:23], v[210:213], v[194:197], v[20:23]
	v_mfma_f32_16x16x32_bf16 v[16:19], v[218:221], v[194:197], v[16:19]
	v_mfma_f32_16x16x32_bf16 v[4:7], v[210:213], v[202:205], v[4:7]
	v_mfma_f32_16x16x32_bf16 v[0:3], v[218:221], v[202:205], v[0:3]
	v_mfma_f32_16x16x32_bf16 v[52:55], v[214:217], v[170:173], v[52:55]
	v_mfma_f32_16x16x32_bf16 v[48:51], v[222:225], v[170:173], v[48:51]
	v_mfma_f32_16x16x32_bf16 v[36:39], v[214:217], v[190:193], v[36:39]
	v_mfma_f32_16x16x32_bf16 v[32:35], v[222:225], v[190:193], v[32:35]
	v_mfma_f32_16x16x32_bf16 v[20:23], v[214:217], v[198:201], v[20:23]
	v_mfma_f32_16x16x32_bf16 v[16:19], v[222:225], v[198:201], v[16:19]
	v_mfma_f32_16x16x32_bf16 v[4:7], v[214:217], v[206:209], v[4:7]
	v_mfma_f32_16x16x32_bf16 v[0:3], v[222:225], v[206:209], v[0:3]
	s_add_i32 s47, 0, 0x18000
	v_add_u32_e32 v162, s47, v149
	s_barrier
	ds_read_b128 v[144:147], v162
	ds_read_b128 v[154:157], v162 offset:1024
	ds_read_b128 v[158:161], v162 offset:2048
	ds_read_b128 v[162:165], v162 offset:3072
	s_add_u32 s20, s20, 0x40000
	s_addc_u32 s21, s21, 0
	s_mov_b32 m0, s30
	v_lshl_add_u64 v[210:211], s[20:21], 0, v[134:135]
	ds_read_b128 v[166:169], v152 offset:32768
	ds_read_b128 v[170:173], v152 offset:33792
	ds_read_b128 v[182:185], v152 offset:34816
	ds_read_b128 v[190:193], v152 offset:35840
	ds_read_b128 v[194:197], v152 offset:36864
	ds_read_b128 v[198:201], v152 offset:37888
	ds_read_b128 v[202:205], v152 offset:38912
	ds_read_b128 v[206:209], v152 offset:39936
	global_load_lds_dwordx4 v[210:211], off
	v_lshl_add_u64 v[210:211], s[20:21], 0, v[130:131]
	s_mov_b32 m0, s31
	s_nop 0
	global_load_lds_dwordx4 v[210:211], off
	s_waitcnt lgkmcnt(8)
	s_barrier
	s_waitcnt lgkmcnt(0)
	v_mfma_f32_16x16x32_bf16 v[124:127], v[144:147], v[166:169], v[124:127]
	v_mfma_f32_16x16x32_bf16 v[120:123], v[158:161], v[166:169], v[120:123]
	v_mfma_f32_16x16x32_bf16 v[108:111], v[144:147], v[182:185], v[108:111]
	v_mfma_f32_16x16x32_bf16 v[104:107], v[158:161], v[182:185], v[104:107]
	v_mfma_f32_16x16x32_bf16 v[92:95], v[144:147], v[194:197], v[92:95]
	v_mfma_f32_16x16x32_bf16 v[88:91], v[158:161], v[194:197], v[88:91]
	v_mfma_f32_16x16x32_bf16 v[76:79], v[144:147], v[202:205], v[76:79]
	v_mfma_f32_16x16x32_bf16 v[72:75], v[158:161], v[202:205], v[72:75]
	v_mfma_f32_16x16x32_bf16 v[124:127], v[154:157], v[170:173], v[124:127]
	v_mfma_f32_16x16x32_bf16 v[120:123], v[162:165], v[170:173], v[120:123]
	v_mfma_f32_16x16x32_bf16 v[108:111], v[154:157], v[190:193], v[108:111]
	v_mfma_f32_16x16x32_bf16 v[104:107], v[162:165], v[190:193], v[104:107]
	v_mfma_f32_16x16x32_bf16 v[92:95], v[154:157], v[198:201], v[92:95]
	v_mfma_f32_16x16x32_bf16 v[88:91], v[162:165], v[198:201], v[88:91]
	v_mfma_f32_16x16x32_bf16 v[76:79], v[154:157], v[206:209], v[76:79]
	v_mfma_f32_16x16x32_bf16 v[72:75], v[162:165], v[206:209], v[72:75]
	s_barrier
	s_add_i32 s20, 0, 0x1c000
	s_add_i32 s21, s47, s26
	v_add_u32_e32 v179, s20, v149
	v_lshl_add_u64 v[174:175], v[174:175], 0, s[4:5]
	s_mov_b32 m0, s21
	ds_read_b128 v[210:213], v179
	ds_read_b128 v[214:217], v179 offset:1024
	ds_read_b128 v[218:221], v179 offset:2048
	ds_read_b128 v[222:225], v179 offset:3072
	global_load_lds_dwordx4 v[174:175], off
	v_lshl_add_u64 v[174:175], v[186:187], 0, s[4:5]
	s_add_i32 m0, s21, 0x2000
	s_nop 0
	global_load_lds_dwordx4 v[174:175], off
	s_barrier
	s_waitcnt lgkmcnt(0)
	v_mfma_f32_16x16x32_bf16 v[116:119], v[210:213], v[166:169], v[116:119]
	v_mfma_f32_16x16x32_bf16 v[112:115], v[218:221], v[166:169], v[112:115]
	v_mfma_f32_16x16x32_bf16 v[100:103], v[210:213], v[182:185], v[100:103]
	v_mfma_f32_16x16x32_bf16 v[96:99], v[218:221], v[182:185], v[96:99]
	v_mfma_f32_16x16x32_bf16 v[84:87], v[210:213], v[194:197], v[84:87]
	v_mfma_f32_16x16x32_bf16 v[80:83], v[218:221], v[194:197], v[80:83]
	v_mfma_f32_16x16x32_bf16 v[68:71], v[210:213], v[202:205], v[68:71]
	v_mfma_f32_16x16x32_bf16 v[64:67], v[218:221], v[202:205], v[64:67]
	v_mfma_f32_16x16x32_bf16 v[116:119], v[214:217], v[170:173], v[116:119]
	v_mfma_f32_16x16x32_bf16 v[112:115], v[222:225], v[170:173], v[112:115]
	v_mfma_f32_16x16x32_bf16 v[100:103], v[214:217], v[190:193], v[100:103]
	v_mfma_f32_16x16x32_bf16 v[96:99], v[222:225], v[190:193], v[96:99]
	v_mfma_f32_16x16x32_bf16 v[84:87], v[214:217], v[198:201], v[84:87]
	v_mfma_f32_16x16x32_bf16 v[80:83], v[222:225], v[198:201], v[80:83]
	v_mfma_f32_16x16x32_bf16 v[68:71], v[214:217], v[206:209], v[68:71]
	v_mfma_f32_16x16x32_bf16 v[64:67], v[222:225], v[206:209], v[64:67]
	s_mov_b32 m0, s35
	v_lshl_add_u64 v[174:175], v[226:227], 0, s[4:5]
	s_barrier
	ds_read_b128 v[166:169], v152 offset:49152
	ds_read_b128 v[170:173], v152 offset:50176
	ds_read_b128 v[182:185], v152 offset:51200
	ds_read_b128 v[190:193], v152 offset:52224
	ds_read_b128 v[194:197], v152 offset:53248
	ds_read_b128 v[198:201], v152 offset:54272
	ds_read_b128 v[202:205], v152 offset:55296
	ds_read_b128 v[206:209], v152 offset:56320
	global_load_lds_dwordx4 v[174:175], off
	v_lshl_add_u64 v[174:175], v[228:229], 0, s[4:5]
	s_mov_b32 m0, s36
	s_nop 0
	global_load_lds_dwordx4 v[174:175], off
	s_barrier
; __device__ __forceinline__ unsigned cvt_pk_bf16(float lo, float hi) { unsigned r; asm volatile("v_cvt_pk_bf16_f32 %0, %1, %2" : "=v"(r) : "v"(lo), "v"(hi)); return r; }
; #define PG8_STAGE(bufoff, gbase, voff) do { _Pragma("unroll") for (int _i = 0; _i < 2; ++_i) \
;         __builtin_amdgcn_global_load_lds((const unsigned*)((const char*)(gbase) + (voff)[_i]), (PG8_LAS unsigned*)(lds + (bufoff) + ldsw + _i * 8192), 16, 0, 0); } while (0)
; #define PG8_MMA(ai, bj, At, Bt) do { __builtin_amdgcn_s_setprio(1); _Pragma("unroll") for (int m = 0; m < 4; ++m) _Pragma("unroll") for (int n = 0; n < 2; ++n) _Pragma("unroll") for (int k = 0; k < 2; ++k) \
;         acc[ai][bj][m][n] = __builtin_amdgcn_mfma_f32_16x16x32_bf16(Bt[n][k], At[m][k], acc[ai][bj][m][n], 0, 0, 0); __builtin_amdgcn_s_setprio(0); } while (0)
; #define PG8_WAIT_V(n) asm volatile("s_waitcnt vmcnt(" #n ")" ::: "memory")
; #define PG8_WAIT_L(n) asm volatile("s_waitcnt lgkmcnt(" #n ")" ::: "memory")
; #define PG8_BAR __builtin_amdgcn_s_barrier()
; #define PG8_SCHED __builtin_amdgcn_sched_barrier(0)
;     __device__ __forceinline__ void operator()(const f32x4 (&acc)[2][2][4][2], const Unit& u, int wr, int wc, int fr, int fq) const {
;     ...
;             for (int m = 0; m < 4; ++m) { bf16_t* rowp = O + (size_t)(row0 + ai * HALF + m * 16) * ldc + col0;
;                 f32x4 v0, v1;
; #pragma unroll
;                 for (int j = 0; j < 1; ++j) { v0 = acc[ai][0][m][0] * sigmoid4(acc[ai][0][m][0]) * acc[ai][1][m][0]; v1 = acc[ai][0][m][1] * sigmoid4(acc[ai][0][m][1]) * acc[ai][1][m][1]; }
;                 u32x4 w; w.x = cvt_pk_bf16(v0[0], v0[1]); w.y = cvt_pk_bf16(v0[2], v0[3]); w.z = cvt_pk_bf16(v1[0], v1[1]); w.w = cvt_pk_bf16(v1[2], v1[3]);
; template <class Epi, class Sched>
; __device__ __forceinline__ void gemm_phase(PG8_LAS unsigned char* lds, const Gemm g, const Sched& S, const Epi& E) {
;     ...
;             PG8_BAR; PG8_WAIT_L(0); PG8_MMA(1, 0, At, B0); PG8_BAR; PG8_SCHED;
;             PG8_STAGE(PG8_SB(1, 1), b3 + hstep, voffB);
;             PG8_WAIT_V(6); PG8_BAR; PG8_MMA(1, 1, At, B1); PG8_BAR;
	s_waitcnt lgkmcnt(0)
	v_mfma_f32_16x16x32_bf16 v[60:63], v[144:147], v[166:169], v[60:63]
	v_mfma_f32_16x16x32_bf16 v[56:59], v[158:161], v[166:169], v[56:59]
	v_mfma_f32_16x16x32_bf16 v[44:47], v[144:147], v[182:185], v[44:47]
	v_mfma_f32_16x16x32_bf16 v[40:43], v[158:161], v[182:185], v[40:43]
	v_mfma_f32_16x16x32_bf16 v[28:31], v[144:147], v[194:197], v[28:31]
	v_mfma_f32_16x16x32_bf16 v[24:27], v[158:161], v[194:197], v[24:27]
	v_mfma_f32_16x16x32_bf16 v[12:15], v[144:147], v[202:205], v[12:15]
	v_mfma_f32_16x16x32_bf16 v[8:11], v[158:161], v[202:205], v[8:11]
	v_mfma_f32_16x16x32_bf16 v[60:63], v[154:157], v[170:173], v[60:63]
	v_mfma_f32_16x16x32_bf16 v[56:59], v[162:165], v[170:173], v[56:59]
	v_mfma_f32_16x16x32_bf16 v[44:47], v[154:157], v[190:193], v[44:47]
	v_mfma_f32_16x16x32_bf16 v[40:43], v[162:165], v[190:193], v[40:43]
	v_mfma_f32_16x16x32_bf16 v[28:31], v[154:157], v[198:201], v[28:31]
	v_mfma_f32_16x16x32_bf16 v[24:27], v[162:165], v[198:201], v[24:27]
	v_mfma_f32_16x16x32_bf16 v[12:15], v[154:157], v[206:209], v[12:15]
	v_mfma_f32_16x16x32_bf16 v[8:11], v[162:165], v[206:209], v[8:11]
	s_barrier
	s_add_u32 s18, s18, 0x40080
	s_addc_u32 s19, s19, 0
	s_add_i32 s20, s20, s26
	v_lshl_add_u64 v[144:145], s[18:19], 0, v[132:133]
	s_mov_b32 m0, s20
	s_nop 0
	global_load_lds_dwordx4 v[144:145], off
	v_lshl_add_u64 v[144:145], s[18:19], 0, v[128:129]
	s_add_i32 m0, s20, 0x2000
	s_nop 0
	global_load_lds_dwordx4 v[144:145], off
	s_waitcnt vmcnt(6)
	s_barrier
	v_mfma_f32_16x16x32_bf16 v[52:55], v[210:213], v[166:169], v[52:55]
	v_mfma_f32_16x16x32_bf16 v[48:51], v[218:221], v[166:169], v[48:51]
	v_mfma_f32_16x16x32_bf16 v[36:39], v[210:213], v[182:185], v[36:39]
	v_mfma_f32_16x16x32_bf16 v[32:35], v[218:221], v[182:185], v[32:35]
	v_mfma_f32_16x16x32_bf16 v[20:23], v[210:213], v[194:197], v[20:23]
	v_mfma_f32_16x16x32_bf16 v[16:19], v[218:221], v[194:197], v[16:19]
	v_mfma_f32_16x16x32_bf16 v[4:7], v[210:213], v[202:205], v[4:7]
	v_mfma_f32_16x16x32_bf16 v[0:3], v[218:221], v[202:205], v[0:3]
	v_mfma_f32_16x16x32_bf16 v[52:55], v[214:217], v[170:173], v[52:55]
	v_mfma_f32_16x16x32_bf16 v[48:51], v[222:225], v[170:173], v[48:51]
	v_mfma_f32_16x16x32_bf16 v[36:39], v[214:217], v[190:193], v[36:39]
	v_mfma_f32_16x16x32_bf16 v[32:35], v[222:225], v[190:193], v[32:35]
	v_mfma_f32_16x16x32_bf16 v[20:23], v[214:217], v[198:201], v[20:23]
	v_mfma_f32_16x16x32_bf16 v[16:19], v[222:225], v[198:201], v[16:19]
	v_mfma_f32_16x16x32_bf16 v[4:7], v[214:217], v[206:209], v[4:7]
	v_mfma_f32_16x16x32_bf16 v[0:3], v[222:225], v[206:209], v[0:3]
	s_add_i32 s46, s46, 2
	s_add_u32 s16, s16, 0x100
	s_addc_u32 s17, s17, 0
	s_add_u32 s44, s44, 0x100
	s_addc_u32 s45, s45, 0
	s_cmp_gt_u32 s46, 13
	s_barrier
	s_cbranch_scc0 .LBB0_1202
	v_max_f32_e32 v144, v124, v124
	v_max_f32_e32 v144, 0xc1a00000, v144
	v_mul_f32_e32 v144, 0xbfb8aa3b, v144
	v_exp_f32_e32 v157, v144
	v_max_f32_e32 v144, v125, v125
	v_max_f32_e32 v144, 0xc1a00000, v144
	v_mul_f32_e32 v144, 0xbfb8aa3b, v144
	v_exp_f32_e32 v156, v144
	v_max_f32_e32 v144, v126, v126
	v_max_f32_e32 v144, 0xc1a00000, v144
	v_mul_f32_e32 v144, 0xbfb8aa3b, v144
	v_exp_f32_e32 v159, v144
	v_max_f32_e32 v144, v127, v127
	v_max_f32_e32 v144, 0xc1a00000, v144
	v_mul_f32_e32 v144, 0xbfb8aa3b, v144
	v_exp_f32_e32 v158, v144
	v_pk_add_f32 v[156:157], v[156:157], 1.0 op_sel_hi:[1,0]
	v_lshl_or_b32 v146, s41, 7, v150
	v_mov_b32_e32 v160, v157
	v_pk_add_f32 v[158:159], v[158:159], 1.0 op_sel_hi:[1,0]
	v_mov_b32_e32 v162, v156
	v_mov_b32_e32 v161, v159
	v_mov_b32_e32 v163, v158
	v_pk_mul_f32 v[160:161], v[160:161], v[162:163]
	v_lshl_add_u32 v154, s14, 8, v148
	v_mul_f32_e32 v155, v160, v161
	v_rcp_f32_e32 v155, v155
	v_ashrrev_i32_e32 v147, 31, v146
	v_mov_b64_e32 v[144:145], s[0:1]
	v_mad_i64_i32 v[162:163], s[16:17], v154, s40, v[144:145]
	v_mul_f32_e32 v164, v161, v155
	v_mul_f32_e32 v160, v160, v155
	v_max_f32_e32 v155, v120, v120
	v_max_f32_e32 v155, 0xc1a00000, v155
	v_mul_f32_e32 v155, 0xbfb8aa3b, v155
	v_pk_mul_f32 v[158:159], v[158:159], v[160:161] op_sel_hi:[1,0]
	v_exp_f32_e32 v161, v155
	v_max_f32_e32 v155, v121, v121
	v_max_f32_e32 v155, 0xc1a00000, v155
	v_mul_f32_e32 v155, 0xbfb8aa3b, v155
	v_exp_f32_e32 v160, v155
	v_max_f32_e32 v155, v122, v122
	v_max_f32_e32 v155, 0xc1a00000, v155
	v_mul_f32_e32 v155, 0xbfb8aa3b, v155
	v_exp_f32_e32 v167, v155
	v_max_f32_e32 v155, v123, v123
	v_max_f32_e32 v155, 0xc1a00000, v155
	v_mul_f32_e32 v155, 0xbfb8aa3b, v155
	v_exp_f32_e32 v166, v155
	v_pk_mul_f32 v[156:157], v[156:157], v[164:165] op_sel_hi:[1,0]
	v_pk_mul_f32 v[126:127], v[126:127], v[158:159]
	v_pk_mul_f32 v[124:125], v[124:125], v[156:157]
	v_pk_add_f32 v[156:157], v[160:161], 1.0 op_sel_hi:[1,0]
	v_pk_add_f32 v[160:161], v[166:167], 1.0 op_sel_hi:[1,0]
	v_mov_b32_e32 v164, v157
	v_mov_b32_e32 v165, v161
	v_mov_b32_e32 v166, v156
	v_mov_b32_e32 v167, v160
	v_pk_mul_f32 v[164:165], v[164:165], v[166:167]
	v_pk_mul_f32 v[118:119], v[126:127], v[118:119]
	v_mul_f32_e32 v155, v164, v165
	v_rcp_f32_e32 v155, v155
	v_pk_mul_f32 v[116:117], v[124:125], v[116:117]
	v_lshlrev_b64 v[146:147], 1, v[146:147]
	v_lshl_add_u64 v[162:163], v[162:163], 0, v[146:147]
	v_mul_f32_e32 v124, v165, v155
	v_mul_f32_e32 v126, v164, v155
	v_pk_mul_f32 v[126:127], v[160:161], v[126:127] op_sel_hi:[1,0]
	v_pk_mul_f32 v[124:125], v[156:157], v[124:125] op_sel_hi:[1,0]
	v_pk_mul_f32 v[122:123], v[122:123], v[126:127]
	v_pk_mul_f32 v[120:121], v[120:121], v[124:125]
	v_pk_mul_f32 v[122:123], v[122:123], v[114:115]
	v_pk_mul_f32 v[114:115], v[120:121], v[112:113]
	v_cvt_pk_bf16_f32 v112, v116, v117
	v_cvt_pk_bf16_f32 v113, v118, v119
; __device__ __forceinline__ unsigned cvt_pk_bf16(float lo, float hi) { unsigned r; asm volatile("v_cvt_pk_bf16_f32 %0, %1, %2" : "=v"(r) : "v"(lo), "v"(hi)); return r; }
; __device__ __forceinline__ f32x4 sigmoid4(f32x4 x) {
;     f32x4 d;
; #pragma unroll
;     for (int j = 0; j < 4; ++j) d[j] = 1.0f + __expf(-fmaxf(x[j], -20.0f));
;     const float p01 = d[0] * d[1], p23 = d[2] * d[3], r = __builtin_amdgcn_rcpf(p01 * p23), r01 = r * p23, r23 = r * p01;
;     return (f32x4){r01 * d[1], r01 * d[0], r23 * d[3], r23 * d[2]};
; }
;     __device__ __forceinline__ void operator()(const f32x4 (&acc)[2][2][4][2], const Unit& u, int wr, int wc, int fr, int fq) const {
;     ...
;         for (int ai = 0; ai < 2; ++ai)
; #pragma unroll
;             for (int m = 0; m < 4; ++m) { bf16_t* rowp = O + (size_t)(row0 + ai * HALF + m * 16) * ldc + col0;
;                 f32x4 v0, v1;
; #pragma unroll
;                 for (int j = 0; j < 1; ++j) { v0 = acc[ai][0][m][0] * sigmoid4(acc[ai][0][m][0]) * acc[ai][1][m][0]; v1 = acc[ai][0][m][1] * sigmoid4(acc[ai][0][m][1]) * acc[ai][1][m][1]; }
;                 u32x4 w; w.x = cvt_pk_bf16(v0[0], v0[1]); w.y = cvt_pk_bf16(v0[2], v0[3]); w.z = cvt_pk_bf16(v1[0], v1[1]); w.w = cvt_pk_bf16(v1[2], v1[3]);
;                 *(u32x4*)rowp = w; }
	v_max_f32_e32 v116, v108, v108
	v_max_f32_e32 v118, v110, v110
	v_max_f32_e32 v116, 0xc1a00000, v116
	v_max_f32_e32 v118, 0xc1a00000, v118
	v_mul_f32_e32 v116, 0xbfb8aa3b, v116
	v_mul_f32_e32 v118, 0xbfb8aa3b, v118
	v_exp_f32_e32 v117, v116
	v_max_f32_e32 v116, v109, v109
	v_exp_f32_e32 v119, v118
	v_max_f32_e32 v118, v111, v111
	v_max_f32_e32 v116, 0xc1a00000, v116
	v_max_f32_e32 v118, 0xc1a00000, v118
	v_mul_f32_e32 v116, 0xbfb8aa3b, v116
	v_mul_f32_e32 v118, 0xbfb8aa3b, v118
	v_exp_f32_e32 v116, v116
	v_exp_f32_e32 v118, v118
	v_cvt_pk_bf16_f32 v114, v114, v115
	v_cvt_pk_bf16_f32 v115, v122, v123
	global_store_dwordx4 v[162:163], v[112:115], off
	v_or_b32_e32 v120, 16, v154
	s_and_b64 vcc, exec, s[2:3]
	v_pk_add_f32 v[112:113], v[116:117], 1.0 op_sel_hi:[1,0]
	v_pk_add_f32 v[114:115], v[118:119], 1.0 op_sel_hi:[1,0]
	v_mov_b32_e32 v116, v113
	v_mov_b32_e32 v117, v115
	v_mov_b32_e32 v118, v112
	v_mov_b32_e32 v119, v114
	v_pk_mul_f32 v[116:117], v[116:117], v[118:119]
	s_mov_b32 s41, s6
	v_mul_f32_e32 v118, v116, v117
	v_rcp_f32_e32 v121, v118
	v_mad_i64_i32 v[118:119], s[16:17], v120, s40, v[144:145]
	v_lshl_add_u64 v[118:119], v[118:119], 0, v[146:147]
	v_mul_f32_e32 v116, v116, v121
	v_mul_f32_e32 v120, v117, v121
	v_pk_mul_f32 v[114:115], v[114:115], v[116:117] op_sel_hi:[1,0]
	v_max_f32_e32 v116, v104, v104
	v_max_f32_e32 v121, v106, v106
	v_max_f32_e32 v116, 0xc1a00000, v116
	v_max_f32_e32 v121, 0xc1a00000, v121
	v_mul_f32_e32 v116, 0xbfb8aa3b, v116
	v_mul_f32_e32 v121, 0xbfb8aa3b, v121
	v_exp_f32_e32 v117, v116
	v_max_f32_e32 v116, v105, v105
	v_exp_f32_e32 v123, v121
	v_max_f32_e32 v121, v107, v107
	v_max_f32_e32 v116, 0xc1a00000, v116
	v_max_f32_e32 v121, 0xc1a00000, v121
	v_mul_f32_e32 v116, 0xbfb8aa3b, v116
	v_mul_f32_e32 v121, 0xbfb8aa3b, v121
	v_exp_f32_e32 v116, v116
	v_exp_f32_e32 v122, v121
	v_pk_mul_f32 v[112:113], v[112:113], v[120:121] op_sel_hi:[1,0]
	v_pk_mul_f32 v[110:111], v[110:111], v[114:115]
	v_pk_mul_f32 v[108:109], v[108:109], v[112:113]
	v_pk_add_f32 v[112:113], v[116:117], 1.0 op_sel_hi:[1,0]
	v_pk_add_f32 v[116:117], v[122:123], 1.0 op_sel_hi:[1,0]
	v_mov_b32_e32 v120, v113
	v_mov_b32_e32 v121, v117
	v_mov_b32_e32 v122, v112
	v_mov_b32_e32 v123, v116
	v_pk_mul_f32 v[120:121], v[120:121], v[122:123]
	v_pk_mul_f32 v[102:103], v[110:111], v[102:103]
	v_mul_f32_e32 v122, v120, v121
	v_rcp_f32_e32 v122, v122
	v_pk_mul_f32 v[100:101], v[108:109], v[100:101]
	s_mov_b32 s14, s8
	s_mov_b64 s[18:19], s[12:13]
	v_mul_f32_e32 v108, v121, v122
	v_mul_f32_e32 v110, v120, v122
	v_pk_mul_f32 v[110:111], v[116:117], v[110:111] op_sel_hi:[1,0]
	v_pk_mul_f32 v[108:109], v[112:113], v[108:109] op_sel_hi:[1,0]
	v_pk_mul_f32 v[106:107], v[106:107], v[110:111]
	v_pk_mul_f32 v[104:105], v[104:105], v[108:109]
	v_pk_mul_f32 v[106:107], v[106:107], v[98:99]
	v_pk_mul_f32 v[98:99], v[104:105], v[96:97]
	v_cvt_pk_bf16_f32 v96, v100, v101
	v_cvt_pk_bf16_f32 v97, v102, v103
	v_max_f32_e32 v100, v92, v92
	v_max_f32_e32 v102, v94, v94
	v_max_f32_e32 v100, 0xc1a00000, v100
	v_max_f32_e32 v102, 0xc1a00000, v102
	v_mul_f32_e32 v100, 0xbfb8aa3b, v100
	v_mul_f32_e32 v102, 0xbfb8aa3b, v102
	v_exp_f32_e32 v101, v100
	v_max_f32_e32 v100, v93, v93
	v_exp_f32_e32 v103, v102
	v_max_f32_e32 v102, v95, v95
	v_max_f32_e32 v100, 0xc1a00000, v100
	v_max_f32_e32 v102, 0xc1a00000, v102
	v_mul_f32_e32 v100, 0xbfb8aa3b, v100
	v_mul_f32_e32 v102, 0xbfb8aa3b, v102
	v_exp_f32_e32 v100, v100
	v_exp_f32_e32 v102, v102
	v_cvt_pk_bf16_f32 v98, v98, v99
	v_cvt_pk_bf16_f32 v99, v106, v107
	global_store_dwordx4 v[118:119], v[96:99], off
	v_or_b32_e32 v104, 32, v154
	s_nop 0
	v_pk_add_f32 v[96:97], v[100:101], 1.0 op_sel_hi:[1,0]
	v_pk_add_f32 v[98:99], v[102:103], 1.0 op_sel_hi:[1,0]
	v_mov_b32_e32 v100, v97
	v_mov_b32_e32 v101, v99
	v_mov_b32_e32 v102, v96
	v_mov_b32_e32 v103, v98
	v_pk_mul_f32 v[100:101], v[100:101], v[102:103]
	s_nop 0
	v_mul_f32_e32 v102, v100, v101
	v_rcp_f32_e32 v105, v102
	v_mad_i64_i32 v[102:103], s[16:17], v104, s40, v[144:145]
	v_lshl_add_u64 v[102:103], v[102:103], 0, v[146:147]
	v_mul_f32_e32 v100, v100, v105
	v_mul_f32_e32 v104, v101, v105
	v_pk_mul_f32 v[98:99], v[98:99], v[100:101] op_sel_hi:[1,0]
	v_max_f32_e32 v100, v88, v88
	v_max_f32_e32 v105, v90, v90
	v_max_f32_e32 v100, 0xc1a00000, v100
	v_max_f32_e32 v105, 0xc1a00000, v105
	v_mul_f32_e32 v100, 0xbfb8aa3b, v100
	v_mul_f32_e32 v105, 0xbfb8aa3b, v105
	v_exp_f32_e32 v101, v100
	v_max_f32_e32 v100, v89, v89
	v_exp_f32_e32 v107, v105
	v_max_f32_e32 v105, v91, v91
	v_max_f32_e32 v100, 0xc1a00000, v100
	v_max_f32_e32 v105, 0xc1a00000, v105
	v_mul_f32_e32 v100, 0xbfb8aa3b, v100
	v_mul_f32_e32 v105, 0xbfb8aa3b, v105
	v_exp_f32_e32 v100, v100
	v_exp_f32_e32 v106, v105
	v_pk_mul_f32 v[96:97], v[96:97], v[104:105] op_sel_hi:[1,0]
	v_pk_mul_f32 v[94:95], v[94:95], v[98:99]
	v_pk_mul_f32 v[92:93], v[92:93], v[96:97]
	v_pk_add_f32 v[96:97], v[100:101], 1.0 op_sel_hi:[1,0]
	v_pk_add_f32 v[100:101], v[106:107], 1.0 op_sel_hi:[1,0]
	v_mov_b32_e32 v104, v97
	v_mov_b32_e32 v105, v101
	v_mov_b32_e32 v106, v96
	v_mov_b32_e32 v107, v100
	v_pk_mul_f32 v[104:105], v[104:105], v[106:107]
	v_pk_mul_f32 v[86:87], v[94:95], v[86:87]
	v_mul_f32_e32 v106, v104, v105
	v_rcp_f32_e32 v106, v106
	v_pk_mul_f32 v[84:85], v[92:93], v[84:85]
	v_mul_f32_e32 v92, v105, v106
	v_mul_f32_e32 v94, v104, v106
	v_pk_mul_f32 v[94:95], v[100:101], v[94:95] op_sel_hi:[1,0]
	v_pk_mul_f32 v[92:93], v[96:97], v[92:93] op_sel_hi:[1,0]
	v_pk_mul_f32 v[90:91], v[90:91], v[94:95]
	v_pk_mul_f32 v[88:89], v[88:89], v[92:93]
	v_pk_mul_f32 v[90:91], v[90:91], v[82:83]
	v_pk_mul_f32 v[82:83], v[88:89], v[80:81]
	v_cvt_pk_bf16_f32 v80, v84, v85
; __device__ __forceinline__ unsigned cvt_pk_bf16(float lo, float hi) { unsigned r; asm volatile("v_cvt_pk_bf16_f32 %0, %1, %2" : "=v"(r) : "v"(lo), "v"(hi)); return r; }
; __device__ __forceinline__ f32x4 sigmoid4(f32x4 x) {
;     f32x4 d;
; #pragma unroll
;     for (int j = 0; j < 4; ++j) d[j] = 1.0f + __expf(-fmaxf(x[j], -20.0f));
;     const float p01 = d[0] * d[1], p23 = d[2] * d[3], r = __builtin_amdgcn_rcpf(p01 * p23), r01 = r * p23, r23 = r * p01;
;     return (f32x4){r01 * d[1], r01 * d[0], r23 * d[3], r23 * d[2]};
; }
;     __device__ __forceinline__ void operator()(const f32x4 (&acc)[2][2][4][2], const Unit& u, int wr, int wc, int fr, int fq) const {
;     ...
;         for (int ai = 0; ai < 2; ++ai)
; #pragma unroll
;             for (int m = 0; m < 4; ++m) { bf16_t* rowp = O + (size_t)(row0 + ai * HALF + m * 16) * ldc + col0;
;                 f32x4 v0, v1;
; #pragma unroll
;                 for (int j = 0; j < 1; ++j) { v0 = acc[ai][0][m][0] * sigmoid4(acc[ai][0][m][0]) * acc[ai][1][m][0]; v1 = acc[ai][0][m][1] * sigmoid4(acc[ai][0][m][1]) * acc[ai][1][m][1]; }
;                 u32x4 w; w.x = cvt_pk_bf16(v0[0], v0[1]); w.y = cvt_pk_bf16(v0[2], v0[3]); w.z = cvt_pk_bf16(v1[0], v1[1]); w.w = cvt_pk_bf16(v1[2], v1[3]);
;                 *(u32x4*)rowp = w; }
	v_cvt_pk_bf16_f32 v81, v86, v87
	v_max_f32_e32 v84, v76, v76
	v_max_f32_e32 v86, v78, v78
	v_max_f32_e32 v84, 0xc1a00000, v84
	v_max_f32_e32 v86, 0xc1a00000, v86
	v_mul_f32_e32 v84, 0xbfb8aa3b, v84
	v_mul_f32_e32 v86, 0xbfb8aa3b, v86
	v_exp_f32_e32 v85, v84
	v_max_f32_e32 v84, v77, v77
	v_exp_f32_e32 v87, v86
	v_max_f32_e32 v86, v79, v79
	v_max_f32_e32 v84, 0xc1a00000, v84
	v_max_f32_e32 v86, 0xc1a00000, v86
	v_mul_f32_e32 v84, 0xbfb8aa3b, v84
	v_mul_f32_e32 v86, 0xbfb8aa3b, v86
	v_exp_f32_e32 v84, v84
	v_exp_f32_e32 v86, v86
	v_cvt_pk_bf16_f32 v82, v82, v83
	v_cvt_pk_bf16_f32 v83, v90, v91
	global_store_dwordx4 v[102:103], v[80:83], off
	v_or_b32_e32 v88, 48, v154
	s_nop 0
	v_pk_add_f32 v[80:81], v[84:85], 1.0 op_sel_hi:[1,0]
	v_pk_add_f32 v[82:83], v[86:87], 1.0 op_sel_hi:[1,0]
	v_mov_b32_e32 v84, v81
	v_mov_b32_e32 v85, v83
	v_mov_b32_e32 v86, v80
	v_mov_b32_e32 v87, v82
	v_pk_mul_f32 v[84:85], v[84:85], v[86:87]
	s_nop 0
	v_mul_f32_e32 v86, v84, v85
	v_rcp_f32_e32 v89, v86
	v_mad_i64_i32 v[86:87], s[16:17], v88, s40, v[144:145]
	v_lshl_add_u64 v[86:87], v[86:87], 0, v[146:147]
	v_mul_f32_e32 v84, v84, v89
	v_mul_f32_e32 v88, v85, v89
	v_pk_mul_f32 v[82:83], v[82:83], v[84:85] op_sel_hi:[1,0]
	v_max_f32_e32 v84, v72, v72
	v_max_f32_e32 v89, v74, v74
	v_max_f32_e32 v84, 0xc1a00000, v84
	v_max_f32_e32 v89, 0xc1a00000, v89
	v_mul_f32_e32 v84, 0xbfb8aa3b, v84
	v_mul_f32_e32 v89, 0xbfb8aa3b, v89
	v_exp_f32_e32 v85, v84
	v_max_f32_e32 v84, v73, v73
	v_exp_f32_e32 v91, v89
	v_max_f32_e32 v89, v75, v75
	v_max_f32_e32 v84, 0xc1a00000, v84
	v_max_f32_e32 v89, 0xc1a00000, v89
	v_mul_f32_e32 v84, 0xbfb8aa3b, v84
	v_mul_f32_e32 v89, 0xbfb8aa3b, v89
	v_exp_f32_e32 v84, v84
	v_exp_f32_e32 v90, v89
	v_pk_mul_f32 v[80:81], v[80:81], v[88:89] op_sel_hi:[1,0]
	v_pk_mul_f32 v[78:79], v[78:79], v[82:83]
	v_pk_mul_f32 v[76:77], v[76:77], v[80:81]
	v_pk_add_f32 v[80:81], v[84:85], 1.0 op_sel_hi:[1,0]
	v_pk_add_f32 v[84:85], v[90:91], 1.0 op_sel_hi:[1,0]
	v_mov_b32_e32 v88, v81
	v_mov_b32_e32 v89, v85
	v_mov_b32_e32 v90, v80
	v_mov_b32_e32 v91, v84
	v_pk_mul_f32 v[88:89], v[88:89], v[90:91]
	v_pk_mul_f32 v[70:71], v[78:79], v[70:71]
	v_mul_f32_e32 v90, v88, v89
	v_rcp_f32_e32 v90, v90
	v_pk_mul_f32 v[68:69], v[76:77], v[68:69]
	v_mul_f32_e32 v76, v89, v90
	v_mul_f32_e32 v78, v88, v90
	v_pk_mul_f32 v[78:79], v[84:85], v[78:79] op_sel_hi:[1,0]
	v_pk_mul_f32 v[76:77], v[80:81], v[76:77] op_sel_hi:[1,0]
	v_pk_mul_f32 v[74:75], v[74:75], v[78:79]
	v_pk_mul_f32 v[72:73], v[72:73], v[76:77]
	v_pk_mul_f32 v[74:75], v[74:75], v[66:67]
	v_pk_mul_f32 v[66:67], v[72:73], v[64:65]
	v_cvt_pk_bf16_f32 v64, v68, v69
	v_cvt_pk_bf16_f32 v65, v70, v71
	v_max_f32_e32 v68, v60, v60
	v_max_f32_e32 v70, v62, v62
	v_max_f32_e32 v68, 0xc1a00000, v68
	v_max_f32_e32 v70, 0xc1a00000, v70
	v_mul_f32_e32 v68, 0xbfb8aa3b, v68
	v_mul_f32_e32 v70, 0xbfb8aa3b, v70
	v_exp_f32_e32 v69, v68
	v_max_f32_e32 v68, v61, v61
	v_exp_f32_e32 v71, v70
	v_max_f32_e32 v70, v63, v63
	v_max_f32_e32 v68, 0xc1a00000, v68
	v_max_f32_e32 v70, 0xc1a00000, v70
	v_mul_f32_e32 v68, 0xbfb8aa3b, v68
	v_mul_f32_e32 v70, 0xbfb8aa3b, v70
	v_exp_f32_e32 v68, v68
	v_exp_f32_e32 v70, v70
	v_cvt_pk_bf16_f32 v66, v66, v67
	v_cvt_pk_bf16_f32 v67, v74, v75
	global_store_dwordx4 v[86:87], v[64:67], off
	v_add_u32_e32 v72, 0x80, v154
	s_nop 0
	v_pk_add_f32 v[64:65], v[68:69], 1.0 op_sel_hi:[1,0]
	v_pk_add_f32 v[66:67], v[70:71], 1.0 op_sel_hi:[1,0]
	v_mov_b32_e32 v68, v65
	v_mov_b32_e32 v69, v67
	v_mov_b32_e32 v70, v64
	v_mov_b32_e32 v71, v66
	v_pk_mul_f32 v[68:69], v[68:69], v[70:71]
	s_nop 0
	v_mul_f32_e32 v70, v68, v69
	v_rcp_f32_e32 v73, v70
	v_mad_i64_i32 v[70:71], s[16:17], v72, s40, v[144:145]
	v_lshl_add_u64 v[70:71], v[70:71], 0, v[146:147]
	v_mul_f32_e32 v68, v68, v73
	v_mul_f32_e32 v72, v69, v73
	v_pk_mul_f32 v[66:67], v[66:67], v[68:69] op_sel_hi:[1,0]
	v_max_f32_e32 v68, v56, v56
	v_max_f32_e32 v73, v58, v58
	v_max_f32_e32 v68, 0xc1a00000, v68
	v_max_f32_e32 v73, 0xc1a00000, v73
	v_mul_f32_e32 v68, 0xbfb8aa3b, v68
	v_mul_f32_e32 v73, 0xbfb8aa3b, v73
	v_exp_f32_e32 v69, v68
	v_max_f32_e32 v68, v57, v57
	v_exp_f32_e32 v75, v73
	v_max_f32_e32 v73, v59, v59
	v_max_f32_e32 v68, 0xc1a00000, v68
	v_max_f32_e32 v73, 0xc1a00000, v73
	v_mul_f32_e32 v68, 0xbfb8aa3b, v68
	v_mul_f32_e32 v73, 0xbfb8aa3b, v73
	v_exp_f32_e32 v68, v68
	v_exp_f32_e32 v74, v73
	v_pk_mul_f32 v[64:65], v[64:65], v[72:73] op_sel_hi:[1,0]
	v_pk_mul_f32 v[62:63], v[62:63], v[66:67]
	v_pk_mul_f32 v[60:61], v[60:61], v[64:65]
	v_pk_add_f32 v[64:65], v[68:69], 1.0 op_sel_hi:[1,0]
	v_pk_add_f32 v[68:69], v[74:75], 1.0 op_sel_hi:[1,0]
	v_mov_b32_e32 v72, v65
	v_mov_b32_e32 v73, v69
	v_mov_b32_e32 v74, v64
	v_mov_b32_e32 v75, v68
	v_pk_mul_f32 v[72:73], v[72:73], v[74:75]
	v_pk_mul_f32 v[54:55], v[62:63], v[54:55]
	v_mul_f32_e32 v74, v72, v73
	v_rcp_f32_e32 v74, v74
	v_pk_mul_f32 v[52:53], v[60:61], v[52:53]
	v_mul_f32_e32 v60, v73, v74
	v_mul_f32_e32 v62, v72, v74
	v_pk_mul_f32 v[62:63], v[68:69], v[62:63] op_sel_hi:[1,0]
	v_pk_mul_f32 v[60:61], v[64:65], v[60:61] op_sel_hi:[1,0]
	v_pk_mul_f32 v[58:59], v[58:59], v[62:63]
	v_pk_mul_f32 v[56:57], v[56:57], v[60:61]
	v_pk_mul_f32 v[58:59], v[58:59], v[50:51]
	v_pk_mul_f32 v[50:51], v[56:57], v[48:49]
	v_cvt_pk_bf16_f32 v48, v52, v53
	v_cvt_pk_bf16_f32 v49, v54, v55
	v_max_f32_e32 v52, v44, v44
	v_max_f32_e32 v54, v46, v46
	v_max_f32_e32 v52, 0xc1a00000, v52
	v_max_f32_e32 v54, 0xc1a00000, v54
	v_mul_f32_e32 v52, 0xbfb8aa3b, v52
	v_mul_f32_e32 v54, 0xbfb8aa3b, v54
	v_exp_f32_e32 v53, v52
	v_max_f32_e32 v52, v45, v45
	v_exp_f32_e32 v55, v54
	v_max_f32_e32 v54, v47, v47
	v_max_f32_e32 v52, 0xc1a00000, v52
; __device__ __forceinline__ unsigned cvt_pk_bf16(float lo, float hi) { unsigned r; asm volatile("v_cvt_pk_bf16_f32 %0, %1, %2" : "=v"(r) : "v"(lo), "v"(hi)); return r; }
; __device__ __forceinline__ f32x4 sigmoid4(f32x4 x) {
;     f32x4 d;
; #pragma unroll
;     for (int j = 0; j < 4; ++j) d[j] = 1.0f + __expf(-fmaxf(x[j], -20.0f));
;     const float p01 = d[0] * d[1], p23 = d[2] * d[3], r = __builtin_amdgcn_rcpf(p01 * p23), r01 = r * p23, r23 = r * p01;
;     return (f32x4){r01 * d[1], r01 * d[0], r23 * d[3], r23 * d[2]};
; }
;     __device__ __forceinline__ void operator()(const f32x4 (&acc)[2][2][4][2], const Unit& u, int wr, int wc, int fr, int fq) const {
;     ...
;         for (int ai = 0; ai < 2; ++ai)
; #pragma unroll
;             for (int m = 0; m < 4; ++m) { bf16_t* rowp = O + (size_t)(row0 + ai * HALF + m * 16) * ldc + col0;
;                 f32x4 v0, v1;
; #pragma unroll
;                 for (int j = 0; j < 1; ++j) { v0 = acc[ai][0][m][0] * sigmoid4(acc[ai][0][m][0]) * acc[ai][1][m][0]; v1 = acc[ai][0][m][1] * sigmoid4(acc[ai][0][m][1]) * acc[ai][1][m][1]; }
;                 u32x4 w; w.x = cvt_pk_bf16(v0[0], v0[1]); w.y = cvt_pk_bf16(v0[2], v0[3]); w.z = cvt_pk_bf16(v1[0], v1[1]); w.w = cvt_pk_bf16(v1[2], v1[3]);
;                 *(u32x4*)rowp = w; }
	v_max_f32_e32 v54, 0xc1a00000, v54
	v_mul_f32_e32 v52, 0xbfb8aa3b, v52
	v_mul_f32_e32 v54, 0xbfb8aa3b, v54
	v_exp_f32_e32 v52, v52
	v_exp_f32_e32 v54, v54
	v_cvt_pk_bf16_f32 v50, v50, v51
	v_cvt_pk_bf16_f32 v51, v58, v59
	global_store_dwordx4 v[70:71], v[48:51], off
	v_add_u32_e32 v56, 0x90, v154
	s_nop 0
	v_pk_add_f32 v[48:49], v[52:53], 1.0 op_sel_hi:[1,0]
	v_pk_add_f32 v[50:51], v[54:55], 1.0 op_sel_hi:[1,0]
	v_mov_b32_e32 v52, v49
	v_mov_b32_e32 v53, v51
	v_mov_b32_e32 v54, v48
	v_mov_b32_e32 v55, v50
	v_pk_mul_f32 v[52:53], v[52:53], v[54:55]
	s_nop 0
	v_mul_f32_e32 v54, v52, v53
	v_rcp_f32_e32 v57, v54
	v_mad_i64_i32 v[54:55], s[16:17], v56, s40, v[144:145]
	v_lshl_add_u64 v[54:55], v[54:55], 0, v[146:147]
	v_mul_f32_e32 v52, v52, v57
	v_mul_f32_e32 v56, v53, v57
	v_pk_mul_f32 v[50:51], v[50:51], v[52:53] op_sel_hi:[1,0]
	v_max_f32_e32 v52, v40, v40
	v_max_f32_e32 v57, v42, v42
	v_max_f32_e32 v52, 0xc1a00000, v52
	v_max_f32_e32 v57, 0xc1a00000, v57
	v_mul_f32_e32 v52, 0xbfb8aa3b, v52
	v_mul_f32_e32 v57, 0xbfb8aa3b, v57
	v_exp_f32_e32 v53, v52
	v_max_f32_e32 v52, v41, v41
	v_exp_f32_e32 v59, v57
	v_max_f32_e32 v57, v43, v43
	v_max_f32_e32 v52, 0xc1a00000, v52
	v_max_f32_e32 v57, 0xc1a00000, v57
	v_mul_f32_e32 v52, 0xbfb8aa3b, v52
	v_mul_f32_e32 v57, 0xbfb8aa3b, v57
	v_exp_f32_e32 v52, v52
	v_exp_f32_e32 v58, v57
	v_pk_mul_f32 v[48:49], v[48:49], v[56:57] op_sel_hi:[1,0]
	v_pk_mul_f32 v[46:47], v[46:47], v[50:51]
	v_pk_mul_f32 v[44:45], v[44:45], v[48:49]
	v_pk_add_f32 v[48:49], v[52:53], 1.0 op_sel_hi:[1,0]
	v_pk_add_f32 v[52:53], v[58:59], 1.0 op_sel_hi:[1,0]
	v_mov_b32_e32 v56, v49
	v_mov_b32_e32 v57, v53
	v_mov_b32_e32 v58, v48
	v_mov_b32_e32 v59, v52
	v_pk_mul_f32 v[56:57], v[56:57], v[58:59]
	v_pk_mul_f32 v[38:39], v[46:47], v[38:39]
	v_mul_f32_e32 v58, v56, v57
	v_rcp_f32_e32 v58, v58
	v_pk_mul_f32 v[36:37], v[44:45], v[36:37]
	v_mul_f32_e32 v44, v57, v58
	v_mul_f32_e32 v46, v56, v58
	v_pk_mul_f32 v[46:47], v[52:53], v[46:47] op_sel_hi:[1,0]
	v_pk_mul_f32 v[44:45], v[48:49], v[44:45] op_sel_hi:[1,0]
	v_pk_mul_f32 v[42:43], v[42:43], v[46:47]
	v_pk_mul_f32 v[40:41], v[40:41], v[44:45]
	v_pk_mul_f32 v[42:43], v[42:43], v[34:35]
	v_pk_mul_f32 v[34:35], v[40:41], v[32:33]
	v_cvt_pk_bf16_f32 v32, v36, v37
	v_cvt_pk_bf16_f32 v33, v38, v39
	v_max_f32_e32 v36, v28, v28
	v_max_f32_e32 v38, v30, v30
	v_max_f32_e32 v36, 0xc1a00000, v36
	v_max_f32_e32 v38, 0xc1a00000, v38
	v_mul_f32_e32 v36, 0xbfb8aa3b, v36
	v_mul_f32_e32 v38, 0xbfb8aa3b, v38
	v_exp_f32_e32 v37, v36
	v_max_f32_e32 v36, v29, v29
	v_exp_f32_e32 v39, v38
	v_max_f32_e32 v38, v31, v31
	v_max_f32_e32 v36, 0xc1a00000, v36
	v_max_f32_e32 v38, 0xc1a00000, v38
	v_mul_f32_e32 v36, 0xbfb8aa3b, v36
	v_mul_f32_e32 v38, 0xbfb8aa3b, v38
	v_exp_f32_e32 v36, v36
	v_exp_f32_e32 v38, v38
	v_cvt_pk_bf16_f32 v34, v34, v35
	v_cvt_pk_bf16_f32 v35, v42, v43
	global_store_dwordx4 v[54:55], v[32:35], off
	v_add_u32_e32 v40, 0xa0, v154
	s_nop 0
	v_pk_add_f32 v[32:33], v[36:37], 1.0 op_sel_hi:[1,0]
	v_pk_add_f32 v[34:35], v[38:39], 1.0 op_sel_hi:[1,0]
	v_mov_b32_e32 v36, v33
	v_mov_b32_e32 v37, v35
	v_mov_b32_e32 v38, v32
	v_mov_b32_e32 v39, v34
	v_pk_mul_f32 v[36:37], v[36:37], v[38:39]
	s_nop 0
	v_mul_f32_e32 v38, v36, v37
	v_rcp_f32_e32 v41, v38
	v_mad_i64_i32 v[38:39], s[16:17], v40, s40, v[144:145]
	v_lshl_add_u64 v[38:39], v[38:39], 0, v[146:147]
	v_mul_f32_e32 v36, v36, v41
	v_mul_f32_e32 v40, v37, v41
	v_pk_mul_f32 v[34:35], v[34:35], v[36:37] op_sel_hi:[1,0]
	v_max_f32_e32 v36, v24, v24
	v_max_f32_e32 v41, v26, v26
	v_max_f32_e32 v36, 0xc1a00000, v36
	v_max_f32_e32 v41, 0xc1a00000, v41
	v_mul_f32_e32 v36, 0xbfb8aa3b, v36
	v_mul_f32_e32 v41, 0xbfb8aa3b, v41
	v_exp_f32_e32 v37, v36
	v_max_f32_e32 v36, v25, v25
	v_exp_f32_e32 v43, v41
	v_max_f32_e32 v41, v27, v27
	v_max_f32_e32 v36, 0xc1a00000, v36
	v_max_f32_e32 v41, 0xc1a00000, v41
	v_mul_f32_e32 v36, 0xbfb8aa3b, v36
; __device__ __forceinline__ unsigned cvt_pk_bf16(float lo, float hi) { unsigned r; asm volatile("v_cvt_pk_bf16_f32 %0, %1, %2" : "=v"(r) : "v"(lo), "v"(hi)); return r; }
; __device__ __forceinline__ f32x4 sigmoid4(f32x4 x) {
;     f32x4 d;
; #pragma unroll
;     for (int j = 0; j < 4; ++j) d[j] = 1.0f + __expf(-fmaxf(x[j], -20.0f));
;     const float p01 = d[0] * d[1], p23 = d[2] * d[3], r = __builtin_amdgcn_rcpf(p01 * p23), r01 = r * p23, r23 = r * p01;
;     return (f32x4){r01 * d[1], r01 * d[0], r23 * d[3], r23 * d[2]};
; }
;     __device__ __forceinline__ void operator()(const f32x4 (&acc)[2][2][4][2], const Unit& u, int wr, int wc, int fr, int fq) const {
;     ...
;         for (int ai = 0; ai < 2; ++ai)
; #pragma unroll
;             for (int m = 0; m < 4; ++m) { bf16_t* rowp = O + (size_t)(row0 + ai * HALF + m * 16) * ldc + col0;
;                 f32x4 v0, v1;
; #pragma unroll
;                 for (int j = 0; j < 1; ++j) { v0 = acc[ai][0][m][0] * sigmoid4(acc[ai][0][m][0]) * acc[ai][1][m][0]; v1 = acc[ai][0][m][1] * sigmoid4(acc[ai][0][m][1]) * acc[ai][1][m][1]; }
;                 u32x4 w; w.x = cvt_pk_bf16(v0[0], v0[1]); w.y = cvt_pk_bf16(v0[2], v0[3]); w.z = cvt_pk_bf16(v1[0], v1[1]); w.w = cvt_pk_bf16(v1[2], v1[3]);
;                 *(u32x4*)rowp = w; }
	v_mul_f32_e32 v41, 0xbfb8aa3b, v41
	v_exp_f32_e32 v36, v36
	v_exp_f32_e32 v42, v41
	v_pk_mul_f32 v[32:33], v[32:33], v[40:41] op_sel_hi:[1,0]
	v_pk_mul_f32 v[30:31], v[30:31], v[34:35]
	v_pk_mul_f32 v[28:29], v[28:29], v[32:33]
	v_pk_add_f32 v[32:33], v[36:37], 1.0 op_sel_hi:[1,0]
	v_pk_add_f32 v[36:37], v[42:43], 1.0 op_sel_hi:[1,0]
	v_mov_b32_e32 v40, v33
	v_mov_b32_e32 v41, v37
	v_mov_b32_e32 v42, v32
	v_mov_b32_e32 v43, v36
	v_pk_mul_f32 v[40:41], v[40:41], v[42:43]
	v_pk_mul_f32 v[22:23], v[30:31], v[22:23]
	v_mul_f32_e32 v42, v40, v41
	v_rcp_f32_e32 v42, v42
	v_pk_mul_f32 v[20:21], v[28:29], v[20:21]
	v_mul_f32_e32 v28, v41, v42
	v_mul_f32_e32 v30, v40, v42
	v_pk_mul_f32 v[30:31], v[36:37], v[30:31] op_sel_hi:[1,0]
	v_pk_mul_f32 v[28:29], v[32:33], v[28:29] op_sel_hi:[1,0]
	v_pk_mul_f32 v[26:27], v[26:27], v[30:31]
	v_pk_mul_f32 v[24:25], v[24:25], v[28:29]
	v_pk_mul_f32 v[26:27], v[26:27], v[18:19]
	v_pk_mul_f32 v[18:19], v[24:25], v[16:17]
	v_cvt_pk_bf16_f32 v16, v20, v21
	v_cvt_pk_bf16_f32 v17, v22, v23
	v_max_f32_e32 v20, v12, v12
	v_max_f32_e32 v22, v14, v14
	v_max_f32_e32 v20, 0xc1a00000, v20
	v_max_f32_e32 v22, 0xc1a00000, v22
	v_mul_f32_e32 v20, 0xbfb8aa3b, v20
	v_mul_f32_e32 v22, 0xbfb8aa3b, v22
	v_exp_f32_e32 v21, v20
	v_max_f32_e32 v20, v13, v13
	v_exp_f32_e32 v23, v22
	v_max_f32_e32 v22, v15, v15
	v_max_f32_e32 v20, 0xc1a00000, v20
	v_max_f32_e32 v22, 0xc1a00000, v22
	v_mul_f32_e32 v20, 0xbfb8aa3b, v20
	v_mul_f32_e32 v22, 0xbfb8aa3b, v22
	v_exp_f32_e32 v20, v20
	v_exp_f32_e32 v22, v22
	v_cvt_pk_bf16_f32 v18, v18, v19
	v_cvt_pk_bf16_f32 v19, v26, v27
	global_store_dwordx4 v[38:39], v[16:19], off
	v_add_u32_e32 v24, 0xb0, v154
	s_nop 0
	v_pk_add_f32 v[16:17], v[20:21], 1.0 op_sel_hi:[1,0]
	v_pk_add_f32 v[18:19], v[22:23], 1.0 op_sel_hi:[1,0]
	v_mov_b32_e32 v20, v17
	v_mov_b32_e32 v21, v19
	v_mov_b32_e32 v22, v16
	v_mov_b32_e32 v23, v18
	v_pk_mul_f32 v[20:21], v[20:21], v[22:23]
	s_nop 0
	v_mul_f32_e32 v22, v20, v21
	v_rcp_f32_e32 v25, v22
	v_mad_i64_i32 v[22:23], s[16:17], v24, s40, v[144:145]
	v_lshl_add_u64 v[22:23], v[22:23], 0, v[146:147]
	v_mul_f32_e32 v20, v20, v25
	v_mul_f32_e32 v24, v21, v25
	v_pk_mul_f32 v[18:19], v[18:19], v[20:21] op_sel_hi:[1,0]
	v_max_f32_e32 v20, v8, v8
	v_max_f32_e32 v25, v10, v10
	v_max_f32_e32 v20, 0xc1a00000, v20
	v_max_f32_e32 v25, 0xc1a00000, v25
	v_mul_f32_e32 v20, 0xbfb8aa3b, v20
	v_mul_f32_e32 v25, 0xbfb8aa3b, v25
	v_exp_f32_e32 v21, v20
	v_max_f32_e32 v20, v9, v9
	v_exp_f32_e32 v27, v25
	v_max_f32_e32 v25, v11, v11
	v_max_f32_e32 v20, 0xc1a00000, v20
	v_max_f32_e32 v25, 0xc1a00000, v25
	v_mul_f32_e32 v20, 0xbfb8aa3b, v20
	v_mul_f32_e32 v25, 0xbfb8aa3b, v25
	v_exp_f32_e32 v20, v20
	v_exp_f32_e32 v26, v25
	v_pk_mul_f32 v[16:17], v[16:17], v[24:25] op_sel_hi:[1,0]
	v_pk_mul_f32 v[14:15], v[14:15], v[18:19]
	v_pk_mul_f32 v[12:13], v[12:13], v[16:17]
	v_pk_add_f32 v[16:17], v[20:21], 1.0 op_sel_hi:[1,0]
	v_pk_add_f32 v[20:21], v[26:27], 1.0 op_sel_hi:[1,0]
	v_mov_b32_e32 v24, v17
	v_mov_b32_e32 v25, v21
	v_mov_b32_e32 v26, v16
	v_mov_b32_e32 v27, v20
	v_pk_mul_f32 v[24:25], v[24:25], v[26:27]
	v_pk_mul_f32 v[6:7], v[14:15], v[6:7]
	v_mul_f32_e32 v26, v24, v25
	v_rcp_f32_e32 v26, v26
	v_pk_mul_f32 v[4:5], v[12:13], v[4:5]
	s_mov_b64 s[16:17], s[10:11]
	v_mul_f32_e32 v12, v25, v26
	v_mul_f32_e32 v14, v24, v26
	v_pk_mul_f32 v[14:15], v[20:21], v[14:15] op_sel_hi:[1,0]
	v_pk_mul_f32 v[12:13], v[16:17], v[12:13] op_sel_hi:[1,0]
	v_pk_mul_f32 v[10:11], v[10:11], v[14:15]
	v_pk_mul_f32 v[8:9], v[8:9], v[12:13]
	v_pk_mul_f32 v[10:11], v[10:11], v[2:3]
	v_pk_mul_f32 v[2:3], v[8:9], v[0:1]
	v_cvt_pk_bf16_f32 v0, v4, v5
	v_cvt_pk_bf16_f32 v1, v6, v7
	s_nop 0
	v_cvt_pk_bf16_f32 v2, v2, v3
	v_cvt_pk_bf16_f32 v3, v10, v11
	global_store_dwordx4 v[22:23], v[0:3], off
	s_cbranch_vccz .LBB0_1199
	s_waitcnt vmcnt(0)
	s_cmpk_gt_u32 s23, 0xff
	s_cbranch_scc1 .LBB0_1206
	s_barrier

; #define PG8_STAGE(bufoff, gbase, voff) do { _Pragma("unroll") for (int _i = 0; _i < 2; ++_i) \
;         __builtin_amdgcn_global_load_lds((const unsigned*)((const char*)(gbase) + (voff)[_i]), (PG8_LAS unsigned*)(lds + (bufoff) + ldsw + _i * 8192), 16, 0, 0); } while (0)
; #define PG8_LDA(dst, b, h) do { _Pragma("unroll") for (int m = 0; m < 4; ++m) _Pragma("unroll") for (int k = 0; k < 2; ++k) dst[m][k] = *(const PG8_LAS bf16x8*)(lds + PG8_SA(b, h) + aoff + m * 2048 + k * 1024); } while (0)
; #define PG8_LDB(dst, b, h) do { _Pragma("unroll") for (int n = 0; n < 2; ++n) _Pragma("unroll") for (int k = 0; k < 2; ++k) dst[n][k] = *(const PG8_LAS bf16x8*)(lds + PG8_SB(b, h) + boff + n * 2048 + k * 1024); } while (0)
; #define PG8_MMA(ai, bj, At, Bt) do { __builtin_amdgcn_s_setprio(1); _Pragma("unroll") for (int m = 0; m < 4; ++m) _Pragma("unroll") for (int n = 0; n < 2; ++n) _Pragma("unroll") for (int k = 0; k < 2; ++k) \
;         acc[ai][bj][m][n] = __builtin_amdgcn_mfma_f32_16x16x32_bf16(Bt[n][k], At[m][k], acc[ai][bj][m][n], 0, 0, 0); __builtin_amdgcn_s_setprio(0); } while (0)
; #define PG8_WAIT_L(n) asm volatile("s_waitcnt lgkmcnt(" #n ")" ::: "memory")
; #define PG8_BAR __builtin_amdgcn_s_barrier()
; #define PG8_SCHED __builtin_amdgcn_sched_barrier(0)
; template <class Epi, class Sched>
; __device__ __forceinline__ void gemm_phase(PG8_LAS unsigned char* lds, const Gemm g, const Sched& S, const Epi& E) {
;     ...
;             PG8_LDB(B0, 0, 0); PG8_SCHED; PG8_LDA(At, 0, 0); PG8_STAGE(PG8_SA(1, 1), a1 + hstep, voffA);
;             PG8_WAIT_L(8); PG8_BAR; PG8_WAIT_L(0); PG8_MMA(0, 0, At, B0); PG8_BAR; PG8_SCHED;
;             PG8_LDB(B1, 0, 1); PG8_STAGE(PG8_SB(0, 0), b2, voffB);
;             PG8_BAR; PG8_WAIT_L(0); PG8_MMA(0, 1, At, B1); PG8_BAR;
;             PG8_LDA(At, 0, 1); PG8_STAGE(PG8_SA(0, 0), a2, voffA);
;             PG8_BAR; PG8_WAIT_L(0); PG8_MMA(1, 0, At, B0); PG8_BAR; PG8_SCHED;
.LBB0_1278:
	ds_read_b128 v[152:155], v149
	ds_read_b128 v[156:159], v149 offset:1024
	ds_read_b128 v[160:163], v149 offset:2048
	ds_read_b128 v[164:167], v149 offset:3072
	s_add_u32 s20, s18, 0x100
	s_addc_u32 s21, s19, 0
	s_cmp_eq_u32 s54, 40
	s_cselect_b32 s25, s1, s21
	s_cselect_b32 s24, s0, s20
	s_cselect_b32 s23, s5, s53
	s_cselect_b32 s22, s4, s52
	v_lshl_add_u64 v[144:145], s[18:19], 0, v[136:137]
	s_add_i32 m0, s34, 0xc000
	ds_read_b128 v[168:171], v150
	ds_read_b128 v[172:175], v150 offset:1024
	ds_read_b128 v[182:185], v150 offset:2048
	ds_read_b128 v[190:193], v150 offset:3072
	ds_read_b128 v[194:197], v150 offset:4096
	ds_read_b128 v[198:201], v150 offset:5120
	ds_read_b128 v[202:205], v150 offset:6144
	ds_read_b128 v[206:209], v150 offset:7168
	global_load_lds_dwordx4 v[144:145], off
	v_lshl_add_u64 v[144:145], s[18:19], 0, v[138:139]
	s_add_i32 m0, s34, 0xe000
	s_nop 0
	global_load_lds_dwordx4 v[144:145], off
	s_waitcnt lgkmcnt(8)
	s_barrier
	s_waitcnt lgkmcnt(0)
	v_mfma_f32_16x16x32_bf16 v[124:127], v[152:155], v[168:171], v[124:127]
	v_mfma_f32_16x16x32_bf16 v[120:123], v[160:163], v[168:171], v[120:123]
	v_mfma_f32_16x16x32_bf16 v[108:111], v[152:155], v[182:185], v[108:111]
	v_mfma_f32_16x16x32_bf16 v[104:107], v[160:163], v[182:185], v[104:107]
	v_mfma_f32_16x16x32_bf16 v[92:95], v[152:155], v[194:197], v[92:95]
	v_mfma_f32_16x16x32_bf16 v[88:91], v[160:163], v[194:197], v[88:91]
	v_mfma_f32_16x16x32_bf16 v[76:79], v[152:155], v[202:205], v[76:79]
	v_mfma_f32_16x16x32_bf16 v[72:75], v[160:163], v[202:205], v[72:75]
	v_mfma_f32_16x16x32_bf16 v[124:127], v[156:159], v[172:175], v[124:127]
	v_mfma_f32_16x16x32_bf16 v[120:123], v[164:167], v[172:175], v[120:123]
	v_mfma_f32_16x16x32_bf16 v[108:111], v[156:159], v[190:193], v[108:111]
	v_mfma_f32_16x16x32_bf16 v[104:107], v[164:167], v[190:193], v[104:107]
	v_mfma_f32_16x16x32_bf16 v[92:95], v[156:159], v[198:201], v[92:95]
	v_mfma_f32_16x16x32_bf16 v[88:91], v[164:167], v[198:201], v[88:91]
	v_mfma_f32_16x16x32_bf16 v[76:79], v[156:159], v[206:209], v[76:79]
	v_mfma_f32_16x16x32_bf16 v[72:75], v[164:167], v[206:209], v[72:75]
	s_barrier
	s_add_i32 s18, s42, s31
	v_lshl_add_u64 v[144:145], s[22:23], 0, v[130:131]
	s_mov_b32 m0, s18
	ds_read_b128 v[210:213], v151
	ds_read_b128 v[214:217], v151 offset:1024
	ds_read_b128 v[218:221], v151 offset:2048
	ds_read_b128 v[222:225], v151 offset:3072
	global_load_lds_dwordx4 v[144:145], off
	v_lshl_add_u64 v[186:187], s[22:23], 0, v[134:135]
	s_add_i32 m0, s18, 0x2000
	s_nop 0
	global_load_lds_dwordx4 v[186:187], off
	s_barrier
	s_waitcnt lgkmcnt(0)
	v_mfma_f32_16x16x32_bf16 v[116:119], v[210:213], v[168:171], v[116:119]
	v_mfma_f32_16x16x32_bf16 v[112:115], v[218:221], v[168:171], v[112:115]
	v_mfma_f32_16x16x32_bf16 v[100:103], v[210:213], v[182:185], v[100:103]
	v_mfma_f32_16x16x32_bf16 v[96:99], v[218:221], v[182:185], v[96:99]
	v_mfma_f32_16x16x32_bf16 v[84:87], v[210:213], v[194:197], v[84:87]
	v_mfma_f32_16x16x32_bf16 v[80:83], v[218:221], v[194:197], v[80:83]
	v_mfma_f32_16x16x32_bf16 v[68:71], v[210:213], v[202:205], v[68:71]
	v_mfma_f32_16x16x32_bf16 v[64:67], v[218:221], v[202:205], v[64:67]
	v_mfma_f32_16x16x32_bf16 v[116:119], v[214:217], v[172:175], v[116:119]
	v_mfma_f32_16x16x32_bf16 v[112:115], v[222:225], v[172:175], v[112:115]
	v_mfma_f32_16x16x32_bf16 v[100:103], v[214:217], v[190:193], v[100:103]
	v_mfma_f32_16x16x32_bf16 v[96:99], v[222:225], v[190:193], v[96:99]
	v_mfma_f32_16x16x32_bf16 v[84:87], v[214:217], v[198:201], v[84:87]
	v_mfma_f32_16x16x32_bf16 v[80:83], v[222:225], v[198:201], v[80:83]
	v_mfma_f32_16x16x32_bf16 v[68:71], v[214:217], v[206:209], v[68:71]
	v_mfma_f32_16x16x32_bf16 v[64:67], v[222:225], v[206:209], v[64:67]
	s_mov_b32 m0, s34
	v_lshl_add_u64 v[226:227], s[24:25], 0, v[128:129]
	s_barrier
	ds_read_b128 v[168:171], v150 offset:16384
	ds_read_b128 v[172:175], v150 offset:17408
	ds_read_b128 v[182:185], v150 offset:18432
	ds_read_b128 v[190:193], v150 offset:19456
	ds_read_b128 v[194:197], v150 offset:20480
	ds_read_b128 v[198:201], v150 offset:21504
	ds_read_b128 v[202:205], v150 offset:22528
	ds_read_b128 v[206:209], v150 offset:23552
	global_load_lds_dwordx4 v[226:227], off
	v_lshl_add_u64 v[228:229], s[24:25], 0, v[132:133]
	s_mov_b32 m0, s35
	s_nop 0
	global_load_lds_dwordx4 v[228:229], off
	s_barrier
	s_waitcnt lgkmcnt(0)
	v_mfma_f32_16x16x32_bf16 v[60:63], v[152:155], v[168:171], v[60:63]
	v_mfma_f32_16x16x32_bf16 v[56:59], v[160:163], v[168:171], v[56:59]
	v_mfma_f32_16x16x32_bf16 v[48:51], v[152:155], v[182:185], v[48:51]
	v_mfma_f32_16x16x32_bf16 v[40:43], v[160:163], v[182:185], v[40:43]
	v_mfma_f32_16x16x32_bf16 v[32:35], v[152:155], v[194:197], v[32:35]
	v_mfma_f32_16x16x32_bf16 v[24:27], v[160:163], v[194:197], v[24:27]
	v_mfma_f32_16x16x32_bf16 v[16:19], v[152:155], v[202:205], v[16:19]
	v_mfma_f32_16x16x32_bf16 v[8:11], v[160:163], v[202:205], v[8:11]
	v_mfma_f32_16x16x32_bf16 v[60:63], v[156:159], v[172:175], v[60:63]
	v_mfma_f32_16x16x32_bf16 v[56:59], v[164:167], v[172:175], v[56:59]
	v_mfma_f32_16x16x32_bf16 v[48:51], v[156:159], v[190:193], v[48:51]
	v_mfma_f32_16x16x32_bf16 v[40:43], v[164:167], v[190:193], v[40:43]
	v_mfma_f32_16x16x32_bf16 v[32:35], v[156:159], v[198:201], v[32:35]
	v_mfma_f32_16x16x32_bf16 v[24:27], v[164:167], v[198:201], v[24:27]
	v_mfma_f32_16x16x32_bf16 v[16:19], v[156:159], v[206:209], v[16:19]
	v_mfma_f32_16x16x32_bf16 v[8:11], v[164:167], v[206:209], v[8:11]
	s_barrier
; #define PG8_STAGE(bufoff, gbase, voff) do { _Pragma("unroll") for (int _i = 0; _i < 2; ++_i) \
;         __builtin_amdgcn_global_load_lds((const unsigned*)((const char*)(gbase) + (voff)[_i]), (PG8_LAS unsigned*)(lds + (bufoff) + ldsw + _i * 8192), 16, 0, 0); } while (0)
; #define PG8_LDA(dst, b, h) do { _Pragma("unroll") for (int m = 0; m < 4; ++m) _Pragma("unroll") for (int k = 0; k < 2; ++k) dst[m][k] = *(const PG8_LAS bf16x8*)(lds + PG8_SA(b, h) + aoff + m * 2048 + k * 1024); } while (0)
; #define PG8_LDB(dst, b, h) do { _Pragma("unroll") for (int n = 0; n < 2; ++n) _Pragma("unroll") for (int k = 0; k < 2; ++k) dst[n][k] = *(const PG8_LAS bf16x8*)(lds + PG8_SB(b, h) + boff + n * 2048 + k * 1024); } while (0)
; #define PG8_MMA(ai, bj, At, Bt) do { __builtin_amdgcn_s_setprio(1); _Pragma("unroll") for (int m = 0; m < 4; ++m) _Pragma("unroll") for (int n = 0; n < 2; ++n) _Pragma("unroll") for (int k = 0; k < 2; ++k) \
;         acc[ai][bj][m][n] = __builtin_amdgcn_mfma_f32_16x16x32_bf16(Bt[n][k], At[m][k], acc[ai][bj][m][n], 0, 0, 0); __builtin_amdgcn_s_setprio(0); } while (0)
; #define PG8_WAIT_V(n) asm volatile("s_waitcnt vmcnt(" #n ")" ::: "memory")
; #define PG8_WAIT_L(n) asm volatile("s_waitcnt lgkmcnt(" #n ")" ::: "memory")
; #define PG8_BAR __builtin_amdgcn_s_barrier()
; #define PG8_SCHED __builtin_amdgcn_sched_barrier(0)
; template <class Epi, class Sched>
; __device__ __forceinline__ void gemm_phase(PG8_LAS unsigned char* lds, const Gemm g, const Sched& S, const Epi& E) {
;     ...
;             PG8_STAGE(PG8_SB(0, 1), b2 + hstep, voffB);
;             PG8_WAIT_V(6); PG8_BAR; PG8_MMA(1, 1, At, B1); PG8_BAR;
;             PG8_LDB(B0, 1, 0); PG8_SCHED; PG8_LDA(At, 1, 0); PG8_STAGE(PG8_SA(0, 1), a2 + hstep, voffA);
;             PG8_WAIT_L(8); PG8_BAR; PG8_WAIT_L(0); PG8_MMA(0, 0, At, B0); PG8_BAR; PG8_SCHED;
;             PG8_LDB(B1, 1, 1); PG8_STAGE(PG8_SB(1, 0), b3, voffB);
;             PG8_BAR; PG8_WAIT_L(0); PG8_MMA(0, 1, At, B1); PG8_BAR;
;             PG8_LDA(At, 1, 1); PG8_STAGE(PG8_SA(1, 0), a3, voffA);
	s_add_u32 s18, s22, 0xb0000
	s_addc_u32 s19, s23, 0
	s_add_i32 s55, s43, s31
	v_lshl_add_u64 v[152:153], s[18:19], 0, v[130:131]
	s_mov_b32 m0, s55
	s_nop 0
	global_load_lds_dwordx4 v[152:153], off
	v_lshl_add_u64 v[152:153], s[18:19], 0, v[134:135]
	s_add_i32 m0, s55, 0x2000
	s_nop 0
	global_load_lds_dwordx4 v[152:153], off
	s_waitcnt vmcnt(6)
	s_barrier
	v_mfma_f32_16x16x32_bf16 v[52:55], v[210:213], v[168:171], v[52:55]
	v_mfma_f32_16x16x32_bf16 v[44:47], v[218:221], v[168:171], v[44:47]
	v_mfma_f32_16x16x32_bf16 v[36:39], v[210:213], v[182:185], v[36:39]
	v_mfma_f32_16x16x32_bf16 v[28:31], v[218:221], v[182:185], v[28:31]
	v_mfma_f32_16x16x32_bf16 v[20:23], v[210:213], v[194:197], v[20:23]
	v_mfma_f32_16x16x32_bf16 v[12:15], v[218:221], v[194:197], v[12:15]
	v_mfma_f32_16x16x32_bf16 v[4:7], v[210:213], v[202:205], v[4:7]
	v_mfma_f32_16x16x32_bf16 v[0:3], v[218:221], v[202:205], v[0:3]
	v_mfma_f32_16x16x32_bf16 v[52:55], v[214:217], v[172:175], v[52:55]
	v_mfma_f32_16x16x32_bf16 v[44:47], v[222:225], v[172:175], v[44:47]
	v_mfma_f32_16x16x32_bf16 v[36:39], v[214:217], v[190:193], v[36:39]
	v_mfma_f32_16x16x32_bf16 v[28:31], v[222:225], v[190:193], v[28:31]
	v_mfma_f32_16x16x32_bf16 v[20:23], v[214:217], v[198:201], v[20:23]
	v_mfma_f32_16x16x32_bf16 v[12:15], v[222:225], v[198:201], v[12:15]
	v_mfma_f32_16x16x32_bf16 v[4:7], v[214:217], v[206:209], v[4:7]
	v_mfma_f32_16x16x32_bf16 v[0:3], v[222:225], v[206:209], v[0:3]
	s_add_i32 s55, 0, 0x18000
	v_add_u32_e32 v164, s55, v147
	s_barrier
	ds_read_b128 v[152:155], v164
	ds_read_b128 v[156:159], v164 offset:1024
	ds_read_b128 v[160:163], v164 offset:2048
	ds_read_b128 v[164:167], v164 offset:3072
	s_add_u32 s18, s24, 0xb0000
	s_addc_u32 s19, s25, 0
	s_mov_b32 m0, s36
	v_lshl_add_u64 v[210:211], s[18:19], 0, v[128:129]
	ds_read_b128 v[168:171], v150 offset:32768
	ds_read_b128 v[172:175], v150 offset:33792
	ds_read_b128 v[182:185], v150 offset:34816
	ds_read_b128 v[190:193], v150 offset:35840
	ds_read_b128 v[194:197], v150 offset:36864
	ds_read_b128 v[198:201], v150 offset:37888
	ds_read_b128 v[202:205], v150 offset:38912
	ds_read_b128 v[206:209], v150 offset:39936
	global_load_lds_dwordx4 v[210:211], off
	v_lshl_add_u64 v[210:211], s[18:19], 0, v[132:133]
	s_mov_b32 m0, s37
	s_nop 0
	global_load_lds_dwordx4 v[210:211], off
	s_waitcnt lgkmcnt(8)
	s_barrier
	s_waitcnt lgkmcnt(0)
	v_mfma_f32_16x16x32_bf16 v[124:127], v[152:155], v[168:171], v[124:127]
	v_mfma_f32_16x16x32_bf16 v[120:123], v[160:163], v[168:171], v[120:123]
	v_mfma_f32_16x16x32_bf16 v[108:111], v[152:155], v[182:185], v[108:111]
	v_mfma_f32_16x16x32_bf16 v[104:107], v[160:163], v[182:185], v[104:107]
	v_mfma_f32_16x16x32_bf16 v[92:95], v[152:155], v[194:197], v[92:95]
	v_mfma_f32_16x16x32_bf16 v[88:91], v[160:163], v[194:197], v[88:91]
	v_mfma_f32_16x16x32_bf16 v[76:79], v[152:155], v[202:205], v[76:79]
	v_mfma_f32_16x16x32_bf16 v[72:75], v[160:163], v[202:205], v[72:75]
	v_mfma_f32_16x16x32_bf16 v[124:127], v[156:159], v[172:175], v[124:127]
	v_mfma_f32_16x16x32_bf16 v[120:123], v[164:167], v[172:175], v[120:123]
	v_mfma_f32_16x16x32_bf16 v[108:111], v[156:159], v[190:193], v[108:111]
	v_mfma_f32_16x16x32_bf16 v[104:107], v[164:167], v[190:193], v[104:107]
	v_mfma_f32_16x16x32_bf16 v[92:95], v[156:159], v[198:201], v[92:95]
	v_mfma_f32_16x16x32_bf16 v[88:91], v[164:167], v[198:201], v[88:91]
	v_mfma_f32_16x16x32_bf16 v[76:79], v[156:159], v[206:209], v[76:79]
	v_mfma_f32_16x16x32_bf16 v[72:75], v[164:167], v[206:209], v[72:75]
	s_barrier
	s_add_i32 s24, 0, 0x1c000
	s_add_i32 s18, s55, s31
	v_add_u32_e32 v179, s24, v147
	v_lshl_add_u64 v[144:145], v[144:145], 0, s[8:9]
	s_mov_b32 m0, s18
	ds_read_b128 v[210:213], v179
	ds_read_b128 v[214:217], v179 offset:1024
	ds_read_b128 v[218:221], v179 offset:2048
	ds_read_b128 v[222:225], v179 offset:3072
	global_load_lds_dwordx4 v[144:145], off
	v_lshl_add_u64 v[144:145], v[186:187], 0, s[8:9]
	s_add_i32 m0, s18, 0x2000
	s_nop 0
	global_load_lds_dwordx4 v[144:145], off
	s_barrier
	s_waitcnt lgkmcnt(0)
	v_mfma_f32_16x16x32_bf16 v[116:119], v[210:213], v[168:171], v[116:119]
	v_mfma_f32_16x16x32_bf16 v[112:115], v[218:221], v[168:171], v[112:115]
	v_mfma_f32_16x16x32_bf16 v[100:103], v[210:213], v[182:185], v[100:103]
	v_mfma_f32_16x16x32_bf16 v[96:99], v[218:221], v[182:185], v[96:99]
	v_mfma_f32_16x16x32_bf16 v[84:87], v[210:213], v[194:197], v[84:87]
	v_mfma_f32_16x16x32_bf16 v[80:83], v[218:221], v[194:197], v[80:83]
	v_mfma_f32_16x16x32_bf16 v[68:71], v[210:213], v[202:205], v[68:71]
	v_mfma_f32_16x16x32_bf16 v[64:67], v[218:221], v[202:205], v[64:67]
	v_mfma_f32_16x16x32_bf16 v[116:119], v[214:217], v[172:175], v[116:119]
	v_mfma_f32_16x16x32_bf16 v[112:115], v[222:225], v[172:175], v[112:115]
	v_mfma_f32_16x16x32_bf16 v[100:103], v[214:217], v[190:193], v[100:103]
	v_mfma_f32_16x16x32_bf16 v[96:99], v[222:225], v[190:193], v[96:99]
	v_mfma_f32_16x16x32_bf16 v[84:87], v[214:217], v[198:201], v[84:87]
	v_mfma_f32_16x16x32_bf16 v[80:83], v[222:225], v[198:201], v[80:83]
	v_mfma_f32_16x16x32_bf16 v[68:71], v[214:217], v[206:209], v[68:71]
	v_mfma_f32_16x16x32_bf16 v[64:67], v[222:225], v[206:209], v[64:67]
	s_mov_b32 m0, s39
	v_lshl_add_u64 v[144:145], v[226:227], 0, s[8:9]
	s_barrier
	ds_read_b128 v[168:171], v150 offset:49152
	ds_read_b128 v[172:175], v150 offset:50176
	ds_read_b128 v[182:185], v150 offset:51200
	ds_read_b128 v[190:193], v150 offset:52224
	ds_read_b128 v[194:197], v150 offset:53248
	ds_read_b128 v[198:201], v150 offset:54272
	ds_read_b128 v[202:205], v150 offset:55296
	ds_read_b128 v[206:209], v150 offset:56320
	global_load_lds_dwordx4 v[144:145], off
	v_lshl_add_u64 v[144:145], v[228:229], 0, s[8:9]
	s_mov_b32 m0, s40
	s_nop 0
	global_load_lds_dwordx4 v[144:145], off
	s_barrier
; __device__ __forceinline__ unsigned cvt_pk_bf16(float lo, float hi) { unsigned r; asm volatile("v_cvt_pk_bf16_f32 %0, %1, %2" : "=v"(r) : "v"(lo), "v"(hi)); return r; }
; __device__ __forceinline__ float flogsig16(float x) { return (fminf(x, 0.f) - __logf(1.0f + __expf(-fabsf(x)))) * 0.0625f; }
; #define PG8_STAGE(bufoff, gbase, voff) do { _Pragma("unroll") for (int _i = 0; _i < 2; ++_i) \
;         __builtin_amdgcn_global_load_lds((const unsigned*)((const char*)(gbase) + (voff)[_i]), (PG8_LAS unsigned*)(lds + (bufoff) + ldsw + _i * 8192), 16, 0, 0); } while (0)
; #define PG8_WAIT_V(n) asm volatile("s_waitcnt vmcnt(" #n ")" ::: "memory")
; #define PG8_WAIT_L(n) asm volatile("s_waitcnt lgkmcnt(" #n ")" ::: "memory")
; #define PG8_BAR __builtin_amdgcn_s_barrier()
; #define PG8_SCHED __builtin_amdgcn_sched_barrier(0)
;     __device__ __forceinline__ void operator()(const f32x4 (&acc)[2][2][4][2], const Unit& u, int wr, int wc, int fr, int fq) const {
;     ...
;             for (int m = 0; m < 4; ++m) { bf16_t* rowp = O + (size_t)(row0 + ai * HALF + m * 16) * ldc + col0;
; #pragma unroll
;                 for (int bj = 0; bj < 2; ++bj) { f32x4 v0 = acc[ai][bj][m][0] + bv[bj][0], v1 = acc[ai][bj][m][1] + bv[bj][1];
;                     if (act == 1) {
; #pragma unroll
;                         for (int j = 0; j < 1; ++j) { v0 = v0 * sigmoid4(v0); v1 = v1 * sigmoid4(v1); } }
;                     else if (act == 2) {
; #pragma unroll
;                         for (int j = 0; j < 1; ++j) { v0 = sigmoid4(v0); v1 = sigmoid4(v1); } }
;                     else if (act == 3) {
; #pragma unroll
;                         for (int j = 0; j < 4; ++j) { v0[j] = flogsig16(v0[j]); v1[j] = flogsig16(v1[j]); } }
;                     u32x4 w; w.x = cvt_pk_bf16(v0[0], v0[1]); w.y = cvt_pk_bf16(v0[2], v0[3]); w.z = cvt_pk_bf16(v1[0], v1[1]); w.w = cvt_pk_bf16(v1[2], v1[3]);
;                     *(u32x4*)(rowp + bj * HALF) = w; } }
; template <class Epi, class Sched>
; __device__ __forceinline__ void gemm_phase(PG8_LAS unsigned char* lds, const Gemm g, const Sched& S, const Epi& E) {
;     ...
;             PG8_BAR; PG8_WAIT_L(0); PG8_MMA(1, 0, At, B0); PG8_BAR; PG8_SCHED;
;             PG8_STAGE(PG8_SB(1, 1), b3 + hstep, voffB);
;             PG8_WAIT_V(6); PG8_BAR; PG8_MMA(1, 1, At, B1); PG8_BAR;
	s_waitcnt lgkmcnt(0)
	v_mfma_f32_16x16x32_bf16 v[60:63], v[152:155], v[168:171], v[60:63]
	v_mfma_f32_16x16x32_bf16 v[56:59], v[160:163], v[168:171], v[56:59]
	v_mfma_f32_16x16x32_bf16 v[48:51], v[152:155], v[182:185], v[48:51]
	v_mfma_f32_16x16x32_bf16 v[40:43], v[160:163], v[182:185], v[40:43]
	v_mfma_f32_16x16x32_bf16 v[32:35], v[152:155], v[194:197], v[32:35]
	v_mfma_f32_16x16x32_bf16 v[24:27], v[160:163], v[194:197], v[24:27]
	v_mfma_f32_16x16x32_bf16 v[16:19], v[152:155], v[202:205], v[16:19]
	v_mfma_f32_16x16x32_bf16 v[8:11], v[160:163], v[202:205], v[8:11]
	v_mfma_f32_16x16x32_bf16 v[60:63], v[156:159], v[172:175], v[60:63]
	v_mfma_f32_16x16x32_bf16 v[56:59], v[164:167], v[172:175], v[56:59]
	v_mfma_f32_16x16x32_bf16 v[48:51], v[156:159], v[190:193], v[48:51]
	v_mfma_f32_16x16x32_bf16 v[40:43], v[164:167], v[190:193], v[40:43]
	v_mfma_f32_16x16x32_bf16 v[32:35], v[156:159], v[198:201], v[32:35]
	v_mfma_f32_16x16x32_bf16 v[24:27], v[164:167], v[198:201], v[24:27]
	v_mfma_f32_16x16x32_bf16 v[16:19], v[156:159], v[206:209], v[16:19]
	v_mfma_f32_16x16x32_bf16 v[8:11], v[164:167], v[206:209], v[8:11]
	s_barrier
	s_add_u32 s18, s22, 0xb0080
	s_addc_u32 s19, s23, 0
	s_add_i32 s22, s24, s31
	v_lshl_add_u64 v[144:145], s[18:19], 0, v[130:131]
	s_mov_b32 m0, s22
	s_nop 0
	global_load_lds_dwordx4 v[144:145], off
	v_lshl_add_u64 v[144:145], s[18:19], 0, v[134:135]
	s_add_i32 m0, s22, 0x2000
	s_nop 0
	global_load_lds_dwordx4 v[144:145], off
	s_waitcnt vmcnt(6)
	s_barrier
	v_mfma_f32_16x16x32_bf16 v[52:55], v[210:213], v[168:171], v[52:55]
	v_mfma_f32_16x16x32_bf16 v[44:47], v[218:221], v[168:171], v[44:47]
	v_mfma_f32_16x16x32_bf16 v[36:39], v[210:213], v[182:185], v[36:39]
	v_mfma_f32_16x16x32_bf16 v[28:31], v[218:221], v[182:185], v[28:31]
	v_mfma_f32_16x16x32_bf16 v[20:23], v[210:213], v[194:197], v[20:23]
	v_mfma_f32_16x16x32_bf16 v[12:15], v[218:221], v[194:197], v[12:15]
	v_mfma_f32_16x16x32_bf16 v[4:7], v[210:213], v[202:205], v[4:7]
	v_mfma_f32_16x16x32_bf16 v[0:3], v[218:221], v[202:205], v[0:3]
	v_mfma_f32_16x16x32_bf16 v[52:55], v[214:217], v[172:175], v[52:55]
	v_mfma_f32_16x16x32_bf16 v[44:47], v[222:225], v[172:175], v[44:47]
	v_mfma_f32_16x16x32_bf16 v[36:39], v[214:217], v[190:193], v[36:39]
	v_mfma_f32_16x16x32_bf16 v[28:31], v[222:225], v[190:193], v[28:31]
	v_mfma_f32_16x16x32_bf16 v[20:23], v[214:217], v[198:201], v[20:23]
	v_mfma_f32_16x16x32_bf16 v[12:15], v[222:225], v[198:201], v[12:15]
	v_mfma_f32_16x16x32_bf16 v[4:7], v[214:217], v[206:209], v[4:7]
	v_mfma_f32_16x16x32_bf16 v[0:3], v[222:225], v[206:209], v[0:3]
	s_add_i32 s54, s54, 2
	s_add_u32 s52, s52, 0x100
	s_addc_u32 s53, s53, 0
	s_cmp_gt_u32 s54, 41
	s_mov_b64 s[18:19], s[20:21]
	s_barrier
	s_cbranch_scc0 .LBB0_1278
	v_lshl_add_u32 v152, s50, 8, v146
	v_lshl_or_b32 v144, s51, 8, v148
	v_ashrrev_i32_e32 v153, 31, v152
	v_ashrrev_i32_e32 v145, 31, v144
	v_lshlrev_b64 v[154:155], 11, v[152:153]
	v_lshl_add_u64 v[154:155], s[6:7], 0, v[154:155]
	v_lshlrev_b64 v[156:157], 1, v[144:145]
	v_lshl_add_u64 v[144:145], v[154:155], 0, v[156:157]
	v_pk_add_f32 v[126:127], v[126:127], 0 op_sel_hi:[1,0]
	v_pk_add_f32 v[124:125], v[124:125], 0 op_sel_hi:[1,0]
	v_pk_add_f32 v[154:155], v[122:123], 0 op_sel_hi:[1,0]
	v_pk_add_f32 v[122:123], v[120:121], 0 op_sel_hi:[1,0]
	v_cvt_pk_bf16_f32 v120, v124, v125
	v_cvt_pk_bf16_f32 v121, v126, v127
	v_pk_add_f32 v[116:117], v[116:117], 0 op_sel_hi:[1,0]
	v_cvt_pk_bf16_f32 v122, v122, v123
	v_cvt_pk_bf16_f32 v123, v154, v155
	global_store_dwordx4 v[144:145], v[120:123], off
	v_pk_add_f32 v[118:119], v[118:119], 0 op_sel_hi:[1,0]
	v_pk_add_f32 v[110:111], v[110:111], 0 op_sel_hi:[1,0]
	v_pk_add_f32 v[120:121], v[114:115], 0 op_sel_hi:[1,0]
	v_pk_add_f32 v[114:115], v[112:113], 0 op_sel_hi:[1,0]
	v_cvt_pk_bf16_f32 v112, v116, v117
	v_cvt_pk_bf16_f32 v113, v118, v119
	v_pk_add_f32 v[108:109], v[108:109], 0 op_sel_hi:[1,0]
	v_cvt_pk_bf16_f32 v114, v114, v115
	v_cvt_pk_bf16_f32 v115, v120, v121
	global_store_dwordx4 v[144:145], v[112:115], off offset:256
	v_pk_add_f32 v[100:101], v[100:101], 0 op_sel_hi:[1,0]
	v_pk_add_f32 v[102:103], v[102:103], 0 op_sel_hi:[1,0]
	v_or_b32_e32 v112, 16, v152
	v_ashrrev_i32_e32 v113, 31, v112
	v_lshlrev_b64 v[112:113], 11, v[112:113]
	v_lshl_add_u64 v[112:113], s[6:7], 0, v[112:113]
	v_lshl_add_u64 v[112:113], v[112:113], 0, v[156:157]
	v_pk_add_f32 v[114:115], v[106:107], 0 op_sel_hi:[1,0]
	v_pk_add_f32 v[106:107], v[104:105], 0 op_sel_hi:[1,0]
	v_cvt_pk_bf16_f32 v104, v108, v109
	v_cvt_pk_bf16_f32 v105, v110, v111
	v_pk_add_f32 v[94:95], v[94:95], 0 op_sel_hi:[1,0]
	v_cvt_pk_bf16_f32 v106, v106, v107
	v_cvt_pk_bf16_f32 v107, v114, v115
	global_store_dwordx4 v[112:113], v[104:107], off
	v_pk_add_f32 v[92:93], v[92:93], 0 op_sel_hi:[1,0]
	v_pk_add_f32 v[84:85], v[84:85], 0 op_sel_hi:[1,0]
	v_pk_add_f32 v[104:105], v[98:99], 0 op_sel_hi:[1,0]
	v_pk_add_f32 v[98:99], v[96:97], 0 op_sel_hi:[1,0]
	v_cvt_pk_bf16_f32 v96, v100, v101
	v_cvt_pk_bf16_f32 v97, v102, v103
	v_pk_add_f32 v[86:87], v[86:87], 0 op_sel_hi:[1,0]
	v_cvt_pk_bf16_f32 v98, v98, v99
	v_cvt_pk_bf16_f32 v99, v104, v105
	global_store_dwordx4 v[112:113], v[96:99], off offset:256
	v_pk_add_f32 v[78:79], v[78:79], 0 op_sel_hi:[1,0]
	v_pk_add_f32 v[76:77], v[76:77], 0 op_sel_hi:[1,0]
	v_or_b32_e32 v96, 32, v152
	v_ashrrev_i32_e32 v97, 31, v96
	v_lshlrev_b64 v[96:97], 11, v[96:97]
	v_lshl_add_u64 v[96:97], s[6:7], 0, v[96:97]
; __device__ __forceinline__ unsigned cvt_pk_bf16(float lo, float hi) { unsigned r; asm volatile("v_cvt_pk_bf16_f32 %0, %1, %2" : "=v"(r) : "v"(lo), "v"(hi)); return r; }
; __device__ __forceinline__ float flogsig16(float x) { return (fminf(x, 0.f) - __logf(1.0f + __expf(-fabsf(x)))) * 0.0625f; }
;     __device__ __forceinline__ void operator()(const f32x4 (&acc)[2][2][4][2], const Unit& u, int wr, int wc, int fr, int fq) const {
;     ...
;             for (int m = 0; m < 4; ++m) { bf16_t* rowp = O + (size_t)(row0 + ai * HALF + m * 16) * ldc + col0;
; #pragma unroll
;                 for (int bj = 0; bj < 2; ++bj) { f32x4 v0 = acc[ai][bj][m][0] + bv[bj][0], v1 = acc[ai][bj][m][1] + bv[bj][1];
;                     if (act == 1) {
; #pragma unroll
;                         for (int j = 0; j < 1; ++j) { v0 = v0 * sigmoid4(v0); v1 = v1 * sigmoid4(v1); } }
;                     else if (act == 2) {
; #pragma unroll
;                         for (int j = 0; j < 1; ++j) { v0 = sigmoid4(v0); v1 = sigmoid4(v1); } }
;                     else if (act == 3) {
; #pragma unroll
;                         for (int j = 0; j < 4; ++j) { v0[j] = flogsig16(v0[j]); v1[j] = flogsig16(v1[j]); } }
;                     u32x4 w; w.x = cvt_pk_bf16(v0[0], v0[1]); w.y = cvt_pk_bf16(v0[2], v0[3]); w.z = cvt_pk_bf16(v1[0], v1[1]); w.w = cvt_pk_bf16(v1[2], v1[3]);
;                     *(u32x4*)(rowp + bj * HALF) = w; } }
	v_lshl_add_u64 v[96:97], v[96:97], 0, v[156:157]
	v_pk_add_f32 v[98:99], v[90:91], 0 op_sel_hi:[1,0]
	v_pk_add_f32 v[90:91], v[88:89], 0 op_sel_hi:[1,0]
	v_cvt_pk_bf16_f32 v88, v92, v93
	v_cvt_pk_bf16_f32 v89, v94, v95
	v_pk_add_f32 v[70:71], v[70:71], 0 op_sel_hi:[1,0]
	v_cvt_pk_bf16_f32 v90, v90, v91
	v_cvt_pk_bf16_f32 v91, v98, v99
	global_store_dwordx4 v[96:97], v[88:91], off
	v_pk_add_f32 v[68:69], v[68:69], 0 op_sel_hi:[1,0]
	v_pk_add_f32 v[60:61], v[60:61], 0 op_sel_hi:[1,0]
	v_pk_add_f32 v[88:89], v[82:83], 0 op_sel_hi:[1,0]
	v_pk_add_f32 v[82:83], v[80:81], 0 op_sel_hi:[1,0]
	v_cvt_pk_bf16_f32 v80, v84, v85
	v_cvt_pk_bf16_f32 v81, v86, v87
	v_pk_add_f32 v[62:63], v[62:63], 0 op_sel_hi:[1,0]
	v_cvt_pk_bf16_f32 v82, v82, v83
	v_cvt_pk_bf16_f32 v83, v88, v89
	global_store_dwordx4 v[96:97], v[80:83], off offset:256
	v_pk_add_f32 v[54:55], v[54:55], 0 op_sel_hi:[1,0]
	v_pk_add_f32 v[52:53], v[52:53], 0 op_sel_hi:[1,0]
	v_or_b32_e32 v80, 48, v152
	v_ashrrev_i32_e32 v81, 31, v80
	v_lshlrev_b64 v[80:81], 11, v[80:81]
	v_lshl_add_u64 v[80:81], s[6:7], 0, v[80:81]
	v_lshl_add_u64 v[80:81], v[80:81], 0, v[156:157]
	v_pk_add_f32 v[82:83], v[74:75], 0 op_sel_hi:[1,0]
	v_pk_add_f32 v[74:75], v[72:73], 0 op_sel_hi:[1,0]
	v_cvt_pk_bf16_f32 v72, v76, v77
	v_cvt_pk_bf16_f32 v73, v78, v79
	v_pk_add_f32 v[48:49], v[48:49], 0 op_sel_hi:[1,0]
	v_cvt_pk_bf16_f32 v74, v74, v75
	v_cvt_pk_bf16_f32 v75, v82, v83
	global_store_dwordx4 v[80:81], v[72:75], off
	v_pk_add_f32 v[38:39], v[38:39], 0 op_sel_hi:[1,0]
	v_pk_add_f32 v[36:37], v[36:37], 0 op_sel_hi:[1,0]
	v_pk_add_f32 v[72:73], v[66:67], 0 op_sel_hi:[1,0]
	v_pk_add_f32 v[66:67], v[64:65], 0 op_sel_hi:[1,0]
	v_cvt_pk_bf16_f32 v64, v68, v69
	v_cvt_pk_bf16_f32 v65, v70, v71
	v_pk_add_f32 v[32:33], v[32:33], 0 op_sel_hi:[1,0]
	v_cvt_pk_bf16_f32 v66, v66, v67
	v_cvt_pk_bf16_f32 v67, v72, v73
	global_store_dwordx4 v[80:81], v[64:67], off offset:256
	v_pk_add_f32 v[22:23], v[22:23], 0 op_sel_hi:[1,0]
	v_pk_add_f32 v[20:21], v[20:21], 0 op_sel_hi:[1,0]
	v_pk_add_f32 v[66:67], v[58:59], 0 op_sel_hi:[1,0]
	v_pk_add_f32 v[58:59], v[56:57], 0 op_sel_hi:[1,0]
	v_cvt_pk_bf16_f32 v56, v60, v61
	v_add_co_u32_e32 v60, vcc, s44, v144
	v_cvt_pk_bf16_f32 v57, v62, v63
	v_cvt_pk_bf16_f32 v58, v58, v59
	v_cvt_pk_bf16_f32 v59, v66, v67
	v_lshl_add_u64 v[64:65], v[144:145], 0, s[10:11]
	s_nop 0
	v_addc_co_u32_e32 v61, vcc, 0, v145, vcc
	global_store_dwordx4 v[60:61], v[56:59], off
	v_pk_add_f32 v[16:17], v[16:17], 0 op_sel_hi:[1,0]
	s_mov_b32 s51, s48
	v_pk_add_f32 v[56:57], v[46:47], 0 op_sel_hi:[1,0]
	v_pk_add_f32 v[46:47], v[44:45], 0 op_sel_hi:[1,0]
	v_cvt_pk_bf16_f32 v44, v52, v53
	v_cvt_pk_bf16_f32 v45, v54, v55
	s_mov_b32 s50, s49
	v_cvt_pk_bf16_f32 v46, v46, v47
	v_cvt_pk_bf16_f32 v47, v56, v57
	global_store_dwordx4 v[64:65], v[44:47], off offset:256
	s_mov_b64 s[20:21], s[4:5]
	s_mov_b64 s[18:19], s[0:1]
	v_pk_add_f32 v[46:47], v[50:51], 0 op_sel_hi:[1,0]
	v_pk_add_f32 v[50:51], v[42:43], 0 op_sel_hi:[1,0]
	v_pk_add_f32 v[42:43], v[40:41], 0 op_sel_hi:[1,0]
	v_cvt_pk_bf16_f32 v40, v48, v49
	v_cvt_pk_bf16_f32 v41, v46, v47
	v_add_co_u32_e32 v46, vcc, s45, v144
	v_cvt_pk_bf16_f32 v42, v42, v43
	v_cvt_pk_bf16_f32 v43, v50, v51
	v_lshl_add_u64 v[44:45], v[144:145], 0, s[12:13]
	s_nop 0
	v_addc_co_u32_e32 v47, vcc, 0, v145, vcc
	global_store_dwordx4 v[46:47], v[40:43], off
	v_pk_add_f32 v[6:7], v[6:7], 0 op_sel_hi:[1,0]
	v_pk_add_f32 v[4:5], v[4:5], 0 op_sel_hi:[1,0]
	v_pk_add_f32 v[40:41], v[30:31], 0 op_sel_hi:[1,0]
	v_pk_add_f32 v[30:31], v[28:29], 0 op_sel_hi:[1,0]
	v_cvt_pk_bf16_f32 v28, v36, v37
	v_cvt_pk_bf16_f32 v29, v38, v39
	s_nop 0
	v_cvt_pk_bf16_f32 v30, v30, v31
	v_cvt_pk_bf16_f32 v31, v40, v41
	global_store_dwordx4 v[44:45], v[28:31], off offset:256
	s_nop 1
	v_pk_add_f32 v[30:31], v[34:35], 0 op_sel_hi:[1,0]
	v_pk_add_f32 v[34:35], v[26:27], 0 op_sel_hi:[1,0]
	v_pk_add_f32 v[26:27], v[24:25], 0 op_sel_hi:[1,0]
	v_cvt_pk_bf16_f32 v24, v32, v33
	v_cvt_pk_bf16_f32 v25, v30, v31
	v_add_co_u32_e32 v30, vcc, s46, v144
	v_cvt_pk_bf16_f32 v26, v26, v27
	v_cvt_pk_bf16_f32 v27, v34, v35
	v_lshl_add_u64 v[28:29], v[144:145], 0, s[14:15]
	s_nop 0
	v_addc_co_u32_e32 v31, vcc, 0, v145, vcc
	global_store_dwordx4 v[30:31], v[24:27], off
	s_nop 1
	v_pk_add_f32 v[24:25], v[14:15], 0 op_sel_hi:[1,0]
	v_pk_add_f32 v[14:15], v[12:13], 0 op_sel_hi:[1,0]
	v_cvt_pk_bf16_f32 v12, v20, v21
	v_cvt_pk_bf16_f32 v13, v22, v23
	s_nop 0
	v_cvt_pk_bf16_f32 v14, v14, v15
	v_cvt_pk_bf16_f32 v15, v24, v25
	global_store_dwordx4 v[28:29], v[12:15], off offset:256
	s_nop 1
	v_pk_add_f32 v[14:15], v[18:19], 0 op_sel_hi:[1,0]
	v_pk_add_f32 v[18:19], v[10:11], 0 op_sel_hi:[1,0]
	v_pk_add_f32 v[10:11], v[8:9], 0 op_sel_hi:[1,0]
	v_cvt_pk_bf16_f32 v8, v16, v17
	v_cvt_pk_bf16_f32 v9, v14, v15
	v_add_co_u32_e32 v14, vcc, s47, v144
	v_lshl_add_u64 v[12:13], v[144:145], 0, s[16:17]
	s_nop 0
	v_addc_co_u32_e32 v15, vcc, 0, v145, vcc
	v_cvt_pk_bf16_f32 v10, v10, v11
	v_cvt_pk_bf16_f32 v11, v18, v19
	global_store_dwordx4 v[14:15], v[8:11], off
	s_and_b64 vcc, exec, s[2:3]
	s_nop 0
	v_pk_add_f32 v[8:9], v[2:3], 0 op_sel_hi:[1,0]
	v_pk_add_f32 v[2:3], v[0:1], 0 op_sel_hi:[1,0]
	v_cvt_pk_bf16_f32 v0, v4, v5
	v_cvt_pk_bf16_f32 v1, v6, v7
	s_nop 0
	v_cvt_pk_bf16_f32 v2, v2, v3
	v_cvt_pk_bf16_f32 v3, v8, v9
	global_store_dwordx4 v[12:13], v[0:3], off offset:256
	s_cbranch_vccz .LBB0_1267
	s_waitcnt vmcnt(0)
	s_cmpk_gt_u32 s27, 0xff
	s_cbranch_scc1 .LBB0_1282
	s_barrier
